# one workgroup barrier per GEMM phase and wave half (two K-loop copies, stagger by barrier placement, MFMA prio 3 for the lagging half) on top of v20
# speedup vs baseline: 1.3363x; 1.0081x over previous
;     __host__ __device__ bool next(int i, Unit& u) const { const long L = (long)i * G + c; if (L >= nwg) return false; u.pm = 0; u.pn = c % nN; return true; }
; #define PG8_WAIT_V(n) asm volatile("s_waitcnt vmcnt(" #n ")" ::: "memory")
; #define PG8_BAR __builtin_amdgcn_s_barrier()
; template <class Epi, class Sched, bool ALIGN_EPI = false, bool SP2 = false, bool F8 = false>
; __device__ __forceinline__ void gemm_phase(PG8_LAS unsigned char* lds, const Gemm g, const Sched& S, const Epi& E) {
;     const int tid = threadIdx.x, wid = __builtin_amdgcn_readfirstlane(tid >> 6), lane = tid & 63, wr = wid >> 2, wc = wid & 3, fr = lane & 15, fq = lane >> 4;
;     const int K = g.K, nt = K / BK;
;     unsigned voffA[2], voffB[2];
; #pragma unroll
;     for (int i = 0; i < 2; ++i) { int R, C; stage_rc(tid * 16 + i * 8192, R, C); const int Rb = Epi::PERM ? ((R & ~31) + perm32(R & 31)) : R;
;         const int Ra = Epi::GRIDMAP ? ((R & 63) * 64 + (R >> 6)) : R;
;         voffA[i] = (unsigned)(Ra * K + C) * 2u; voffB[i] = (unsigned)(Rb * K + C) * 2u; }
;     const size_t kstep = (size_t)(BK * 2);
;     const size_t hstep = (size_t)HALF * K * 2;
;     const size_t tstep = 2 * hstep;
;     const size_t hstepA = Epi::GRIDMAP ? (size_t)4096 * K * 2 : hstep;
;     ...
;     const unsigned ldsw = (unsigned)wid * 1024u;
;     const int aoff = lds_byte(wr * 64 + fr, fq * 8), boff = lds_byte(wc * 32 + fr, fq * 8);
;     ...
;     Unit cur, nxt; int ui = 0;
;     if (!S.next(0, cur)) return;
;     f32x4 acc[2][2][4][2];
; #pragma unroll
;     for (int a = 0; a < 2; ++a)
; #pragma unroll
;         for (int b = 0; b < 2; ++b)
; #pragma unroll
;             for (int m = 0; m < 4; ++m)
; #pragma unroll
;                 for (int n = 0; n < 2; ++n) acc[a][b][m][n] = (f32x4){0.f, 0.f, 0.f, 0.f};
;     bf16x8 At[4][2], B0[2][2], B1[2][2];
;     const char* cA = PG8_ABASE(cur.pm); const char* cB = (const char*)g.Bt + (size_t)cur.pn * tstep;
;     S.a_ready(cur);
;     if constexpr (SP2) {
;         PG8_STAGE(PG8_SB(0, 0), cB, voffB); PG8_STAGE(PG8_SB(0, 1), cB + hstep, voffB); PG8_STAGE(PG8_SA(0, 0), cA, voffA); PG8_STAGE(PG8_SA(0, 1), cA + hstepA, voffA);
;         if (wr == 1) PG8_BAR;
;         PG8_WAIT_V(2); PG8_BAR;
;         PG8_STAGE(PG8_SB(1, 0), cB + kstep, voffB); PG8_STAGE(PG8_SA(1, 0), cA + kstep, voffA); PG8_STAGE(PG8_SB(1, 1), cB + hstep + kstep, voffB);
;         PG8_WAIT_V(6); PG8_BAR;
.LBB0_245:
	s_add_u32 s3, s18, 0x138000
	s_addc_u32 s21, s19, 0
	s_add_u32 s46, s18, 0x400000
	s_addc_u32 s47, s19, 0
	s_add_u32 s42, s18, 0xc00000
	s_addc_u32 s43, s19, 0
	s_add_u32 s80, s18, 0x3800000
	s_addc_u32 s81, s19, 0
	s_add_u32 s56, s18, 0x9000000
	s_addc_u32 s57, s19, 0
	s_add_u32 s38, s18, 0x9200000
	s_addc_u32 s39, s19, 0
	s_add_u32 s48, s18, 0xf200000
	s_addc_u32 s49, s19, 0
	s_cmp_lt_i32 s94, 3
	s_cselect_b64 s[4:5], -1, 0
	s_cmp_gt_i32 s95, 2
	s_cselect_b64 s[6:7], -1, 0
	s_and_b64 s[4:5], s[4:5], s[6:7]
	v_writelane_b32 v255, s80, 8
	s_andn2_b64 vcc, exec, s[4:5]
	s_nop 0
	v_writelane_b32 v255, s81, 9
	s_cbranch_vccnz .LBB0_533
	v_lshlrev_b32_e32 v1, 4, v0
	s_waitcnt vmcnt(15)
	v_and_b32_e32 v2, 32, v0
	v_bitop3_b32 v208, v1, v2, 48 bitop3:0x6c
	v_lshrrev_b32_e32 v2, 1, v0
	v_lshrrev_b32_e32 v3, 5, v0
	v_or_b32_e32 v211, 0x2000, v1
	v_bfe_u32 v210, v0, 2, 4
	v_and_b32_e32 v2, 24, v2
	v_and_b32_e32 v3, 4, v3
	v_bfe_u32 v4, v0, 2, 2
	v_lshrrev_b32_e32 v1, 7, v211
	s_movk_i32 s4, 0x70
	v_or3_b32 v2, v3, v4, v2
	v_and_or_b32 v220, v1, s4, v210
	s_movk_i32 s4, 0x60
	v_lshrrev_b32_e32 v3, 3, v0
	v_and_or_b32 v221, v1, s4, v2
	v_lshlrev_b32_e32 v1, 6, v0
	s_add_u32 s58, s18, 0x11200000
	v_and_or_b32 v219, v3, 32, v2
	v_bfe_u32 v254, v0, 4, 2
	v_and_b32_e32 v2, 0x3c0, v1
	v_lshlrev_b32_e32 v1, 2, v0
	s_addc_u32 s59, s19, 0
	v_and_b32_e32 v209, 64, v0
	v_and_or_b32 v218, v3, 48, v210
	v_lshlrev_b32_e32 v214, 4, v254
	v_and_b32_e32 v3, 32, v1
	v_readfirstlane_b32 s5, v0
	v_or_b32_e32 v217, v208, v209
	v_and_b32_e32 v163, 15, v0
	v_lshlrev_b32_e32 v229, 3, v254
	s_cmpk_gt_i32 s2, 0x6ff
	v_bitop3_b32 v215, v214, v3, v2 bitop3:0x36
	s_barrier
	s_cbranch_scc1 .LBB0_272
	s_ashr_i32 s93, s2, 31
	s_lshr_b32 s4, s93, 29
	s_add_i32 s4, s2, s4
	s_lshr_b32 s8, s5, 6
	s_ashr_i32 s7, s4, 3
	s_and_b32 s4, s4, -8
	s_lshr_b32 s6, s5, 8
	s_lshl_b32 s23, s8, 10
	s_sub_i32 s4, s2, s4
	s_cmp_lt_i32 s4, 0
	s_movk_i32 s94, 0xe1
	s_cselect_b32 s9, s94, 0xe0
	s_mul_i32 s4, s4, s9
	s_add_i32 s4, s4, s7
	s_mul_hi_i32 s7, s4, 0x92492493
	s_add_i32 s7, s7, s4
	s_lshr_b32 s9, s7, 31
	s_ashr_i32 s7, s7, 7
	s_add_i32 s7, s7, s9
	s_lshl_b32 s9, s7, 3
	s_mulk_i32 s7, 0xe0
	s_sub_i32 s7, s4, s7
	s_sext_i32_i16 s4, s7
	s_bfe_u32 s4, s4, 0x3001c
	s_add_i32 s10, s7, s4
	s_sext_i32_i16 s4, s10
	s_and_b32 s10, s10, 0xfff8
	s_sub_i32 s7, s7, s10
	s_sext_i32_i16 s7, s7
	s_lshr_b32 s4, s4, 3
	s_add_i32 s12, s9, s7
	s_ashr_i32 s13, s12, 31
	s_bfe_i64 s[14:15], s[4:5], 0x100000
	s_lshl_b64 s[10:11], s[12:13], 20
	s_lshl_b64 s[14:15], s[14:15], 20
	s_add_u32 s86, s58, s14
	s_addc_u32 s87, s59, s15
	s_add_i32 s95, s23, 0
	v_lshl_or_b32 v168, v219, 12, v217
	s_add_i32 m0, s95, 0x10000
	v_lshl_or_b32 v164, v221, 12, v217
	global_load_lds_dwordx4 v168, s[86:87]
	s_add_i32 m0, s95, 0x12000
	s_add_u32 s14, s86, 0x80000
	global_load_lds_dwordx4 v164, s[86:87]
	s_addc_u32 s15, s87, 0
	s_add_i32 m0, s95, 0x14000
	v_writelane_b32 v255, s88, 10
	global_load_lds_dwordx4 v168, s[14:15]
	s_add_i32 m0, s95, 0x16000
	v_writelane_b32 v255, s96, 11
	s_add_u32 s84, s30, s10
	s_addc_u32 s85, s31, s11
	v_writelane_b32 v255, s97, 12
	s_add_i32 s96, s95, 0x2000
	v_lshl_or_b32 v170, v218, 12, v217
	global_load_lds_dwordx4 v164, s[14:15]
	s_mov_b32 m0, s95
	s_add_u32 s10, s84, 0x80000
	v_lshl_or_b32 v166, v220, 12, v217
	global_load_lds_dwordx4 v170, s[84:85]
	s_mov_b32 m0, s96
	s_addc_u32 s11, s85, 0
	s_add_i32 s97, s95, 0x4000
	global_load_lds_dwordx4 v166, s[84:85]
	s_mov_b32 m0, s97
	s_add_i32 s28, s95, 0x6000
	global_load_lds_dwordx4 v170, s[10:11]
	s_mov_b32 m0, s28
	s_load_dwordx2 s[62:63], s[0:1], 0x50
	global_load_lds_dwordx4 v166, s[10:11]
	v_mov_b32_e32 v173, 0
	v_mov_b32_e32 v169, v173
	v_mov_b32_e32 v165, v173
	v_mov_b32_e32 v171, v173
	v_mov_b32_e32 v167, v173
	s_cmp_eq_u32 s6, 1
	s_mov_b32 s37, s91
	s_mov_b32 s29, 0
	s_waitcnt vmcnt(0)
	v_lshl_add_u64 v[8:9], s[86:87], 0, v[168:169]
	v_lshl_add_u64 v[6:7], s[86:87], 0, v[164:165]
	v_lshl_add_u64 v[2:3], s[84:85], 0, v[170:171]
	s_cselect_b64 s[64:65], -1, 0
	s_cmp_lg_u32 s6, 1
	v_lshl_add_u64 v[4:5], s[84:85], 0, v[166:167]
	s_cbranch_scc1 .LBB0_249
.LBB0_249:
	s_add_u32 s66, s18, 0x17200800
	s_mov_b64 s[68:69], 0x80
	s_addc_u32 s67, s19, 0
	s_add_i32 m0, s95, 0x18000
	v_lshl_add_u64 v[8:9], v[8:9], 0, s[68:69]
	s_and_b32 s13, s8, 3
	s_lshl_b32 s14, s6, 6
	s_lshl_b32 s9, s6, 13
	s_waitcnt vmcnt(2)
	s_barrier
	global_load_lds_dwordx4 v[8:9], off
	v_lshl_add_u64 v[6:7], v[6:7], 0, s[68:69]
	s_add_i32 m0, s95, 0x1a000
	s_add_i32 s15, s95, 0x8000
	s_add_i32 s26, s95, 0xa000
	global_load_lds_dwordx4 v[6:7], off
	v_lshl_add_u64 v[2:3], v[2:3], 0, s[68:69]
	s_mov_b32 m0, s15
	s_add_u32 s6, s86, 0x80080
	global_load_lds_dwordx4 v[2:3], off
	v_lshl_add_u64 v[2:3], v[4:5], 0, s[68:69]
	s_mov_b32 m0, s26
	s_addc_u32 s7, s87, 0
	global_load_lds_dwordx4 v[2:3], off
	s_add_i32 m0, s95, 0x1c000
	v_lshl_add_u64 v[2:3], s[6:7], 0, v[168:169]
	global_load_lds_dwordx4 v[2:3], off
	v_lshl_add_u64 v[2:3], s[6:7], 0, v[164:165]
	s_add_i32 m0, s95, 0x1e000
	s_cmpk_lt_u32 s5, 0x100
	global_load_lds_dwordx4 v[2:3], off
	v_lshlrev_b32_e32 v3, 2, v163
	v_lshl_or_b32 v2, v163, 6, v214
	v_and_b32_e32 v3, 32, v3
	s_cselect_b64 s[70:71], -1, 0
	s_lshl_b32 s10, s8, 4
	v_bitop3_b32 v2, v2, s9, v3 bitop3:0xde
	v_lshlrev_b32_e32 v3, 2, v254
	s_cmp_gt_u32 s13, 1
	s_cselect_b64 s[8:9], -1, 0
	v_and_or_b32 v4, s10, 16, v3
	v_lshl_or_b32 v3, s13, 4, v3
	s_and_b64 s[10:11], s[8:9], exec
	v_or_b32_e32 v223, 0xfffffd00, v3
	v_lshlrev_b32_e32 v3, 9, v0
	s_cselect_b32 s27, 16, 0x80
	s_ashr_i32 s91, s90, 31
	v_lshlrev_b32_e32 v172, 2, v4
	v_and_b32_e32 v3, 0x30000, v3
	v_lshlrev_b32_e32 v4, 12, v210
	s_waitcnt lgkmcnt(0)
	s_add_u32 s72, s62, 0x1000
	v_writelane_b32 v255, s54, 6
	v_or3_b32 v3, v208, v3, v4
	v_lshlrev_b32_e32 v5, 7, v163
	s_addc_u32 s73, s63, 0
	v_writelane_b32 v255, s55, 7
	v_add_u32_e32 v186, v3, v209
	v_lshlrev_b32_e32 v3, 5, v211
	s_waitcnt vmcnt(6)
	s_add_u32 s74, s62, 0x2000
	v_lshl_add_u64 v[174:175], s[54:55], 0, v[172:173]
	v_writelane_b32 v255, s82, 4
	v_and_b32_e32 v3, 0x70000, v3
	v_lshl_or_b32 v222, s13, 12, v215
	v_lshl_add_u64 v[176:177], s[82:83], 0, v[172:173]
	v_or_b32_e32 v172, 0x1000, v5
	s_addc_u32 s75, s63, 0
	v_lshl_add_u64 v[178:179], v[174:175], 0, v[172:173]
	v_lshl_add_u64 v[180:181], v[176:177], 0, v[172:173]
	v_or_b32_e32 v172, 0x1800, v5
	v_or3_b32 v3, v208, v3, v4
	s_add_i32 s45, 0, 0x10000
	s_add_i32 s33, 0, 0x14000
	s_sext_i32_i16 s52, s4
	v_cmp_eq_u32_e64 s[4:5], 0, v163
	v_cmp_eq_u32_e64 s[6:7], 15, v163
	v_writelane_b32 v255, s83, 5
	s_movk_i32 s44, 0x1800
	v_lshl_add_u64 v[182:183], v[174:175], 0, v[172:173]
	v_lshl_add_u64 v[184:185], v[176:177], 0, v[172:173]
	v_lshl_or_b32 v224, s13, 5, v229
	v_mov_b32_e32 v187, v173
	v_add_u32_e32 v188, v3, v209
	v_mov_b32_e32 v189, v173
	v_mov_b64_e32 v[190:191], 0x6ff
	v_add_u32_e32 v225, s45, v222
	v_add_u32_e32 v226, s33, v222
	v_add_u32_e32 v227, 0, v2
	v_mov_b32_e32 v228, 0x3db504f3
	s_barrier
	s_branch .LBB0_252

; #define PG8_STAGE(bufoff, gbase, voff) do { _Pragma("unroll") for (int _i = 0; _i < 2; ++_i) \
;         __builtin_amdgcn_global_load_lds((const unsigned*)((const char*)(gbase) + (voff)[_i]), (PG8_LAS unsigned*)(lds + (bufoff) + ldsw + _i * 8192), 16, 0, 0); } while (0)
; #define PG8_LDA(dst, b, h) do { _Pragma("unroll") for (int m = 0; m < 4; ++m) _Pragma("unroll") for (int k = 0; k < 2; ++k) dst[m][k] = *(const PG8_LAS bf16x8*)(lds + PG8_SA(b, h) + aoff + m * 2048 + k * 1024); } while (0)
; #define PG8_LDB(dst, b, h) do { _Pragma("unroll") for (int n = 0; n < 2; ++n) _Pragma("unroll") for (int k = 0; k < 2; ++k) dst[n][k] = *(const PG8_LAS bf16x8*)(lds + PG8_SB(b, h) + boff + n * 2048 + k * 1024); } while (0)
; #define PG8_WAIT_V(n) asm volatile("s_waitcnt vmcnt(" #n ")" ::: "memory")
; #define PG8_WAIT_L(n) asm volatile("s_waitcnt lgkmcnt(" #n ")" ::: "memory")
; #define PG8_BAR __builtin_amdgcn_s_barrier()
; #define PG8_SCHED __builtin_amdgcn_sched_barrier(0)
; template <class Epi, class Sched, bool ALIGN_EPI = false, bool SP2 = false, bool F8 = false>
; __device__ __forceinline__ void gemm_phase(PG8_LAS unsigned char* lds, const Gemm g, const Sched& S, const Epi& E) {
;     ...
;         const char* nA = has_next ? PG8_ABASE(nxt.pm) : cA; const char* nB = has_next ? (const char*)g.Bt + (size_t)nxt.pn * tstep : cB;
;         for (int t = 0; t < nt; t += 2) {
;             const bool last = (t == nt - 2);
;             const char* a1 = cA + (size_t)(t + 1) * kstep;
;             const char* a2 = last ? nA : cA + (size_t)(t + 2) * kstep; const char* b2 = last ? nB : cB + (size_t)(t + 2) * kstep;
;             const char* a3 = a2 + kstep; const char* b3 = b2 + kstep;
;             if (last && has_next) S.a_ready(nxt);
;             if constexpr (SP2) {
;             PG8_LDB(B0, 0, 0); PG8_LDB(B1, 0, 1); PG8_SCHED; PG8_LDA(At, 0, 0); PG8_STAGE(PG8_SA(1, 1), a1 + hstepA, voffA);
;             PG8_WAIT_V(8); PG8_WAIT_L(0); PG8_BAR; PG8_MMA(0, 0, At, B0); PG8_MMA(0, 1, At, B1); PG8_BAR; PG8_SCHED;
;     ...
;         for (int a = 0; a < 2; ++a)
; #pragma unroll
;             for (int b = 0; b < 2; ++b)
; #pragma unroll
;                 for (int m = 0; m < 4; ++m)
; #pragma unroll
;                     for (int n = 0; n < 2; ++n) acc[a][b][m][n] = (f32x4){0.f, 0.f, 0.f, 0.f};
.LBB0_254:
	s_ashr_i32 s79, s78, 31
	s_lshl_b64 s[54:55], s[78:79], 20
	s_add_u32 s80, s30, s54
	s_addc_u32 s81, s31, s55
	s_and_b64 s[54:55], s[10:11], exec
	s_cselect_b32 s13, s81, s85
	s_cselect_b32 s53, s80, s84
	s_ashr_i32 s77, s76, 31
	s_lshl_b64 s[54:55], s[76:77], 20
	s_add_u32 s82, s58, s54
	s_addc_u32 s83, s59, s55
	s_and_b64 s[54:55], s[10:11], exec
	s_cselect_b32 s77, s83, s87
	s_cselect_b32 s79, s82, s86
	s_add_u32 s84, s84, 0x80080
	s_addc_u32 s85, s85, 0
	s_add_u32 vcc_lo, s86, 0x100
	v_mov_b32_e32 v2, 0
	s_addc_u32 vcc_hi, s87, 0
	s_mov_b32 s54, -2
	v_mov_b32_e32 v3, 0
	v_pk_mul_f32 v[4:5], v[2:3], v[2:3]
	v_pk_mul_f32 v[6:7], v[2:3], v[2:3]
	v_pk_mul_f32 v[8:9], v[2:3], v[2:3]
	v_pk_mul_f32 v[10:11], v[2:3], v[2:3]
	v_pk_mul_f32 v[12:13], v[2:3], v[2:3]
	v_pk_mul_f32 v[14:15], v[2:3], v[2:3]
	v_pk_mul_f32 v[16:17], v[2:3], v[2:3]
	v_pk_mul_f32 v[18:19], v[2:3], v[2:3]
	v_pk_mul_f32 v[20:21], v[2:3], v[2:3]
	v_pk_mul_f32 v[22:23], v[2:3], v[2:3]
	v_pk_mul_f32 v[24:25], v[2:3], v[2:3]
	v_pk_mul_f32 v[26:27], v[2:3], v[2:3]
	v_pk_mul_f32 v[28:29], v[2:3], v[2:3]
	v_pk_mul_f32 v[30:31], v[2:3], v[2:3]
	v_pk_mul_f32 v[32:33], v[2:3], v[2:3]
	v_pk_mul_f32 v[34:35], v[2:3], v[2:3]
	v_pk_mul_f32 v[36:37], v[2:3], v[2:3]
	v_pk_mul_f32 v[38:39], v[2:3], v[2:3]
	v_pk_mul_f32 v[40:41], v[2:3], v[2:3]
	v_pk_mul_f32 v[42:43], v[2:3], v[2:3]
	v_pk_mul_f32 v[44:45], v[2:3], v[2:3]
	v_pk_mul_f32 v[46:47], v[2:3], v[2:3]
	v_pk_mul_f32 v[48:49], v[2:3], v[2:3]
	v_pk_mul_f32 v[50:51], v[2:3], v[2:3]
	v_pk_mul_f32 v[52:53], v[2:3], v[2:3]
	v_pk_mul_f32 v[54:55], v[2:3], v[2:3]
	v_pk_mul_f32 v[56:57], v[2:3], v[2:3]
	v_pk_mul_f32 v[58:59], v[2:3], v[2:3]
	v_pk_mul_f32 v[60:61], v[2:3], v[2:3]
	v_pk_mul_f32 v[62:63], v[2:3], v[2:3]
	v_pk_mul_f32 v[64:65], v[2:3], v[2:3]
	v_pk_mul_f32 v[66:67], v[2:3], v[2:3]
	v_pk_mul_f32 v[68:69], v[2:3], v[2:3]
	v_pk_mul_f32 v[70:71], v[2:3], v[2:3]
	v_pk_mul_f32 v[72:73], v[2:3], v[2:3]
	v_pk_mul_f32 v[74:75], v[2:3], v[2:3]
	v_pk_mul_f32 v[76:77], v[2:3], v[2:3]
	v_pk_mul_f32 v[78:79], v[2:3], v[2:3]
	v_pk_mul_f32 v[80:81], v[2:3], v[2:3]
	v_pk_mul_f32 v[82:83], v[2:3], v[2:3]
	v_pk_mul_f32 v[84:85], v[2:3], v[2:3]
	v_pk_mul_f32 v[86:87], v[2:3], v[2:3]
	v_pk_mul_f32 v[88:89], v[2:3], v[2:3]
	v_pk_mul_f32 v[90:91], v[2:3], v[2:3]
	v_pk_mul_f32 v[92:93], v[2:3], v[2:3]
	v_pk_mul_f32 v[94:95], v[2:3], v[2:3]
	v_pk_mul_f32 v[96:97], v[2:3], v[2:3]
	v_pk_mul_f32 v[98:99], v[2:3], v[2:3]
	v_pk_mul_f32 v[100:101], v[2:3], v[2:3]
	v_pk_mul_f32 v[102:103], v[2:3], v[2:3]
	v_pk_mul_f32 v[104:105], v[2:3], v[2:3]
	v_pk_mul_f32 v[106:107], v[2:3], v[2:3]
	v_pk_mul_f32 v[108:109], v[2:3], v[2:3]
	v_pk_mul_f32 v[110:111], v[2:3], v[2:3]
	v_pk_mul_f32 v[112:113], v[2:3], v[2:3]
	v_pk_mul_f32 v[114:115], v[2:3], v[2:3]
	v_pk_mul_f32 v[116:117], v[2:3], v[2:3]
	v_pk_mul_f32 v[118:119], v[2:3], v[2:3]
	v_pk_mul_f32 v[120:121], v[2:3], v[2:3]
	v_pk_mul_f32 v[122:123], v[2:3], v[2:3]
	v_pk_mul_f32 v[124:125], v[2:3], v[2:3]
	v_pk_mul_f32 v[126:127], v[2:3], v[2:3]
	v_pk_mul_f32 v[128:129], v[2:3], v[2:3]
	s_cmp_lg_u64 s[64:65], 0
	s_cbranch_scc1 .Lk0_Y
.LBB0_255:
	ds_read_b128 v[130:133], v225
	ds_read_b128 v[134:137], v225 offset:1024
	ds_read_b128 v[138:141], v225 offset:2048
	ds_read_b128 v[142:145], v225 offset:3072
	ds_read_b128 v[146:149], v226
	ds_read_b128 v[150:153], v226 offset:1024
	ds_read_b128 v[154:157], v226 offset:2048
	ds_read_b128 v[158:161], v226 offset:3072
	s_add_u32 s24, s84, 0xfff80080
	s_addc_u32 s25, s85, -1
	s_cmp_eq_u32 s54, 28
	s_cselect_b32 s89, s13, s25
	s_cselect_b32 s88, s53, s24
	s_cselect_b32 s87, s77, vcc_hi
	s_cselect_b32 s86, s79, vcc_lo
	v_lshl_add_u64 v[246:247], s[84:85], 0, v[186:187]
	s_add_i32 m0, s95, 0xc000
	ds_read_b128 v[192:195], v227
	ds_read_b128 v[196:199], v227 offset:1024
	ds_read_b128 v[200:203], v227 offset:2048
	ds_read_b128 v[204:207], v227 offset:3072
	ds_read_b128 v[230:233], v227 offset:4096
	ds_read_b128 v[234:237], v227 offset:5120
	ds_read_b128 v[238:241], v227 offset:6144
	ds_read_b128 v[242:245], v227 offset:7168
	global_load_lds_dwordx4 v[246:247], off
	v_lshl_add_u64 v[246:247], s[84:85], 0, v[188:189]
	s_add_i32 m0, s95, 0xe000
	s_nop 0
	global_load_lds_dwordx4 v[246:247], off
	s_waitcnt vmcnt(8)
	s_waitcnt lgkmcnt(0)
	s_setprio 1
	s_waitcnt lgkmcnt(0)
	v_mfma_f32_16x16x32_bf16 v[126:129], v[130:133], v[192:195], v[126:129]
	v_mfma_f32_16x16x32_bf16 v[122:125], v[138:141], v[192:195], v[122:125]
	v_mfma_f32_16x16x32_bf16 v[110:113], v[130:133], v[200:203], v[110:113]
	v_mfma_f32_16x16x32_bf16 v[106:109], v[138:141], v[200:203], v[106:109]
	v_mfma_f32_16x16x32_bf16 v[94:97], v[130:133], v[230:233], v[94:97]
	v_mfma_f32_16x16x32_bf16 v[90:93], v[138:141], v[230:233], v[90:93]
	v_mfma_f32_16x16x32_bf16 v[78:81], v[130:133], v[238:241], v[78:81]
	v_mfma_f32_16x16x32_bf16 v[74:77], v[138:141], v[238:241], v[74:77]
	v_mfma_f32_16x16x32_bf16 v[126:129], v[134:137], v[196:199], v[126:129]
	v_mfma_f32_16x16x32_bf16 v[122:125], v[142:145], v[196:199], v[122:125]
	v_mfma_f32_16x16x32_bf16 v[110:113], v[134:137], v[204:207], v[110:113]
	v_mfma_f32_16x16x32_bf16 v[106:109], v[142:145], v[204:207], v[106:109]
	v_mfma_f32_16x16x32_bf16 v[94:97], v[134:137], v[234:237], v[94:97]
	v_mfma_f32_16x16x32_bf16 v[90:93], v[142:145], v[234:237], v[90:93]
	v_mfma_f32_16x16x32_bf16 v[78:81], v[134:137], v[242:245], v[78:81]
	v_mfma_f32_16x16x32_bf16 v[74:77], v[142:145], v[242:245], v[74:77]
	s_setprio 0
	s_setprio 1
	v_mfma_f32_16x16x32_bf16 v[118:121], v[146:149], v[192:195], v[118:121]
	v_mfma_f32_16x16x32_bf16 v[114:117], v[154:157], v[192:195], v[114:117]
	v_mfma_f32_16x16x32_bf16 v[102:105], v[146:149], v[200:203], v[102:105]
	v_mfma_f32_16x16x32_bf16 v[98:101], v[154:157], v[200:203], v[98:101]
	v_mfma_f32_16x16x32_bf16 v[86:89], v[146:149], v[230:233], v[86:89]
	v_mfma_f32_16x16x32_bf16 v[82:85], v[154:157], v[230:233], v[82:85]
	v_mfma_f32_16x16x32_bf16 v[70:73], v[146:149], v[238:241], v[70:73]
	v_mfma_f32_16x16x32_bf16 v[66:69], v[154:157], v[238:241], v[66:69]
	v_mfma_f32_16x16x32_bf16 v[118:121], v[150:153], v[196:199], v[118:121]
	v_mfma_f32_16x16x32_bf16 v[114:117], v[158:161], v[196:199], v[114:117]
	v_mfma_f32_16x16x32_bf16 v[102:105], v[150:153], v[204:207], v[102:105]
	v_mfma_f32_16x16x32_bf16 v[98:101], v[158:161], v[204:207], v[98:101]
	v_mfma_f32_16x16x32_bf16 v[86:89], v[150:153], v[234:237], v[86:89]
	v_mfma_f32_16x16x32_bf16 v[82:85], v[158:161], v[234:237], v[82:85]
	v_mfma_f32_16x16x32_bf16 v[70:73], v[150:153], v[242:245], v[70:73]
	v_mfma_f32_16x16x32_bf16 v[66:69], v[158:161], v[242:245], v[66:69]
	s_setprio 0
	s_barrier
; #define PG8_STAGE(bufoff, gbase, voff) do { _Pragma("unroll") for (int _i = 0; _i < 2; ++_i) \
;         __builtin_amdgcn_global_load_lds((const unsigned*)((const char*)(gbase) + (voff)[_i]), (PG8_LAS unsigned*)(lds + (bufoff) + ldsw + _i * 8192), 16, 0, 0); } while (0)
; #define PG8_LDA(dst, b, h) do { _Pragma("unroll") for (int m = 0; m < 4; ++m) _Pragma("unroll") for (int k = 0; k < 2; ++k) dst[m][k] = *(const PG8_LAS bf16x8*)(lds + PG8_SA(b, h) + aoff + m * 2048 + k * 1024); } while (0)
; #define PG8_LDB(dst, b, h) do { _Pragma("unroll") for (int n = 0; n < 2; ++n) _Pragma("unroll") for (int k = 0; k < 2; ++k) dst[n][k] = *(const PG8_LAS bf16x8*)(lds + PG8_SB(b, h) + boff + n * 2048 + k * 1024); } while (0)
; #define PG8_WAIT_V(n) asm volatile("s_waitcnt vmcnt(" #n ")" ::: "memory")
; #define PG8_WAIT_L(n) asm volatile("s_waitcnt lgkmcnt(" #n ")" ::: "memory")
; #define PG8_BAR __builtin_amdgcn_s_barrier()
; #define PG8_SCHED __builtin_amdgcn_sched_barrier(0)
; template <class Epi, class Sched, bool ALIGN_EPI = false, bool SP2 = false, bool F8 = false>
; __device__ __forceinline__ void gemm_phase(PG8_LAS unsigned char* lds, const Gemm g, const Sched& S, const Epi& E) {
;     ...
;             PG8_LDA(At, 0, 1); PG8_STAGE(PG8_SB(0, 0), b2, voffB); PG8_STAGE(PG8_SB(0, 1), b2 + hstep, voffB); PG8_STAGE(PG8_SA(0, 0), a2, voffA);
;             PG8_WAIT_V(8); PG8_WAIT_L(0); PG8_BAR; PG8_MMA(1, 0, At, B0); PG8_MMA(1, 1, At, B1); PG8_BAR; PG8_SCHED;
;             PG8_LDB(B0, 1, 0); PG8_LDB(B1, 1, 1); PG8_SCHED; PG8_LDA(At, 1, 0); PG8_STAGE(PG8_SA(0, 1), a2 + hstepA, voffA);
;             PG8_WAIT_V(8); PG8_WAIT_L(0); PG8_BAR; PG8_MMA(0, 0, At, B0); PG8_MMA(0, 1, At, B1); PG8_BAR; PG8_SCHED;
	s_add_i32 s24, s45, s23
	v_lshl_add_u64 v[246:247], s[86:87], 0, v[168:169]
	s_mov_b32 m0, s24
	ds_read_b128 v[192:195], v227 offset:16384
	ds_read_b128 v[196:199], v227 offset:17408
	ds_read_b128 v[200:203], v227 offset:18432
	ds_read_b128 v[204:207], v227 offset:19456
	ds_read_b128 v[230:233], v227 offset:20480
	ds_read_b128 v[234:237], v227 offset:21504
	ds_read_b128 v[238:241], v227 offset:22528
	ds_read_b128 v[242:245], v227 offset:23552
	global_load_lds_dwordx4 v[246:247], off
	s_add_i32 m0, s24, 0x2000
	s_add_u32 s24, s86, 0x80000
	v_lshl_add_u64 v[248:249], s[86:87], 0, v[164:165]
	s_addc_u32 s25, s87, 0
	s_add_i32 s55, s33, s23
	global_load_lds_dwordx4 v[248:249], off
	v_lshl_add_u64 v[250:251], s[24:25], 0, v[168:169]
	s_mov_b32 m0, s55
	v_lshl_add_u64 v[252:253], s[88:89], 0, v[166:167]
	global_load_lds_dwordx4 v[250:251], off
	v_lshl_add_u64 v[250:251], s[24:25], 0, v[164:165]
	s_add_i32 m0, s55, 0x2000
	s_nop 0
	global_load_lds_dwordx4 v[250:251], off
	v_lshl_add_u64 v[250:251], s[88:89], 0, v[170:171]
	s_mov_b32 m0, s95
	s_nop 0
	global_load_lds_dwordx4 v[250:251], off
	s_mov_b32 m0, s96
	s_nop 0
	global_load_lds_dwordx4 v[252:253], off
	s_waitcnt vmcnt(8)
	s_waitcnt lgkmcnt(0)
	s_setprio 1
	s_waitcnt lgkmcnt(0)
	v_mfma_f32_16x16x32_bf16 v[62:65], v[130:133], v[192:195], v[62:65]
	v_mfma_f32_16x16x32_bf16 v[58:61], v[138:141], v[192:195], v[58:61]
	v_mfma_f32_16x16x32_bf16 v[46:49], v[130:133], v[200:203], v[46:49]
	v_mfma_f32_16x16x32_bf16 v[42:45], v[138:141], v[200:203], v[42:45]
	v_mfma_f32_16x16x32_bf16 v[30:33], v[130:133], v[230:233], v[30:33]
	v_mfma_f32_16x16x32_bf16 v[26:29], v[138:141], v[230:233], v[26:29]
	v_mfma_f32_16x16x32_bf16 v[14:17], v[130:133], v[238:241], v[14:17]
	v_mfma_f32_16x16x32_bf16 v[10:13], v[138:141], v[238:241], v[10:13]
	v_mfma_f32_16x16x32_bf16 v[62:65], v[134:137], v[196:199], v[62:65]
	v_mfma_f32_16x16x32_bf16 v[58:61], v[142:145], v[196:199], v[58:61]
	v_mfma_f32_16x16x32_bf16 v[46:49], v[134:137], v[204:207], v[46:49]
	v_mfma_f32_16x16x32_bf16 v[42:45], v[142:145], v[204:207], v[42:45]
	v_mfma_f32_16x16x32_bf16 v[30:33], v[134:137], v[234:237], v[30:33]
	v_mfma_f32_16x16x32_bf16 v[26:29], v[142:145], v[234:237], v[26:29]
	v_mfma_f32_16x16x32_bf16 v[14:17], v[134:137], v[242:245], v[14:17]
	v_mfma_f32_16x16x32_bf16 v[10:13], v[142:145], v[242:245], v[10:13]
	s_setprio 0
	s_setprio 1
	v_mfma_f32_16x16x32_bf16 v[54:57], v[146:149], v[192:195], v[54:57]
	v_mfma_f32_16x16x32_bf16 v[50:53], v[154:157], v[192:195], v[50:53]
	v_mfma_f32_16x16x32_bf16 v[38:41], v[146:149], v[200:203], v[38:41]
	v_mfma_f32_16x16x32_bf16 v[34:37], v[154:157], v[200:203], v[34:37]
	v_mfma_f32_16x16x32_bf16 v[22:25], v[146:149], v[230:233], v[22:25]
	v_mfma_f32_16x16x32_bf16 v[18:21], v[154:157], v[230:233], v[18:21]
	v_mfma_f32_16x16x32_bf16 v[6:9], v[146:149], v[238:241], v[6:9]
	v_mfma_f32_16x16x32_bf16 v[2:5], v[154:157], v[238:241], v[2:5]
	v_mfma_f32_16x16x32_bf16 v[54:57], v[150:153], v[196:199], v[54:57]
	v_mfma_f32_16x16x32_bf16 v[50:53], v[158:161], v[196:199], v[50:53]
	v_mfma_f32_16x16x32_bf16 v[38:41], v[150:153], v[204:207], v[38:41]
	v_mfma_f32_16x16x32_bf16 v[34:37], v[158:161], v[204:207], v[34:37]
	v_mfma_f32_16x16x32_bf16 v[22:25], v[150:153], v[234:237], v[22:25]
	v_mfma_f32_16x16x32_bf16 v[18:21], v[158:161], v[234:237], v[18:21]
	v_mfma_f32_16x16x32_bf16 v[6:9], v[150:153], v[242:245], v[6:9]
	v_mfma_f32_16x16x32_bf16 v[2:5], v[158:161], v[242:245], v[2:5]
	s_setprio 0
	s_barrier
	s_add_i32 s55, 0, 0x18000
	s_add_i32 s36, 0, 0x1c000
	v_add_u32_e32 v142, s55, v222
	v_add_u32_e32 v158, s36, v222
	ds_read_b128 v[130:133], v142
	ds_read_b128 v[134:137], v142 offset:1024
	ds_read_b128 v[138:141], v142 offset:2048
	ds_read_b128 v[142:145], v142 offset:3072
	ds_read_b128 v[146:149], v158
	ds_read_b128 v[150:153], v158 offset:1024
	ds_read_b128 v[154:157], v158 offset:2048
	ds_read_b128 v[158:161], v158 offset:3072
	s_add_u32 s24, s88, 0x80000
	s_addc_u32 s25, s89, 0
	s_mov_b32 m0, s97
	v_lshl_add_u64 v[212:213], s[24:25], 0, v[170:171]
	ds_read_b128 v[192:195], v227 offset:32768
	ds_read_b128 v[196:199], v227 offset:33792
	ds_read_b128 v[200:203], v227 offset:34816
	ds_read_b128 v[204:207], v227 offset:35840
	ds_read_b128 v[230:233], v227 offset:36864
	ds_read_b128 v[234:237], v227 offset:37888
	ds_read_b128 v[238:241], v227 offset:38912
	ds_read_b128 v[242:245], v227 offset:39936
	global_load_lds_dwordx4 v[212:213], off
	v_lshl_add_u64 v[212:213], s[24:25], 0, v[166:167]
	s_mov_b32 m0, s28
	s_nop 0
	global_load_lds_dwordx4 v[212:213], off
	s_waitcnt vmcnt(8)
	s_waitcnt lgkmcnt(0)
	s_setprio 1
	s_waitcnt lgkmcnt(0)
	v_mfma_f32_16x16x32_bf16 v[126:129], v[130:133], v[192:195], v[126:129]
	v_mfma_f32_16x16x32_bf16 v[122:125], v[138:141], v[192:195], v[122:125]
	v_mfma_f32_16x16x32_bf16 v[110:113], v[130:133], v[200:203], v[110:113]
	v_mfma_f32_16x16x32_bf16 v[106:109], v[138:141], v[200:203], v[106:109]
	v_mfma_f32_16x16x32_bf16 v[94:97], v[130:133], v[230:233], v[94:97]
	v_mfma_f32_16x16x32_bf16 v[90:93], v[138:141], v[230:233], v[90:93]
	v_mfma_f32_16x16x32_bf16 v[78:81], v[130:133], v[238:241], v[78:81]
	v_mfma_f32_16x16x32_bf16 v[74:77], v[138:141], v[238:241], v[74:77]
	v_mfma_f32_16x16x32_bf16 v[126:129], v[134:137], v[196:199], v[126:129]
	v_mfma_f32_16x16x32_bf16 v[122:125], v[142:145], v[196:199], v[122:125]
	v_mfma_f32_16x16x32_bf16 v[110:113], v[134:137], v[204:207], v[110:113]
	v_mfma_f32_16x16x32_bf16 v[106:109], v[142:145], v[204:207], v[106:109]
	v_mfma_f32_16x16x32_bf16 v[94:97], v[134:137], v[234:237], v[94:97]
	v_mfma_f32_16x16x32_bf16 v[90:93], v[142:145], v[234:237], v[90:93]
	v_mfma_f32_16x16x32_bf16 v[78:81], v[134:137], v[242:245], v[78:81]
	v_mfma_f32_16x16x32_bf16 v[74:77], v[142:145], v[242:245], v[74:77]
	s_setprio 0
	s_setprio 1
	v_mfma_f32_16x16x32_bf16 v[118:121], v[146:149], v[192:195], v[118:121]
	v_mfma_f32_16x16x32_bf16 v[114:117], v[154:157], v[192:195], v[114:117]
	v_mfma_f32_16x16x32_bf16 v[102:105], v[146:149], v[200:203], v[102:105]
	v_mfma_f32_16x16x32_bf16 v[98:101], v[154:157], v[200:203], v[98:101]
	v_mfma_f32_16x16x32_bf16 v[86:89], v[146:149], v[230:233], v[86:89]
	v_mfma_f32_16x16x32_bf16 v[82:85], v[154:157], v[230:233], v[82:85]
	v_mfma_f32_16x16x32_bf16 v[70:73], v[146:149], v[238:241], v[70:73]
	v_mfma_f32_16x16x32_bf16 v[66:69], v[154:157], v[238:241], v[66:69]
	v_mfma_f32_16x16x32_bf16 v[118:121], v[150:153], v[196:199], v[118:121]
	v_mfma_f32_16x16x32_bf16 v[114:117], v[158:161], v[196:199], v[114:117]
	v_mfma_f32_16x16x32_bf16 v[102:105], v[150:153], v[204:207], v[102:105]
	v_mfma_f32_16x16x32_bf16 v[98:101], v[158:161], v[204:207], v[98:101]
	v_mfma_f32_16x16x32_bf16 v[86:89], v[150:153], v[234:237], v[86:89]
	v_mfma_f32_16x16x32_bf16 v[82:85], v[158:161], v[234:237], v[82:85]
	v_mfma_f32_16x16x32_bf16 v[70:73], v[150:153], v[242:245], v[70:73]
	v_mfma_f32_16x16x32_bf16 v[66:69], v[158:161], v[242:245], v[66:69]
	s_setprio 0
	s_barrier
; #define PG8_STAGE(bufoff, gbase, voff) do { _Pragma("unroll") for (int _i = 0; _i < 2; ++_i) \
;         __builtin_amdgcn_global_load_lds((const unsigned*)((const char*)(gbase) + (voff)[_i]), (PG8_LAS unsigned*)(lds + (bufoff) + ldsw + _i * 8192), 16, 0, 0); } while (0)
; #define PG8_LDA(dst, b, h) do { _Pragma("unroll") for (int m = 0; m < 4; ++m) _Pragma("unroll") for (int k = 0; k < 2; ++k) dst[m][k] = *(const PG8_LAS bf16x8*)(lds + PG8_SA(b, h) + aoff + m * 2048 + k * 1024); } while (0)
; #define PG8_LDB(dst, b, h) do { _Pragma("unroll") for (int n = 0; n < 2; ++n) _Pragma("unroll") for (int k = 0; k < 2; ++k) dst[n][k] = *(const PG8_LAS bf16x8*)(lds + PG8_SB(b, h) + boff + n * 2048 + k * 1024); } while (0)
; #define PG8_WAIT_V(n) asm volatile("s_waitcnt vmcnt(" #n ")" ::: "memory")
; #define PG8_WAIT_L(n) asm volatile("s_waitcnt lgkmcnt(" #n ")" ::: "memory")
; #define PG8_BAR __builtin_amdgcn_s_barrier()
; #define PG8_SCHED __builtin_amdgcn_sched_barrier(0)
; template <class Epi, class Sched, bool ALIGN_EPI = false, bool SP2 = false, bool F8 = false>
; __device__ __forceinline__ void gemm_phase(PG8_LAS unsigned char* lds, const Gemm g, const Sched& S, const Epi& E) {
;     ...
;             PG8_LDB(B0, 0, 0); PG8_LDB(B1, 0, 1); PG8_SCHED; PG8_LDA(At, 0, 0); PG8_STAGE(PG8_SA(1, 1), a1 + hstepA, voffA);
;             PG8_WAIT_V(8); PG8_WAIT_L(0); PG8_BAR; PG8_MMA(0, 0, At, B0); PG8_MMA(0, 1, At, B1); PG8_BAR; PG8_SCHED;
;     ...
;             PG8_LDA(At, 1, 1); PG8_STAGE(PG8_SB(1, 0), b3, voffB); PG8_STAGE(PG8_SB(1, 1), b3 + hstep, voffB); PG8_STAGE(PG8_SA(1, 0), a3, voffA);
;             PG8_WAIT_V(8); PG8_WAIT_L(0); PG8_BAR; PG8_MMA(1, 0, At, B0); PG8_MMA(1, 1, At, B1); PG8_BAR; PG8_SCHED;
	s_add_i32 s24, s55, s23
	v_lshl_add_u64 v[212:213], v[246:247], 0, s[68:69]
	s_mov_b32 m0, s24
	ds_read_b128 v[192:195], v227 offset:49152
	ds_read_b128 v[196:199], v227 offset:50176
	ds_read_b128 v[200:203], v227 offset:51200
	ds_read_b128 v[204:207], v227 offset:52224
	ds_read_b128 v[230:233], v227 offset:53248
	ds_read_b128 v[234:237], v227 offset:54272
	ds_read_b128 v[238:241], v227 offset:55296
	ds_read_b128 v[242:245], v227 offset:56320
	global_load_lds_dwordx4 v[212:213], off
	s_add_i32 m0, s24, 0x2000
	s_add_u32 s24, s86, 0x80080
	v_lshl_add_u64 v[212:213], v[248:249], 0, s[68:69]
	s_addc_u32 s25, s87, 0
	s_add_i32 s36, s36, s23
	global_load_lds_dwordx4 v[212:213], off
	v_lshl_add_u64 v[212:213], s[24:25], 0, v[168:169]
	s_mov_b32 m0, s36
	s_nop 0
	global_load_lds_dwordx4 v[212:213], off
	v_lshl_add_u64 v[212:213], s[24:25], 0, v[164:165]
	s_add_i32 m0, s36, 0x2000
	s_nop 0
	global_load_lds_dwordx4 v[212:213], off
	v_lshl_add_u64 v[212:213], v[250:251], 0, s[68:69]
	s_mov_b32 m0, s15
	s_nop 0
	global_load_lds_dwordx4 v[212:213], off
	v_lshl_add_u64 v[212:213], v[252:253], 0, s[68:69]
	s_mov_b32 m0, s26
	s_nop 0
	global_load_lds_dwordx4 v[212:213], off
	s_waitcnt vmcnt(8)
	s_waitcnt lgkmcnt(0)
	s_setprio 1
	s_waitcnt lgkmcnt(0)
	v_mfma_f32_16x16x32_bf16 v[62:65], v[130:133], v[192:195], v[62:65]
	v_mfma_f32_16x16x32_bf16 v[58:61], v[138:141], v[192:195], v[58:61]
	v_mfma_f32_16x16x32_bf16 v[46:49], v[130:133], v[200:203], v[46:49]
	v_mfma_f32_16x16x32_bf16 v[42:45], v[138:141], v[200:203], v[42:45]
	v_mfma_f32_16x16x32_bf16 v[30:33], v[130:133], v[230:233], v[30:33]
	v_mfma_f32_16x16x32_bf16 v[26:29], v[138:141], v[230:233], v[26:29]
	v_mfma_f32_16x16x32_bf16 v[14:17], v[130:133], v[238:241], v[14:17]
	v_mfma_f32_16x16x32_bf16 v[10:13], v[138:141], v[238:241], v[10:13]
	v_mfma_f32_16x16x32_bf16 v[62:65], v[134:137], v[196:199], v[62:65]
	v_mfma_f32_16x16x32_bf16 v[58:61], v[142:145], v[196:199], v[58:61]
	v_mfma_f32_16x16x32_bf16 v[46:49], v[134:137], v[204:207], v[46:49]
	v_mfma_f32_16x16x32_bf16 v[42:45], v[142:145], v[204:207], v[42:45]
	v_mfma_f32_16x16x32_bf16 v[30:33], v[134:137], v[234:237], v[30:33]
	v_mfma_f32_16x16x32_bf16 v[26:29], v[142:145], v[234:237], v[26:29]
	v_mfma_f32_16x16x32_bf16 v[14:17], v[134:137], v[242:245], v[14:17]
	v_mfma_f32_16x16x32_bf16 v[10:13], v[142:145], v[242:245], v[10:13]
	s_setprio 0
	s_setprio 1
	v_mfma_f32_16x16x32_bf16 v[54:57], v[146:149], v[192:195], v[54:57]
	v_mfma_f32_16x16x32_bf16 v[50:53], v[154:157], v[192:195], v[50:53]
	v_mfma_f32_16x16x32_bf16 v[38:41], v[146:149], v[200:203], v[38:41]
	v_mfma_f32_16x16x32_bf16 v[34:37], v[154:157], v[200:203], v[34:37]
	v_mfma_f32_16x16x32_bf16 v[22:25], v[146:149], v[230:233], v[22:25]
	v_mfma_f32_16x16x32_bf16 v[18:21], v[154:157], v[230:233], v[18:21]
	v_mfma_f32_16x16x32_bf16 v[6:9], v[146:149], v[238:241], v[6:9]
	v_mfma_f32_16x16x32_bf16 v[2:5], v[154:157], v[238:241], v[2:5]
	v_mfma_f32_16x16x32_bf16 v[54:57], v[150:153], v[196:199], v[54:57]
	v_mfma_f32_16x16x32_bf16 v[50:53], v[158:161], v[196:199], v[50:53]
	v_mfma_f32_16x16x32_bf16 v[38:41], v[150:153], v[204:207], v[38:41]
	v_mfma_f32_16x16x32_bf16 v[34:37], v[158:161], v[204:207], v[34:37]
	v_mfma_f32_16x16x32_bf16 v[22:25], v[150:153], v[234:237], v[22:25]
	v_mfma_f32_16x16x32_bf16 v[18:21], v[158:161], v[234:237], v[18:21]
	v_mfma_f32_16x16x32_bf16 v[6:9], v[150:153], v[242:245], v[6:9]
	v_mfma_f32_16x16x32_bf16 v[2:5], v[158:161], v[242:245], v[2:5]
	s_setprio 0
	s_barrier
	s_add_i32 s54, s54, 2
	s_add_u32 s84, s84, 0x100
	s_addc_u32 s85, s85, 0
	s_add_u32 vcc_lo, vcc_lo, 0x100
	s_addc_u32 vcc_hi, vcc_hi, 0
	s_cmp_gt_u32 s54, 29
	s_cbranch_scc0 .LBB0_255
	s_branch .Lk0_exit
.Lk0_Y:
	ds_read_b128 v[130:133], v225
	ds_read_b128 v[134:137], v225 offset:1024
	ds_read_b128 v[138:141], v225 offset:2048
	ds_read_b128 v[142:145], v225 offset:3072
	ds_read_b128 v[146:149], v226
	ds_read_b128 v[150:153], v226 offset:1024
	ds_read_b128 v[154:157], v226 offset:2048
	ds_read_b128 v[158:161], v226 offset:3072
	s_add_u32 s24, s84, 0xfff80080
	s_addc_u32 s25, s85, -1
	s_cmp_eq_u32 s54, 28
	s_cselect_b32 s89, s13, s25
	s_cselect_b32 s88, s53, s24
	s_cselect_b32 s87, s77, vcc_hi
	s_cselect_b32 s86, s79, vcc_lo
	v_lshl_add_u64 v[246:247], s[84:85], 0, v[186:187]
	s_add_i32 m0, s95, 0xc000
	ds_read_b128 v[192:195], v227
	ds_read_b128 v[196:199], v227 offset:1024
	ds_read_b128 v[200:203], v227 offset:2048
	ds_read_b128 v[204:207], v227 offset:3072
	ds_read_b128 v[230:233], v227 offset:4096
	ds_read_b128 v[234:237], v227 offset:5120
	ds_read_b128 v[238:241], v227 offset:6144
	ds_read_b128 v[242:245], v227 offset:7168
	global_load_lds_dwordx4 v[246:247], off
	v_lshl_add_u64 v[246:247], s[84:85], 0, v[188:189]
	s_add_i32 m0, s95, 0xe000
	s_nop 0
	global_load_lds_dwordx4 v[246:247], off
	s_waitcnt vmcnt(8)
	s_waitcnt lgkmcnt(0)
	s_barrier
; #define PG8_STAGE(bufoff, gbase, voff) do { _Pragma("unroll") for (int _i = 0; _i < 2; ++_i) \
;         __builtin_amdgcn_global_load_lds((const unsigned*)((const char*)(gbase) + (voff)[_i]), (PG8_LAS unsigned*)(lds + (bufoff) + ldsw + _i * 8192), 16, 0, 0); } while (0)
; #define PG8_LDA(dst, b, h) do { _Pragma("unroll") for (int m = 0; m < 4; ++m) _Pragma("unroll") for (int k = 0; k < 2; ++k) dst[m][k] = *(const PG8_LAS bf16x8*)(lds + PG8_SA(b, h) + aoff + m * 2048 + k * 1024); } while (0)
; #define PG8_LDB(dst, b, h) do { _Pragma("unroll") for (int n = 0; n < 2; ++n) _Pragma("unroll") for (int k = 0; k < 2; ++k) dst[n][k] = *(const PG8_LAS bf16x8*)(lds + PG8_SB(b, h) + boff + n * 2048 + k * 1024); } while (0)
; #define PG8_WAIT_V(n) asm volatile("s_waitcnt vmcnt(" #n ")" ::: "memory")
; #define PG8_WAIT_L(n) asm volatile("s_waitcnt lgkmcnt(" #n ")" ::: "memory")
; #define PG8_BAR __builtin_amdgcn_s_barrier()
; #define PG8_SCHED __builtin_amdgcn_sched_barrier(0)
; template <class Epi, class Sched, bool ALIGN_EPI = false, bool SP2 = false, bool F8 = false>
; __device__ __forceinline__ void gemm_phase(PG8_LAS unsigned char* lds, const Gemm g, const Sched& S, const Epi& E) {
;     ...
;             PG8_WAIT_V(8); PG8_WAIT_L(0); PG8_BAR; PG8_MMA(0, 0, At, B0); PG8_MMA(0, 1, At, B1); PG8_BAR; PG8_SCHED;
;             PG8_LDA(At, 0, 1); PG8_STAGE(PG8_SB(0, 0), b2, voffB); PG8_STAGE(PG8_SB(0, 1), b2 + hstep, voffB); PG8_STAGE(PG8_SA(0, 0), a2, voffA);
;             PG8_WAIT_V(8); PG8_WAIT_L(0); PG8_BAR; PG8_MMA(1, 0, At, B0); PG8_MMA(1, 1, At, B1); PG8_BAR; PG8_SCHED;
;             PG8_LDB(B0, 1, 0); PG8_LDB(B1, 1, 1); PG8_SCHED; PG8_LDA(At, 1, 0); PG8_STAGE(PG8_SA(0, 1), a2 + hstepA, voffA);
;             PG8_WAIT_V(8); PG8_WAIT_L(0); PG8_BAR; PG8_MMA(0, 0, At, B0); PG8_MMA(0, 1, At, B1); PG8_BAR; PG8_SCHED;
	s_setprio 3
	s_waitcnt lgkmcnt(0)
	v_mfma_f32_16x16x32_bf16 v[126:129], v[130:133], v[192:195], v[126:129]
	v_mfma_f32_16x16x32_bf16 v[122:125], v[138:141], v[192:195], v[122:125]
	v_mfma_f32_16x16x32_bf16 v[110:113], v[130:133], v[200:203], v[110:113]
	v_mfma_f32_16x16x32_bf16 v[106:109], v[138:141], v[200:203], v[106:109]
	v_mfma_f32_16x16x32_bf16 v[94:97], v[130:133], v[230:233], v[94:97]
	v_mfma_f32_16x16x32_bf16 v[90:93], v[138:141], v[230:233], v[90:93]
	v_mfma_f32_16x16x32_bf16 v[78:81], v[130:133], v[238:241], v[78:81]
	v_mfma_f32_16x16x32_bf16 v[74:77], v[138:141], v[238:241], v[74:77]
	v_mfma_f32_16x16x32_bf16 v[126:129], v[134:137], v[196:199], v[126:129]
	v_mfma_f32_16x16x32_bf16 v[122:125], v[142:145], v[196:199], v[122:125]
	v_mfma_f32_16x16x32_bf16 v[110:113], v[134:137], v[204:207], v[110:113]
	v_mfma_f32_16x16x32_bf16 v[106:109], v[142:145], v[204:207], v[106:109]
	v_mfma_f32_16x16x32_bf16 v[94:97], v[134:137], v[234:237], v[94:97]
	v_mfma_f32_16x16x32_bf16 v[90:93], v[142:145], v[234:237], v[90:93]
	v_mfma_f32_16x16x32_bf16 v[78:81], v[134:137], v[242:245], v[78:81]
	v_mfma_f32_16x16x32_bf16 v[74:77], v[142:145], v[242:245], v[74:77]
	s_setprio 0
	s_setprio 3
	v_mfma_f32_16x16x32_bf16 v[118:121], v[146:149], v[192:195], v[118:121]
	v_mfma_f32_16x16x32_bf16 v[114:117], v[154:157], v[192:195], v[114:117]
	v_mfma_f32_16x16x32_bf16 v[102:105], v[146:149], v[200:203], v[102:105]
	v_mfma_f32_16x16x32_bf16 v[98:101], v[154:157], v[200:203], v[98:101]
	v_mfma_f32_16x16x32_bf16 v[86:89], v[146:149], v[230:233], v[86:89]
	v_mfma_f32_16x16x32_bf16 v[82:85], v[154:157], v[230:233], v[82:85]
	v_mfma_f32_16x16x32_bf16 v[70:73], v[146:149], v[238:241], v[70:73]
	v_mfma_f32_16x16x32_bf16 v[66:69], v[154:157], v[238:241], v[66:69]
	v_mfma_f32_16x16x32_bf16 v[118:121], v[150:153], v[196:199], v[118:121]
	v_mfma_f32_16x16x32_bf16 v[114:117], v[158:161], v[196:199], v[114:117]
	v_mfma_f32_16x16x32_bf16 v[102:105], v[150:153], v[204:207], v[102:105]
	v_mfma_f32_16x16x32_bf16 v[98:101], v[158:161], v[204:207], v[98:101]
	v_mfma_f32_16x16x32_bf16 v[86:89], v[150:153], v[234:237], v[86:89]
	v_mfma_f32_16x16x32_bf16 v[82:85], v[158:161], v[234:237], v[82:85]
	v_mfma_f32_16x16x32_bf16 v[70:73], v[150:153], v[242:245], v[70:73]
	v_mfma_f32_16x16x32_bf16 v[66:69], v[158:161], v[242:245], v[66:69]
	s_setprio 0
	s_add_i32 s24, s45, s23
	v_lshl_add_u64 v[246:247], s[86:87], 0, v[168:169]
	s_mov_b32 m0, s24
	ds_read_b128 v[192:195], v227 offset:16384
	ds_read_b128 v[196:199], v227 offset:17408
	ds_read_b128 v[200:203], v227 offset:18432
	ds_read_b128 v[204:207], v227 offset:19456
	ds_read_b128 v[230:233], v227 offset:20480
	ds_read_b128 v[234:237], v227 offset:21504
	ds_read_b128 v[238:241], v227 offset:22528
	ds_read_b128 v[242:245], v227 offset:23552
	global_load_lds_dwordx4 v[246:247], off
	s_add_i32 m0, s24, 0x2000
	s_add_u32 s24, s86, 0x80000
	v_lshl_add_u64 v[248:249], s[86:87], 0, v[164:165]
	s_addc_u32 s25, s87, 0
	s_add_i32 s55, s33, s23
	global_load_lds_dwordx4 v[248:249], off
	v_lshl_add_u64 v[250:251], s[24:25], 0, v[168:169]
	s_mov_b32 m0, s55
	v_lshl_add_u64 v[252:253], s[88:89], 0, v[166:167]
	global_load_lds_dwordx4 v[250:251], off
	v_lshl_add_u64 v[250:251], s[24:25], 0, v[164:165]
	s_add_i32 m0, s55, 0x2000
	s_nop 0
	global_load_lds_dwordx4 v[250:251], off
	v_lshl_add_u64 v[250:251], s[88:89], 0, v[170:171]
	s_mov_b32 m0, s95
	s_nop 0
	global_load_lds_dwordx4 v[250:251], off
	s_mov_b32 m0, s96
	s_nop 0
	global_load_lds_dwordx4 v[252:253], off
	s_waitcnt vmcnt(8)
	s_waitcnt lgkmcnt(0)
	s_barrier
	s_setprio 3
	s_waitcnt lgkmcnt(0)
	v_mfma_f32_16x16x32_bf16 v[62:65], v[130:133], v[192:195], v[62:65]
	v_mfma_f32_16x16x32_bf16 v[58:61], v[138:141], v[192:195], v[58:61]
	v_mfma_f32_16x16x32_bf16 v[46:49], v[130:133], v[200:203], v[46:49]
	v_mfma_f32_16x16x32_bf16 v[42:45], v[138:141], v[200:203], v[42:45]
	v_mfma_f32_16x16x32_bf16 v[30:33], v[130:133], v[230:233], v[30:33]
	v_mfma_f32_16x16x32_bf16 v[26:29], v[138:141], v[230:233], v[26:29]
	v_mfma_f32_16x16x32_bf16 v[14:17], v[130:133], v[238:241], v[14:17]
	v_mfma_f32_16x16x32_bf16 v[10:13], v[138:141], v[238:241], v[10:13]
	v_mfma_f32_16x16x32_bf16 v[62:65], v[134:137], v[196:199], v[62:65]
	v_mfma_f32_16x16x32_bf16 v[58:61], v[142:145], v[196:199], v[58:61]
	v_mfma_f32_16x16x32_bf16 v[46:49], v[134:137], v[204:207], v[46:49]
	v_mfma_f32_16x16x32_bf16 v[42:45], v[142:145], v[204:207], v[42:45]
	v_mfma_f32_16x16x32_bf16 v[30:33], v[134:137], v[234:237], v[30:33]
	v_mfma_f32_16x16x32_bf16 v[26:29], v[142:145], v[234:237], v[26:29]
	v_mfma_f32_16x16x32_bf16 v[14:17], v[134:137], v[242:245], v[14:17]
	v_mfma_f32_16x16x32_bf16 v[10:13], v[142:145], v[242:245], v[10:13]
	s_setprio 0
	s_setprio 3
	v_mfma_f32_16x16x32_bf16 v[54:57], v[146:149], v[192:195], v[54:57]
	v_mfma_f32_16x16x32_bf16 v[50:53], v[154:157], v[192:195], v[50:53]
	v_mfma_f32_16x16x32_bf16 v[38:41], v[146:149], v[200:203], v[38:41]
	v_mfma_f32_16x16x32_bf16 v[34:37], v[154:157], v[200:203], v[34:37]
	v_mfma_f32_16x16x32_bf16 v[22:25], v[146:149], v[230:233], v[22:25]
	v_mfma_f32_16x16x32_bf16 v[18:21], v[154:157], v[230:233], v[18:21]
	v_mfma_f32_16x16x32_bf16 v[6:9], v[146:149], v[238:241], v[6:9]
	v_mfma_f32_16x16x32_bf16 v[2:5], v[154:157], v[238:241], v[2:5]
	v_mfma_f32_16x16x32_bf16 v[54:57], v[150:153], v[196:199], v[54:57]
	v_mfma_f32_16x16x32_bf16 v[50:53], v[158:161], v[196:199], v[50:53]
	v_mfma_f32_16x16x32_bf16 v[38:41], v[150:153], v[204:207], v[38:41]
	v_mfma_f32_16x16x32_bf16 v[34:37], v[158:161], v[204:207], v[34:37]
	v_mfma_f32_16x16x32_bf16 v[22:25], v[150:153], v[234:237], v[22:25]
	v_mfma_f32_16x16x32_bf16 v[18:21], v[158:161], v[234:237], v[18:21]
	v_mfma_f32_16x16x32_bf16 v[6:9], v[150:153], v[242:245], v[6:9]
	v_mfma_f32_16x16x32_bf16 v[2:5], v[158:161], v[242:245], v[2:5]
	s_setprio 0
	s_add_i32 s55, 0, 0x18000
	s_add_i32 s36, 0, 0x1c000
	v_add_u32_e32 v142, s55, v222
	v_add_u32_e32 v158, s36, v222
	ds_read_b128 v[130:133], v142
	ds_read_b128 v[134:137], v142 offset:1024
	ds_read_b128 v[138:141], v142 offset:2048
	ds_read_b128 v[142:145], v142 offset:3072
	ds_read_b128 v[146:149], v158
	ds_read_b128 v[150:153], v158 offset:1024
	ds_read_b128 v[154:157], v158 offset:2048
	ds_read_b128 v[158:161], v158 offset:3072
	s_add_u32 s24, s88, 0x80000
	s_addc_u32 s25, s89, 0
	s_mov_b32 m0, s97
	v_lshl_add_u64 v[212:213], s[24:25], 0, v[170:171]
	ds_read_b128 v[192:195], v227 offset:32768
	ds_read_b128 v[196:199], v227 offset:33792
	ds_read_b128 v[200:203], v227 offset:34816
	ds_read_b128 v[204:207], v227 offset:35840
	ds_read_b128 v[230:233], v227 offset:36864
	ds_read_b128 v[234:237], v227 offset:37888
	ds_read_b128 v[238:241], v227 offset:38912
	ds_read_b128 v[242:245], v227 offset:39936
	global_load_lds_dwordx4 v[212:213], off
	v_lshl_add_u64 v[212:213], s[24:25], 0, v[166:167]
	s_mov_b32 m0, s28
	s_nop 0
	global_load_lds_dwordx4 v[212:213], off
	s_waitcnt vmcnt(8)
	s_waitcnt lgkmcnt(0)
	s_barrier
; #define PG8_STAGE(bufoff, gbase, voff) do { _Pragma("unroll") for (int _i = 0; _i < 2; ++_i) \
;         __builtin_amdgcn_global_load_lds((const unsigned*)((const char*)(gbase) + (voff)[_i]), (PG8_LAS unsigned*)(lds + (bufoff) + ldsw + _i * 8192), 16, 0, 0); } while (0)
; #define PG8_LDA(dst, b, h) do { _Pragma("unroll") for (int m = 0; m < 4; ++m) _Pragma("unroll") for (int k = 0; k < 2; ++k) dst[m][k] = *(const PG8_LAS bf16x8*)(lds + PG8_SA(b, h) + aoff + m * 2048 + k * 1024); } while (0)
; #define PG8_WAIT_V(n) asm volatile("s_waitcnt vmcnt(" #n ")" ::: "memory")
; #define PG8_WAIT_L(n) asm volatile("s_waitcnt lgkmcnt(" #n ")" ::: "memory")
; #define PG8_BAR __builtin_amdgcn_s_barrier()
; #define PG8_SCHED __builtin_amdgcn_sched_barrier(0)
;     __device__ __forceinline__ void operator()(const f32x4 (&acc)[2][2][4][2], const Unit& u, int wr, int wc, int fr, int fq) const {
;         const int row0 = u.pm * BM + wr * 64 + fr;
;         if (u.pn < 12) {
; template <class Epi, class Sched, bool ALIGN_EPI = false, bool SP2 = false, bool F8 = false>
; __device__ __forceinline__ void gemm_phase(PG8_LAS unsigned char* lds, const Gemm g, const Sched& S, const Epi& E) {
;     ...
;             PG8_WAIT_V(8); PG8_WAIT_L(0); PG8_BAR; PG8_MMA(0, 0, At, B0); PG8_MMA(0, 1, At, B1); PG8_BAR; PG8_SCHED;
;             PG8_LDA(At, 1, 1); PG8_STAGE(PG8_SB(1, 0), b3, voffB); PG8_STAGE(PG8_SB(1, 1), b3 + hstep, voffB); PG8_STAGE(PG8_SA(1, 0), a3, voffA);
;             PG8_WAIT_V(8); PG8_WAIT_L(0); PG8_BAR; PG8_MMA(1, 0, At, B0); PG8_MMA(1, 1, At, B1); PG8_BAR; PG8_SCHED;
;     ...
;         if constexpr (ALIGN_EPI) { if (wr == 0) PG8_BAR; }
;         if constexpr (!Epi::AFTER_DRAIN) { E(acc, cur, wr, wc, fr, fq); S.done(cur); }
	s_setprio 3
	s_waitcnt lgkmcnt(0)
	v_mfma_f32_16x16x32_bf16 v[126:129], v[130:133], v[192:195], v[126:129]
	v_mfma_f32_16x16x32_bf16 v[122:125], v[138:141], v[192:195], v[122:125]
	v_mfma_f32_16x16x32_bf16 v[110:113], v[130:133], v[200:203], v[110:113]
	v_mfma_f32_16x16x32_bf16 v[106:109], v[138:141], v[200:203], v[106:109]
	v_mfma_f32_16x16x32_bf16 v[94:97], v[130:133], v[230:233], v[94:97]
	v_mfma_f32_16x16x32_bf16 v[90:93], v[138:141], v[230:233], v[90:93]
	v_mfma_f32_16x16x32_bf16 v[78:81], v[130:133], v[238:241], v[78:81]
	v_mfma_f32_16x16x32_bf16 v[74:77], v[138:141], v[238:241], v[74:77]
	v_mfma_f32_16x16x32_bf16 v[126:129], v[134:137], v[196:199], v[126:129]
	v_mfma_f32_16x16x32_bf16 v[122:125], v[142:145], v[196:199], v[122:125]
	v_mfma_f32_16x16x32_bf16 v[110:113], v[134:137], v[204:207], v[110:113]
	v_mfma_f32_16x16x32_bf16 v[106:109], v[142:145], v[204:207], v[106:109]
	v_mfma_f32_16x16x32_bf16 v[94:97], v[134:137], v[234:237], v[94:97]
	v_mfma_f32_16x16x32_bf16 v[90:93], v[142:145], v[234:237], v[90:93]
	v_mfma_f32_16x16x32_bf16 v[78:81], v[134:137], v[242:245], v[78:81]
	v_mfma_f32_16x16x32_bf16 v[74:77], v[142:145], v[242:245], v[74:77]
	s_setprio 0
	s_setprio 3
	v_mfma_f32_16x16x32_bf16 v[118:121], v[146:149], v[192:195], v[118:121]
	v_mfma_f32_16x16x32_bf16 v[114:117], v[154:157], v[192:195], v[114:117]
	v_mfma_f32_16x16x32_bf16 v[102:105], v[146:149], v[200:203], v[102:105]
	v_mfma_f32_16x16x32_bf16 v[98:101], v[154:157], v[200:203], v[98:101]
	v_mfma_f32_16x16x32_bf16 v[86:89], v[146:149], v[230:233], v[86:89]
	v_mfma_f32_16x16x32_bf16 v[82:85], v[154:157], v[230:233], v[82:85]
	v_mfma_f32_16x16x32_bf16 v[70:73], v[146:149], v[238:241], v[70:73]
	v_mfma_f32_16x16x32_bf16 v[66:69], v[154:157], v[238:241], v[66:69]
	v_mfma_f32_16x16x32_bf16 v[118:121], v[150:153], v[196:199], v[118:121]
	v_mfma_f32_16x16x32_bf16 v[114:117], v[158:161], v[196:199], v[114:117]
	v_mfma_f32_16x16x32_bf16 v[102:105], v[150:153], v[204:207], v[102:105]
	v_mfma_f32_16x16x32_bf16 v[98:101], v[158:161], v[204:207], v[98:101]
	v_mfma_f32_16x16x32_bf16 v[86:89], v[150:153], v[234:237], v[86:89]
	v_mfma_f32_16x16x32_bf16 v[82:85], v[158:161], v[234:237], v[82:85]
	v_mfma_f32_16x16x32_bf16 v[70:73], v[150:153], v[242:245], v[70:73]
	v_mfma_f32_16x16x32_bf16 v[66:69], v[158:161], v[242:245], v[66:69]
	s_setprio 0
	s_add_i32 s24, s55, s23
	v_lshl_add_u64 v[212:213], v[246:247], 0, s[68:69]
	s_mov_b32 m0, s24
	ds_read_b128 v[192:195], v227 offset:49152
	ds_read_b128 v[196:199], v227 offset:50176
	ds_read_b128 v[200:203], v227 offset:51200
	ds_read_b128 v[204:207], v227 offset:52224
	ds_read_b128 v[230:233], v227 offset:53248
	ds_read_b128 v[234:237], v227 offset:54272
	ds_read_b128 v[238:241], v227 offset:55296
	ds_read_b128 v[242:245], v227 offset:56320
	global_load_lds_dwordx4 v[212:213], off
	s_add_i32 m0, s24, 0x2000
	s_add_u32 s24, s86, 0x80080
	v_lshl_add_u64 v[212:213], v[248:249], 0, s[68:69]
	s_addc_u32 s25, s87, 0
	s_add_i32 s36, s36, s23
	global_load_lds_dwordx4 v[212:213], off
	v_lshl_add_u64 v[212:213], s[24:25], 0, v[168:169]
	s_mov_b32 m0, s36
	s_nop 0
	global_load_lds_dwordx4 v[212:213], off
	v_lshl_add_u64 v[212:213], s[24:25], 0, v[164:165]
	s_add_i32 m0, s36, 0x2000
	s_nop 0
	global_load_lds_dwordx4 v[212:213], off
	v_lshl_add_u64 v[212:213], v[250:251], 0, s[68:69]
	s_mov_b32 m0, s15
	s_nop 0
	global_load_lds_dwordx4 v[212:213], off
	v_lshl_add_u64 v[212:213], v[252:253], 0, s[68:69]
	s_mov_b32 m0, s26
	s_nop 0
	global_load_lds_dwordx4 v[212:213], off
	s_waitcnt vmcnt(8)
	s_waitcnt lgkmcnt(0)
	s_barrier
	s_setprio 3
	s_waitcnt lgkmcnt(0)
	v_mfma_f32_16x16x32_bf16 v[62:65], v[130:133], v[192:195], v[62:65]
	v_mfma_f32_16x16x32_bf16 v[58:61], v[138:141], v[192:195], v[58:61]
	v_mfma_f32_16x16x32_bf16 v[46:49], v[130:133], v[200:203], v[46:49]
	v_mfma_f32_16x16x32_bf16 v[42:45], v[138:141], v[200:203], v[42:45]
	v_mfma_f32_16x16x32_bf16 v[30:33], v[130:133], v[230:233], v[30:33]
	v_mfma_f32_16x16x32_bf16 v[26:29], v[138:141], v[230:233], v[26:29]
	v_mfma_f32_16x16x32_bf16 v[14:17], v[130:133], v[238:241], v[14:17]
	v_mfma_f32_16x16x32_bf16 v[10:13], v[138:141], v[238:241], v[10:13]
	v_mfma_f32_16x16x32_bf16 v[62:65], v[134:137], v[196:199], v[62:65]
	v_mfma_f32_16x16x32_bf16 v[58:61], v[142:145], v[196:199], v[58:61]
	v_mfma_f32_16x16x32_bf16 v[46:49], v[134:137], v[204:207], v[46:49]
	v_mfma_f32_16x16x32_bf16 v[42:45], v[142:145], v[204:207], v[42:45]
	v_mfma_f32_16x16x32_bf16 v[30:33], v[134:137], v[234:237], v[30:33]
	v_mfma_f32_16x16x32_bf16 v[26:29], v[142:145], v[234:237], v[26:29]
	v_mfma_f32_16x16x32_bf16 v[14:17], v[134:137], v[242:245], v[14:17]
	v_mfma_f32_16x16x32_bf16 v[10:13], v[142:145], v[242:245], v[10:13]
	s_setprio 0
	s_setprio 3
	v_mfma_f32_16x16x32_bf16 v[54:57], v[146:149], v[192:195], v[54:57]
	v_mfma_f32_16x16x32_bf16 v[50:53], v[154:157], v[192:195], v[50:53]
	v_mfma_f32_16x16x32_bf16 v[38:41], v[146:149], v[200:203], v[38:41]
	v_mfma_f32_16x16x32_bf16 v[34:37], v[154:157], v[200:203], v[34:37]
	v_mfma_f32_16x16x32_bf16 v[22:25], v[146:149], v[230:233], v[22:25]
	v_mfma_f32_16x16x32_bf16 v[18:21], v[154:157], v[230:233], v[18:21]
	v_mfma_f32_16x16x32_bf16 v[6:9], v[146:149], v[238:241], v[6:9]
	v_mfma_f32_16x16x32_bf16 v[2:5], v[154:157], v[238:241], v[2:5]
	v_mfma_f32_16x16x32_bf16 v[54:57], v[150:153], v[196:199], v[54:57]
	v_mfma_f32_16x16x32_bf16 v[50:53], v[158:161], v[196:199], v[50:53]
	v_mfma_f32_16x16x32_bf16 v[38:41], v[150:153], v[204:207], v[38:41]
	v_mfma_f32_16x16x32_bf16 v[34:37], v[158:161], v[204:207], v[34:37]
	v_mfma_f32_16x16x32_bf16 v[22:25], v[150:153], v[234:237], v[22:25]
	v_mfma_f32_16x16x32_bf16 v[18:21], v[158:161], v[234:237], v[18:21]
	v_mfma_f32_16x16x32_bf16 v[6:9], v[150:153], v[242:245], v[6:9]
	v_mfma_f32_16x16x32_bf16 v[2:5], v[158:161], v[242:245], v[2:5]
	s_setprio 0
	s_add_i32 s54, s54, 2
	s_add_u32 s84, s84, 0x100
	s_addc_u32 s85, s85, 0
	s_add_u32 vcc_lo, vcc_lo, 0x100
	s_addc_u32 vcc_hi, vcc_hi, 0
	s_cmp_gt_u32 s54, 29
	s_cbranch_scc0 .Lk0_Y
.Lk0_exit:
	s_and_b64 vcc, exec, s[70:71]
	s_cbranch_vccz .LBB0_258
.LBB0_258:
	s_lshl_b32 s53, s12, 8
	s_add_i32 s53, s53, s14
	v_or_b32_e32 v192, s53, v163
	s_mov_b64 s[12:13], -1
	s_cmp_gt_i32 s52, 11
	v_or_b32_e32 v202, 16, v192
	v_or_b32_e32 v200, 32, v192
	v_or_b32_e32 v198, 48, v192
	v_add_u32_e32 v196, 0x80, v192
	v_add_u32_e32 v194, 0x90, v192
	s_cbranch_scc1 .LBB0_261
	s_andn2_b64 vcc, exec, s[12:13]
	s_cbranch_vccz .LBB0_262

; #define PG8_BAR __builtin_amdgcn_s_barrier()
; template <class Epi, class Sched, bool ALIGN_EPI = false, bool SP2 = false, bool F8 = false>
; __device__ __forceinline__ void gemm_phase(PG8_LAS unsigned char* lds, const Gemm g, const Sched& S, const Epi& E) {
;     ...
;         cur = nxt; cA = nA; cB = nB; ++ui;
;         if constexpr (ALIGN_EPI) { if (wr == 1) PG8_BAR; }
.LBB0_269:
	s_andn2_b64 vcc, exec, s[64:65]
	s_cbranch_vccnz .LBB0_250
	s_branch .LBB0_250

; #define PG8_STAGE(bufoff, gbase, voff) do { _Pragma("unroll") for (int _i = 0; _i < 2; ++_i) \
;         __builtin_amdgcn_global_load_lds((const unsigned*)((const char*)(gbase) + (voff)[_i]), (PG8_LAS unsigned*)(lds + (bufoff) + ldsw + _i * 8192), 16, 0, 0); } while (0)
; #define PG8_WAIT_V(n) asm volatile("s_waitcnt vmcnt(" #n ")" ::: "memory")
; #define PG8_BAR __builtin_amdgcn_s_barrier()
; template <class Epi, class Sched, bool ALIGN_EPI = false, bool SP2 = false, bool F8 = false>
; __device__ __forceinline__ void gemm_phase(PG8_LAS unsigned char* lds, const Gemm g, const Sched& S, const Epi& E) {
;     ...
;     const char* cA = PG8_ABASE(cur.pm); const char* cB = (const char*)g.Bt + (size_t)cur.pn * tstep;
;     S.a_ready(cur);
;     if constexpr (SP2) {
;         PG8_STAGE(PG8_SB(0, 0), cB, voffB); PG8_STAGE(PG8_SB(0, 1), cB + hstep, voffB); PG8_STAGE(PG8_SA(0, 0), cA, voffA); PG8_STAGE(PG8_SA(0, 1), cA + hstepA, voffA);
;         if (wr == 1) PG8_BAR;
;         PG8_WAIT_V(2); PG8_BAR;
;         PG8_STAGE(PG8_SB(1, 0), cB + kstep, voffB); PG8_STAGE(PG8_SA(1, 0), cA + kstep, voffA); PG8_STAGE(PG8_SB(1, 1), cB + hstep + kstep, voffB);
;         PG8_WAIT_V(6); PG8_BAR;
.LBB0_278:
	s_andn2_b64 vcc, exec, s[4:5]
	s_cbranch_vccnz .LBB0_314
	s_lshr_b32 s52, s12, 6
	s_lshr_b32 s4, s12, 8
	s_lshl_b32 s14, s52, 10
	s_add_u32 s15, s18, 0x4800000
	s_addc_u32 s23, s19, 0
	s_ashr_i32 s71, s70, 31
	s_ashr_i32 s7, s6, 31
	s_lshl_b64 s[8:9], s[70:71], 19
	s_lshl_b64 s[10:11], s[6:7], 19
	s_add_u32 s74, s50, s10
	s_addc_u32 s75, s51, s11
	s_add_i32 s26, s14, 0
	v_lshl_or_b32 v166, v219, 11, v217
	s_add_i32 m0, s26, 0x10000
	v_lshl_or_b32 v170, v221, 11, v217
	global_load_lds_dwordx4 v166, s[74:75]
	s_add_i32 m0, s26, 0x12000
	s_add_u32 s10, s74, 0x40000
	global_load_lds_dwordx4 v170, s[74:75]
	s_addc_u32 s11, s75, 0
	s_add_i32 m0, s26, 0x14000
	v_lshl_or_b32 v164, v218, 11, v217
	global_load_lds_dwordx4 v166, s[10:11]
	s_add_i32 m0, s26, 0x16000
	s_add_u32 s72, s15, s8
	s_addc_u32 s73, s23, s9
	s_add_i32 s27, s26, 0x2000
	global_load_lds_dwordx4 v170, s[10:11]
	s_mov_b32 m0, s26
	s_add_u32 s8, s72, 0x40000
	v_lshl_or_b32 v168, v220, 11, v217
	global_load_lds_dwordx4 v164, s[72:73]
	s_mov_b32 m0, s27
	s_addc_u32 s9, s73, 0
	s_add_i32 s28, s26, 0x4000
	global_load_lds_dwordx4 v168, s[72:73]
	s_mov_b32 m0, s28
	s_add_i32 s29, s26, 0x6000
	global_load_lds_dwordx4 v164, s[8:9]
	s_mov_b32 m0, s29
	v_mov_b32_e32 v173, 0
	global_load_lds_dwordx4 v168, s[8:9]
	v_mov_b32_e32 v167, v173
	v_mov_b32_e32 v171, v173
	v_mov_b32_e32 v165, v173
	v_mov_b32_e32 v169, v173
	s_cmp_eq_u32 s4, 1
	s_mov_b32 s33, 0
	s_waitcnt vmcnt(0)
	v_lshl_add_u64 v[8:9], s[74:75], 0, v[166:167]
	v_lshl_add_u64 v[6:7], s[74:75], 0, v[170:171]
	v_lshl_add_u64 v[2:3], s[72:73], 0, v[164:165]
	s_cselect_b64 s[8:9], -1, 0
	s_cmp_lg_u32 s4, 1
	v_lshl_add_u64 v[4:5], s[72:73], 0, v[168:169]
	s_cbranch_scc1 .LBB0_281
.LBB0_281:
	s_mov_b64 s[10:11], 0x80
	s_add_i32 m0, s26, 0x18000
	v_lshl_add_u64 v[8:9], v[8:9], 0, s[10:11]
	s_and_b32 s7, s52, 3
	s_lshl_b32 s44, s4, 6
	s_lshl_b32 s13, s4, 13
	s_waitcnt vmcnt(2)
	s_barrier
	global_load_lds_dwordx4 v[8:9], off
	v_lshl_add_u64 v[6:7], v[6:7], 0, s[10:11]
	s_add_i32 m0, s26, 0x1a000
	s_add_i32 s45, s26, 0x8000
	s_add_i32 s78, s26, 0xa000
	global_load_lds_dwordx4 v[6:7], off
	v_lshl_add_u64 v[2:3], v[2:3], 0, s[10:11]
	s_mov_b32 m0, s45
	s_add_u32 s4, s74, 0x40080
	global_load_lds_dwordx4 v[2:3], off
	v_lshl_add_u64 v[2:3], v[4:5], 0, s[10:11]
	s_mov_b32 m0, s78
	s_addc_u32 s5, s75, 0
	global_load_lds_dwordx4 v[2:3], off
	s_add_i32 m0, s26, 0x1c000
	v_lshl_add_u64 v[2:3], s[4:5], 0, v[166:167]
	global_load_lds_dwordx4 v[2:3], off
	v_lshl_add_u64 v[2:3], s[4:5], 0, v[170:171]
	s_add_i32 m0, s26, 0x1e000
	s_cmpk_lt_u32 s12, 0x100
	global_load_lds_dwordx4 v[2:3], off
	v_lshlrev_b32_e32 v3, 2, v163
	v_lshl_or_b32 v2, v163, 6, v214
	v_and_b32_e32 v3, 32, v3
	v_bitop3_b32 v2, v2, s13, v3 bitop3:0xde
	v_lshlrev_b32_e32 v3, 8, v0
	s_cselect_b64 s[12:13], -1, 0
	s_cmp_lt_u32 s7, 2
	v_and_b32_e32 v3, 0x18000, v3
	v_lshlrev_b32_e32 v4, 11, v210
	s_cselect_b64 s[4:5], -1, 0
	s_lshl_b32 s24, s52, 6
	v_or3_b32 v3, v208, v3, v4
	s_and_b32 s24, s24, 64
	v_add_u32_e32 v178, v3, v209
	v_lshlrev_b32_e32 v3, 4, v211
	s_waitcnt vmcnt(6)
	v_lshl_or_b32 v172, v254, 4, s24
	v_and_b32_e32 v3, 0x38000, v3
	v_lshl_or_b32 v190, s7, 12, v215
	v_lshl_add_u64 v[174:175], s[82:83], 0, v[172:173]
	v_or3_b32 v3, v208, v3, v4
	s_add_i32 s81, 0, 0x10000
	s_add_i32 s82, 0, 0x14000
	v_or_b32_e32 v191, 16, v163
	v_or_b32_e32 v192, 32, v163
	v_or_b32_e32 v193, 48, v163
	s_ashr_i32 s79, s90, 31
	s_ashr_i32 s80, s2, 31
	v_lshl_add_u64 v[176:177], s[54:55], 0, v[172:173]
	v_lshl_or_b32 v194, s7, 5, v229
	v_mov_b32_e32 v179, v173
	v_add_u32_e32 v180, v3, v209
	v_mov_b32_e32 v181, v173
	v_add_u32_e32 v195, s81, v190
	v_add_u32_e32 v196, s82, v190
	v_add_u32_e32 v197, 0, v2
	s_mov_b32 s83, 0xa0000
	s_mov_b64 s[52:53], 0xb0000
	s_mov_b32 s84, 0xb0000
	v_mov_b32_e32 v198, 0x3c800000
	v_mov_b32_e32 v199, 0x3ab504f3
	s_barrier
	s_branch .LBB0_284

; #define PG8_STAGE(bufoff, gbase, voff) do { _Pragma("unroll") for (int _i = 0; _i < 2; ++_i) \
;         __builtin_amdgcn_global_load_lds((const unsigned*)((const char*)(gbase) + (voff)[_i]), (PG8_LAS unsigned*)(lds + (bufoff) + ldsw + _i * 8192), 16, 0, 0); } while (0)
; #define PG8_LDA(dst, b, h) do { _Pragma("unroll") for (int m = 0; m < 4; ++m) _Pragma("unroll") for (int k = 0; k < 2; ++k) dst[m][k] = *(const PG8_LAS bf16x8*)(lds + PG8_SA(b, h) + aoff + m * 2048 + k * 1024); } while (0)
; #define PG8_LDB(dst, b, h) do { _Pragma("unroll") for (int n = 0; n < 2; ++n) _Pragma("unroll") for (int k = 0; k < 2; ++k) dst[n][k] = *(const PG8_LAS bf16x8*)(lds + PG8_SB(b, h) + boff + n * 2048 + k * 1024); } while (0)
; #define PG8_WAIT_V(n) asm volatile("s_waitcnt vmcnt(" #n ")" ::: "memory")
; #define PG8_WAIT_L(n) asm volatile("s_waitcnt lgkmcnt(" #n ")" ::: "memory")
; #define PG8_BAR __builtin_amdgcn_s_barrier()
; #define PG8_SCHED __builtin_amdgcn_sched_barrier(0)
; template <class Epi, class Sched, bool ALIGN_EPI = false, bool SP2 = false, bool F8 = false>
; __device__ __forceinline__ void gemm_phase(PG8_LAS unsigned char* lds, const Gemm g, const Sched& S, const Epi& E) {
;     ...
;         const char* nA = has_next ? PG8_ABASE(nxt.pm) : cA; const char* nB = has_next ? (const char*)g.Bt + (size_t)nxt.pn * tstep : cB;
;         for (int t = 0; t < nt; t += 2) {
;             const bool last = (t == nt - 2);
;             const char* a1 = cA + (size_t)(t + 1) * kstep;
;             const char* a2 = last ? nA : cA + (size_t)(t + 2) * kstep; const char* b2 = last ? nB : cB + (size_t)(t + 2) * kstep;
;             const char* a3 = a2 + kstep; const char* b3 = b2 + kstep;
;             if (last && has_next) S.a_ready(nxt);
;             if constexpr (SP2) {
;             PG8_LDB(B0, 0, 0); PG8_LDB(B1, 0, 1); PG8_SCHED; PG8_LDA(At, 0, 0); PG8_STAGE(PG8_SA(1, 1), a1 + hstepA, voffA);
;             PG8_WAIT_V(8); PG8_WAIT_L(0); PG8_BAR; PG8_MMA(0, 0, At, B0); PG8_MMA(0, 1, At, B1); PG8_BAR; PG8_SCHED;
;     ...
;         for (int a = 0; a < 2; ++a)
; #pragma unroll
;             for (int b = 0; b < 2; ++b)
; #pragma unroll
;                 for (int m = 0; m < 4; ++m)
; #pragma unroll
;                     for (int n = 0; n < 2; ++n) acc[a][b][m][n] = (f32x4){0.f, 0.f, 0.f, 0.f};
.LBB0_290:
	s_ashr_i32 s65, s64, 31
	s_lshl_b64 s[24:25], s[64:65], 19
	s_add_u32 s66, s15, s24
	s_addc_u32 s67, s23, s25
	s_and_b64 s[24:25], s[54:55], exec
	s_cselect_b32 s7, s67, s73
	s_cselect_b32 s65, s66, s72
	s_ashr_i32 s63, s62, 31
	s_lshl_b64 s[24:25], s[62:63], 19
	s_add_u32 s68, s50, s24
	s_addc_u32 s69, s51, s25
	s_and_b64 s[24:25], s[54:55], exec
	s_cselect_b32 s63, s69, s75
	s_cselect_b32 s71, s68, s74
	s_add_u32 s72, s72, 0x40080
	s_addc_u32 s73, s73, 0
	s_add_u32 s85, s74, 0x100
	v_mov_b32_e32 v34, 0
	s_addc_u32 s86, s75, 0
	s_mov_b32 s87, -2
	v_mov_b32_e32 v35, 0
	v_pk_mul_f32 v[36:37], v[34:35], v[34:35]
	v_pk_mul_f32 v[38:39], v[34:35], v[34:35]
	v_pk_mul_f32 v[40:41], v[34:35], v[34:35]
	v_pk_mul_f32 v[42:43], v[34:35], v[34:35]
	v_pk_mul_f32 v[44:45], v[34:35], v[34:35]
	v_pk_mul_f32 v[46:47], v[34:35], v[34:35]
	v_pk_mul_f32 v[48:49], v[34:35], v[34:35]
	v_pk_mul_f32 v[50:51], v[34:35], v[34:35]
	v_pk_mul_f32 v[52:53], v[34:35], v[34:35]
	v_pk_mul_f32 v[54:55], v[34:35], v[34:35]
	v_pk_mul_f32 v[56:57], v[34:35], v[34:35]
	v_pk_mul_f32 v[58:59], v[34:35], v[34:35]
	v_pk_mul_f32 v[60:61], v[34:35], v[34:35]
	v_pk_mul_f32 v[62:63], v[34:35], v[34:35]
	v_pk_mul_f32 v[64:65], v[34:35], v[34:35]
	v_pk_mul_f32 v[66:67], v[34:35], v[34:35]
	v_pk_mul_f32 v[68:69], v[34:35], v[34:35]
	v_pk_mul_f32 v[70:71], v[34:35], v[34:35]
	v_pk_mul_f32 v[72:73], v[34:35], v[34:35]
	v_pk_mul_f32 v[74:75], v[34:35], v[34:35]
	v_pk_mul_f32 v[76:77], v[34:35], v[34:35]
	v_pk_mul_f32 v[78:79], v[34:35], v[34:35]
	v_pk_mul_f32 v[80:81], v[34:35], v[34:35]
	v_pk_mul_f32 v[82:83], v[34:35], v[34:35]
	v_pk_mul_f32 v[84:85], v[34:35], v[34:35]
	v_pk_mul_f32 v[86:87], v[34:35], v[34:35]
	v_pk_mul_f32 v[88:89], v[34:35], v[34:35]
	v_pk_mul_f32 v[90:91], v[34:35], v[34:35]
	v_pk_mul_f32 v[92:93], v[34:35], v[34:35]
	v_pk_mul_f32 v[94:95], v[34:35], v[34:35]
	v_pk_mul_f32 v[96:97], v[34:35], v[34:35]
	v_pk_mul_f32 v[98:99], v[34:35], v[34:35]
	v_pk_mul_f32 v[100:101], v[34:35], v[34:35]
	v_pk_mul_f32 v[102:103], v[34:35], v[34:35]
	v_pk_mul_f32 v[104:105], v[34:35], v[34:35]
	v_pk_mul_f32 v[106:107], v[34:35], v[34:35]
	v_pk_mul_f32 v[108:109], v[34:35], v[34:35]
	v_pk_mul_f32 v[110:111], v[34:35], v[34:35]
	v_pk_mul_f32 v[112:113], v[34:35], v[34:35]
	v_pk_mul_f32 v[114:115], v[34:35], v[34:35]
	v_pk_mul_f32 v[116:117], v[34:35], v[34:35]
	v_pk_mul_f32 v[118:119], v[34:35], v[34:35]
	v_pk_mul_f32 v[120:121], v[34:35], v[34:35]
	v_pk_mul_f32 v[122:123], v[34:35], v[34:35]
	v_pk_mul_f32 v[124:125], v[34:35], v[34:35]
	v_pk_mul_f32 v[126:127], v[34:35], v[34:35]
	v_pk_mul_f32 v[128:129], v[34:35], v[34:35]
	v_pk_mul_f32 v[130:131], v[34:35], v[34:35]
	v_pk_mul_f32 v[132:133], v[34:35], v[34:35]
	v_pk_mul_f32 v[134:135], v[34:35], v[34:35]
	v_pk_mul_f32 v[136:137], v[34:35], v[34:35]
	v_pk_mul_f32 v[138:139], v[34:35], v[34:35]
	v_pk_mul_f32 v[140:141], v[34:35], v[34:35]
	v_pk_mul_f32 v[142:143], v[34:35], v[34:35]
	v_pk_mul_f32 v[144:145], v[34:35], v[34:35]
	v_pk_mul_f32 v[146:147], v[34:35], v[34:35]
	v_pk_mul_f32 v[148:149], v[34:35], v[34:35]
	v_pk_mul_f32 v[150:151], v[34:35], v[34:35]
	v_pk_mul_f32 v[152:153], v[34:35], v[34:35]
	v_pk_mul_f32 v[154:155], v[34:35], v[34:35]
	v_pk_mul_f32 v[156:157], v[34:35], v[34:35]
	v_pk_mul_f32 v[158:159], v[34:35], v[34:35]
	v_pk_mul_f32 v[160:161], v[34:35], v[34:35]
	s_cmp_lg_u64 s[8:9], 0
	s_cbranch_scc1 .Lk1_Y
.LBB0_291:
	ds_read_b128 v[26:29], v195
	ds_read_b128 v[30:33], v195 offset:1024
	ds_read_b128 v[18:21], v195 offset:2048
	ds_read_b128 v[22:25], v195 offset:3072
	ds_read_b128 v[10:13], v196
	ds_read_b128 v[14:17], v196 offset:1024
	ds_read_b128 v[2:5], v196 offset:2048
	ds_read_b128 v[6:9], v196 offset:3072
	s_add_u32 s24, s72, 0xfffc0080
	s_addc_u32 s25, s73, -1
	s_cmp_eq_u32 s87, 12
	s_cselect_b32 s77, s7, s25
	s_cselect_b32 s76, s65, s24
	s_cselect_b32 s75, s63, s86
	s_cselect_b32 s74, s71, s85
	v_lshl_add_u64 v[226:227], s[72:73], 0, v[178:179]
	s_add_i32 m0, s26, 0xc000
	ds_read_b128 v[182:185], v197
	ds_read_b128 v[186:189], v197 offset:1024
	ds_read_b128 v[200:203], v197 offset:2048
	ds_read_b128 v[204:207], v197 offset:3072
	ds_read_b128 v[208:211], v197 offset:4096
	ds_read_b128 v[212:215], v197 offset:5120
	ds_read_b128 v[218:221], v197 offset:6144
	ds_read_b128 v[222:225], v197 offset:7168
	global_load_lds_dwordx4 v[226:227], off
	v_lshl_add_u64 v[226:227], s[72:73], 0, v[180:181]
	s_add_i32 m0, s26, 0xe000
	s_nop 0
	global_load_lds_dwordx4 v[226:227], off
	s_waitcnt vmcnt(8)
	s_waitcnt lgkmcnt(0)
	s_setprio 1
	s_waitcnt lgkmcnt(0)
	v_mfma_f32_16x16x128_f8f6f4 v[158:161], v[26:33], v[182:189], v[158:161]
	v_mfma_f32_16x16x128_f8f6f4 v[154:157], v[18:25], v[182:189], v[154:157]
	v_mfma_f32_16x16x128_f8f6f4 v[142:145], v[26:33], v[200:207], v[142:145]
	v_mfma_f32_16x16x128_f8f6f4 v[138:141], v[18:25], v[200:207], v[138:141]
	v_mfma_f32_16x16x128_f8f6f4 v[126:129], v[26:33], v[208:215], v[126:129]
	v_mfma_f32_16x16x128_f8f6f4 v[122:125], v[18:25], v[208:215], v[122:125]
	v_mfma_f32_16x16x128_f8f6f4 v[110:113], v[26:33], v[218:225], v[110:113]
	v_mfma_f32_16x16x128_f8f6f4 v[106:109], v[18:25], v[218:225], v[106:109]
	s_setprio 0
	s_setprio 1
	v_mfma_f32_16x16x128_f8f6f4 v[150:153], v[10:17], v[182:189], v[150:153]
	v_mfma_f32_16x16x128_f8f6f4 v[146:149], v[2:9], v[182:189], v[146:149]
	v_mfma_f32_16x16x128_f8f6f4 v[134:137], v[10:17], v[200:207], v[134:137]
	v_mfma_f32_16x16x128_f8f6f4 v[130:133], v[2:9], v[200:207], v[130:133]
	v_mfma_f32_16x16x128_f8f6f4 v[118:121], v[10:17], v[208:215], v[118:121]
	v_mfma_f32_16x16x128_f8f6f4 v[114:117], v[2:9], v[208:215], v[114:117]
	v_mfma_f32_16x16x128_f8f6f4 v[102:105], v[10:17], v[218:225], v[102:105]
	v_mfma_f32_16x16x128_f8f6f4 v[98:101], v[2:9], v[218:225], v[98:101]
	s_setprio 0
	s_barrier
; #define PG8_STAGE(bufoff, gbase, voff) do { _Pragma("unroll") for (int _i = 0; _i < 2; ++_i) \
;         __builtin_amdgcn_global_load_lds((const unsigned*)((const char*)(gbase) + (voff)[_i]), (PG8_LAS unsigned*)(lds + (bufoff) + ldsw + _i * 8192), 16, 0, 0); } while (0)
; #define PG8_LDA(dst, b, h) do { _Pragma("unroll") for (int m = 0; m < 4; ++m) _Pragma("unroll") for (int k = 0; k < 2; ++k) dst[m][k] = *(const PG8_LAS bf16x8*)(lds + PG8_SA(b, h) + aoff + m * 2048 + k * 1024); } while (0)
; #define PG8_LDB(dst, b, h) do { _Pragma("unroll") for (int n = 0; n < 2; ++n) _Pragma("unroll") for (int k = 0; k < 2; ++k) dst[n][k] = *(const PG8_LAS bf16x8*)(lds + PG8_SB(b, h) + boff + n * 2048 + k * 1024); } while (0)
; #define PG8_WAIT_V(n) asm volatile("s_waitcnt vmcnt(" #n ")" ::: "memory")
; #define PG8_WAIT_L(n) asm volatile("s_waitcnt lgkmcnt(" #n ")" ::: "memory")
; #define PG8_BAR __builtin_amdgcn_s_barrier()
; #define PG8_SCHED __builtin_amdgcn_sched_barrier(0)
; template <class Epi, class Sched, bool ALIGN_EPI = false, bool SP2 = false, bool F8 = false>
; __device__ __forceinline__ void gemm_phase(PG8_LAS unsigned char* lds, const Gemm g, const Sched& S, const Epi& E) {
;     ...
;             PG8_LDA(At, 0, 1); PG8_STAGE(PG8_SB(0, 0), b2, voffB); PG8_STAGE(PG8_SB(0, 1), b2 + hstep, voffB); PG8_STAGE(PG8_SA(0, 0), a2, voffA);
;             PG8_WAIT_V(8); PG8_WAIT_L(0); PG8_BAR; PG8_MMA(1, 0, At, B0); PG8_MMA(1, 1, At, B1); PG8_BAR; PG8_SCHED;
;             PG8_LDB(B0, 1, 0); PG8_LDB(B1, 1, 1); PG8_SCHED; PG8_LDA(At, 1, 0); PG8_STAGE(PG8_SA(0, 1), a2 + hstepA, voffA);
;             PG8_WAIT_V(8); PG8_WAIT_L(0); PG8_BAR; PG8_MMA(0, 0, At, B0); PG8_MMA(0, 1, At, B1); PG8_BAR; PG8_SCHED;
	s_add_i32 s24, s81, s14
	v_lshl_add_u64 v[182:183], s[74:75], 0, v[166:167]
	s_mov_b32 m0, s24
	ds_read_b128 v[200:203], v197 offset:16384
	ds_read_b128 v[204:207], v197 offset:17408
	ds_read_b128 v[208:211], v197 offset:18432
	ds_read_b128 v[212:215], v197 offset:19456
	ds_read_b128 v[218:221], v197 offset:20480
	ds_read_b128 v[222:225], v197 offset:21504
	ds_read_b128 v[226:229], v197 offset:22528
	ds_read_b128 v[230:233], v197 offset:23552
	global_load_lds_dwordx4 v[182:183], off
	s_add_i32 m0, s24, 0x2000
	s_add_u32 s24, s74, 0x40000
	v_lshl_add_u64 v[184:185], s[74:75], 0, v[170:171]
	s_addc_u32 s25, s75, 0
	s_add_i32 s36, s82, s14
	global_load_lds_dwordx4 v[184:185], off
	v_lshl_add_u64 v[186:187], s[24:25], 0, v[166:167]
	s_mov_b32 m0, s36
	v_lshl_add_u64 v[188:189], s[76:77], 0, v[168:169]
	global_load_lds_dwordx4 v[186:187], off
	v_lshl_add_u64 v[186:187], s[24:25], 0, v[170:171]
	s_add_i32 m0, s36, 0x2000
	s_nop 0
	global_load_lds_dwordx4 v[186:187], off
	v_lshl_add_u64 v[186:187], s[76:77], 0, v[164:165]
	s_mov_b32 m0, s26
	s_nop 0
	global_load_lds_dwordx4 v[186:187], off
	s_mov_b32 m0, s27
	s_nop 0
	global_load_lds_dwordx4 v[188:189], off
	s_waitcnt vmcnt(8)
	s_waitcnt lgkmcnt(0)
	s_setprio 1
	s_waitcnt lgkmcnt(0)
	v_mfma_f32_16x16x128_f8f6f4 v[94:97], v[26:33], v[200:207], v[94:97]
	v_mfma_f32_16x16x128_f8f6f4 v[90:93], v[18:25], v[200:207], v[90:93]
	v_mfma_f32_16x16x128_f8f6f4 v[78:81], v[26:33], v[208:215], v[78:81]
	v_mfma_f32_16x16x128_f8f6f4 v[74:77], v[18:25], v[208:215], v[74:77]
	v_mfma_f32_16x16x128_f8f6f4 v[62:65], v[26:33], v[218:225], v[62:65]
	v_mfma_f32_16x16x128_f8f6f4 v[58:61], v[18:25], v[218:225], v[58:61]
	v_mfma_f32_16x16x128_f8f6f4 v[46:49], v[26:33], v[226:233], v[46:49]
	v_mfma_f32_16x16x128_f8f6f4 v[42:45], v[18:25], v[226:233], v[42:45]
	s_setprio 0
	s_setprio 1
	v_mfma_f32_16x16x128_f8f6f4 v[86:89], v[10:17], v[200:207], v[86:89]
	v_mfma_f32_16x16x128_f8f6f4 v[82:85], v[2:9], v[200:207], v[82:85]
	v_mfma_f32_16x16x128_f8f6f4 v[70:73], v[10:17], v[208:215], v[70:73]
	v_mfma_f32_16x16x128_f8f6f4 v[66:69], v[2:9], v[208:215], v[66:69]
	v_mfma_f32_16x16x128_f8f6f4 v[54:57], v[10:17], v[218:225], v[54:57]
	v_mfma_f32_16x16x128_f8f6f4 v[50:53], v[2:9], v[218:225], v[50:53]
	v_mfma_f32_16x16x128_f8f6f4 v[38:41], v[10:17], v[226:233], v[38:41]
	v_mfma_f32_16x16x128_f8f6f4 v[34:37], v[2:9], v[226:233], v[34:37]
	s_setprio 0
	s_barrier
	s_add_i32 s36, 0, 0x18000
	s_add_i32 s37, 0, 0x1c000
	v_add_u32_e32 v14, s36, v190
	v_add_u32_e32 v30, s37, v190
	ds_read_b128 v[2:5], v14
	ds_read_b128 v[6:9], v14 offset:1024
	ds_read_b128 v[10:13], v14 offset:2048
	ds_read_b128 v[14:17], v14 offset:3072
	ds_read_b128 v[18:21], v30
	ds_read_b128 v[22:25], v30 offset:1024
	ds_read_b128 v[26:29], v30 offset:2048
	ds_read_b128 v[30:33], v30 offset:3072
	s_add_u32 s24, s76, 0x40000
	s_addc_u32 s25, s77, 0
	s_mov_b32 m0, s28
	v_lshl_add_u64 v[234:235], s[24:25], 0, v[164:165]
	ds_read_b128 v[200:203], v197 offset:32768
	ds_read_b128 v[204:207], v197 offset:33792
	ds_read_b128 v[208:211], v197 offset:34816
	ds_read_b128 v[212:215], v197 offset:35840
	ds_read_b128 v[218:221], v197 offset:36864
	ds_read_b128 v[222:225], v197 offset:37888
	ds_read_b128 v[226:229], v197 offset:38912
	ds_read_b128 v[230:233], v197 offset:39936
	global_load_lds_dwordx4 v[234:235], off
	v_lshl_add_u64 v[234:235], s[24:25], 0, v[168:169]
	s_mov_b32 m0, s29
	s_nop 0
	global_load_lds_dwordx4 v[234:235], off
	s_waitcnt vmcnt(8)
	s_waitcnt lgkmcnt(0)
	s_setprio 1
	s_waitcnt lgkmcnt(0)
	v_mfma_f32_16x16x128_f8f6f4 v[158:161], v[2:9], v[200:207], v[158:161]
	v_mfma_f32_16x16x128_f8f6f4 v[154:157], v[10:17], v[200:207], v[154:157]
	v_mfma_f32_16x16x128_f8f6f4 v[142:145], v[2:9], v[208:215], v[142:145]
	v_mfma_f32_16x16x128_f8f6f4 v[138:141], v[10:17], v[208:215], v[138:141]
	v_mfma_f32_16x16x128_f8f6f4 v[126:129], v[2:9], v[218:225], v[126:129]
	v_mfma_f32_16x16x128_f8f6f4 v[122:125], v[10:17], v[218:225], v[122:125]
	v_mfma_f32_16x16x128_f8f6f4 v[110:113], v[2:9], v[226:233], v[110:113]
	v_mfma_f32_16x16x128_f8f6f4 v[106:109], v[10:17], v[226:233], v[106:109]
	s_setprio 0
	s_setprio 1
	v_mfma_f32_16x16x128_f8f6f4 v[150:153], v[18:25], v[200:207], v[150:153]
	v_mfma_f32_16x16x128_f8f6f4 v[146:149], v[26:33], v[200:207], v[146:149]
	v_mfma_f32_16x16x128_f8f6f4 v[134:137], v[18:25], v[208:215], v[134:137]
	v_mfma_f32_16x16x128_f8f6f4 v[130:133], v[26:33], v[208:215], v[130:133]
	v_mfma_f32_16x16x128_f8f6f4 v[118:121], v[18:25], v[218:225], v[118:121]
	v_mfma_f32_16x16x128_f8f6f4 v[114:117], v[26:33], v[218:225], v[114:117]
	v_mfma_f32_16x16x128_f8f6f4 v[102:105], v[18:25], v[226:233], v[102:105]
	v_mfma_f32_16x16x128_f8f6f4 v[98:101], v[26:33], v[226:233], v[98:101]
	s_setprio 0
	s_barrier
; #define PG8_STAGE(bufoff, gbase, voff) do { _Pragma("unroll") for (int _i = 0; _i < 2; ++_i) \
;         __builtin_amdgcn_global_load_lds((const unsigned*)((const char*)(gbase) + (voff)[_i]), (PG8_LAS unsigned*)(lds + (bufoff) + ldsw + _i * 8192), 16, 0, 0); } while (0)
; #define PG8_LDA(dst, b, h) do { _Pragma("unroll") for (int m = 0; m < 4; ++m) _Pragma("unroll") for (int k = 0; k < 2; ++k) dst[m][k] = *(const PG8_LAS bf16x8*)(lds + PG8_SA(b, h) + aoff + m * 2048 + k * 1024); } while (0)
; #define PG8_LDB(dst, b, h) do { _Pragma("unroll") for (int n = 0; n < 2; ++n) _Pragma("unroll") for (int k = 0; k < 2; ++k) dst[n][k] = *(const PG8_LAS bf16x8*)(lds + PG8_SB(b, h) + boff + n * 2048 + k * 1024); } while (0)
; #define PG8_WAIT_V(n) asm volatile("s_waitcnt vmcnt(" #n ")" ::: "memory")
; #define PG8_WAIT_L(n) asm volatile("s_waitcnt lgkmcnt(" #n ")" ::: "memory")
; #define PG8_BAR __builtin_amdgcn_s_barrier()
; #define PG8_SCHED __builtin_amdgcn_sched_barrier(0)
; template <class Epi, class Sched, bool ALIGN_EPI = false, bool SP2 = false, bool F8 = false>
; __device__ __forceinline__ void gemm_phase(PG8_LAS unsigned char* lds, const Gemm g, const Sched& S, const Epi& E) {
;     ...
;             PG8_LDB(B0, 0, 0); PG8_LDB(B1, 0, 1); PG8_SCHED; PG8_LDA(At, 0, 0); PG8_STAGE(PG8_SA(1, 1), a1 + hstepA, voffA);
;             PG8_WAIT_V(8); PG8_WAIT_L(0); PG8_BAR; PG8_MMA(0, 0, At, B0); PG8_MMA(0, 1, At, B1); PG8_BAR; PG8_SCHED;
;             PG8_LDA(At, 0, 1); PG8_STAGE(PG8_SB(0, 0), b2, voffB); PG8_STAGE(PG8_SB(0, 1), b2 + hstep, voffB); PG8_STAGE(PG8_SA(0, 0), a2, voffA);
;     ...
;             PG8_LDA(At, 1, 1); PG8_STAGE(PG8_SB(1, 0), b3, voffB); PG8_STAGE(PG8_SB(1, 1), b3 + hstep, voffB); PG8_STAGE(PG8_SA(1, 0), a3, voffA);
;             PG8_WAIT_V(8); PG8_WAIT_L(0); PG8_BAR; PG8_MMA(1, 0, At, B0); PG8_MMA(1, 1, At, B1); PG8_BAR; PG8_SCHED;
	s_add_i32 s24, s36, s14
	v_lshl_add_u64 v[182:183], v[182:183], 0, s[10:11]
	s_mov_b32 m0, s24
	ds_read_b128 v[200:203], v197 offset:49152
	ds_read_b128 v[204:207], v197 offset:50176
	ds_read_b128 v[208:211], v197 offset:51200
	ds_read_b128 v[212:215], v197 offset:52224
	ds_read_b128 v[218:221], v197 offset:53248
	ds_read_b128 v[222:225], v197 offset:54272
	ds_read_b128 v[226:229], v197 offset:55296
	ds_read_b128 v[230:233], v197 offset:56320
	global_load_lds_dwordx4 v[182:183], off
	s_add_i32 m0, s24, 0x2000
	s_add_u32 s24, s74, 0x40080
	v_lshl_add_u64 v[182:183], v[184:185], 0, s[10:11]
	s_addc_u32 s25, s75, 0
	s_add_i32 s36, s37, s14
	global_load_lds_dwordx4 v[182:183], off
	v_lshl_add_u64 v[182:183], s[24:25], 0, v[166:167]
	s_mov_b32 m0, s36
	s_nop 0
	global_load_lds_dwordx4 v[182:183], off
	v_lshl_add_u64 v[182:183], s[24:25], 0, v[170:171]
	s_add_i32 m0, s36, 0x2000
	s_nop 0
	global_load_lds_dwordx4 v[182:183], off
	v_lshl_add_u64 v[182:183], v[186:187], 0, s[10:11]
	s_mov_b32 m0, s45
	s_nop 0
	global_load_lds_dwordx4 v[182:183], off
	v_lshl_add_u64 v[182:183], v[188:189], 0, s[10:11]
	s_mov_b32 m0, s78
	s_nop 0
	global_load_lds_dwordx4 v[182:183], off
	s_waitcnt vmcnt(8)
	s_waitcnt lgkmcnt(0)
	s_setprio 1
	s_waitcnt lgkmcnt(0)
	v_mfma_f32_16x16x128_f8f6f4 v[94:97], v[2:9], v[200:207], v[94:97]
	v_mfma_f32_16x16x128_f8f6f4 v[90:93], v[10:17], v[200:207], v[90:93]
	v_mfma_f32_16x16x128_f8f6f4 v[78:81], v[2:9], v[208:215], v[78:81]
	v_mfma_f32_16x16x128_f8f6f4 v[74:77], v[10:17], v[208:215], v[74:77]
	v_mfma_f32_16x16x128_f8f6f4 v[62:65], v[2:9], v[218:225], v[62:65]
	v_mfma_f32_16x16x128_f8f6f4 v[58:61], v[10:17], v[218:225], v[58:61]
	v_mfma_f32_16x16x128_f8f6f4 v[46:49], v[2:9], v[226:233], v[46:49]
	v_mfma_f32_16x16x128_f8f6f4 v[42:45], v[10:17], v[226:233], v[42:45]
	s_setprio 0
	s_setprio 1
	v_mfma_f32_16x16x128_f8f6f4 v[86:89], v[18:25], v[200:207], v[86:89]
	v_mfma_f32_16x16x128_f8f6f4 v[82:85], v[26:33], v[200:207], v[82:85]
	v_mfma_f32_16x16x128_f8f6f4 v[70:73], v[18:25], v[208:215], v[70:73]
	v_mfma_f32_16x16x128_f8f6f4 v[66:69], v[26:33], v[208:215], v[66:69]
	v_mfma_f32_16x16x128_f8f6f4 v[54:57], v[18:25], v[218:225], v[54:57]
	v_mfma_f32_16x16x128_f8f6f4 v[50:53], v[26:33], v[218:225], v[50:53]
	v_mfma_f32_16x16x128_f8f6f4 v[38:41], v[18:25], v[226:233], v[38:41]
	v_mfma_f32_16x16x128_f8f6f4 v[34:37], v[26:33], v[226:233], v[34:37]
	s_setprio 0
	s_barrier
	s_add_i32 s87, s87, 2
	s_add_u32 s72, s72, 0x100
	s_addc_u32 s73, s73, 0
	s_add_u32 s85, s85, 0x100
	s_addc_u32 s86, s86, 0
	s_cmp_gt_u32 s87, 13
	s_cbranch_scc0 .LBB0_291
	s_branch .Lk1_exit
.Lk1_Y:
	ds_read_b128 v[26:29], v195
	ds_read_b128 v[30:33], v195 offset:1024
	ds_read_b128 v[18:21], v195 offset:2048
	ds_read_b128 v[22:25], v195 offset:3072
	ds_read_b128 v[10:13], v196
	ds_read_b128 v[14:17], v196 offset:1024
	ds_read_b128 v[2:5], v196 offset:2048
	ds_read_b128 v[6:9], v196 offset:3072
	s_add_u32 s24, s72, 0xfffc0080
	s_addc_u32 s25, s73, -1
	s_cmp_eq_u32 s87, 12
	s_cselect_b32 s77, s7, s25
	s_cselect_b32 s76, s65, s24
	s_cselect_b32 s75, s63, s86
	s_cselect_b32 s74, s71, s85
	v_lshl_add_u64 v[226:227], s[72:73], 0, v[178:179]
	s_add_i32 m0, s26, 0xc000
	ds_read_b128 v[182:185], v197
	ds_read_b128 v[186:189], v197 offset:1024
	ds_read_b128 v[200:203], v197 offset:2048
	ds_read_b128 v[204:207], v197 offset:3072
	ds_read_b128 v[208:211], v197 offset:4096
	ds_read_b128 v[212:215], v197 offset:5120
	ds_read_b128 v[218:221], v197 offset:6144
	ds_read_b128 v[222:225], v197 offset:7168
	global_load_lds_dwordx4 v[226:227], off
	v_lshl_add_u64 v[226:227], s[72:73], 0, v[180:181]
	s_add_i32 m0, s26, 0xe000
	s_nop 0
	global_load_lds_dwordx4 v[226:227], off
	s_waitcnt vmcnt(8)
	s_waitcnt lgkmcnt(0)
	s_barrier
	s_setprio 3
	s_waitcnt lgkmcnt(0)
	v_mfma_f32_16x16x128_f8f6f4 v[158:161], v[26:33], v[182:189], v[158:161]
	v_mfma_f32_16x16x128_f8f6f4 v[154:157], v[18:25], v[182:189], v[154:157]
	v_mfma_f32_16x16x128_f8f6f4 v[142:145], v[26:33], v[200:207], v[142:145]
	v_mfma_f32_16x16x128_f8f6f4 v[138:141], v[18:25], v[200:207], v[138:141]
	v_mfma_f32_16x16x128_f8f6f4 v[126:129], v[26:33], v[208:215], v[126:129]
	v_mfma_f32_16x16x128_f8f6f4 v[122:125], v[18:25], v[208:215], v[122:125]
	v_mfma_f32_16x16x128_f8f6f4 v[110:113], v[26:33], v[218:225], v[110:113]
	v_mfma_f32_16x16x128_f8f6f4 v[106:109], v[18:25], v[218:225], v[106:109]
	s_setprio 0
	s_setprio 3
	v_mfma_f32_16x16x128_f8f6f4 v[150:153], v[10:17], v[182:189], v[150:153]
	v_mfma_f32_16x16x128_f8f6f4 v[146:149], v[2:9], v[182:189], v[146:149]
	v_mfma_f32_16x16x128_f8f6f4 v[134:137], v[10:17], v[200:207], v[134:137]
	v_mfma_f32_16x16x128_f8f6f4 v[130:133], v[2:9], v[200:207], v[130:133]
	v_mfma_f32_16x16x128_f8f6f4 v[118:121], v[10:17], v[208:215], v[118:121]
	v_mfma_f32_16x16x128_f8f6f4 v[114:117], v[2:9], v[208:215], v[114:117]
	v_mfma_f32_16x16x128_f8f6f4 v[102:105], v[10:17], v[218:225], v[102:105]
	v_mfma_f32_16x16x128_f8f6f4 v[98:101], v[2:9], v[218:225], v[98:101]
	s_setprio 0
	s_add_i32 s24, s81, s14
	v_lshl_add_u64 v[182:183], s[74:75], 0, v[166:167]
	s_mov_b32 m0, s24
	ds_read_b128 v[200:203], v197 offset:16384
	ds_read_b128 v[204:207], v197 offset:17408
	ds_read_b128 v[208:211], v197 offset:18432
	ds_read_b128 v[212:215], v197 offset:19456
	ds_read_b128 v[218:221], v197 offset:20480
	ds_read_b128 v[222:225], v197 offset:21504
	ds_read_b128 v[226:229], v197 offset:22528
	ds_read_b128 v[230:233], v197 offset:23552
	global_load_lds_dwordx4 v[182:183], off
	s_add_i32 m0, s24, 0x2000
	s_add_u32 s24, s74, 0x40000
	v_lshl_add_u64 v[184:185], s[74:75], 0, v[170:171]
	s_addc_u32 s25, s75, 0
	s_add_i32 s36, s82, s14
	global_load_lds_dwordx4 v[184:185], off
	v_lshl_add_u64 v[186:187], s[24:25], 0, v[166:167]
	s_mov_b32 m0, s36
	v_lshl_add_u64 v[188:189], s[76:77], 0, v[168:169]
	global_load_lds_dwordx4 v[186:187], off
	v_lshl_add_u64 v[186:187], s[24:25], 0, v[170:171]
	s_add_i32 m0, s36, 0x2000
	s_nop 0
	global_load_lds_dwordx4 v[186:187], off
	v_lshl_add_u64 v[186:187], s[76:77], 0, v[164:165]
	s_mov_b32 m0, s26
	s_nop 0
	global_load_lds_dwordx4 v[186:187], off
	s_mov_b32 m0, s27
	s_nop 0
	global_load_lds_dwordx4 v[188:189], off
	s_waitcnt vmcnt(8)
	s_waitcnt lgkmcnt(0)
	s_barrier
; #define PG8_STAGE(bufoff, gbase, voff) do { _Pragma("unroll") for (int _i = 0; _i < 2; ++_i) \
;         __builtin_amdgcn_global_load_lds((const unsigned*)((const char*)(gbase) + (voff)[_i]), (PG8_LAS unsigned*)(lds + (bufoff) + ldsw + _i * 8192), 16, 0, 0); } while (0)
; #define PG8_LDA(dst, b, h) do { _Pragma("unroll") for (int m = 0; m < 4; ++m) _Pragma("unroll") for (int k = 0; k < 2; ++k) dst[m][k] = *(const PG8_LAS bf16x8*)(lds + PG8_SA(b, h) + aoff + m * 2048 + k * 1024); } while (0)
; #define PG8_BAR __builtin_amdgcn_s_barrier()
; template <class Epi, class Sched, bool ALIGN_EPI = false, bool SP2 = false, bool F8 = false>
; __device__ __forceinline__ void gemm_phase(PG8_LAS unsigned char* lds, const Gemm g, const Sched& S, const Epi& E) {
;     ...
;             PG8_WAIT_V(8); PG8_WAIT_L(0); PG8_BAR; PG8_MMA(1, 0, At, B0); PG8_MMA(1, 1, At, B1); PG8_BAR; PG8_SCHED;
;             PG8_LDB(B0, 1, 0); PG8_LDB(B1, 1, 1); PG8_SCHED; PG8_LDA(At, 1, 0); PG8_STAGE(PG8_SA(0, 1), a2 + hstepA, voffA);
;             PG8_WAIT_V(8); PG8_WAIT_L(0); PG8_BAR; PG8_MMA(0, 0, At, B0); PG8_MMA(0, 1, At, B1); PG8_BAR; PG8_SCHED;
;             PG8_LDA(At, 1, 1); PG8_STAGE(PG8_SB(1, 0), b3, voffB); PG8_STAGE(PG8_SB(1, 1), b3 + hstep, voffB); PG8_STAGE(PG8_SA(1, 0), a3, voffA);
;             PG8_WAIT_V(8); PG8_WAIT_L(0); PG8_BAR; PG8_MMA(1, 0, At, B0); PG8_MMA(1, 1, At, B1); PG8_BAR; PG8_SCHED;
;     ...
;         if constexpr (F8) {
;             asm volatile("s_nop 7\n\ts_nop 7\n\ts_nop 7" : "+v"(acc[0][0][0][0]), "+v"(acc[0][0][0][1]), "+v"(acc[0][0][1][0]), "+v"(acc[0][0][1][1]), "+v"(acc[0][0][2][0]), "+v"(acc[0][0][2][1]), "+v"(acc[0][0][3][0]), "+v"(acc[0][0][3][1]) :: "memory");
;             asm volatile("" : "+v"(acc[0][1][0][0]), "+v"(acc[0][1][0][1]), "+v"(acc[0][1][1][0]), "+v"(acc[0][1][1][1]), "+v"(acc[0][1][2][0]), "+v"(acc[0][1][2][1]), "+v"(acc[0][1][3][0]), "+v"(acc[0][1][3][1]));
;             asm volatile("" : "+v"(acc[1][0][0][0]), "+v"(acc[1][0][0][1]), "+v"(acc[1][0][1][0]), "+v"(acc[1][0][1][1]), "+v"(acc[1][0][2][0]), "+v"(acc[1][0][2][1]), "+v"(acc[1][0][3][0]), "+v"(acc[1][0][3][1]));
;             asm volatile("" : "+v"(acc[1][1][0][0]), "+v"(acc[1][1][0][1]), "+v"(acc[1][1][1][0]), "+v"(acc[1][1][1][1]), "+v"(acc[1][1][2][0]), "+v"(acc[1][1][2][1]), "+v"(acc[1][1][3][0]), "+v"(acc[1][1][3][1])); }
;         if constexpr (ALIGN_EPI) { if (wr == 0) PG8_BAR; }
	s_setprio 3
	s_waitcnt lgkmcnt(0)
	v_mfma_f32_16x16x128_f8f6f4 v[94:97], v[26:33], v[200:207], v[94:97]
	v_mfma_f32_16x16x128_f8f6f4 v[90:93], v[18:25], v[200:207], v[90:93]
	v_mfma_f32_16x16x128_f8f6f4 v[78:81], v[26:33], v[208:215], v[78:81]
	v_mfma_f32_16x16x128_f8f6f4 v[74:77], v[18:25], v[208:215], v[74:77]
	v_mfma_f32_16x16x128_f8f6f4 v[62:65], v[26:33], v[218:225], v[62:65]
	v_mfma_f32_16x16x128_f8f6f4 v[58:61], v[18:25], v[218:225], v[58:61]
	v_mfma_f32_16x16x128_f8f6f4 v[46:49], v[26:33], v[226:233], v[46:49]
	v_mfma_f32_16x16x128_f8f6f4 v[42:45], v[18:25], v[226:233], v[42:45]
	s_setprio 0
	s_setprio 3
	v_mfma_f32_16x16x128_f8f6f4 v[86:89], v[10:17], v[200:207], v[86:89]
	v_mfma_f32_16x16x128_f8f6f4 v[82:85], v[2:9], v[200:207], v[82:85]
	v_mfma_f32_16x16x128_f8f6f4 v[70:73], v[10:17], v[208:215], v[70:73]
	v_mfma_f32_16x16x128_f8f6f4 v[66:69], v[2:9], v[208:215], v[66:69]
	v_mfma_f32_16x16x128_f8f6f4 v[54:57], v[10:17], v[218:225], v[54:57]
	v_mfma_f32_16x16x128_f8f6f4 v[50:53], v[2:9], v[218:225], v[50:53]
	v_mfma_f32_16x16x128_f8f6f4 v[38:41], v[10:17], v[226:233], v[38:41]
	v_mfma_f32_16x16x128_f8f6f4 v[34:37], v[2:9], v[226:233], v[34:37]
	s_setprio 0
	s_add_i32 s36, 0, 0x18000
	s_add_i32 s37, 0, 0x1c000
	v_add_u32_e32 v14, s36, v190
	v_add_u32_e32 v30, s37, v190
	ds_read_b128 v[2:5], v14
	ds_read_b128 v[6:9], v14 offset:1024
	ds_read_b128 v[10:13], v14 offset:2048
	ds_read_b128 v[14:17], v14 offset:3072
	ds_read_b128 v[18:21], v30
	ds_read_b128 v[22:25], v30 offset:1024
	ds_read_b128 v[26:29], v30 offset:2048
	ds_read_b128 v[30:33], v30 offset:3072
	s_add_u32 s24, s76, 0x40000
	s_addc_u32 s25, s77, 0
	s_mov_b32 m0, s28
	v_lshl_add_u64 v[234:235], s[24:25], 0, v[164:165]
	ds_read_b128 v[200:203], v197 offset:32768
	ds_read_b128 v[204:207], v197 offset:33792
	ds_read_b128 v[208:211], v197 offset:34816
	ds_read_b128 v[212:215], v197 offset:35840
	ds_read_b128 v[218:221], v197 offset:36864
	ds_read_b128 v[222:225], v197 offset:37888
	ds_read_b128 v[226:229], v197 offset:38912
	ds_read_b128 v[230:233], v197 offset:39936
	global_load_lds_dwordx4 v[234:235], off
	v_lshl_add_u64 v[234:235], s[24:25], 0, v[168:169]
	s_mov_b32 m0, s29
	s_nop 0
	global_load_lds_dwordx4 v[234:235], off
	s_waitcnt vmcnt(8)
	s_waitcnt lgkmcnt(0)
	s_barrier
	s_setprio 3
	s_waitcnt lgkmcnt(0)
	v_mfma_f32_16x16x128_f8f6f4 v[158:161], v[2:9], v[200:207], v[158:161]
	v_mfma_f32_16x16x128_f8f6f4 v[154:157], v[10:17], v[200:207], v[154:157]
	v_mfma_f32_16x16x128_f8f6f4 v[142:145], v[2:9], v[208:215], v[142:145]
	v_mfma_f32_16x16x128_f8f6f4 v[138:141], v[10:17], v[208:215], v[138:141]
	v_mfma_f32_16x16x128_f8f6f4 v[126:129], v[2:9], v[218:225], v[126:129]
	v_mfma_f32_16x16x128_f8f6f4 v[122:125], v[10:17], v[218:225], v[122:125]
	v_mfma_f32_16x16x128_f8f6f4 v[110:113], v[2:9], v[226:233], v[110:113]
	v_mfma_f32_16x16x128_f8f6f4 v[106:109], v[10:17], v[226:233], v[106:109]
	s_setprio 0
	s_setprio 3
	v_mfma_f32_16x16x128_f8f6f4 v[150:153], v[18:25], v[200:207], v[150:153]
	v_mfma_f32_16x16x128_f8f6f4 v[146:149], v[26:33], v[200:207], v[146:149]
	v_mfma_f32_16x16x128_f8f6f4 v[134:137], v[18:25], v[208:215], v[134:137]
	v_mfma_f32_16x16x128_f8f6f4 v[130:133], v[26:33], v[208:215], v[130:133]
	v_mfma_f32_16x16x128_f8f6f4 v[118:121], v[18:25], v[218:225], v[118:121]
	v_mfma_f32_16x16x128_f8f6f4 v[114:117], v[26:33], v[218:225], v[114:117]
	v_mfma_f32_16x16x128_f8f6f4 v[102:105], v[18:25], v[226:233], v[102:105]
	v_mfma_f32_16x16x128_f8f6f4 v[98:101], v[26:33], v[226:233], v[98:101]
	s_setprio 0
	s_add_i32 s24, s36, s14
	v_lshl_add_u64 v[182:183], v[182:183], 0, s[10:11]
	s_mov_b32 m0, s24
	ds_read_b128 v[200:203], v197 offset:49152
	ds_read_b128 v[204:207], v197 offset:50176
	ds_read_b128 v[208:211], v197 offset:51200
	ds_read_b128 v[212:215], v197 offset:52224
	ds_read_b128 v[218:221], v197 offset:53248
	ds_read_b128 v[222:225], v197 offset:54272
	ds_read_b128 v[226:229], v197 offset:55296
	ds_read_b128 v[230:233], v197 offset:56320
	global_load_lds_dwordx4 v[182:183], off
	s_add_i32 m0, s24, 0x2000
	s_add_u32 s24, s74, 0x40080
	v_lshl_add_u64 v[182:183], v[184:185], 0, s[10:11]
	s_addc_u32 s25, s75, 0
	s_add_i32 s36, s37, s14
	global_load_lds_dwordx4 v[182:183], off
	v_lshl_add_u64 v[182:183], s[24:25], 0, v[166:167]
	s_mov_b32 m0, s36
	s_nop 0
	global_load_lds_dwordx4 v[182:183], off
	v_lshl_add_u64 v[182:183], s[24:25], 0, v[170:171]
	s_add_i32 m0, s36, 0x2000
	s_nop 0
	global_load_lds_dwordx4 v[182:183], off
	v_lshl_add_u64 v[182:183], v[186:187], 0, s[10:11]
	s_mov_b32 m0, s45
	s_nop 0
	global_load_lds_dwordx4 v[182:183], off
	v_lshl_add_u64 v[182:183], v[188:189], 0, s[10:11]
	s_mov_b32 m0, s78
	s_nop 0
	global_load_lds_dwordx4 v[182:183], off
	s_waitcnt vmcnt(8)
	s_waitcnt lgkmcnt(0)
	s_barrier
	s_setprio 3
	s_waitcnt lgkmcnt(0)
	v_mfma_f32_16x16x128_f8f6f4 v[94:97], v[2:9], v[200:207], v[94:97]
	v_mfma_f32_16x16x128_f8f6f4 v[90:93], v[10:17], v[200:207], v[90:93]
	v_mfma_f32_16x16x128_f8f6f4 v[78:81], v[2:9], v[208:215], v[78:81]
	v_mfma_f32_16x16x128_f8f6f4 v[74:77], v[10:17], v[208:215], v[74:77]
	v_mfma_f32_16x16x128_f8f6f4 v[62:65], v[2:9], v[218:225], v[62:65]
	v_mfma_f32_16x16x128_f8f6f4 v[58:61], v[10:17], v[218:225], v[58:61]
	v_mfma_f32_16x16x128_f8f6f4 v[46:49], v[2:9], v[226:233], v[46:49]
	v_mfma_f32_16x16x128_f8f6f4 v[42:45], v[10:17], v[226:233], v[42:45]
	s_setprio 0
	s_setprio 3
	v_mfma_f32_16x16x128_f8f6f4 v[86:89], v[18:25], v[200:207], v[86:89]
	v_mfma_f32_16x16x128_f8f6f4 v[82:85], v[26:33], v[200:207], v[82:85]
	v_mfma_f32_16x16x128_f8f6f4 v[70:73], v[18:25], v[208:215], v[70:73]
	v_mfma_f32_16x16x128_f8f6f4 v[66:69], v[26:33], v[208:215], v[66:69]
	v_mfma_f32_16x16x128_f8f6f4 v[54:57], v[18:25], v[218:225], v[54:57]
	v_mfma_f32_16x16x128_f8f6f4 v[50:53], v[26:33], v[218:225], v[50:53]
	v_mfma_f32_16x16x128_f8f6f4 v[38:41], v[18:25], v[226:233], v[38:41]
	v_mfma_f32_16x16x128_f8f6f4 v[34:37], v[26:33], v[226:233], v[34:37]
	s_setprio 0
	s_add_i32 s87, s87, 2
	s_add_u32 s72, s72, 0x100
	s_addc_u32 s73, s73, 0
	s_add_u32 s85, s85, 0x100
	s_addc_u32 s86, s86, 0
	s_cmp_gt_u32 s87, 13
	s_cbranch_scc0 .Lk1_Y
.Lk1_exit:
	s_nop 7
	s_nop 7
	s_nop 7
	s_and_b64 vcc, exec, s[12:13]
	s_cbranch_vccz .LBB0_294

; __device__ __forceinline__ unsigned cvt_pk_bf16(float lo, float hi) { unsigned r; asm volatile("v_cvt_pk_bf16_f32 %0, %1, %2" : "=v"(r) : "v"(lo), "v"(hi)); return r; }
; #define PG8_BAR __builtin_amdgcn_s_barrier()
;     __device__ __forceinline__ void operator()(const f32x4 (&acc)[2][2][4][2], const Unit& u, int wr, int wc, int fr, int fq) const {
;     ...
;                 const int r = row0 + ai * HALF + m * 16;
;                 f32x4 cs = (f32x4){1.f, 1.f, 1.f, 1.f}, sn = (f32x4){0.f, 0.f, 0.f, 0.f};
;                 if (rope) { const int ntok = r & 8191; const int pos = (wc >> 1) ? (ntok & 63) : (ntok >> 6); cs = *(const f32x4*)(cosT + pos * 32 + ti); sn = *(const f32x4*)(sinT + pos * 32 + ti); }
;                 bf16_t* rowp = base + (size_t)r * ldc + col0;
; #pragma unroll
;                 for (int bj = 0; bj < 2; ++bj) {
;                     const f32x4 v0 = acc[ai][bj][m][0], v1 = acc[ai][bj][m][1]; f32x4 o0, o1;
;                     o0[0] = v0[0] * cs[0] - v0[1] * sn[0]; o0[1] = v0[0] * sn[0] + v0[1] * cs[0];
;                     o0[2] = v0[2] * cs[1] - v0[3] * sn[1]; o0[3] = v0[2] * sn[1] + v0[3] * cs[1];
;                     o1[0] = v1[0] * cs[2] - v1[1] * sn[2]; o1[1] = v1[0] * sn[2] + v1[1] * cs[2];
;                     o1[2] = v1[2] * cs[3] - v1[3] * sn[3]; o1[3] = v1[2] * sn[3] + v1[3] * cs[3];
;                     o0 = o0 * s; o1 = o1 * s;
;                     u32x4 w; w.x = cvt_pk_bf16(o0[0], o0[1]); w.y = cvt_pk_bf16(o0[2], o0[3]); w.z = cvt_pk_bf16(o1[0], o1[1]); w.w = cvt_pk_bf16(o1[2], o1[3]);
;                     *(u32x4*)(rowp + bj * HALF) = w; }
; template <class Epi, class Sched, bool ALIGN_EPI = false, bool SP2 = false, bool F8 = false>
; __device__ __forceinline__ void gemm_phase(PG8_LAS unsigned char* lds, const Gemm g, const Sched& S, const Epi& E) {
;     ...
;         cur = nxt; cA = nA; cB = nB; ++ui;
;         if constexpr (ALIGN_EPI) { if (wr == 1) PG8_BAR; }
.LBB0_310:
	v_lshlrev_b64 v[18:19], 12, v[18:19]
	v_lshl_add_u64 v[24:25], v[20:21], 0, v[18:19]
	v_pk_mul_f32 v[18:19], v[46:47], v[6:7] op_sel_hi:[1,0]
	v_pk_mul_f32 v[32:33], v[42:43], v[8:9] op_sel_hi:[1,0]
	v_pk_fma_f32 v[20:21], v[46:47], v[2:3], v[18:19] op_sel:[0,0,1] op_sel_hi:[1,0,0] neg_lo:[0,0,1] neg_hi:[0,0,1]
	v_pk_fma_f32 v[18:19], v[46:47], v[2:3], v[18:19] op_sel:[0,0,1] op_sel_hi:[1,0,0]
	v_pk_mul_f32 v[28:29], v[48:49], v[12:13] op_sel_hi:[1,0]
	v_pk_fma_f32 v[46:47], v[42:43], v[4:5], v[32:33] op_sel:[0,0,1] op_sel_hi:[1,0,0] neg_lo:[0,0,1] neg_hi:[0,0,1]
	v_pk_fma_f32 v[32:33], v[42:43], v[4:5], v[32:33] op_sel:[0,0,1] op_sel_hi:[1,0,0]
	v_pk_mul_f32 v[42:43], v[44:45], v[10:11] op_sel_hi:[1,0]
	v_pk_fma_f32 v[30:31], v[48:49], v[22:23], v[28:29] op_sel:[0,0,1] op_sel_hi:[1,0,0] neg_lo:[0,0,1] neg_hi:[0,0,1]
	v_pk_fma_f32 v[28:29], v[48:49], v[22:23], v[28:29] op_sel:[0,0,1] op_sel_hi:[1,0,0]
	v_pk_fma_f32 v[48:49], v[44:45], v[14:15], v[42:43] op_sel:[0,0,1] op_sel_hi:[1,0,0] neg_lo:[0,0,1] neg_hi:[0,0,1]
	v_pk_fma_f32 v[42:43], v[44:45], v[14:15], v[42:43] op_sel:[0,0,1] op_sel_hi:[1,0,0]
	v_mov_b32_e32 v21, v19
	v_mov_b32_e32 v47, v33
	v_lshl_add_u64 v[26:27], v[24:25], 0, s[52:53]
	v_mov_b32_e32 v31, v29
	v_mov_b32_e32 v28, v16
	v_mov_b32_e32 v29, v16
	v_pk_mul_f32 v[18:19], v[16:17], v[20:21]
	v_mov_b32_e32 v49, v43
	v_pk_mul_f32 v[20:21], v[16:17], v[46:47]
	v_add_co_u32_e32 v24, vcc, s84, v24
	v_pk_mul_f32 v[30:31], v[28:29], v[30:31]
	v_pk_mul_f32 v[42:43], v[28:29], v[48:49]
	v_cvt_pk_bf16_f32 v18, v18, v19
	v_cvt_pk_bf16_f32 v19, v30, v31
	v_cvt_pk_bf16_f32 v20, v20, v21
	v_addc_co_u32_e32 v25, vcc, 0, v25, vcc
	v_cvt_pk_bf16_f32 v21, v42, v43
	v_pk_mul_f32 v[6:7], v[38:39], v[6:7] op_sel_hi:[1,0]
	v_pk_mul_f32 v[8:9], v[34:35], v[8:9] op_sel_hi:[1,0]
	global_store_dwordx4 v[24:25], v[18:21], off
	s_andn2_b64 vcc, exec, s[54:55]
	s_mov_b64 s[6:7], -1
	v_pk_fma_f32 v[18:19], v[38:39], v[2:3], v[6:7] op_sel:[0,0,1] op_sel_hi:[1,0,0] neg_lo:[0,0,1] neg_hi:[0,0,1]
	v_pk_fma_f32 v[2:3], v[38:39], v[2:3], v[6:7] op_sel:[0,0,1] op_sel_hi:[1,0,0]
	v_pk_mul_f32 v[6:7], v[40:41], v[12:13] op_sel_hi:[1,0]
	v_pk_fma_f32 v[20:21], v[34:35], v[4:5], v[8:9] op_sel:[0,0,1] op_sel_hi:[1,0,0] neg_lo:[0,0,1] neg_hi:[0,0,1]
	v_pk_fma_f32 v[4:5], v[34:35], v[4:5], v[8:9] op_sel:[0,0,1] op_sel_hi:[1,0,0]
	v_pk_mul_f32 v[8:9], v[36:37], v[10:11] op_sel_hi:[1,0]
	v_pk_fma_f32 v[12:13], v[40:41], v[22:23], v[6:7] op_sel:[0,0,1] op_sel_hi:[1,0,0] neg_lo:[0,0,1] neg_hi:[0,0,1]
	v_pk_fma_f32 v[6:7], v[40:41], v[22:23], v[6:7] op_sel:[0,0,1] op_sel_hi:[1,0,0]
	v_pk_fma_f32 v[10:11], v[36:37], v[14:15], v[8:9] op_sel:[0,0,1] op_sel_hi:[1,0,0] neg_lo:[0,0,1] neg_hi:[0,0,1]
	v_pk_fma_f32 v[8:9], v[36:37], v[14:15], v[8:9] op_sel:[0,0,1] op_sel_hi:[1,0,0]
	v_mov_b32_e32 v19, v3
	v_mov_b32_e32 v21, v5
	v_mov_b32_e32 v13, v7
	v_pk_mul_f32 v[2:3], v[16:17], v[18:19]
	v_mov_b32_e32 v11, v9
	v_pk_mul_f32 v[4:5], v[16:17], v[20:21]
	v_pk_mul_f32 v[6:7], v[28:29], v[12:13]
	v_pk_mul_f32 v[8:9], v[28:29], v[10:11]
	v_cvt_pk_bf16_f32 v2, v2, v3
	v_cvt_pk_bf16_f32 v3, v6, v7
	v_cvt_pk_bf16_f32 v4, v4, v5
	s_nop 0
	v_cvt_pk_bf16_f32 v5, v8, v9
	global_store_dwordx4 v[26:27], v[2:5], off offset:256
	s_cbranch_vccnz .LBB0_283
	s_andn2_b64 vcc, exec, s[8:9]
	s_cbranch_vccnz .LBB0_282
	s_branch .LBB0_282

;     __host__ __device__ bool next(int i, Unit& u) const { const long L = (long)i * G + c; if (L >= nwg) return false; u.pm = 0; u.pn = c % nN; return true; }
; #define PG8_STAGE(bufoff, gbase, voff) do { _Pragma("unroll") for (int _i = 0; _i < 2; ++_i) \
;         __builtin_amdgcn_global_load_lds((const unsigned*)((const char*)(gbase) + (voff)[_i]), (PG8_LAS unsigned*)(lds + (bufoff) + ldsw + _i * 8192), 16, 0, 0); } while (0)
; #define PG8_WAIT_V(n) asm volatile("s_waitcnt vmcnt(" #n ")" ::: "memory")
; template <class Epi, class Sched, bool ALIGN_EPI = false, bool SP2 = false, bool F8 = false>
; __device__ __forceinline__ void gemm_phase(PG8_LAS unsigned char* lds, const Gemm g, const Sched& S, const Epi& E) {
;     ...
; #pragma unroll
;     for (int i = 0; i < 2; ++i) { int R, C; stage_rc(tid * 16 + i * 8192, R, C); const int Rb = Epi::PERM ? ((R & ~31) + perm32(R & 31)) : R;
;         const int Ra = Epi::GRIDMAP ? ((R & 63) * 64 + (R >> 6)) : R;
;         voffA[i] = (unsigned)(Ra * K + C) * 2u; voffB[i] = (unsigned)(Rb * K + C) * 2u; }
;     const size_t kstep = (size_t)(BK * 2);
;     const size_t hstep = (size_t)HALF * K * 2;
;     const size_t tstep = 2 * hstep;
;     const size_t hstepA = Epi::GRIDMAP ? (size_t)4096 * K * 2 : hstep;
;     ...
;     const unsigned ldsw = (unsigned)wid * 1024u;
;     const int aoff = lds_byte(wr * 64 + fr, fq * 8), boff = lds_byte(wc * 32 + fr, fq * 8);
;     ...
;     Unit cur, nxt; int ui = 0;
;     if (!S.next(0, cur)) return;
;     f32x4 acc[2][2][4][2];
; #pragma unroll
;     for (int a = 0; a < 2; ++a)
; #pragma unroll
;         for (int b = 0; b < 2; ++b)
; #pragma unroll
;             for (int m = 0; m < 4; ++m)
; #pragma unroll
;                 for (int n = 0; n < 2; ++n) acc[a][b][m][n] = (f32x4){0.f, 0.f, 0.f, 0.f};
;     bf16x8 At[4][2], B0[2][2], B1[2][2];
;     const char* cA = PG8_ABASE(cur.pm); const char* cB = (const char*)g.Bt + (size_t)cur.pn * tstep;
;     S.a_ready(cur);
;     if constexpr (SP2) {
;         PG8_STAGE(PG8_SB(0, 0), cB, voffB); PG8_STAGE(PG8_SB(0, 1), cB + hstep, voffB); PG8_STAGE(PG8_SA(0, 0), cA, voffA); PG8_STAGE(PG8_SA(0, 1), cA + hstepA, voffA);
;         if (wr == 1) PG8_BAR;
;         PG8_WAIT_V(2); PG8_BAR;
;         PG8_STAGE(PG8_SB(1, 0), cB + kstep, voffB); PG8_STAGE(PG8_SA(1, 0), cA + kstep, voffA); PG8_STAGE(PG8_SB(1, 1), cB + hstep + kstep, voffB);
;         PG8_WAIT_V(6); PG8_BAR;
.LBB0_760:
	s_waitcnt vmcnt(6)
	v_lshrrev_b32_e32 v3, 1, v0
	v_lshrrev_b32_e32 v4, 5, v0
	v_lshlrev_b32_e32 v1, 4, v0
	v_and_b32_e32 v2, 32, v0
	v_and_b32_e32 v3, 24, v3
	v_and_b32_e32 v4, 4, v4
	v_bfe_u32 v5, v0, 2, 2
	s_waitcnt vmcnt(4)
	v_bfe_u32 v12, v0, 2, 4
	v_bitop3_b32 v10, v1, v2, 48 bitop3:0x6c
	v_and_b32_e32 v11, 64, v0
	v_or3_b32 v3, v4, v5, v3
	v_lshrrev_b32_e32 v4, 3, v0
	v_or_b32_e32 v13, 0x2000, v1
	v_or_b32_e32 v2, v10, v11
	v_and_or_b32 v5, v4, 48, v12
	v_and_or_b32 v4, v4, 32, v3
	v_lshrrev_b32_e32 v1, 7, v13
	s_movk_i32 s4, 0x70
	s_lshr_b32 s5, s50, 6
	v_lshl_or_b32 v180, v4, 12, v2
	v_and_or_b32 v4, v1, s4, v12
	s_movk_i32 s4, 0x60
	s_ashr_i32 s61, s60, 31
	s_ashr_i32 s13, s12, 31
	v_and_or_b32 v1, v1, s4, v3
	s_lshr_b32 s4, s50, 8
	s_lshl_b32 s14, s5, 10
	s_lshl_b64 s[6:7], s[60:61], 20
	s_lshl_b64 s[24:25], s[12:13], 20
	s_add_u32 s64, s46, s24
	s_addc_u32 s65, s47, s25
	s_add_i32 s15, s14, 0
	s_add_i32 m0, s15, 0x10000
	v_lshl_or_b32 v184, v1, 12, v2
	global_load_lds_dwordx4 v180, s[64:65]
	s_add_i32 m0, s15, 0x12000
	s_add_u32 s24, s64, 0x80000
	global_load_lds_dwordx4 v184, s[64:65]
	s_addc_u32 s25, s65, 0
	s_add_i32 m0, s15, 0x14000
	v_lshl_or_b32 v178, v5, 12, v2
	global_load_lds_dwordx4 v180, s[24:25]
	s_add_i32 m0, s15, 0x16000
	s_add_u32 s62, s8, s6
	s_addc_u32 s63, s9, s7
	s_add_i32 s23, s15, 0x2000
	global_load_lds_dwordx4 v184, s[24:25]
	s_mov_b32 m0, s15
	s_add_u32 s6, s62, 0x80000
	v_lshl_or_b32 v182, v4, 12, v2
	global_load_lds_dwordx4 v178, s[62:63]
	s_mov_b32 m0, s23
	s_addc_u32 s7, s63, 0
	s_add_i32 s26, s15, 0x4000
	global_load_lds_dwordx4 v182, s[62:63]
	s_mov_b32 m0, s26
	s_add_i32 s27, s15, 0x6000
	global_load_lds_dwordx4 v178, s[6:7]
	s_mov_b32 m0, s27
	v_mov_b32_e32 v181, 0
	global_load_lds_dwordx4 v182, s[6:7]
	v_mov_b32_e32 v185, v181
	v_mov_b32_e32 v179, v181
	v_mov_b32_e32 v183, v181
	s_cmp_eq_u32 s4, 1
	s_mov_b32 s13, 0
	v_lshl_add_u64 v[8:9], s[64:65], 0, v[180:181]
	v_lshl_add_u64 v[6:7], s[64:65], 0, v[184:185]
	v_lshl_add_u64 v[2:3], s[62:63], 0, v[178:179]
	s_cselect_b64 s[40:41], -1, 0
	s_cmp_lg_u32 s4, 1
	v_lshl_add_u64 v[4:5], s[62:63], 0, v[182:183]
	s_cbranch_scc1 .LBB0_762
.LBB0_762:
	s_add_u32 s28, s18, 0x114000
	s_mov_b64 s[48:49], 0x80
	s_addc_u32 s29, s19, 0
	s_and_b32 s33, s5, 3
	s_add_i32 m0, s15, 0x18000
	v_lshl_add_u64 v[8:9], v[8:9], 0, s[48:49]
	s_lshl_b32 s5, s4, 13
	s_lshl_b32 s24, s33, 12
	s_waitcnt vmcnt(2)
	s_barrier
	global_load_lds_dwordx4 v[8:9], off
	v_lshl_add_u64 v[6:7], v[6:7], 0, s[48:49]
	s_add_i32 m0, s15, 0x1a000
	s_add_i32 s44, s15, 0x8000
	s_add_i32 s45, s15, 0xa000
	global_load_lds_dwordx4 v[6:7], off
	v_lshl_add_u64 v[2:3], v[2:3], 0, s[48:49]
	s_mov_b32 m0, s44
	s_add_u32 s6, s64, 0x80080
	global_load_lds_dwordx4 v[2:3], off
	v_lshl_add_u64 v[2:3], v[4:5], 0, s[48:49]
	s_mov_b32 m0, s45
	s_addc_u32 s7, s65, 0
	global_load_lds_dwordx4 v[2:3], off
	s_add_i32 m0, s15, 0x1c000
	v_lshl_add_u64 v[2:3], s[6:7], 0, v[180:181]
	global_load_lds_dwordx4 v[2:3], off
	v_lshl_add_u64 v[2:3], s[6:7], 0, v[184:185]
	s_add_i32 m0, s15, 0x1e000
	v_lshlrev_b32_e32 v6, 2, v0
	global_load_lds_dwordx4 v[2:3], off
	v_bfe_u32 v3, v0, 4, 2
	v_and_b32_e32 v2, 15, v0
	v_lshlrev_b32_e32 v5, 4, v3
	v_lshl_or_b32 v1, s4, 6, v2
	v_lshl_or_b32 v2, v2, 6, v5
	v_and_b32_e32 v6, 32, v6
	v_lshlrev_b32_e32 v7, 6, v0
	s_movk_i32 s4, 0x3c0
	v_lshlrev_b32_e32 v4, 3, v3
	v_bitop3_b32 v2, v2, s5, v6 bitop3:0xde
	v_and_or_b32 v5, v7, s4, v5
	v_cmp_eq_u32_e64 s[4:5], 0, v3
	v_lshlrev_b32_e32 v3, 9, v0
	v_lshl_or_b32 v203, s33, 5, v4
	v_and_b32_e32 v3, 0x30000, v3
	v_lshlrev_b32_e32 v4, 12, v12
	v_or3_b32 v3, v10, v3, v4
	v_add_u32_e32 v186, v3, v11
	v_lshlrev_b32_e32 v3, 5, v13
	s_waitcnt vmcnt(6)
	s_cmpk_lt_u32 s50, 0x100
	v_and_b32_e32 v3, 0x70000, v3
	v_bitop3_b32 v202, s24, v5, v6 bitop3:0xf6
	s_cselect_b64 s[50:51], -1, 0
	v_or3_b32 v3, v10, v3, v4
	s_add_i32 s70, 0, 0x10000
	s_add_i32 s71, 0, 0x14000
	v_add_u32_e32 v206, 0, v2
	v_mbcnt_lo_u32_b32 v2, -1, 0
	s_ashr_i32 s68, s90, 31
	s_ashr_i32 s69, s2, 31
	v_mov_b32_e32 v187, v181
	v_add_u32_e32 v188, v3, v11
	v_mov_b32_e32 v189, v181
	v_mov_b64_e32 v[190:191], 0x200
	v_mov_b64_e32 v[192:193], 0x1ff
	v_add_u32_e32 v204, s70, v202
	v_add_u32_e32 v205, s71, v202
	v_mbcnt_hi_u32_b32 v207, -1, v2
	s_mov_b32 s72, 0
	s_barrier
	s_branch .LBB0_765

;     __host__ __device__ bool next(int i, Unit& u) const { const long L = (long)i * G + c; if (L >= nwg) return false; u.pm = 0; u.pn = c % nN; return true; }
; #define PG8_STAGE(bufoff, gbase, voff) do { _Pragma("unroll") for (int _i = 0; _i < 2; ++_i) \
;         __builtin_amdgcn_global_load_lds((const unsigned*)((const char*)(gbase) + (voff)[_i]), (PG8_LAS unsigned*)(lds + (bufoff) + ldsw + _i * 8192), 16, 0, 0); } while (0)
; #define PG8_LDA(dst, b, h) do { _Pragma("unroll") for (int m = 0; m < 4; ++m) _Pragma("unroll") for (int k = 0; k < 2; ++k) dst[m][k] = *(const PG8_LAS bf16x8*)(lds + PG8_SA(b, h) + aoff + m * 2048 + k * 1024); } while (0)
; #define PG8_LDB(dst, b, h) do { _Pragma("unroll") for (int n = 0; n < 2; ++n) _Pragma("unroll") for (int k = 0; k < 2; ++k) dst[n][k] = *(const PG8_LAS bf16x8*)(lds + PG8_SB(b, h) + boff + n * 2048 + k * 1024); } while (0)
; #define PG8_WAIT_V(n) asm volatile("s_waitcnt vmcnt(" #n ")" ::: "memory")
; #define PG8_BAR __builtin_amdgcn_s_barrier()
; template <class Epi, class Sched, bool ALIGN_EPI = false, bool SP2 = false, bool F8 = false>
; __device__ __forceinline__ void gemm_phase(PG8_LAS unsigned char* lds, const Gemm g, const Sched& S, const Epi& E) {
;     ...
;         const bool has_next = S.next(ui + 1, nxt);
;         const char* nA = has_next ? PG8_ABASE(nxt.pm) : cA; const char* nB = has_next ? (const char*)g.Bt + (size_t)nxt.pn * tstep : cB;
;         for (int t = 0; t < nt; t += 2) {
;             const bool last = (t == nt - 2);
;             const char* a1 = cA + (size_t)(t + 1) * kstep;
;             const char* a2 = last ? nA : cA + (size_t)(t + 2) * kstep; const char* b2 = last ? nB : cB + (size_t)(t + 2) * kstep;
;             const char* a3 = a2 + kstep; const char* b3 = b2 + kstep;
;             if (last && has_next) S.a_ready(nxt);
;             if constexpr (SP2) {
;             PG8_LDB(B0, 0, 0); PG8_LDB(B1, 0, 1); PG8_SCHED; PG8_LDA(At, 0, 0); PG8_STAGE(PG8_SA(1, 1), a1 + hstepA, voffA);
;             PG8_WAIT_V(8); PG8_WAIT_L(0); PG8_BAR; PG8_MMA(0, 0, At, B0); PG8_MMA(0, 1, At, B1); PG8_BAR; PG8_SCHED;
;     ...
; #pragma unroll
;         for (int a = 0; a < 2; ++a)
; #pragma unroll
;             for (int b = 0; b < 2; ++b)
; #pragma unroll
;                 for (int m = 0; m < 4; ++m)
; #pragma unroll
;                     for (int n = 0; n < 2; ++n) acc[a][b][m][n] = (f32x4){0.f, 0.f, 0.f, 0.f};
.LBB0_771:
	s_ashr_i32 s55, s54, 31
	s_lshl_b64 s[24:25], s[54:55], 20
	s_add_u32 s56, s8, s24
	s_addc_u32 s57, s9, s25
	s_and_b64 s[24:25], s[6:7], exec
	s_cselect_b32 s55, s57, s63
	s_cselect_b32 s61, s56, s62
	s_ashr_i32 s53, s52, 31
	s_lshl_b64 s[24:25], s[52:53], 20
	s_add_u32 s58, s46, s24
	s_addc_u32 s59, s47, s25
	s_and_b64 s[24:25], s[6:7], exec
	s_cselect_b32 s53, s59, s65
	s_cselect_b32 s73, s58, s64
	s_add_u32 s62, s62, 0x80080
	s_addc_u32 s63, s63, 0
	s_add_u32 s74, s64, 0x100
	v_mov_b32_e32 v2, 0
	s_addc_u32 s75, s65, 0
	s_mov_b32 s76, -2
	s_waitcnt lgkmcnt(0)
	s_waitcnt vmcnt(0)
	v_mov_b32_e32 v3, 0
	v_pk_mul_f32 v[4:5], v[2:3], v[2:3]
	v_pk_mul_f32 v[6:7], v[2:3], v[2:3]
	v_pk_mul_f32 v[8:9], v[2:3], v[2:3]
	v_pk_mul_f32 v[10:11], v[2:3], v[2:3]
	v_pk_mul_f32 v[12:13], v[2:3], v[2:3]
	v_pk_mul_f32 v[14:15], v[2:3], v[2:3]
	v_pk_mul_f32 v[16:17], v[2:3], v[2:3]
	v_pk_mul_f32 v[18:19], v[2:3], v[2:3]
	v_pk_mul_f32 v[20:21], v[2:3], v[2:3]
	v_pk_mul_f32 v[22:23], v[2:3], v[2:3]
	v_pk_mul_f32 v[24:25], v[2:3], v[2:3]
	v_pk_mul_f32 v[26:27], v[2:3], v[2:3]
	v_pk_mul_f32 v[28:29], v[2:3], v[2:3]
	v_pk_mul_f32 v[30:31], v[2:3], v[2:3]
	v_pk_mul_f32 v[32:33], v[2:3], v[2:3]
	v_pk_mul_f32 v[34:35], v[2:3], v[2:3]
	v_pk_mul_f32 v[36:37], v[2:3], v[2:3]
	v_pk_mul_f32 v[38:39], v[2:3], v[2:3]
	v_pk_mul_f32 v[40:41], v[2:3], v[2:3]
	v_pk_mul_f32 v[42:43], v[2:3], v[2:3]
	v_pk_mul_f32 v[44:45], v[2:3], v[2:3]
	v_pk_mul_f32 v[46:47], v[2:3], v[2:3]
	v_pk_mul_f32 v[48:49], v[2:3], v[2:3]
	v_pk_mul_f32 v[50:51], v[2:3], v[2:3]
	v_pk_mul_f32 v[52:53], v[2:3], v[2:3]
	v_pk_mul_f32 v[54:55], v[2:3], v[2:3]
	v_pk_mul_f32 v[56:57], v[2:3], v[2:3]
	v_pk_mul_f32 v[58:59], v[2:3], v[2:3]
	v_pk_mul_f32 v[60:61], v[2:3], v[2:3]
	v_pk_mul_f32 v[62:63], v[2:3], v[2:3]
	v_pk_mul_f32 v[64:65], v[2:3], v[2:3]
	v_pk_mul_f32 v[66:67], v[2:3], v[2:3]
	v_pk_mul_f32 v[68:69], v[2:3], v[2:3]
	v_pk_mul_f32 v[70:71], v[2:3], v[2:3]
	v_pk_mul_f32 v[72:73], v[2:3], v[2:3]
	v_pk_mul_f32 v[74:75], v[2:3], v[2:3]
	v_pk_mul_f32 v[76:77], v[2:3], v[2:3]
	v_pk_mul_f32 v[78:79], v[2:3], v[2:3]
	v_pk_mul_f32 v[80:81], v[2:3], v[2:3]
	v_pk_mul_f32 v[98:99], v[2:3], v[2:3]
	v_pk_mul_f32 v[100:101], v[2:3], v[2:3]
	v_pk_mul_f32 v[110:111], v[2:3], v[2:3]
	v_pk_mul_f32 v[112:113], v[2:3], v[2:3]
	v_pk_mul_f32 v[122:123], v[2:3], v[2:3]
	v_pk_mul_f32 v[124:125], v[2:3], v[2:3]
	v_pk_mul_f32 v[126:127], v[2:3], v[2:3]
	v_pk_mul_f32 v[128:129], v[2:3], v[2:3]
	v_pk_mul_f32 v[130:131], v[2:3], v[2:3]
	v_pk_mul_f32 v[132:133], v[2:3], v[2:3]
	v_pk_mul_f32 v[134:135], v[2:3], v[2:3]
	v_pk_mul_f32 v[136:137], v[2:3], v[2:3]
	v_pk_mul_f32 v[138:139], v[2:3], v[2:3]
	v_pk_mul_f32 v[140:141], v[2:3], v[2:3]
	v_pk_mul_f32 v[142:143], v[2:3], v[2:3]
	v_pk_mul_f32 v[144:145], v[2:3], v[2:3]
	v_pk_mul_f32 v[146:147], v[2:3], v[2:3]
	v_pk_mul_f32 v[148:149], v[2:3], v[2:3]
	v_pk_mul_f32 v[150:151], v[2:3], v[2:3]
	v_pk_mul_f32 v[152:153], v[2:3], v[2:3]
	v_pk_mul_f32 v[154:155], v[2:3], v[2:3]
	v_pk_mul_f32 v[156:157], v[2:3], v[2:3]
	v_pk_mul_f32 v[158:159], v[2:3], v[2:3]
	v_pk_mul_f32 v[160:161], v[2:3], v[2:3]
	s_cmp_lg_u64 s[40:41], 0
	s_cbranch_scc1 .Lk2_Y
.LBB0_772:
	ds_read_b128 v[82:85], v204
	ds_read_b128 v[86:89], v204 offset:1024
	ds_read_b128 v[90:93], v204 offset:2048
	ds_read_b128 v[94:97], v204 offset:3072
	ds_read_b128 v[102:105], v205
	ds_read_b128 v[106:109], v205 offset:1024
	ds_read_b128 v[114:117], v205 offset:2048
	ds_read_b128 v[118:121], v205 offset:3072
	s_add_u32 s24, s62, 0xfff80080
	s_addc_u32 s25, s63, -1
	s_cmp_eq_u32 s76, 28
	s_cselect_b32 s67, s55, s25
	s_cselect_b32 s66, s61, s24
	s_cselect_b32 s65, s53, s75
	s_cselect_b32 s64, s73, s74
	v_lshl_add_u64 v[218:219], s[62:63], 0, v[186:187]
	s_add_i32 m0, s15, 0xc000
	ds_read_b128 v[162:165], v206
	ds_read_b128 v[166:169], v206 offset:1024
	ds_read_b128 v[170:173], v206 offset:2048
	ds_read_b128 v[174:177], v206 offset:3072
	ds_read_b128 v[194:197], v206 offset:4096
	ds_read_b128 v[198:201], v206 offset:5120
	ds_read_b128 v[208:211], v206 offset:6144
	ds_read_b128 v[212:215], v206 offset:7168
	global_load_lds_dwordx4 v[218:219], off
	v_lshl_add_u64 v[218:219], s[62:63], 0, v[188:189]
	s_add_i32 m0, s15, 0xe000
	s_nop 0
	global_load_lds_dwordx4 v[218:219], off
	s_waitcnt vmcnt(8)
	s_waitcnt lgkmcnt(0)
	s_setprio 1
	s_waitcnt lgkmcnt(0)
	v_mfma_f32_16x16x32_bf16 v[158:161], v[82:85], v[162:165], v[158:161]
	v_mfma_f32_16x16x32_bf16 v[154:157], v[90:93], v[162:165], v[154:157]
	v_mfma_f32_16x16x32_bf16 v[142:145], v[82:85], v[170:173], v[142:145]
	v_mfma_f32_16x16x32_bf16 v[138:141], v[90:93], v[170:173], v[138:141]
	v_mfma_f32_16x16x32_bf16 v[126:129], v[82:85], v[194:197], v[126:129]
	v_mfma_f32_16x16x32_bf16 v[122:125], v[90:93], v[194:197], v[122:125]
	v_mfma_f32_16x16x32_bf16 v[78:81], v[82:85], v[208:211], v[78:81]
	v_mfma_f32_16x16x32_bf16 v[74:77], v[90:93], v[208:211], v[74:77]
	v_mfma_f32_16x16x32_bf16 v[158:161], v[86:89], v[166:169], v[158:161]
	v_mfma_f32_16x16x32_bf16 v[154:157], v[94:97], v[166:169], v[154:157]
	v_mfma_f32_16x16x32_bf16 v[142:145], v[86:89], v[174:177], v[142:145]
	v_mfma_f32_16x16x32_bf16 v[138:141], v[94:97], v[174:177], v[138:141]
	v_mfma_f32_16x16x32_bf16 v[126:129], v[86:89], v[198:201], v[126:129]
	v_mfma_f32_16x16x32_bf16 v[122:125], v[94:97], v[198:201], v[122:125]
	v_mfma_f32_16x16x32_bf16 v[78:81], v[86:89], v[212:215], v[78:81]
	v_mfma_f32_16x16x32_bf16 v[74:77], v[94:97], v[212:215], v[74:77]
	s_setprio 0
	s_setprio 1
	v_mfma_f32_16x16x32_bf16 v[150:153], v[102:105], v[162:165], v[150:153]
	v_mfma_f32_16x16x32_bf16 v[146:149], v[114:117], v[162:165], v[146:149]
	v_mfma_f32_16x16x32_bf16 v[134:137], v[102:105], v[170:173], v[134:137]
	v_mfma_f32_16x16x32_bf16 v[130:133], v[114:117], v[170:173], v[130:133]
	v_mfma_f32_16x16x32_bf16 v[110:113], v[102:105], v[194:197], v[110:113]
	v_mfma_f32_16x16x32_bf16 v[98:101], v[114:117], v[194:197], v[98:101]
	v_mfma_f32_16x16x32_bf16 v[70:73], v[102:105], v[208:211], v[70:73]
	v_mfma_f32_16x16x32_bf16 v[66:69], v[114:117], v[208:211], v[66:69]
	v_mfma_f32_16x16x32_bf16 v[150:153], v[106:109], v[166:169], v[150:153]
	v_mfma_f32_16x16x32_bf16 v[146:149], v[118:121], v[166:169], v[146:149]
	v_mfma_f32_16x16x32_bf16 v[134:137], v[106:109], v[174:177], v[134:137]
	v_mfma_f32_16x16x32_bf16 v[130:133], v[118:121], v[174:177], v[130:133]
	v_mfma_f32_16x16x32_bf16 v[110:113], v[106:109], v[198:201], v[110:113]
	v_mfma_f32_16x16x32_bf16 v[98:101], v[118:121], v[198:201], v[98:101]
	v_mfma_f32_16x16x32_bf16 v[70:73], v[106:109], v[212:215], v[70:73]
	v_mfma_f32_16x16x32_bf16 v[66:69], v[118:121], v[212:215], v[66:69]
	s_setprio 0
	s_barrier
; #define PG8_STAGE(bufoff, gbase, voff) do { _Pragma("unroll") for (int _i = 0; _i < 2; ++_i) \
;         __builtin_amdgcn_global_load_lds((const unsigned*)((const char*)(gbase) + (voff)[_i]), (PG8_LAS unsigned*)(lds + (bufoff) + ldsw + _i * 8192), 16, 0, 0); } while (0)
; #define PG8_LDA(dst, b, h) do { _Pragma("unroll") for (int m = 0; m < 4; ++m) _Pragma("unroll") for (int k = 0; k < 2; ++k) dst[m][k] = *(const PG8_LAS bf16x8*)(lds + PG8_SA(b, h) + aoff + m * 2048 + k * 1024); } while (0)
; #define PG8_LDB(dst, b, h) do { _Pragma("unroll") for (int n = 0; n < 2; ++n) _Pragma("unroll") for (int k = 0; k < 2; ++k) dst[n][k] = *(const PG8_LAS bf16x8*)(lds + PG8_SB(b, h) + boff + n * 2048 + k * 1024); } while (0)
; #define PG8_WAIT_V(n) asm volatile("s_waitcnt vmcnt(" #n ")" ::: "memory")
; #define PG8_WAIT_L(n) asm volatile("s_waitcnt lgkmcnt(" #n ")" ::: "memory")
; #define PG8_BAR __builtin_amdgcn_s_barrier()
; #define PG8_SCHED __builtin_amdgcn_sched_barrier(0)
; template <class Epi, class Sched, bool ALIGN_EPI = false, bool SP2 = false, bool F8 = false>
; __device__ __forceinline__ void gemm_phase(PG8_LAS unsigned char* lds, const Gemm g, const Sched& S, const Epi& E) {
;     ...
;             PG8_LDA(At, 0, 1); PG8_STAGE(PG8_SB(0, 0), b2, voffB); PG8_STAGE(PG8_SB(0, 1), b2 + hstep, voffB); PG8_STAGE(PG8_SA(0, 0), a2, voffA);
;             PG8_WAIT_V(8); PG8_WAIT_L(0); PG8_BAR; PG8_MMA(1, 0, At, B0); PG8_MMA(1, 1, At, B1); PG8_BAR; PG8_SCHED;
;             PG8_LDB(B0, 1, 0); PG8_LDB(B1, 1, 1); PG8_SCHED; PG8_LDA(At, 1, 0); PG8_STAGE(PG8_SA(0, 1), a2 + hstepA, voffA);
;             PG8_WAIT_V(8); PG8_WAIT_L(0); PG8_BAR; PG8_MMA(0, 0, At, B0); PG8_MMA(0, 1, At, B1); PG8_BAR; PG8_SCHED;
	s_add_i32 s24, s70, s14
	v_lshl_add_u64 v[218:219], s[64:65], 0, v[180:181]
	s_mov_b32 m0, s24
	ds_read_b128 v[162:165], v206 offset:16384
	ds_read_b128 v[166:169], v206 offset:17408
	ds_read_b128 v[170:173], v206 offset:18432
	ds_read_b128 v[174:177], v206 offset:19456
	ds_read_b128 v[194:197], v206 offset:20480
	ds_read_b128 v[198:201], v206 offset:21504
	ds_read_b128 v[208:211], v206 offset:22528
	ds_read_b128 v[212:215], v206 offset:23552
	global_load_lds_dwordx4 v[218:219], off
	s_add_i32 m0, s24, 0x2000
	s_add_u32 s24, s64, 0x80000
	v_lshl_add_u64 v[220:221], s[64:65], 0, v[184:185]
	s_addc_u32 s25, s65, 0
	s_add_i32 s36, s71, s14
	global_load_lds_dwordx4 v[220:221], off
	v_lshl_add_u64 v[222:223], s[24:25], 0, v[180:181]
	s_mov_b32 m0, s36
	v_lshl_add_u64 v[224:225], s[66:67], 0, v[182:183]
	global_load_lds_dwordx4 v[222:223], off
	v_lshl_add_u64 v[222:223], s[24:25], 0, v[184:185]
	s_add_i32 m0, s36, 0x2000
	s_nop 0
	global_load_lds_dwordx4 v[222:223], off
	v_lshl_add_u64 v[222:223], s[66:67], 0, v[178:179]
	s_mov_b32 m0, s15
	s_nop 0
	global_load_lds_dwordx4 v[222:223], off
	s_mov_b32 m0, s23
	s_nop 0
	global_load_lds_dwordx4 v[224:225], off
	s_waitcnt vmcnt(8)
	s_waitcnt lgkmcnt(0)
	s_setprio 1
	s_waitcnt lgkmcnt(0)
	v_mfma_f32_16x16x32_bf16 v[62:65], v[82:85], v[162:165], v[62:65]
	v_mfma_f32_16x16x32_bf16 v[58:61], v[90:93], v[162:165], v[58:61]
	v_mfma_f32_16x16x32_bf16 v[46:49], v[82:85], v[170:173], v[46:49]
	v_mfma_f32_16x16x32_bf16 v[42:45], v[90:93], v[170:173], v[42:45]
	v_mfma_f32_16x16x32_bf16 v[30:33], v[82:85], v[194:197], v[30:33]
	v_mfma_f32_16x16x32_bf16 v[26:29], v[90:93], v[194:197], v[26:29]
	v_mfma_f32_16x16x32_bf16 v[14:17], v[82:85], v[208:211], v[14:17]
	v_mfma_f32_16x16x32_bf16 v[10:13], v[90:93], v[208:211], v[10:13]
	v_mfma_f32_16x16x32_bf16 v[62:65], v[86:89], v[166:169], v[62:65]
	v_mfma_f32_16x16x32_bf16 v[58:61], v[94:97], v[166:169], v[58:61]
	v_mfma_f32_16x16x32_bf16 v[46:49], v[86:89], v[174:177], v[46:49]
	v_mfma_f32_16x16x32_bf16 v[42:45], v[94:97], v[174:177], v[42:45]
	v_mfma_f32_16x16x32_bf16 v[30:33], v[86:89], v[198:201], v[30:33]
	v_mfma_f32_16x16x32_bf16 v[26:29], v[94:97], v[198:201], v[26:29]
	v_mfma_f32_16x16x32_bf16 v[14:17], v[86:89], v[212:215], v[14:17]
	v_mfma_f32_16x16x32_bf16 v[10:13], v[94:97], v[212:215], v[10:13]
	s_setprio 0
	s_setprio 1
	v_mfma_f32_16x16x32_bf16 v[54:57], v[102:105], v[162:165], v[54:57]
	v_mfma_f32_16x16x32_bf16 v[50:53], v[114:117], v[162:165], v[50:53]
	v_mfma_f32_16x16x32_bf16 v[38:41], v[102:105], v[170:173], v[38:41]
	v_mfma_f32_16x16x32_bf16 v[34:37], v[114:117], v[170:173], v[34:37]
	v_mfma_f32_16x16x32_bf16 v[22:25], v[102:105], v[194:197], v[22:25]
	v_mfma_f32_16x16x32_bf16 v[18:21], v[114:117], v[194:197], v[18:21]
	v_mfma_f32_16x16x32_bf16 v[6:9], v[102:105], v[208:211], v[6:9]
	v_mfma_f32_16x16x32_bf16 v[2:5], v[114:117], v[208:211], v[2:5]
	v_mfma_f32_16x16x32_bf16 v[54:57], v[106:109], v[166:169], v[54:57]
	v_mfma_f32_16x16x32_bf16 v[50:53], v[118:121], v[166:169], v[50:53]
	v_mfma_f32_16x16x32_bf16 v[38:41], v[106:109], v[174:177], v[38:41]
	v_mfma_f32_16x16x32_bf16 v[34:37], v[118:121], v[174:177], v[34:37]
	v_mfma_f32_16x16x32_bf16 v[22:25], v[106:109], v[198:201], v[22:25]
	v_mfma_f32_16x16x32_bf16 v[18:21], v[118:121], v[198:201], v[18:21]
	v_mfma_f32_16x16x32_bf16 v[6:9], v[106:109], v[212:215], v[6:9]
	v_mfma_f32_16x16x32_bf16 v[2:5], v[118:121], v[212:215], v[2:5]
	s_setprio 0
	s_barrier
	s_add_i32 s36, 0, 0x18000
	s_add_i32 s37, 0, 0x1c000
	v_add_u32_e32 v94, s36, v202
	v_add_u32_e32 v118, s37, v202
	ds_read_b128 v[82:85], v94
	ds_read_b128 v[86:89], v94 offset:1024
	ds_read_b128 v[90:93], v94 offset:2048
	ds_read_b128 v[94:97], v94 offset:3072
	ds_read_b128 v[102:105], v118
	ds_read_b128 v[106:109], v118 offset:1024
	ds_read_b128 v[114:117], v118 offset:2048
	ds_read_b128 v[118:121], v118 offset:3072
	s_add_u32 s24, s66, 0x80000
	s_addc_u32 s25, s67, 0
	s_mov_b32 m0, s26
	v_lshl_add_u64 v[226:227], s[24:25], 0, v[178:179]
	ds_read_b128 v[162:165], v206 offset:32768
	ds_read_b128 v[166:169], v206 offset:33792
	ds_read_b128 v[170:173], v206 offset:34816
	ds_read_b128 v[174:177], v206 offset:35840
	ds_read_b128 v[194:197], v206 offset:36864
	ds_read_b128 v[198:201], v206 offset:37888
	ds_read_b128 v[208:211], v206 offset:38912
	ds_read_b128 v[212:215], v206 offset:39936
	global_load_lds_dwordx4 v[226:227], off
	v_lshl_add_u64 v[226:227], s[24:25], 0, v[182:183]
	s_mov_b32 m0, s27
	s_nop 0
	global_load_lds_dwordx4 v[226:227], off
	s_waitcnt vmcnt(8)
	s_waitcnt lgkmcnt(0)
	s_setprio 1
	s_waitcnt lgkmcnt(0)
	v_mfma_f32_16x16x32_bf16 v[158:161], v[82:85], v[162:165], v[158:161]
	v_mfma_f32_16x16x32_bf16 v[154:157], v[90:93], v[162:165], v[154:157]
	v_mfma_f32_16x16x32_bf16 v[142:145], v[82:85], v[170:173], v[142:145]
	v_mfma_f32_16x16x32_bf16 v[138:141], v[90:93], v[170:173], v[138:141]
	v_mfma_f32_16x16x32_bf16 v[126:129], v[82:85], v[194:197], v[126:129]
	v_mfma_f32_16x16x32_bf16 v[122:125], v[90:93], v[194:197], v[122:125]
	v_mfma_f32_16x16x32_bf16 v[78:81], v[82:85], v[208:211], v[78:81]
	v_mfma_f32_16x16x32_bf16 v[74:77], v[90:93], v[208:211], v[74:77]
	v_mfma_f32_16x16x32_bf16 v[158:161], v[86:89], v[166:169], v[158:161]
	v_mfma_f32_16x16x32_bf16 v[154:157], v[94:97], v[166:169], v[154:157]
	v_mfma_f32_16x16x32_bf16 v[142:145], v[86:89], v[174:177], v[142:145]
	v_mfma_f32_16x16x32_bf16 v[138:141], v[94:97], v[174:177], v[138:141]
	v_mfma_f32_16x16x32_bf16 v[126:129], v[86:89], v[198:201], v[126:129]
	v_mfma_f32_16x16x32_bf16 v[122:125], v[94:97], v[198:201], v[122:125]
	v_mfma_f32_16x16x32_bf16 v[78:81], v[86:89], v[212:215], v[78:81]
	v_mfma_f32_16x16x32_bf16 v[74:77], v[94:97], v[212:215], v[74:77]
	s_setprio 0
	s_setprio 1
	v_mfma_f32_16x16x32_bf16 v[150:153], v[102:105], v[162:165], v[150:153]
	v_mfma_f32_16x16x32_bf16 v[146:149], v[114:117], v[162:165], v[146:149]
	v_mfma_f32_16x16x32_bf16 v[134:137], v[102:105], v[170:173], v[134:137]
	v_mfma_f32_16x16x32_bf16 v[130:133], v[114:117], v[170:173], v[130:133]
	v_mfma_f32_16x16x32_bf16 v[110:113], v[102:105], v[194:197], v[110:113]
	v_mfma_f32_16x16x32_bf16 v[98:101], v[114:117], v[194:197], v[98:101]
	v_mfma_f32_16x16x32_bf16 v[70:73], v[102:105], v[208:211], v[70:73]
	v_mfma_f32_16x16x32_bf16 v[66:69], v[114:117], v[208:211], v[66:69]
	v_mfma_f32_16x16x32_bf16 v[150:153], v[106:109], v[166:169], v[150:153]
	v_mfma_f32_16x16x32_bf16 v[146:149], v[118:121], v[166:169], v[146:149]
	v_mfma_f32_16x16x32_bf16 v[134:137], v[106:109], v[174:177], v[134:137]
	v_mfma_f32_16x16x32_bf16 v[130:133], v[118:121], v[174:177], v[130:133]
	v_mfma_f32_16x16x32_bf16 v[110:113], v[106:109], v[198:201], v[110:113]
	v_mfma_f32_16x16x32_bf16 v[98:101], v[118:121], v[198:201], v[98:101]
	v_mfma_f32_16x16x32_bf16 v[70:73], v[106:109], v[212:215], v[70:73]
	v_mfma_f32_16x16x32_bf16 v[66:69], v[118:121], v[212:215], v[66:69]
	s_setprio 0
	s_barrier
; #define PG8_STAGE(bufoff, gbase, voff) do { _Pragma("unroll") for (int _i = 0; _i < 2; ++_i) \
;         __builtin_amdgcn_global_load_lds((const unsigned*)((const char*)(gbase) + (voff)[_i]), (PG8_LAS unsigned*)(lds + (bufoff) + ldsw + _i * 8192), 16, 0, 0); } while (0)
; #define PG8_LDA(dst, b, h) do { _Pragma("unroll") for (int m = 0; m < 4; ++m) _Pragma("unroll") for (int k = 0; k < 2; ++k) dst[m][k] = *(const PG8_LAS bf16x8*)(lds + PG8_SA(b, h) + aoff + m * 2048 + k * 1024); } while (0)
; #define PG8_LDB(dst, b, h) do { _Pragma("unroll") for (int n = 0; n < 2; ++n) _Pragma("unroll") for (int k = 0; k < 2; ++k) dst[n][k] = *(const PG8_LAS bf16x8*)(lds + PG8_SB(b, h) + boff + n * 2048 + k * 1024); } while (0)
; #define PG8_WAIT_V(n) asm volatile("s_waitcnt vmcnt(" #n ")" ::: "memory")
; #define PG8_WAIT_L(n) asm volatile("s_waitcnt lgkmcnt(" #n ")" ::: "memory")
; #define PG8_BAR __builtin_amdgcn_s_barrier()
; #define PG8_SCHED __builtin_amdgcn_sched_barrier(0)
; template <class Epi, class Sched, bool ALIGN_EPI = false, bool SP2 = false, bool F8 = false>
; __device__ __forceinline__ void gemm_phase(PG8_LAS unsigned char* lds, const Gemm g, const Sched& S, const Epi& E) {
;     ...
;             PG8_LDB(B0, 0, 0); PG8_LDB(B1, 0, 1); PG8_SCHED; PG8_LDA(At, 0, 0); PG8_STAGE(PG8_SA(1, 1), a1 + hstepA, voffA);
;             PG8_WAIT_V(8); PG8_WAIT_L(0); PG8_BAR; PG8_MMA(0, 0, At, B0); PG8_MMA(0, 1, At, B1); PG8_BAR; PG8_SCHED;
;     ...
;             PG8_LDA(At, 1, 1); PG8_STAGE(PG8_SB(1, 0), b3, voffB); PG8_STAGE(PG8_SB(1, 1), b3 + hstep, voffB); PG8_STAGE(PG8_SA(1, 0), a3, voffA);
;             PG8_WAIT_V(8); PG8_WAIT_L(0); PG8_BAR; PG8_MMA(1, 0, At, B0); PG8_MMA(1, 1, At, B1); PG8_BAR; PG8_SCHED;
	s_add_i32 s24, s36, s14
	v_lshl_add_u64 v[218:219], v[218:219], 0, s[48:49]
	s_mov_b32 m0, s24
	ds_read_b128 v[162:165], v206 offset:49152
	ds_read_b128 v[166:169], v206 offset:50176
	ds_read_b128 v[170:173], v206 offset:51200
	ds_read_b128 v[174:177], v206 offset:52224
	ds_read_b128 v[194:197], v206 offset:53248
	ds_read_b128 v[198:201], v206 offset:54272
	ds_read_b128 v[208:211], v206 offset:55296
	ds_read_b128 v[212:215], v206 offset:56320
	global_load_lds_dwordx4 v[218:219], off
	s_add_i32 m0, s24, 0x2000
	s_add_u32 s24, s64, 0x80080
	v_lshl_add_u64 v[218:219], v[220:221], 0, s[48:49]
	s_addc_u32 s25, s65, 0
	s_add_i32 s36, s37, s14
	global_load_lds_dwordx4 v[218:219], off
	v_lshl_add_u64 v[218:219], s[24:25], 0, v[180:181]
	s_mov_b32 m0, s36
	s_nop 0
	global_load_lds_dwordx4 v[218:219], off
	v_lshl_add_u64 v[218:219], s[24:25], 0, v[184:185]
	s_add_i32 m0, s36, 0x2000
	s_nop 0
	global_load_lds_dwordx4 v[218:219], off
	v_lshl_add_u64 v[218:219], v[222:223], 0, s[48:49]
	s_mov_b32 m0, s44
	s_nop 0
	global_load_lds_dwordx4 v[218:219], off
	v_lshl_add_u64 v[218:219], v[224:225], 0, s[48:49]
	s_mov_b32 m0, s45
	s_nop 0
	global_load_lds_dwordx4 v[218:219], off
	s_waitcnt vmcnt(8)
	s_waitcnt lgkmcnt(0)
	s_setprio 1
	s_waitcnt lgkmcnt(0)
	v_mfma_f32_16x16x32_bf16 v[62:65], v[82:85], v[162:165], v[62:65]
	v_mfma_f32_16x16x32_bf16 v[58:61], v[90:93], v[162:165], v[58:61]
	v_mfma_f32_16x16x32_bf16 v[46:49], v[82:85], v[170:173], v[46:49]
	v_mfma_f32_16x16x32_bf16 v[42:45], v[90:93], v[170:173], v[42:45]
	v_mfma_f32_16x16x32_bf16 v[30:33], v[82:85], v[194:197], v[30:33]
	v_mfma_f32_16x16x32_bf16 v[26:29], v[90:93], v[194:197], v[26:29]
	v_mfma_f32_16x16x32_bf16 v[14:17], v[82:85], v[208:211], v[14:17]
	v_mfma_f32_16x16x32_bf16 v[10:13], v[90:93], v[208:211], v[10:13]
	v_mfma_f32_16x16x32_bf16 v[62:65], v[86:89], v[166:169], v[62:65]
	v_mfma_f32_16x16x32_bf16 v[58:61], v[94:97], v[166:169], v[58:61]
	v_mfma_f32_16x16x32_bf16 v[46:49], v[86:89], v[174:177], v[46:49]
	v_mfma_f32_16x16x32_bf16 v[42:45], v[94:97], v[174:177], v[42:45]
	v_mfma_f32_16x16x32_bf16 v[30:33], v[86:89], v[198:201], v[30:33]
	v_mfma_f32_16x16x32_bf16 v[26:29], v[94:97], v[198:201], v[26:29]
	v_mfma_f32_16x16x32_bf16 v[14:17], v[86:89], v[212:215], v[14:17]
	v_mfma_f32_16x16x32_bf16 v[10:13], v[94:97], v[212:215], v[10:13]
	s_setprio 0
	s_setprio 1
	v_mfma_f32_16x16x32_bf16 v[54:57], v[102:105], v[162:165], v[54:57]
	v_mfma_f32_16x16x32_bf16 v[50:53], v[114:117], v[162:165], v[50:53]
	v_mfma_f32_16x16x32_bf16 v[38:41], v[102:105], v[170:173], v[38:41]
	v_mfma_f32_16x16x32_bf16 v[34:37], v[114:117], v[170:173], v[34:37]
	v_mfma_f32_16x16x32_bf16 v[22:25], v[102:105], v[194:197], v[22:25]
	v_mfma_f32_16x16x32_bf16 v[18:21], v[114:117], v[194:197], v[18:21]
	v_mfma_f32_16x16x32_bf16 v[6:9], v[102:105], v[208:211], v[6:9]
	v_mfma_f32_16x16x32_bf16 v[2:5], v[114:117], v[208:211], v[2:5]
	v_mfma_f32_16x16x32_bf16 v[54:57], v[106:109], v[166:169], v[54:57]
	v_mfma_f32_16x16x32_bf16 v[50:53], v[118:121], v[166:169], v[50:53]
	v_mfma_f32_16x16x32_bf16 v[38:41], v[106:109], v[174:177], v[38:41]
	v_mfma_f32_16x16x32_bf16 v[34:37], v[118:121], v[174:177], v[34:37]
	v_mfma_f32_16x16x32_bf16 v[22:25], v[106:109], v[198:201], v[22:25]
	v_mfma_f32_16x16x32_bf16 v[18:21], v[118:121], v[198:201], v[18:21]
	v_mfma_f32_16x16x32_bf16 v[6:9], v[106:109], v[212:215], v[6:9]
	v_mfma_f32_16x16x32_bf16 v[2:5], v[118:121], v[212:215], v[2:5]
	s_setprio 0
	s_barrier
	s_add_i32 s76, s76, 2
	s_add_u32 s62, s62, 0x100
	s_addc_u32 s63, s63, 0
	s_add_u32 s74, s74, 0x100
	s_addc_u32 s75, s75, 0
	s_cmp_gt_u32 s76, 29
	s_cbranch_scc0 .LBB0_772
	s_branch .Lk2_exit
.Lk2_Y:
	ds_read_b128 v[82:85], v204
	ds_read_b128 v[86:89], v204 offset:1024
	ds_read_b128 v[90:93], v204 offset:2048
	ds_read_b128 v[94:97], v204 offset:3072
	ds_read_b128 v[102:105], v205
	ds_read_b128 v[106:109], v205 offset:1024
	ds_read_b128 v[114:117], v205 offset:2048
	ds_read_b128 v[118:121], v205 offset:3072
	s_add_u32 s24, s62, 0xfff80080
	s_addc_u32 s25, s63, -1
	s_cmp_eq_u32 s76, 28
	s_cselect_b32 s67, s55, s25
	s_cselect_b32 s66, s61, s24
	s_cselect_b32 s65, s53, s75
	s_cselect_b32 s64, s73, s74
	v_lshl_add_u64 v[218:219], s[62:63], 0, v[186:187]
	s_add_i32 m0, s15, 0xc000
	ds_read_b128 v[162:165], v206
	ds_read_b128 v[166:169], v206 offset:1024
	ds_read_b128 v[170:173], v206 offset:2048
	ds_read_b128 v[174:177], v206 offset:3072
	ds_read_b128 v[194:197], v206 offset:4096
	ds_read_b128 v[198:201], v206 offset:5120
	ds_read_b128 v[208:211], v206 offset:6144
	ds_read_b128 v[212:215], v206 offset:7168
	global_load_lds_dwordx4 v[218:219], off
	v_lshl_add_u64 v[218:219], s[62:63], 0, v[188:189]
	s_add_i32 m0, s15, 0xe000
	s_nop 0
	global_load_lds_dwordx4 v[218:219], off
	s_waitcnt vmcnt(8)
	s_waitcnt lgkmcnt(0)
	s_barrier
; #define PG8_STAGE(bufoff, gbase, voff) do { _Pragma("unroll") for (int _i = 0; _i < 2; ++_i) \
;         __builtin_amdgcn_global_load_lds((const unsigned*)((const char*)(gbase) + (voff)[_i]), (PG8_LAS unsigned*)(lds + (bufoff) + ldsw + _i * 8192), 16, 0, 0); } while (0)
; #define PG8_LDA(dst, b, h) do { _Pragma("unroll") for (int m = 0; m < 4; ++m) _Pragma("unroll") for (int k = 0; k < 2; ++k) dst[m][k] = *(const PG8_LAS bf16x8*)(lds + PG8_SA(b, h) + aoff + m * 2048 + k * 1024); } while (0)
; #define PG8_LDB(dst, b, h) do { _Pragma("unroll") for (int n = 0; n < 2; ++n) _Pragma("unroll") for (int k = 0; k < 2; ++k) dst[n][k] = *(const PG8_LAS bf16x8*)(lds + PG8_SB(b, h) + boff + n * 2048 + k * 1024); } while (0)
; #define PG8_WAIT_V(n) asm volatile("s_waitcnt vmcnt(" #n ")" ::: "memory")
; #define PG8_WAIT_L(n) asm volatile("s_waitcnt lgkmcnt(" #n ")" ::: "memory")
; #define PG8_BAR __builtin_amdgcn_s_barrier()
; #define PG8_SCHED __builtin_amdgcn_sched_barrier(0)
; template <class Epi, class Sched, bool ALIGN_EPI = false, bool SP2 = false, bool F8 = false>
; __device__ __forceinline__ void gemm_phase(PG8_LAS unsigned char* lds, const Gemm g, const Sched& S, const Epi& E) {
;     ...
;             PG8_WAIT_V(8); PG8_WAIT_L(0); PG8_BAR; PG8_MMA(0, 0, At, B0); PG8_MMA(0, 1, At, B1); PG8_BAR; PG8_SCHED;
;             PG8_LDA(At, 0, 1); PG8_STAGE(PG8_SB(0, 0), b2, voffB); PG8_STAGE(PG8_SB(0, 1), b2 + hstep, voffB); PG8_STAGE(PG8_SA(0, 0), a2, voffA);
;             PG8_WAIT_V(8); PG8_WAIT_L(0); PG8_BAR; PG8_MMA(1, 0, At, B0); PG8_MMA(1, 1, At, B1); PG8_BAR; PG8_SCHED;
;             PG8_LDB(B0, 1, 0); PG8_LDB(B1, 1, 1); PG8_SCHED; PG8_LDA(At, 1, 0); PG8_STAGE(PG8_SA(0, 1), a2 + hstepA, voffA);
;             PG8_WAIT_V(8); PG8_WAIT_L(0); PG8_BAR; PG8_MMA(0, 0, At, B0); PG8_MMA(0, 1, At, B1); PG8_BAR; PG8_SCHED;
	s_setprio 3
	s_waitcnt lgkmcnt(0)
	v_mfma_f32_16x16x32_bf16 v[158:161], v[82:85], v[162:165], v[158:161]
	v_mfma_f32_16x16x32_bf16 v[154:157], v[90:93], v[162:165], v[154:157]
	v_mfma_f32_16x16x32_bf16 v[142:145], v[82:85], v[170:173], v[142:145]
	v_mfma_f32_16x16x32_bf16 v[138:141], v[90:93], v[170:173], v[138:141]
	v_mfma_f32_16x16x32_bf16 v[126:129], v[82:85], v[194:197], v[126:129]
	v_mfma_f32_16x16x32_bf16 v[122:125], v[90:93], v[194:197], v[122:125]
	v_mfma_f32_16x16x32_bf16 v[78:81], v[82:85], v[208:211], v[78:81]
	v_mfma_f32_16x16x32_bf16 v[74:77], v[90:93], v[208:211], v[74:77]
	v_mfma_f32_16x16x32_bf16 v[158:161], v[86:89], v[166:169], v[158:161]
	v_mfma_f32_16x16x32_bf16 v[154:157], v[94:97], v[166:169], v[154:157]
	v_mfma_f32_16x16x32_bf16 v[142:145], v[86:89], v[174:177], v[142:145]
	v_mfma_f32_16x16x32_bf16 v[138:141], v[94:97], v[174:177], v[138:141]
	v_mfma_f32_16x16x32_bf16 v[126:129], v[86:89], v[198:201], v[126:129]
	v_mfma_f32_16x16x32_bf16 v[122:125], v[94:97], v[198:201], v[122:125]
	v_mfma_f32_16x16x32_bf16 v[78:81], v[86:89], v[212:215], v[78:81]
	v_mfma_f32_16x16x32_bf16 v[74:77], v[94:97], v[212:215], v[74:77]
	s_setprio 0
	s_setprio 3
	v_mfma_f32_16x16x32_bf16 v[150:153], v[102:105], v[162:165], v[150:153]
	v_mfma_f32_16x16x32_bf16 v[146:149], v[114:117], v[162:165], v[146:149]
	v_mfma_f32_16x16x32_bf16 v[134:137], v[102:105], v[170:173], v[134:137]
	v_mfma_f32_16x16x32_bf16 v[130:133], v[114:117], v[170:173], v[130:133]
	v_mfma_f32_16x16x32_bf16 v[110:113], v[102:105], v[194:197], v[110:113]
	v_mfma_f32_16x16x32_bf16 v[98:101], v[114:117], v[194:197], v[98:101]
	v_mfma_f32_16x16x32_bf16 v[70:73], v[102:105], v[208:211], v[70:73]
	v_mfma_f32_16x16x32_bf16 v[66:69], v[114:117], v[208:211], v[66:69]
	v_mfma_f32_16x16x32_bf16 v[150:153], v[106:109], v[166:169], v[150:153]
	v_mfma_f32_16x16x32_bf16 v[146:149], v[118:121], v[166:169], v[146:149]
	v_mfma_f32_16x16x32_bf16 v[134:137], v[106:109], v[174:177], v[134:137]
	v_mfma_f32_16x16x32_bf16 v[130:133], v[118:121], v[174:177], v[130:133]
	v_mfma_f32_16x16x32_bf16 v[110:113], v[106:109], v[198:201], v[110:113]
	v_mfma_f32_16x16x32_bf16 v[98:101], v[118:121], v[198:201], v[98:101]
	v_mfma_f32_16x16x32_bf16 v[70:73], v[106:109], v[212:215], v[70:73]
	v_mfma_f32_16x16x32_bf16 v[66:69], v[118:121], v[212:215], v[66:69]
	s_setprio 0
	s_add_i32 s24, s70, s14
	v_lshl_add_u64 v[218:219], s[64:65], 0, v[180:181]
	s_mov_b32 m0, s24
	ds_read_b128 v[162:165], v206 offset:16384
	ds_read_b128 v[166:169], v206 offset:17408
	ds_read_b128 v[170:173], v206 offset:18432
	ds_read_b128 v[174:177], v206 offset:19456
	ds_read_b128 v[194:197], v206 offset:20480
	ds_read_b128 v[198:201], v206 offset:21504
	ds_read_b128 v[208:211], v206 offset:22528
	ds_read_b128 v[212:215], v206 offset:23552
	global_load_lds_dwordx4 v[218:219], off
	s_add_i32 m0, s24, 0x2000
	s_add_u32 s24, s64, 0x80000
	v_lshl_add_u64 v[220:221], s[64:65], 0, v[184:185]
	s_addc_u32 s25, s65, 0
	s_add_i32 s36, s71, s14
	global_load_lds_dwordx4 v[220:221], off
	v_lshl_add_u64 v[222:223], s[24:25], 0, v[180:181]
	s_mov_b32 m0, s36
	v_lshl_add_u64 v[224:225], s[66:67], 0, v[182:183]
	global_load_lds_dwordx4 v[222:223], off
	v_lshl_add_u64 v[222:223], s[24:25], 0, v[184:185]
	s_add_i32 m0, s36, 0x2000
	s_nop 0
	global_load_lds_dwordx4 v[222:223], off
	v_lshl_add_u64 v[222:223], s[66:67], 0, v[178:179]
	s_mov_b32 m0, s15
	s_nop 0
	global_load_lds_dwordx4 v[222:223], off
	s_mov_b32 m0, s23
	s_nop 0
	global_load_lds_dwordx4 v[224:225], off
	s_waitcnt vmcnt(8)
	s_waitcnt lgkmcnt(0)
	s_barrier
	s_setprio 3
	s_waitcnt lgkmcnt(0)
	v_mfma_f32_16x16x32_bf16 v[62:65], v[82:85], v[162:165], v[62:65]
	v_mfma_f32_16x16x32_bf16 v[58:61], v[90:93], v[162:165], v[58:61]
	v_mfma_f32_16x16x32_bf16 v[46:49], v[82:85], v[170:173], v[46:49]
	v_mfma_f32_16x16x32_bf16 v[42:45], v[90:93], v[170:173], v[42:45]
	v_mfma_f32_16x16x32_bf16 v[30:33], v[82:85], v[194:197], v[30:33]
	v_mfma_f32_16x16x32_bf16 v[26:29], v[90:93], v[194:197], v[26:29]
	v_mfma_f32_16x16x32_bf16 v[14:17], v[82:85], v[208:211], v[14:17]
	v_mfma_f32_16x16x32_bf16 v[10:13], v[90:93], v[208:211], v[10:13]
	v_mfma_f32_16x16x32_bf16 v[62:65], v[86:89], v[166:169], v[62:65]
	v_mfma_f32_16x16x32_bf16 v[58:61], v[94:97], v[166:169], v[58:61]
	v_mfma_f32_16x16x32_bf16 v[46:49], v[86:89], v[174:177], v[46:49]
	v_mfma_f32_16x16x32_bf16 v[42:45], v[94:97], v[174:177], v[42:45]
	v_mfma_f32_16x16x32_bf16 v[30:33], v[86:89], v[198:201], v[30:33]
	v_mfma_f32_16x16x32_bf16 v[26:29], v[94:97], v[198:201], v[26:29]
	v_mfma_f32_16x16x32_bf16 v[14:17], v[86:89], v[212:215], v[14:17]
	v_mfma_f32_16x16x32_bf16 v[10:13], v[94:97], v[212:215], v[10:13]
	s_setprio 0
	s_setprio 3
	v_mfma_f32_16x16x32_bf16 v[54:57], v[102:105], v[162:165], v[54:57]
	v_mfma_f32_16x16x32_bf16 v[50:53], v[114:117], v[162:165], v[50:53]
	v_mfma_f32_16x16x32_bf16 v[38:41], v[102:105], v[170:173], v[38:41]
	v_mfma_f32_16x16x32_bf16 v[34:37], v[114:117], v[170:173], v[34:37]
	v_mfma_f32_16x16x32_bf16 v[22:25], v[102:105], v[194:197], v[22:25]
	v_mfma_f32_16x16x32_bf16 v[18:21], v[114:117], v[194:197], v[18:21]
	v_mfma_f32_16x16x32_bf16 v[6:9], v[102:105], v[208:211], v[6:9]
	v_mfma_f32_16x16x32_bf16 v[2:5], v[114:117], v[208:211], v[2:5]
	v_mfma_f32_16x16x32_bf16 v[54:57], v[106:109], v[166:169], v[54:57]
	v_mfma_f32_16x16x32_bf16 v[50:53], v[118:121], v[166:169], v[50:53]
	v_mfma_f32_16x16x32_bf16 v[38:41], v[106:109], v[174:177], v[38:41]
	v_mfma_f32_16x16x32_bf16 v[34:37], v[118:121], v[174:177], v[34:37]
	v_mfma_f32_16x16x32_bf16 v[22:25], v[106:109], v[198:201], v[22:25]
	v_mfma_f32_16x16x32_bf16 v[18:21], v[118:121], v[198:201], v[18:21]
	v_mfma_f32_16x16x32_bf16 v[6:9], v[106:109], v[212:215], v[6:9]
	v_mfma_f32_16x16x32_bf16 v[2:5], v[118:121], v[212:215], v[2:5]
	s_setprio 0
	s_add_i32 s36, 0, 0x18000
	s_add_i32 s37, 0, 0x1c000
	v_add_u32_e32 v94, s36, v202
	v_add_u32_e32 v118, s37, v202
	ds_read_b128 v[82:85], v94
	ds_read_b128 v[86:89], v94 offset:1024
	ds_read_b128 v[90:93], v94 offset:2048
	ds_read_b128 v[94:97], v94 offset:3072
	ds_read_b128 v[102:105], v118
	ds_read_b128 v[106:109], v118 offset:1024
	ds_read_b128 v[114:117], v118 offset:2048
	ds_read_b128 v[118:121], v118 offset:3072
	s_add_u32 s24, s66, 0x80000
	s_addc_u32 s25, s67, 0
	s_mov_b32 m0, s26
	v_lshl_add_u64 v[226:227], s[24:25], 0, v[178:179]
	ds_read_b128 v[162:165], v206 offset:32768
	ds_read_b128 v[166:169], v206 offset:33792
	ds_read_b128 v[170:173], v206 offset:34816
	ds_read_b128 v[174:177], v206 offset:35840
	ds_read_b128 v[194:197], v206 offset:36864
	ds_read_b128 v[198:201], v206 offset:37888
	ds_read_b128 v[208:211], v206 offset:38912
	ds_read_b128 v[212:215], v206 offset:39936
	global_load_lds_dwordx4 v[226:227], off
	v_lshl_add_u64 v[226:227], s[24:25], 0, v[182:183]
	s_mov_b32 m0, s27
	s_nop 0
	global_load_lds_dwordx4 v[226:227], off
	s_waitcnt vmcnt(8)
	s_waitcnt lgkmcnt(0)
	s_barrier
; #define PG8_STAGE(bufoff, gbase, voff) do { _Pragma("unroll") for (int _i = 0; _i < 2; ++_i) \
;         __builtin_amdgcn_global_load_lds((const unsigned*)((const char*)(gbase) + (voff)[_i]), (PG8_LAS unsigned*)(lds + (bufoff) + ldsw + _i * 8192), 16, 0, 0); } while (0)
; #define PG8_LDA(dst, b, h) do { _Pragma("unroll") for (int m = 0; m < 4; ++m) _Pragma("unroll") for (int k = 0; k < 2; ++k) dst[m][k] = *(const PG8_LAS bf16x8*)(lds + PG8_SA(b, h) + aoff + m * 2048 + k * 1024); } while (0)
; #define PG8_WAIT_V(n) asm volatile("s_waitcnt vmcnt(" #n ")" ::: "memory")
; #define PG8_WAIT_L(n) asm volatile("s_waitcnt lgkmcnt(" #n ")" ::: "memory")
; #define PG8_BAR __builtin_amdgcn_s_barrier()
; #define PG8_SCHED __builtin_amdgcn_sched_barrier(0)
; template <class Epi, class Sched, bool ALIGN_EPI = false, bool SP2 = false, bool F8 = false>
; __device__ __forceinline__ void gemm_phase(PG8_LAS unsigned char* lds, const Gemm g, const Sched& S, const Epi& E) {
;     ...
;             PG8_WAIT_V(8); PG8_WAIT_L(0); PG8_BAR; PG8_MMA(0, 0, At, B0); PG8_MMA(0, 1, At, B1); PG8_BAR; PG8_SCHED;
;             PG8_LDA(At, 1, 1); PG8_STAGE(PG8_SB(1, 0), b3, voffB); PG8_STAGE(PG8_SB(1, 1), b3 + hstep, voffB); PG8_STAGE(PG8_SA(1, 0), a3, voffA);
;             PG8_WAIT_V(8); PG8_WAIT_L(0); PG8_BAR; PG8_MMA(1, 0, At, B0); PG8_MMA(1, 1, At, B1); PG8_BAR; PG8_SCHED;
	s_setprio 3
	s_waitcnt lgkmcnt(0)
	v_mfma_f32_16x16x32_bf16 v[158:161], v[82:85], v[162:165], v[158:161]
	v_mfma_f32_16x16x32_bf16 v[154:157], v[90:93], v[162:165], v[154:157]
	v_mfma_f32_16x16x32_bf16 v[142:145], v[82:85], v[170:173], v[142:145]
	v_mfma_f32_16x16x32_bf16 v[138:141], v[90:93], v[170:173], v[138:141]
	v_mfma_f32_16x16x32_bf16 v[126:129], v[82:85], v[194:197], v[126:129]
	v_mfma_f32_16x16x32_bf16 v[122:125], v[90:93], v[194:197], v[122:125]
	v_mfma_f32_16x16x32_bf16 v[78:81], v[82:85], v[208:211], v[78:81]
	v_mfma_f32_16x16x32_bf16 v[74:77], v[90:93], v[208:211], v[74:77]
	v_mfma_f32_16x16x32_bf16 v[158:161], v[86:89], v[166:169], v[158:161]
	v_mfma_f32_16x16x32_bf16 v[154:157], v[94:97], v[166:169], v[154:157]
	v_mfma_f32_16x16x32_bf16 v[142:145], v[86:89], v[174:177], v[142:145]
	v_mfma_f32_16x16x32_bf16 v[138:141], v[94:97], v[174:177], v[138:141]
	v_mfma_f32_16x16x32_bf16 v[126:129], v[86:89], v[198:201], v[126:129]
	v_mfma_f32_16x16x32_bf16 v[122:125], v[94:97], v[198:201], v[122:125]
	v_mfma_f32_16x16x32_bf16 v[78:81], v[86:89], v[212:215], v[78:81]
	v_mfma_f32_16x16x32_bf16 v[74:77], v[94:97], v[212:215], v[74:77]
	s_setprio 0
	s_setprio 3
	v_mfma_f32_16x16x32_bf16 v[150:153], v[102:105], v[162:165], v[150:153]
	v_mfma_f32_16x16x32_bf16 v[146:149], v[114:117], v[162:165], v[146:149]
	v_mfma_f32_16x16x32_bf16 v[134:137], v[102:105], v[170:173], v[134:137]
	v_mfma_f32_16x16x32_bf16 v[130:133], v[114:117], v[170:173], v[130:133]
	v_mfma_f32_16x16x32_bf16 v[110:113], v[102:105], v[194:197], v[110:113]
	v_mfma_f32_16x16x32_bf16 v[98:101], v[114:117], v[194:197], v[98:101]
	v_mfma_f32_16x16x32_bf16 v[70:73], v[102:105], v[208:211], v[70:73]
	v_mfma_f32_16x16x32_bf16 v[66:69], v[114:117], v[208:211], v[66:69]
	v_mfma_f32_16x16x32_bf16 v[150:153], v[106:109], v[166:169], v[150:153]
	v_mfma_f32_16x16x32_bf16 v[146:149], v[118:121], v[166:169], v[146:149]
	v_mfma_f32_16x16x32_bf16 v[134:137], v[106:109], v[174:177], v[134:137]
	v_mfma_f32_16x16x32_bf16 v[130:133], v[118:121], v[174:177], v[130:133]
	v_mfma_f32_16x16x32_bf16 v[110:113], v[106:109], v[198:201], v[110:113]
	v_mfma_f32_16x16x32_bf16 v[98:101], v[118:121], v[198:201], v[98:101]
	v_mfma_f32_16x16x32_bf16 v[70:73], v[106:109], v[212:215], v[70:73]
	v_mfma_f32_16x16x32_bf16 v[66:69], v[118:121], v[212:215], v[66:69]
	s_setprio 0
	s_add_i32 s24, s36, s14
	v_lshl_add_u64 v[218:219], v[218:219], 0, s[48:49]
	s_mov_b32 m0, s24
	ds_read_b128 v[162:165], v206 offset:49152
	ds_read_b128 v[166:169], v206 offset:50176
	ds_read_b128 v[170:173], v206 offset:51200
	ds_read_b128 v[174:177], v206 offset:52224
	ds_read_b128 v[194:197], v206 offset:53248
	ds_read_b128 v[198:201], v206 offset:54272
	ds_read_b128 v[208:211], v206 offset:55296
	ds_read_b128 v[212:215], v206 offset:56320
	global_load_lds_dwordx4 v[218:219], off
	s_add_i32 m0, s24, 0x2000
	s_add_u32 s24, s64, 0x80080
	v_lshl_add_u64 v[218:219], v[220:221], 0, s[48:49]
	s_addc_u32 s25, s65, 0
	s_add_i32 s36, s37, s14
	global_load_lds_dwordx4 v[218:219], off
	v_lshl_add_u64 v[218:219], s[24:25], 0, v[180:181]
	s_mov_b32 m0, s36
	s_nop 0
	global_load_lds_dwordx4 v[218:219], off
	v_lshl_add_u64 v[218:219], s[24:25], 0, v[184:185]
	s_add_i32 m0, s36, 0x2000
	s_nop 0
	global_load_lds_dwordx4 v[218:219], off
	v_lshl_add_u64 v[218:219], v[222:223], 0, s[48:49]
	s_mov_b32 m0, s44
	s_nop 0
	global_load_lds_dwordx4 v[218:219], off
	v_lshl_add_u64 v[218:219], v[224:225], 0, s[48:49]
	s_mov_b32 m0, s45
	s_nop 0
	global_load_lds_dwordx4 v[218:219], off
	s_waitcnt vmcnt(8)
	s_waitcnt lgkmcnt(0)
	s_barrier
	s_setprio 3
	s_waitcnt lgkmcnt(0)
	v_mfma_f32_16x16x32_bf16 v[62:65], v[82:85], v[162:165], v[62:65]
	v_mfma_f32_16x16x32_bf16 v[58:61], v[90:93], v[162:165], v[58:61]
	v_mfma_f32_16x16x32_bf16 v[46:49], v[82:85], v[170:173], v[46:49]
	v_mfma_f32_16x16x32_bf16 v[42:45], v[90:93], v[170:173], v[42:45]
	v_mfma_f32_16x16x32_bf16 v[30:33], v[82:85], v[194:197], v[30:33]
	v_mfma_f32_16x16x32_bf16 v[26:29], v[90:93], v[194:197], v[26:29]
	v_mfma_f32_16x16x32_bf16 v[14:17], v[82:85], v[208:211], v[14:17]
	v_mfma_f32_16x16x32_bf16 v[10:13], v[90:93], v[208:211], v[10:13]
	v_mfma_f32_16x16x32_bf16 v[62:65], v[86:89], v[166:169], v[62:65]
	v_mfma_f32_16x16x32_bf16 v[58:61], v[94:97], v[166:169], v[58:61]
	v_mfma_f32_16x16x32_bf16 v[46:49], v[86:89], v[174:177], v[46:49]
	v_mfma_f32_16x16x32_bf16 v[42:45], v[94:97], v[174:177], v[42:45]
	v_mfma_f32_16x16x32_bf16 v[30:33], v[86:89], v[198:201], v[30:33]
	v_mfma_f32_16x16x32_bf16 v[26:29], v[94:97], v[198:201], v[26:29]
	v_mfma_f32_16x16x32_bf16 v[14:17], v[86:89], v[212:215], v[14:17]
	v_mfma_f32_16x16x32_bf16 v[10:13], v[94:97], v[212:215], v[10:13]
	s_setprio 0
	s_setprio 3
	v_mfma_f32_16x16x32_bf16 v[54:57], v[102:105], v[162:165], v[54:57]
	v_mfma_f32_16x16x32_bf16 v[50:53], v[114:117], v[162:165], v[50:53]
	v_mfma_f32_16x16x32_bf16 v[38:41], v[102:105], v[170:173], v[38:41]
	v_mfma_f32_16x16x32_bf16 v[34:37], v[114:117], v[170:173], v[34:37]
	v_mfma_f32_16x16x32_bf16 v[22:25], v[102:105], v[194:197], v[22:25]
	v_mfma_f32_16x16x32_bf16 v[18:21], v[114:117], v[194:197], v[18:21]
	v_mfma_f32_16x16x32_bf16 v[6:9], v[102:105], v[208:211], v[6:9]
	v_mfma_f32_16x16x32_bf16 v[2:5], v[114:117], v[208:211], v[2:5]
	v_mfma_f32_16x16x32_bf16 v[54:57], v[106:109], v[166:169], v[54:57]
	v_mfma_f32_16x16x32_bf16 v[50:53], v[118:121], v[166:169], v[50:53]
	v_mfma_f32_16x16x32_bf16 v[38:41], v[106:109], v[174:177], v[38:41]
	v_mfma_f32_16x16x32_bf16 v[34:37], v[118:121], v[174:177], v[34:37]
	v_mfma_f32_16x16x32_bf16 v[22:25], v[106:109], v[198:201], v[22:25]
	v_mfma_f32_16x16x32_bf16 v[18:21], v[118:121], v[198:201], v[18:21]
	v_mfma_f32_16x16x32_bf16 v[6:9], v[106:109], v[212:215], v[6:9]
	v_mfma_f32_16x16x32_bf16 v[2:5], v[118:121], v[212:215], v[2:5]
	s_setprio 0
	s_add_i32 s76, s76, 2
	s_add_u32 s62, s62, 0x100
	s_addc_u32 s63, s63, 0
	s_add_u32 s74, s74, 0x100
	s_addc_u32 s75, s75, 0
	s_cmp_gt_u32 s76, 29
	s_cbranch_scc0 .Lk2_Y
; __device__ __forceinline__ unsigned cvt_pk_bf16(float lo, float hi) { unsigned r; asm volatile("v_cvt_pk_bf16_f32 %0, %1, %2" : "=v"(r) : "v"(lo), "v"(hi)); return r; }
;     __device__ __forceinline__ void operator()(const f32x4 (&acc)[2][2][4][2], const Unit& u, int wr, int wc, int fr, int fq) const {
;         const int row0 = u.pm * BM + wr * 64 + fr, col0 = u.pn * BM + wc * 32 + 8 * fq, b = (u.pm * BM) >> 13;
;         const float* gp = gate + (size_t)b * gate_bstride + col0; const float* mp = mul + (size_t)b * ldc + col0;
;         f32x4 gv[2][2], mvv[2][2];
; #pragma unroll
;         for (int bj = 0; bj < 2; ++bj)
; #pragma unroll
;             for (int n = 0; n < 2; ++n) { gv[bj][n] = *(const f32x4*)(gp + bj * HALF + 4 * n); mvv[bj][n] = *(const f32x4*)(mp + bj * HALF + 4 * n); }
; #pragma unroll
;         for (int hq = 0; hq < 4; ++hq) { const int ai = hq >> 1, m0 = 2 * (hq & 1);
;             f32x4 bsv[2][2][2];
; #pragma unroll
;             for (int mm = 0; mm < 2; ++mm)
; #pragma unroll
;                 for (int bj = 0; bj < 2; ++bj)
; #pragma unroll
;                     for (int n = 0; n < 2; ++n) bsv[mm][bj][n] = __builtin_nontemporal_load((const f32x4*)(base + (size_t)(row0 + ai * HALF + (m0 + mm) * 16) * ldc + col0 + bj * HALF + 4 * n));
;             asm volatile("" ::: "memory");
; #pragma unroll
;             for (int mm = 0; mm < 2; ++mm) { const int m = m0 + mm; const int r = row0 + ai * HALF + m * 16; const size_t off = (size_t)r * ldc + col0; float ss = 0.f;
; #pragma unroll
;                 for (int bj = 0; bj < 2; ++bj) {
;                     const f32x4 v0 = bsv[mm][bj][0] + gv[bj][0] * acc[ai][bj][m][0], v1 = bsv[mm][bj][1] + gv[bj][1] * acc[ai][bj][m][1];
;                     ss += ((v0[0] * v0[0] + v0[1] * v0[1]) + (v0[2] * v0[2] + v0[3] * v0[3])) + ((v1[0] * v1[0] + v1[1] * v1[1]) + (v1[2] * v1[2] + v1[3] * v1[3]));
;                     const f32x4 y0 = v0 * mvv[bj][0], y1 = v1 * mvv[bj][1];
;                     u32x4 wn; wn.x = cvt_pk_bf16(y0[0], y0[1]); wn.y = cvt_pk_bf16(y0[2], y0[3]); wn.z = cvt_pk_bf16(y1[0], y1[1]); wn.w = cvt_pk_bf16(y1[2], y1[3]);
;                     *(u32x4*)(xn + off + bj * HALF) = wn; }
;                 ss += __shfl_xor(ss, 16); ss += __shfl_xor(ss, 32);
;                 if (fq == 0) rowss[(size_t)r * 32 + 4 * u.pn + wc] = ss; }
.Lk2_exit:
	s_and_b64 vcc, exec, s[50:51]
	s_cbranch_vccz .LBB0_775
.LBB0_775:
	v_lshl_or_b32 v194, s12, 8, v203
	s_ashr_i32 s24, s60, 5
	v_ashrrev_i32_e32 v195, 31, v194
	v_lshl_add_u32 v198, s60, 8, v1
	s_ashr_i32 s25, s24, 31
	s_mul_i32 s37, s24, 0xc000
	v_lshlrev_b64 v[82:83], 2, v[194:195]
	v_ashrrev_i32_e32 v199, 31, v198
	s_mul_hi_i32 s36, s24, 0xc000
	s_add_u32 s62, s28, s37
	v_lshl_add_u64 v[196:197], s[78:79], 0, v[82:83]
	v_lshlrev_b64 v[86:87], 13, v[198:199]
	s_addc_u32 s63, s29, s36
	v_lshl_add_u64 v[86:87], v[196:197], 0, v[86:87]
	v_lshl_add_u64 v[84:85], s[62:63], 0, v[82:83]
	global_load_dwordx4 v[208:211], v[86:87], off nt
	global_load_dwordx4 v[118:121], v[84:85], off
	global_load_dwordx4 v[114:117], v[84:85], off offset:16
	global_load_dwordx4 v[212:215], v[86:87], off offset:16 nt
	global_load_dwordx4 v[218:221], v[86:87], off offset:512 nt
	global_load_dwordx4 v[94:97], v[84:85], off offset:512
	global_load_dwordx4 v[90:93], v[84:85], off offset:528
	global_load_dwordx4 v[222:225], v[86:87], off offset:528 nt
	s_lshl_b64 s[24:25], s[24:25], 13
	s_add_u32 s24, s34, s24
	s_addc_u32 s25, s35, s25
	v_lshl_add_u64 v[82:83], s[24:25], 0, v[82:83]
	global_load_dwordx4 v[106:109], v[82:83], off
	global_load_dwordx4 v[102:105], v[82:83], off offset:16
	global_load_dwordx4 v[86:89], v[82:83], off offset:512
	s_nop 0
	global_load_dwordx4 v[82:85], v[82:83], off offset:528
	v_or_b32_e32 v200, 16, v198
	v_ashrrev_i32_e32 v201, 31, v200
	v_lshlrev_b64 v[162:163], 13, v[200:201]
	v_lshl_add_u64 v[166:167], v[196:197], 0, v[162:163]
	global_load_dwordx4 v[170:173], v[166:167], off offset:16 nt
	global_load_dwordx4 v[174:177], v[166:167], off nt
	global_load_dwordx4 v[162:165], v[166:167], off offset:528 nt
	s_nop 0
	global_load_dwordx4 v[166:169], v[166:167], off offset:512 nt
	v_and_b32_e32 v226, 64, v207
	v_add_u32_e32 v228, 64, v226
	v_lshlrev_b64 v[226:227], 12, v[198:199]
	v_xor_b32_e32 v217, 16, v207
	v_lshl_add_u64 v[226:227], s[30:31], 0, v[226:227]
	v_cmp_lt_i32_e32 vcc, v217, v228
	v_lshl_add_u64 v[226:227], v[194:195], 1, v[226:227]
	s_lshl_b32 s60, s12, 2
	v_cndmask_b32_e32 v217, v207, v217, vcc
	s_ashr_i32 s61, s60, 31
	s_waitcnt vmcnt(0)
	v_pk_fma_f32 v[160:161], v[160:161], v[120:121], v[210:211]
	v_pk_fma_f32 v[158:159], v[158:159], v[118:119], v[208:209]
	v_pk_fma_f32 v[156:157], v[156:157], v[116:117], v[214:215]
	v_pk_fma_f32 v[154:155], v[154:155], v[114:115], v[212:213]
	v_pk_fma_f32 v[152:153], v[152:153], v[96:97], v[220:221]
	v_pk_fma_f32 v[208:209], v[150:151], v[94:95], v[218:219]
	v_pk_fma_f32 v[210:211], v[148:149], v[92:93], v[224:225]
	v_pk_fma_f32 v[212:213], v[146:147], v[90:91], v[222:223]
	v_mul_f32_e32 v214, v159, v159
	v_mul_f32_e32 v215, v161, v161
	v_mul_f32_e32 v218, v155, v155
	v_mul_f32_e32 v219, v157, v157
	v_mul_f32_e32 v220, v209, v209
	v_mul_f32_e32 v221, v153, v153
	v_mul_f32_e32 v222, v213, v213
	v_mul_f32_e32 v223, v211, v211
	v_fmac_f32_e32 v214, v158, v158
	v_fmac_f32_e32 v215, v160, v160
	v_fmac_f32_e32 v218, v154, v154
	v_fmac_f32_e32 v219, v156, v156
	v_pk_mul_f32 v[148:149], v[108:109], v[160:161]
	v_pk_mul_f32 v[146:147], v[106:107], v[158:159]
	v_pk_mul_f32 v[150:151], v[104:105], v[156:157]
	v_fmac_f32_e32 v220, v208, v208
	v_fmac_f32_e32 v221, v152, v152
	v_fmac_f32_e32 v222, v212, v212
	v_fmac_f32_e32 v223, v210, v210
	v_pk_mul_f32 v[154:155], v[102:103], v[154:155]
	v_pk_mul_f32 v[156:157], v[88:89], v[152:153]
	v_add_f32_e32 v152, v214, v215
	v_add_f32_e32 v153, v218, v219
	v_cvt_pk_bf16_f32 v146, v146, v147
	v_cvt_pk_bf16_f32 v147, v148, v149
	v_cvt_pk_bf16_f32 v148, v154, v155
	v_cvt_pk_bf16_f32 v149, v150, v151
	v_add_f32_e32 v150, v220, v221
	v_add_f32_e32 v151, v222, v223
	v_add_f32_e32 v152, v152, v153
	global_store_dwordx4 v[226:227], v[146:149], off
	v_pk_mul_f32 v[154:155], v[82:83], v[212:213]
	s_nop 0
	v_add_f32_e32 v146, v150, v151
	v_add_f32_e32 v151, v152, v146
	v_lshlrev_b32_e32 v150, 2, v217
	ds_bpermute_b32 v153, v150, v151
	v_pk_mul_f32 v[146:147], v[86:87], v[208:209]
	v_pk_mul_f32 v[148:149], v[84:85], v[210:211]
	v_cvt_pk_bf16_f32 v152, v146, v147
	v_xor_b32_e32 v147, 32, v207
	v_cmp_lt_i32_e32 vcc, v147, v228
	s_waitcnt lgkmcnt(0)
	v_add_f32_e32 v146, v151, v153
	v_cvt_pk_bf16_f32 v153, v156, v157
	v_cvt_pk_bf16_f32 v154, v154, v155
	v_cvt_pk_bf16_f32 v155, v148, v149
	global_store_dwordx4 v[226:227], v[152:155], off offset:256
	v_cndmask_b32_e32 v147, v207, v147, vcc
	v_lshlrev_b32_e32 v151, 2, v147
	ds_bpermute_b32 v147, v151, v146
	s_and_saveexec_b64 s[62:63], s[4:5]
	s_cbranch_execz .LBB0_777
	v_lshlrev_b64 v[148:149], 7, v[198:199]
	v_lshl_add_u64 v[148:149], s[10:11], 0, v[148:149]
	v_lshl_add_u64 v[148:149], s[60:61], 2, v[148:149]
	s_lshl_b32 s12, s33, 2
	v_lshl_add_u64 v[148:149], v[148:149], 0, s[12:13]
	s_waitcnt lgkmcnt(0)
	v_add_f32_e32 v146, v146, v147
	global_store_dword v[148:149], v146, off

; #define PG8_BAR __builtin_amdgcn_s_barrier()
; template <class Epi, class Sched, bool ALIGN_EPI = false, bool SP2 = false, bool F8 = false>
; __device__ __forceinline__ void gemm_phase(PG8_LAS unsigned char* lds, const Gemm g, const Sched& S, const Epi& E) {
;     ...
;         if constexpr (!Epi::AFTER_DRAIN) { E(acc, cur, wr, wc, fr, fq); S.done(cur); }
;         if (!has_next) break;
; #pragma unroll
;         for (int a = 0; a < 2; ++a)
; #pragma unroll
;             for (int b = 0; b < 2; ++b)
; #pragma unroll
;                 for (int m = 0; m < 4; ++m)
; #pragma unroll
;                     for (int n = 0; n < 2; ++n) acc[a][b][m][n] = (f32x4){0.f, 0.f, 0.f, 0.f};
;         cur = nxt; cA = nA; cB = nB; ++ui;
;         if constexpr (ALIGN_EPI) { if (wr == 1) PG8_BAR; }
;     }
.LBB0_791:
	s_or_b64 exec, exec, s[62:63]
	s_andn2_b64 vcc, exec, s[6:7]
	s_mov_b64 s[6:7], -1
	s_cbranch_vccnz .LBB0_764
	s_andn2_b64 vcc, exec, s[40:41]
	s_cbranch_vccnz .LBB0_763
	s_branch .LBB0_763

; #define PG8_WAIT_V(n) asm volatile("s_waitcnt vmcnt(" #n ")" ::: "memory")
; template <class Epi, class Sched, bool ALIGN_EPI = false, bool SP2 = false, bool F8 = false>
; __device__ __forceinline__ void gemm_phase(PG8_LAS unsigned char* lds, const Gemm g, const Sched& S, const Epi& E) {
;     ...
;     for (int i = 0; i < 2; ++i) { int R, C; stage_rc(tid * 16 + i * 8192, R, C); const int Rb = Epi::PERM ? ((R & ~31) + perm32(R & 31)) : R;
;         const int Ra = Epi::GRIDMAP ? ((R & 63) * 64 + (R >> 6)) : R;
;         voffA[i] = (unsigned)(Ra * K + C) * 2u; voffB[i] = (unsigned)(Rb * K + C) * 2u; }
;     const size_t kstep = (size_t)(BK * 2);
;     const size_t hstep = (size_t)HALF * K * 2;
;     const size_t tstep = 2 * hstep;
;     const size_t hstepA = Epi::GRIDMAP ? (size_t)4096 * K * 2 : hstep;
;     ...
;     const unsigned ldsw = (unsigned)wid * 1024u;
;     const int aoff = lds_byte(wr * 64 + fr, fq * 8), boff = lds_byte(wc * 32 + fr, fq * 8);
;     ...
;     Unit cur, nxt; int ui = 0;
;     if (!S.next(0, cur)) return;
;     f32x4 acc[2][2][4][2];
; #pragma unroll
;     for (int a = 0; a < 2; ++a)
; #pragma unroll
;         for (int b = 0; b < 2; ++b)
; #pragma unroll
;             for (int m = 0; m < 4; ++m)
; #pragma unroll
;                 for (int n = 0; n < 2; ++n) acc[a][b][m][n] = (f32x4){0.f, 0.f, 0.f, 0.f};
;     bf16x8 At[4][2], B0[2][2], B1[2][2];
;     const char* cA = PG8_ABASE(cur.pm); const char* cB = (const char*)g.Bt + (size_t)cur.pn * tstep;
;     S.a_ready(cur);
;     if constexpr (SP2) {
;         PG8_STAGE(PG8_SB(0, 0), cB, voffB); PG8_STAGE(PG8_SB(0, 1), cB + hstep, voffB); PG8_STAGE(PG8_SA(0, 0), cA, voffA); PG8_STAGE(PG8_SA(0, 1), cA + hstepA, voffA);
;         if (wr == 1) PG8_BAR;
;         PG8_WAIT_V(2); PG8_BAR;
;         PG8_STAGE(PG8_SB(1, 0), cB + kstep, voffB); PG8_STAGE(PG8_SA(1, 0), cA + kstep, voffA); PG8_STAGE(PG8_SB(1, 1), cB + hstep + kstep, voffB);
;         PG8_WAIT_V(6); PG8_BAR;
;     } else {
;         PG8_STAGE(PG8_SB(0, 0), cB, voffB); PG8_STAGE(PG8_SA(0, 0), cA, voffA); PG8_STAGE(PG8_SB(0, 1), cB + hstep, voffB); PG8_STAGE(PG8_SA(0, 1), cA + hstepA, voffA);
;         if (wr == 1) PG8_BAR;
;         PG8_WAIT_V(4); PG8_BAR;
;         PG8_STAGE(PG8_SB(1, 0), cB + kstep, voffB); PG8_STAGE(PG8_SA(1, 0), cA + kstep, voffA); PG8_STAGE(PG8_SB(1, 1), cB + hstep + kstep, voffB);
;         PG8_WAIT_V(6); PG8_BAR;
.LBB0_906:
	s_or_b64 exec, exec, s[4:5]
	s_cmpk_lt_i32 s2, 0xb00
	v_readfirstlane_b32 s5, v0
	s_waitcnt lgkmcnt(0)
	s_barrier
	s_cbranch_scc0 .LBB0_924
	v_lshrrev_b32_e32 v2, 5, v0
	v_and_b32_e32 v2, 4, v2
	v_bfe_u32 v3, v0, 2, 2
	v_and_b32_e32 v1, 24, v1
	v_or3_b32 v2, v2, v3, v1
	v_lshlrev_b32_e32 v1, 4, v0
	s_waitcnt vmcnt(4)
	v_or_b32_e32 v10, 0x2000, v1
	v_lshrrev_b32_e32 v3, 7, v10
	s_movk_i32 s4, 0x60
	s_ashr_i32 s63, s2, 31
	v_and_or_b32 v4, v3, s4, v2
	s_lshr_b32 s4, s63, 29
	s_add_i32 s4, s2, s4
	s_lshr_b32 s6, s5, 6
	s_ashr_i32 s7, s4, 3
	s_and_b32 s4, s4, -8
	s_lshr_b32 s23, s5, 8
	s_lshl_b32 s62, s6, 10
	s_sub_i32 s4, s2, s4
	s_cmp_lt_i32 s4, 0
	s_movk_i32 s64, 0x161
	s_cselect_b32 s8, s64, 0x160
	s_mul_i32 s4, s4, s8
	s_add_i32 s4, s4, s7
	s_mul_hi_i32 s7, s4, 0x2e8ba2e9
	s_lshr_b32 s8, s7, 31
	s_ashr_i32 s7, s7, 6
	s_add_i32 s7, s7, s8
	s_lshl_b32 s8, s7, 3
	s_mulk_i32 s7, 0x160
	s_sub_i32 s7, s4, s7
	s_sext_i32_i16 s4, s7
	s_bfe_u32 s4, s4, 0x3001c
	s_add_i32 s9, s7, s4
	s_sext_i32_i16 s4, s9
	s_and_b32 s9, s9, 0xfff8
	s_sub_i32 s7, s7, s9
	s_sext_i32_i16 s7, s7
	s_add_i32 s84, s8, s7
	s_lshl_b32 s7, s84, 8
	s_lshl_b32 s8, s84, 1
	s_and_b32 s7, s7, 0xffffe000
	s_and_b32 s8, s8, 62
	v_and_b32_e32 v5, 32, v0
	v_bfe_u32 v13, v0, 2, 4
	s_lshr_b32 s4, s4, 3
	s_or_b32 s8, s7, s8
	v_bitop3_b32 v11, v1, v5, 48 bitop3:0x6c
	v_and_b32_e32 v12, 64, v0
	v_bfe_u32 v1, v3, 4, 2
	v_lshl_or_b32 v1, v13, 3, v1
	s_ashr_i32 s9, s8, 31
	s_bfe_i64 s[10:11], s[4:5], 0x100000
	v_or_b32_e32 v5, v11, v12
	v_lshlrev_b32_e32 v3, 18, v1
	v_mov_b32_e32 v1, 0x1000
	s_lshl_b64 s[8:9], s[8:9], 12
	s_lshl_b64 s[10:11], s[10:11], 20
	v_or3_b32 v132, v3, v5, v1
	v_lshrrev_b32_e32 v3, 3, v0
	s_add_u32 s58, s42, s10
	v_and_or_b32 v2, v3, 32, v2
	s_addc_u32 s59, s43, s11
	s_add_i32 s65, s62, 0
	v_lshl_or_b32 v134, v2, 12, v5
	s_add_i32 m0, s65, 0x10000
	v_lshl_or_b32 v130, v4, 12, v5
	global_load_lds_dwordx4 v134, s[58:59]
	s_add_i32 m0, s65, 0x12000
	s_add_u32 s10, s58, 0x80000
	global_load_lds_dwordx4 v130, s[58:59]
	s_addc_u32 s11, s59, 0
	s_add_i32 m0, s65, 0x14000
	v_bfe_u32 v2, v3, 4, 2
	v_lshl_or_b32 v2, v13, 3, v2
	global_load_lds_dwordx4 v134, s[10:11]
	s_add_i32 m0, s65, 0x16000
	s_add_u32 s56, s30, s8
	s_addc_u32 s57, s31, s9
	s_add_i32 s66, s65, 0x2000
	s_waitcnt vmcnt(0)
	v_lshl_or_b32 v136, v2, 18, v5
	global_load_lds_dwordx4 v130, s[10:11]
	s_mov_b32 m0, s65
	s_add_u32 s8, s56, 0x100000
	global_load_lds_dwordx4 v136, s[56:57]
	s_mov_b32 m0, s66
	s_addc_u32 s9, s57, 0
	s_add_i32 s67, s65, 0x4000
	global_load_lds_dwordx4 v132, s[56:57]
	s_mov_b32 m0, s67
	s_add_i32 s68, s65, 0x6000
	global_load_lds_dwordx4 v136, s[8:9]
	s_mov_b32 m0, s68
	v_mov_b32_e32 v135, 0
	global_load_lds_dwordx4 v132, s[8:9]
	s_load_dwordx4 s[8:11], s[0:1], 0x70
	v_mov_b32_e32 v131, v135
	v_mov_b32_e32 v137, v135
	v_mov_b32_e32 v133, v135
	s_cmp_eq_u32 s23, 1
	s_mov_b32 s69, 0
	v_lshl_add_u64 v[8:9], s[58:59], 0, v[134:135]
	v_lshl_add_u64 v[6:7], s[58:59], 0, v[130:131]
	v_lshl_add_u64 v[2:3], s[56:57], 0, v[136:137]
	s_cselect_b64 s[12:13], -1, 0
	s_cmp_lg_u32 s23, 1
	v_lshl_add_u64 v[4:5], s[56:57], 0, v[132:133]
	s_cbranch_scc1 .LBB0_909
.LBB0_909:
	s_lshl_b32 s6, s6, 5
	s_mov_b64 s[40:41], 0x80
	s_and_b32 s70, s6, 0x60
	s_add_i32 m0, s65, 0x18000
	v_lshl_add_u64 v[8:9], v[8:9], 0, s[40:41]
	s_lshl_b32 s14, s23, 13
	s_lshl_b32 s15, s70, 7
	s_waitcnt vmcnt(2)
	s_barrier
	global_load_lds_dwordx4 v[8:9], off
	v_lshl_add_u64 v[6:7], v[6:7], 0, s[40:41]
	s_add_i32 m0, s65, 0x1a000
	s_add_i32 s71, s65, 0x8000
	s_add_i32 s72, s65, 0xa000
	global_load_lds_dwordx4 v[6:7], off
	v_lshl_add_u64 v[2:3], v[2:3], 0, s[40:41]
	s_mov_b32 m0, s71
	s_add_u32 s6, s58, 0x80080
	global_load_lds_dwordx4 v[2:3], off
	v_lshl_add_u64 v[2:3], v[4:5], 0, s[40:41]
	s_mov_b32 m0, s72
	s_addc_u32 s7, s59, 0
	global_load_lds_dwordx4 v[2:3], off
	s_add_i32 m0, s65, 0x1c000
	v_lshl_add_u64 v[2:3], s[6:7], 0, v[134:135]
	global_load_lds_dwordx4 v[2:3], off
	v_lshl_add_u64 v[2:3], s[6:7], 0, v[130:131]
	s_add_i32 m0, s65, 0x1e000
	v_bfe_u32 v173, v0, 4, 2
	global_load_lds_dwordx4 v[2:3], off
	v_and_b32_e32 v172, 15, v0
	v_lshlrev_b32_e32 v2, 4, v173
	v_lshlrev_b32_e32 v4, 2, v0
	v_lshl_or_b32 v3, v172, 6, v2
	v_and_b32_e32 v4, 32, v4
	v_bitop3_b32 v5, s14, v3, v4 bitop3:0xf6
	v_lshlrev_b32_e32 v3, 6, v0
	s_movk_i32 s6, 0x3c0
	s_cmpk_lt_u32 s5, 0x100
	v_and_or_b32 v2, v3, s6, v2
	s_sext_i32_i16 s14, s4
	s_cselect_b64 s[44:45], -1, 0
	s_and_b32 s4, s5, 0xffffff00
	s_ashr_i32 s73, s90, 31
	v_bitop3_b32 v174, s15, v2, v4 bitop3:0xf6
	s_waitcnt lgkmcnt(0)
	s_add_u32 s46, s8, 0x5800
	v_lshlrev_b32_e32 v2, 11, v0
	s_addc_u32 s47, s9, 0
	v_and_b32_e32 v2, 0xc0000, v2
	v_lshlrev_b32_e32 v4, 21, v13
	s_add_u32 s48, s8, 0xb000
	v_or3_b32 v2, v11, v2, v4
	s_addc_u32 s49, s9, 0
	s_add_i32 s74, s4, 0
	v_add_u32_e32 v2, v2, v12
	v_mov_b32_e32 v3, v135
	s_mov_b64 s[4:5], 0x100080
	v_lshl_add_u64 v[138:139], v[2:3], 0, s[4:5]
	v_lshlrev_b32_e32 v2, 7, v10
	v_and_b32_e32 v2, 0xc0000, v2
	s_waitcnt vmcnt(6)
	v_or3_b32 v2, v11, v2, v4
	v_add3_u32 v2, v2, v1, v12
	s_add_i32 s75, 0, 0x10000
	s_add_i32 s76, 0, 0x14000
	s_add_i32 s74, s74, 0x20000
	v_lshl_add_u64 v[140:141], v[2:3], 0, s[4:5]
	v_mov_b64_e32 v[142:143], 0xb00
	v_mov_b64_e32 v[144:145], 0xaff
	v_add_u32_e32 v175, s75, v174
	v_add_u32_e32 v176, s76, v174
	v_add_u32_e32 v177, 0, v5
	s_add_i32 s77, 0, 0x22004
	s_add_i32 s78, 0, 0x2200c
	s_add_i32 s79, 0, 0x22014
	s_add_i32 s80, 0, 0x2201c
	s_mov_b32 s81, 0xc3e00000
	s_movk_i32 s82, 0x1600
	v_mov_b32_e32 v178, 0x400
	v_mov_b32_e32 v179, 0x800
	v_mov_b32_e32 v180, 0xc00
	v_mov_b32_e32 v181, 0x1400
	v_mov_b32_e32 v182, 0x1800
	v_mov_b32_e32 v183, 0x1c00
	v_mov_b32_e32 v184, 0x43e00000
	s_barrier
	s_branch .LBB0_912

;     __host__ __device__ bool next(int i, Unit& u) const { const long L = (long)i * G + c; if (L >= nwg) return false; u.pm = 0; u.pn = c % nN; return true; }
; #define PG8_STAGE(bufoff, gbase, voff) do { _Pragma("unroll") for (int _i = 0; _i < 2; ++_i) \
;         __builtin_amdgcn_global_load_lds((const unsigned*)((const char*)(gbase) + (voff)[_i]), (PG8_LAS unsigned*)(lds + (bufoff) + ldsw + _i * 8192), 16, 0, 0); } while (0)
; #define PG8_LDA(dst, b, h) do { _Pragma("unroll") for (int m = 0; m < 4; ++m) _Pragma("unroll") for (int k = 0; k < 2; ++k) dst[m][k] = *(const PG8_LAS bf16x8*)(lds + PG8_SA(b, h) + aoff + m * 2048 + k * 1024); } while (0)
; #define PG8_WAIT_V(n) asm volatile("s_waitcnt vmcnt(" #n ")" ::: "memory")
; template <class Epi, class Sched, bool ALIGN_EPI = false, bool SP2 = false, bool F8 = false>
; __device__ __forceinline__ void gemm_phase(PG8_LAS unsigned char* lds, const Gemm g, const Sched& S, const Epi& E) {
;     ...
;         const bool has_next = S.next(ui + 1, nxt);
;         const char* nA = has_next ? PG8_ABASE(nxt.pm) : cA; const char* nB = has_next ? (const char*)g.Bt + (size_t)nxt.pn * tstep : cB;
;         for (int t = 0; t < nt; t += 2) {
;             const bool last = (t == nt - 2);
;             const char* a1 = cA + (size_t)(t + 1) * kstep;
;             const char* a2 = last ? nA : cA + (size_t)(t + 2) * kstep; const char* b2 = last ? nB : cB + (size_t)(t + 2) * kstep;
;             const char* a3 = a2 + kstep; const char* b3 = b2 + kstep;
;             if (last && has_next) S.a_ready(nxt);
;             if constexpr (SP2) {
;             PG8_LDB(B0, 0, 0); PG8_LDB(B1, 0, 1); PG8_SCHED; PG8_LDA(At, 0, 0); PG8_STAGE(PG8_SA(1, 1), a1 + hstepA, voffA);
;             PG8_WAIT_V(8); PG8_WAIT_L(0); PG8_BAR; PG8_MMA(0, 0, At, B0); PG8_MMA(0, 1, At, B1); PG8_BAR; PG8_SCHED;
;             PG8_LDA(At, 0, 1); PG8_STAGE(PG8_SB(0, 0), b2, voffB); PG8_STAGE(PG8_SB(0, 1), b2 + hstep, voffB); PG8_STAGE(PG8_SA(0, 0), a2, voffA);
;             PG8_WAIT_V(8); PG8_WAIT_L(0); PG8_BAR; PG8_MMA(1, 0, At, B0); PG8_MMA(1, 1, At, B1); PG8_BAR; PG8_SCHED;
;     ...
; #pragma unroll
;         for (int a = 0; a < 2; ++a)
; #pragma unroll
;             for (int b = 0; b < 2; ++b)
; #pragma unroll
;                 for (int m = 0; m < 4; ++m)
; #pragma unroll
;                     for (int n = 0; n < 2; ++n) acc[a][b][m][n] = (f32x4){0.f, 0.f, 0.f, 0.f};
.LBB0_916:
	s_ashr_i32 s51, s50, 31
	s_lshl_b64 s[24:25], s[50:51], 20
	s_add_u32 s54, s42, s24
	s_addc_u32 s55, s43, s25
	s_and_b64 s[6:7], s[6:7], exec
	s_cselect_b32 s15, s55, s59
	s_cselect_b32 s26, s54, s58
	s_add_u32 s27, s58, 0x100
	v_mov_b32_e32 v2, 0
	s_addc_u32 s28, s59, 0
	s_mov_b32 s29, -2
	v_mov_b32_e32 v3, 0
	v_pk_mul_f32 v[4:5], v[2:3], v[2:3]
	v_pk_mul_f32 v[6:7], v[2:3], v[2:3]
	v_pk_mul_f32 v[8:9], v[2:3], v[2:3]
	v_pk_mul_f32 v[10:11], v[2:3], v[2:3]
	v_pk_mul_f32 v[12:13], v[2:3], v[2:3]
	v_pk_mul_f32 v[14:15], v[2:3], v[2:3]
	v_pk_mul_f32 v[16:17], v[2:3], v[2:3]
	v_pk_mul_f32 v[18:19], v[2:3], v[2:3]
	v_pk_mul_f32 v[20:21], v[2:3], v[2:3]
	v_pk_mul_f32 v[22:23], v[2:3], v[2:3]
	v_pk_mul_f32 v[24:25], v[2:3], v[2:3]
	v_pk_mul_f32 v[26:27], v[2:3], v[2:3]
	v_pk_mul_f32 v[28:29], v[2:3], v[2:3]
	v_pk_mul_f32 v[30:31], v[2:3], v[2:3]
	v_pk_mul_f32 v[32:33], v[2:3], v[2:3]
	v_pk_mul_f32 v[34:35], v[2:3], v[2:3]
	v_pk_mul_f32 v[36:37], v[2:3], v[2:3]
	v_pk_mul_f32 v[38:39], v[2:3], v[2:3]
	v_pk_mul_f32 v[40:41], v[2:3], v[2:3]
	v_pk_mul_f32 v[42:43], v[2:3], v[2:3]
	v_pk_mul_f32 v[44:45], v[2:3], v[2:3]
	v_pk_mul_f32 v[46:47], v[2:3], v[2:3]
	v_pk_mul_f32 v[48:49], v[2:3], v[2:3]
	v_pk_mul_f32 v[50:51], v[2:3], v[2:3]
	v_pk_mul_f32 v[52:53], v[2:3], v[2:3]
	v_pk_mul_f32 v[54:55], v[2:3], v[2:3]
	v_pk_mul_f32 v[56:57], v[2:3], v[2:3]
	v_pk_mul_f32 v[58:59], v[2:3], v[2:3]
	v_pk_mul_f32 v[60:61], v[2:3], v[2:3]
	v_pk_mul_f32 v[62:63], v[2:3], v[2:3]
	v_pk_mul_f32 v[64:65], v[2:3], v[2:3]
	v_pk_mul_f32 v[66:67], v[2:3], v[2:3]
	v_pk_mul_f32 v[68:69], v[2:3], v[2:3]
	v_pk_mul_f32 v[70:71], v[2:3], v[2:3]
	v_pk_mul_f32 v[72:73], v[2:3], v[2:3]
	v_pk_mul_f32 v[74:75], v[2:3], v[2:3]
	v_pk_mul_f32 v[76:77], v[2:3], v[2:3]
	v_pk_mul_f32 v[78:79], v[2:3], v[2:3]
	v_pk_mul_f32 v[80:81], v[2:3], v[2:3]
	v_pk_mul_f32 v[82:83], v[2:3], v[2:3]
	v_pk_mul_f32 v[84:85], v[2:3], v[2:3]
	v_pk_mul_f32 v[86:87], v[2:3], v[2:3]
	v_pk_mul_f32 v[88:89], v[2:3], v[2:3]
	v_pk_mul_f32 v[90:91], v[2:3], v[2:3]
	v_pk_mul_f32 v[92:93], v[2:3], v[2:3]
	v_pk_mul_f32 v[94:95], v[2:3], v[2:3]
	v_pk_mul_f32 v[96:97], v[2:3], v[2:3]
	v_pk_mul_f32 v[98:99], v[2:3], v[2:3]
	v_pk_mul_f32 v[100:101], v[2:3], v[2:3]
	v_pk_mul_f32 v[102:103], v[2:3], v[2:3]
	v_pk_mul_f32 v[104:105], v[2:3], v[2:3]
	v_pk_mul_f32 v[106:107], v[2:3], v[2:3]
	v_pk_mul_f32 v[108:109], v[2:3], v[2:3]
	v_pk_mul_f32 v[110:111], v[2:3], v[2:3]
	v_pk_mul_f32 v[112:113], v[2:3], v[2:3]
	v_pk_mul_f32 v[114:115], v[2:3], v[2:3]
	v_pk_mul_f32 v[116:117], v[2:3], v[2:3]
	v_pk_mul_f32 v[118:119], v[2:3], v[2:3]
	v_pk_mul_f32 v[120:121], v[2:3], v[2:3]
	v_pk_mul_f32 v[122:123], v[2:3], v[2:3]
	v_pk_mul_f32 v[124:125], v[2:3], v[2:3]
	v_pk_mul_f32 v[126:127], v[2:3], v[2:3]
	v_pk_mul_f32 v[128:129], v[2:3], v[2:3]
	s_cmp_lg_u64 s[12:13], 0
	s_cbranch_scc1 .Lk3_Y
.LBB0_917:
	ds_read_b128 v[146:149], v175
	ds_read_b128 v[150:153], v175 offset:1024
	ds_read_b128 v[154:157], v175 offset:2048
	ds_read_b128 v[158:161], v175 offset:3072
	ds_read_b128 v[162:165], v176
	ds_read_b128 v[166:169], v176 offset:1024
	ds_read_b128 v[186:189], v176 offset:2048
	ds_read_b128 v[190:193], v176 offset:3072
	s_add_u32 s6, s56, 0x100
	s_addc_u32 s7, s57, 0
	s_cmp_eq_u32 s29, 28
	s_cselect_b32 s61, s53, s7
	s_cselect_b32 s60, s52, s6
	s_cselect_b32 s59, s15, s28
	s_cselect_b32 s58, s26, s27
	v_lshl_add_u64 v[170:171], s[56:57], 0, v[138:139]
	s_add_i32 m0, s65, 0xc000
	ds_read_b128 v[194:197], v177
	ds_read_b128 v[198:201], v177 offset:1024
	ds_read_b128 v[202:205], v177 offset:2048
	ds_read_b128 v[206:209], v177 offset:3072
	ds_read_b128 v[210:213], v177 offset:4096
	ds_read_b128 v[218:221], v177 offset:5120
	ds_read_b128 v[222:225], v177 offset:6144
	ds_read_b128 v[226:229], v177 offset:7168
	global_load_lds_dwordx4 v[170:171], off
	v_lshl_add_u64 v[170:171], s[56:57], 0, v[140:141]
	s_add_i32 m0, s65, 0xe000
	s_nop 0
	global_load_lds_dwordx4 v[170:171], off
	s_waitcnt vmcnt(8)
	s_waitcnt lgkmcnt(0)
	s_setprio 1
	s_waitcnt lgkmcnt(0)
	v_mfma_f32_16x16x32_bf16 v[126:129], v[146:149], v[194:197], v[126:129]
	v_mfma_f32_16x16x32_bf16 v[122:125], v[154:157], v[194:197], v[122:125]
	v_mfma_f32_16x16x32_bf16 v[118:121], v[146:149], v[202:205], v[118:121]
	v_mfma_f32_16x16x32_bf16 v[114:117], v[154:157], v[202:205], v[114:117]
	v_mfma_f32_16x16x32_bf16 v[110:113], v[146:149], v[210:213], v[110:113]
	v_mfma_f32_16x16x32_bf16 v[102:105], v[154:157], v[210:213], v[102:105]
	v_mfma_f32_16x16x32_bf16 v[94:97], v[146:149], v[222:225], v[94:97]
	v_mfma_f32_16x16x32_bf16 v[86:89], v[154:157], v[222:225], v[86:89]
	v_mfma_f32_16x16x32_bf16 v[126:129], v[150:153], v[198:201], v[126:129]
	v_mfma_f32_16x16x32_bf16 v[122:125], v[158:161], v[198:201], v[122:125]
	v_mfma_f32_16x16x32_bf16 v[118:121], v[150:153], v[206:209], v[118:121]
	v_mfma_f32_16x16x32_bf16 v[114:117], v[158:161], v[206:209], v[114:117]
	v_mfma_f32_16x16x32_bf16 v[110:113], v[150:153], v[218:221], v[110:113]
	v_mfma_f32_16x16x32_bf16 v[102:105], v[158:161], v[218:221], v[102:105]
	v_mfma_f32_16x16x32_bf16 v[94:97], v[150:153], v[226:229], v[94:97]
	v_mfma_f32_16x16x32_bf16 v[86:89], v[158:161], v[226:229], v[86:89]
	s_setprio 0
	s_setprio 1
	v_mfma_f32_16x16x32_bf16 v[106:109], v[162:165], v[194:197], v[106:109]
	v_mfma_f32_16x16x32_bf16 v[98:101], v[186:189], v[194:197], v[98:101]
	v_mfma_f32_16x16x32_bf16 v[90:93], v[162:165], v[202:205], v[90:93]
	v_mfma_f32_16x16x32_bf16 v[82:85], v[186:189], v[202:205], v[82:85]
	v_mfma_f32_16x16x32_bf16 v[78:81], v[162:165], v[210:213], v[78:81]
	v_mfma_f32_16x16x32_bf16 v[74:77], v[186:189], v[210:213], v[74:77]
	v_mfma_f32_16x16x32_bf16 v[70:73], v[162:165], v[222:225], v[70:73]
	v_mfma_f32_16x16x32_bf16 v[66:69], v[186:189], v[222:225], v[66:69]
	v_mfma_f32_16x16x32_bf16 v[106:109], v[166:169], v[198:201], v[106:109]
	v_mfma_f32_16x16x32_bf16 v[98:101], v[190:193], v[198:201], v[98:101]
	v_mfma_f32_16x16x32_bf16 v[90:93], v[166:169], v[206:209], v[90:93]
	v_mfma_f32_16x16x32_bf16 v[82:85], v[190:193], v[206:209], v[82:85]
	v_mfma_f32_16x16x32_bf16 v[78:81], v[166:169], v[218:221], v[78:81]
	v_mfma_f32_16x16x32_bf16 v[74:77], v[190:193], v[218:221], v[74:77]
	v_mfma_f32_16x16x32_bf16 v[70:73], v[166:169], v[226:229], v[70:73]
	v_mfma_f32_16x16x32_bf16 v[66:69], v[190:193], v[226:229], v[66:69]
	s_setprio 0
	s_barrier
; #define PG8_STAGE(bufoff, gbase, voff) do { _Pragma("unroll") for (int _i = 0; _i < 2; ++_i) \
;         __builtin_amdgcn_global_load_lds((const unsigned*)((const char*)(gbase) + (voff)[_i]), (PG8_LAS unsigned*)(lds + (bufoff) + ldsw + _i * 8192), 16, 0, 0); } while (0)
; #define PG8_LDA(dst, b, h) do { _Pragma("unroll") for (int m = 0; m < 4; ++m) _Pragma("unroll") for (int k = 0; k < 2; ++k) dst[m][k] = *(const PG8_LAS bf16x8*)(lds + PG8_SA(b, h) + aoff + m * 2048 + k * 1024); } while (0)
; #define PG8_LDB(dst, b, h) do { _Pragma("unroll") for (int n = 0; n < 2; ++n) _Pragma("unroll") for (int k = 0; k < 2; ++k) dst[n][k] = *(const PG8_LAS bf16x8*)(lds + PG8_SB(b, h) + boff + n * 2048 + k * 1024); } while (0)
; #define PG8_WAIT_V(n) asm volatile("s_waitcnt vmcnt(" #n ")" ::: "memory")
; #define PG8_WAIT_L(n) asm volatile("s_waitcnt lgkmcnt(" #n ")" ::: "memory")
; #define PG8_BAR __builtin_amdgcn_s_barrier()
; #define PG8_SCHED __builtin_amdgcn_sched_barrier(0)
; template <class Epi, class Sched, bool ALIGN_EPI = false, bool SP2 = false, bool F8 = false>
; __device__ __forceinline__ void gemm_phase(PG8_LAS unsigned char* lds, const Gemm g, const Sched& S, const Epi& E) {
;     ...
;             PG8_LDA(At, 0, 1); PG8_STAGE(PG8_SB(0, 0), b2, voffB); PG8_STAGE(PG8_SB(0, 1), b2 + hstep, voffB); PG8_STAGE(PG8_SA(0, 0), a2, voffA);
;             PG8_WAIT_V(8); PG8_WAIT_L(0); PG8_BAR; PG8_MMA(1, 0, At, B0); PG8_MMA(1, 1, At, B1); PG8_BAR; PG8_SCHED;
;             PG8_LDB(B0, 1, 0); PG8_LDB(B1, 1, 1); PG8_SCHED; PG8_LDA(At, 1, 0); PG8_STAGE(PG8_SA(0, 1), a2 + hstepA, voffA);
;             PG8_WAIT_V(8); PG8_WAIT_L(0); PG8_BAR; PG8_MMA(0, 0, At, B0); PG8_MMA(0, 1, At, B1); PG8_BAR; PG8_SCHED;
	s_add_i32 s24, s75, s62
	v_lshl_add_u64 v[170:171], s[58:59], 0, v[134:135]
	s_mov_b32 m0, s24
	ds_read_b128 v[194:197], v177 offset:16384
	ds_read_b128 v[198:201], v177 offset:17408
	ds_read_b128 v[202:205], v177 offset:18432
	ds_read_b128 v[206:209], v177 offset:19456
	ds_read_b128 v[210:213], v177 offset:20480
	ds_read_b128 v[218:221], v177 offset:21504
	ds_read_b128 v[222:225], v177 offset:22528
	ds_read_b128 v[226:229], v177 offset:23552
	global_load_lds_dwordx4 v[170:171], off
	s_add_i32 m0, s24, 0x2000
	s_add_u32 s24, s58, 0x80000
	v_lshl_add_u64 v[214:215], s[58:59], 0, v[130:131]
	s_addc_u32 s25, s59, 0
	s_add_i32 s33, s76, s62
	global_load_lds_dwordx4 v[214:215], off
	v_lshl_add_u64 v[230:231], s[24:25], 0, v[134:135]
	s_mov_b32 m0, s33
	v_lshl_add_u64 v[232:233], s[60:61], 0, v[132:133]
	global_load_lds_dwordx4 v[230:231], off
	v_lshl_add_u64 v[230:231], s[24:25], 0, v[130:131]
	s_add_i32 m0, s33, 0x2000
	s_nop 0
	global_load_lds_dwordx4 v[230:231], off
	v_lshl_add_u64 v[230:231], s[60:61], 0, v[136:137]
	s_mov_b32 m0, s65
	s_nop 0
	global_load_lds_dwordx4 v[230:231], off
	s_mov_b32 m0, s66
	s_nop 0
	global_load_lds_dwordx4 v[232:233], off
	s_waitcnt vmcnt(8)
	s_waitcnt lgkmcnt(0)
	s_setprio 1
	s_waitcnt lgkmcnt(0)
	v_mfma_f32_16x16x32_bf16 v[62:65], v[146:149], v[194:197], v[62:65]
	v_mfma_f32_16x16x32_bf16 v[58:61], v[154:157], v[194:197], v[58:61]
	v_mfma_f32_16x16x32_bf16 v[54:57], v[146:149], v[202:205], v[54:57]
	v_mfma_f32_16x16x32_bf16 v[50:53], v[154:157], v[202:205], v[50:53]
	v_mfma_f32_16x16x32_bf16 v[38:41], v[146:149], v[210:213], v[38:41]
	v_mfma_f32_16x16x32_bf16 v[34:37], v[154:157], v[210:213], v[34:37]
	v_mfma_f32_16x16x32_bf16 v[22:25], v[146:149], v[222:225], v[22:25]
	v_mfma_f32_16x16x32_bf16 v[18:21], v[154:157], v[222:225], v[18:21]
	v_mfma_f32_16x16x32_bf16 v[62:65], v[150:153], v[198:201], v[62:65]
	v_mfma_f32_16x16x32_bf16 v[58:61], v[158:161], v[198:201], v[58:61]
	v_mfma_f32_16x16x32_bf16 v[54:57], v[150:153], v[206:209], v[54:57]
	v_mfma_f32_16x16x32_bf16 v[50:53], v[158:161], v[206:209], v[50:53]
	v_mfma_f32_16x16x32_bf16 v[38:41], v[150:153], v[218:221], v[38:41]
	v_mfma_f32_16x16x32_bf16 v[34:37], v[158:161], v[218:221], v[34:37]
	v_mfma_f32_16x16x32_bf16 v[22:25], v[150:153], v[226:229], v[22:25]
	v_mfma_f32_16x16x32_bf16 v[18:21], v[158:161], v[226:229], v[18:21]
	s_setprio 0
	s_setprio 1
	v_mfma_f32_16x16x32_bf16 v[46:49], v[162:165], v[194:197], v[46:49]
	v_mfma_f32_16x16x32_bf16 v[42:45], v[186:189], v[194:197], v[42:45]
	v_mfma_f32_16x16x32_bf16 v[30:33], v[162:165], v[202:205], v[30:33]
	v_mfma_f32_16x16x32_bf16 v[26:29], v[186:189], v[202:205], v[26:29]
	v_mfma_f32_16x16x32_bf16 v[14:17], v[162:165], v[210:213], v[14:17]
	v_mfma_f32_16x16x32_bf16 v[10:13], v[186:189], v[210:213], v[10:13]
	v_mfma_f32_16x16x32_bf16 v[6:9], v[162:165], v[222:225], v[6:9]
	v_mfma_f32_16x16x32_bf16 v[2:5], v[186:189], v[222:225], v[2:5]
	v_mfma_f32_16x16x32_bf16 v[46:49], v[166:169], v[198:201], v[46:49]
	v_mfma_f32_16x16x32_bf16 v[42:45], v[190:193], v[198:201], v[42:45]
	v_mfma_f32_16x16x32_bf16 v[30:33], v[166:169], v[206:209], v[30:33]
	v_mfma_f32_16x16x32_bf16 v[26:29], v[190:193], v[206:209], v[26:29]
	v_mfma_f32_16x16x32_bf16 v[14:17], v[166:169], v[218:221], v[14:17]
	v_mfma_f32_16x16x32_bf16 v[10:13], v[190:193], v[218:221], v[10:13]
	v_mfma_f32_16x16x32_bf16 v[6:9], v[166:169], v[226:229], v[6:9]
	v_mfma_f32_16x16x32_bf16 v[2:5], v[190:193], v[226:229], v[2:5]
	s_setprio 0
	s_barrier
	s_add_i32 s33, 0, 0x18000
	s_add_i32 s36, 0, 0x1c000
	v_add_u32_e32 v158, s33, v174
	v_add_u32_e32 v185, s36, v174
	ds_read_b128 v[146:149], v158
	ds_read_b128 v[150:153], v158 offset:1024
	ds_read_b128 v[154:157], v158 offset:2048
	ds_read_b128 v[158:161], v158 offset:3072
	ds_read_b128 v[162:165], v185
	ds_read_b128 v[166:169], v185 offset:1024
	ds_read_b128 v[186:189], v185 offset:2048
	ds_read_b128 v[190:193], v185 offset:3072
	s_add_u32 s24, s60, 0x100000
	s_addc_u32 s25, s61, 0
	s_mov_b32 m0, s67
	v_lshl_add_u64 v[234:235], s[24:25], 0, v[136:137]
	ds_read_b128 v[194:197], v177 offset:32768
	ds_read_b128 v[198:201], v177 offset:33792
	ds_read_b128 v[202:205], v177 offset:34816
	ds_read_b128 v[206:209], v177 offset:35840
	ds_read_b128 v[210:213], v177 offset:36864
	ds_read_b128 v[218:221], v177 offset:37888
	ds_read_b128 v[222:225], v177 offset:38912
	ds_read_b128 v[226:229], v177 offset:39936
	global_load_lds_dwordx4 v[234:235], off
	v_lshl_add_u64 v[234:235], s[24:25], 0, v[132:133]
	s_mov_b32 m0, s68
	s_nop 0
	global_load_lds_dwordx4 v[234:235], off
	s_waitcnt vmcnt(8)
	s_waitcnt lgkmcnt(0)
	s_setprio 1
	s_waitcnt lgkmcnt(0)
	v_mfma_f32_16x16x32_bf16 v[126:129], v[146:149], v[194:197], v[126:129]
	v_mfma_f32_16x16x32_bf16 v[122:125], v[154:157], v[194:197], v[122:125]
	v_mfma_f32_16x16x32_bf16 v[118:121], v[146:149], v[202:205], v[118:121]
	v_mfma_f32_16x16x32_bf16 v[114:117], v[154:157], v[202:205], v[114:117]
	v_mfma_f32_16x16x32_bf16 v[110:113], v[146:149], v[210:213], v[110:113]
	v_mfma_f32_16x16x32_bf16 v[102:105], v[154:157], v[210:213], v[102:105]
	v_mfma_f32_16x16x32_bf16 v[94:97], v[146:149], v[222:225], v[94:97]
	v_mfma_f32_16x16x32_bf16 v[86:89], v[154:157], v[222:225], v[86:89]
	v_mfma_f32_16x16x32_bf16 v[126:129], v[150:153], v[198:201], v[126:129]
	v_mfma_f32_16x16x32_bf16 v[122:125], v[158:161], v[198:201], v[122:125]
	v_mfma_f32_16x16x32_bf16 v[118:121], v[150:153], v[206:209], v[118:121]
	v_mfma_f32_16x16x32_bf16 v[114:117], v[158:161], v[206:209], v[114:117]
	v_mfma_f32_16x16x32_bf16 v[110:113], v[150:153], v[218:221], v[110:113]
	v_mfma_f32_16x16x32_bf16 v[102:105], v[158:161], v[218:221], v[102:105]
	v_mfma_f32_16x16x32_bf16 v[94:97], v[150:153], v[226:229], v[94:97]
	v_mfma_f32_16x16x32_bf16 v[86:89], v[158:161], v[226:229], v[86:89]
	s_setprio 0
	s_setprio 1
	v_mfma_f32_16x16x32_bf16 v[106:109], v[162:165], v[194:197], v[106:109]
	v_mfma_f32_16x16x32_bf16 v[98:101], v[186:189], v[194:197], v[98:101]
	v_mfma_f32_16x16x32_bf16 v[90:93], v[162:165], v[202:205], v[90:93]
	v_mfma_f32_16x16x32_bf16 v[82:85], v[186:189], v[202:205], v[82:85]
	v_mfma_f32_16x16x32_bf16 v[78:81], v[162:165], v[210:213], v[78:81]
	v_mfma_f32_16x16x32_bf16 v[74:77], v[186:189], v[210:213], v[74:77]
	v_mfma_f32_16x16x32_bf16 v[70:73], v[162:165], v[222:225], v[70:73]
	v_mfma_f32_16x16x32_bf16 v[66:69], v[186:189], v[222:225], v[66:69]
	v_mfma_f32_16x16x32_bf16 v[106:109], v[166:169], v[198:201], v[106:109]
	v_mfma_f32_16x16x32_bf16 v[98:101], v[190:193], v[198:201], v[98:101]
	v_mfma_f32_16x16x32_bf16 v[90:93], v[166:169], v[206:209], v[90:93]
	v_mfma_f32_16x16x32_bf16 v[82:85], v[190:193], v[206:209], v[82:85]
	v_mfma_f32_16x16x32_bf16 v[78:81], v[166:169], v[218:221], v[78:81]
	v_mfma_f32_16x16x32_bf16 v[74:77], v[190:193], v[218:221], v[74:77]
	v_mfma_f32_16x16x32_bf16 v[70:73], v[166:169], v[226:229], v[70:73]
	v_mfma_f32_16x16x32_bf16 v[66:69], v[190:193], v[226:229], v[66:69]
	s_setprio 0
	s_barrier
; #define PG8_STAGE(bufoff, gbase, voff) do { _Pragma("unroll") for (int _i = 0; _i < 2; ++_i) \
;         __builtin_amdgcn_global_load_lds((const unsigned*)((const char*)(gbase) + (voff)[_i]), (PG8_LAS unsigned*)(lds + (bufoff) + ldsw + _i * 8192), 16, 0, 0); } while (0)
; #define PG8_LDA(dst, b, h) do { _Pragma("unroll") for (int m = 0; m < 4; ++m) _Pragma("unroll") for (int k = 0; k < 2; ++k) dst[m][k] = *(const PG8_LAS bf16x8*)(lds + PG8_SA(b, h) + aoff + m * 2048 + k * 1024); } while (0)
; #define PG8_LDB(dst, b, h) do { _Pragma("unroll") for (int n = 0; n < 2; ++n) _Pragma("unroll") for (int k = 0; k < 2; ++k) dst[n][k] = *(const PG8_LAS bf16x8*)(lds + PG8_SB(b, h) + boff + n * 2048 + k * 1024); } while (0)
; #define PG8_WAIT_V(n) asm volatile("s_waitcnt vmcnt(" #n ")" ::: "memory")
; #define PG8_WAIT_L(n) asm volatile("s_waitcnt lgkmcnt(" #n ")" ::: "memory")
; #define PG8_BAR __builtin_amdgcn_s_barrier()
; #define PG8_SCHED __builtin_amdgcn_sched_barrier(0)
; template <class Epi, class Sched, bool ALIGN_EPI = false, bool SP2 = false, bool F8 = false>
; __device__ __forceinline__ void gemm_phase(PG8_LAS unsigned char* lds, const Gemm g, const Sched& S, const Epi& E) {
;     ...
;             PG8_LDB(B0, 0, 0); PG8_LDB(B1, 0, 1); PG8_SCHED; PG8_LDA(At, 0, 0); PG8_STAGE(PG8_SA(1, 1), a1 + hstepA, voffA);
;             PG8_WAIT_V(8); PG8_WAIT_L(0); PG8_BAR; PG8_MMA(0, 0, At, B0); PG8_MMA(0, 1, At, B1); PG8_BAR; PG8_SCHED;
;     ...
;             PG8_LDA(At, 1, 1); PG8_STAGE(PG8_SB(1, 0), b3, voffB); PG8_STAGE(PG8_SB(1, 1), b3 + hstep, voffB); PG8_STAGE(PG8_SA(1, 0), a3, voffA);
;             PG8_WAIT_V(8); PG8_WAIT_L(0); PG8_BAR; PG8_MMA(1, 0, At, B0); PG8_MMA(1, 1, At, B1); PG8_BAR; PG8_SCHED;
	s_add_i32 s24, s33, s62
	v_lshl_add_u64 v[170:171], v[170:171], 0, s[40:41]
	s_mov_b32 m0, s24
	ds_read_b128 v[194:197], v177 offset:49152
	ds_read_b128 v[198:201], v177 offset:50176
	ds_read_b128 v[202:205], v177 offset:51200
	ds_read_b128 v[206:209], v177 offset:52224
	ds_read_b128 v[210:213], v177 offset:53248
	ds_read_b128 v[218:221], v177 offset:54272
	ds_read_b128 v[222:225], v177 offset:55296
	ds_read_b128 v[226:229], v177 offset:56320
	global_load_lds_dwordx4 v[170:171], off
	s_add_i32 m0, s24, 0x2000
	s_add_u32 s24, s58, 0x80080
	v_lshl_add_u64 v[170:171], v[214:215], 0, s[40:41]
	s_addc_u32 s25, s59, 0
	s_add_i32 s33, s36, s62
	global_load_lds_dwordx4 v[170:171], off
	v_lshl_add_u64 v[170:171], s[24:25], 0, v[134:135]
	s_mov_b32 m0, s33
	s_nop 0
	global_load_lds_dwordx4 v[170:171], off
	v_lshl_add_u64 v[170:171], s[24:25], 0, v[130:131]
	s_add_i32 m0, s33, 0x2000
	s_nop 0
	global_load_lds_dwordx4 v[170:171], off
	v_lshl_add_u64 v[170:171], v[230:231], 0, s[40:41]
	s_mov_b32 m0, s71
	s_nop 0
	global_load_lds_dwordx4 v[170:171], off
	v_lshl_add_u64 v[170:171], v[232:233], 0, s[40:41]
	s_mov_b32 m0, s72
	s_nop 0
	global_load_lds_dwordx4 v[170:171], off
	s_waitcnt vmcnt(8)
	s_waitcnt lgkmcnt(0)
	s_setprio 1
	s_waitcnt lgkmcnt(0)
	v_mfma_f32_16x16x32_bf16 v[62:65], v[146:149], v[194:197], v[62:65]
	v_mfma_f32_16x16x32_bf16 v[58:61], v[154:157], v[194:197], v[58:61]
	v_mfma_f32_16x16x32_bf16 v[54:57], v[146:149], v[202:205], v[54:57]
	v_mfma_f32_16x16x32_bf16 v[50:53], v[154:157], v[202:205], v[50:53]
	v_mfma_f32_16x16x32_bf16 v[38:41], v[146:149], v[210:213], v[38:41]
	v_mfma_f32_16x16x32_bf16 v[34:37], v[154:157], v[210:213], v[34:37]
	v_mfma_f32_16x16x32_bf16 v[22:25], v[146:149], v[222:225], v[22:25]
	v_mfma_f32_16x16x32_bf16 v[18:21], v[154:157], v[222:225], v[18:21]
	v_mfma_f32_16x16x32_bf16 v[62:65], v[150:153], v[198:201], v[62:65]
	v_mfma_f32_16x16x32_bf16 v[58:61], v[158:161], v[198:201], v[58:61]
	v_mfma_f32_16x16x32_bf16 v[54:57], v[150:153], v[206:209], v[54:57]
	v_mfma_f32_16x16x32_bf16 v[50:53], v[158:161], v[206:209], v[50:53]
	v_mfma_f32_16x16x32_bf16 v[38:41], v[150:153], v[218:221], v[38:41]
	v_mfma_f32_16x16x32_bf16 v[34:37], v[158:161], v[218:221], v[34:37]
	v_mfma_f32_16x16x32_bf16 v[22:25], v[150:153], v[226:229], v[22:25]
	v_mfma_f32_16x16x32_bf16 v[18:21], v[158:161], v[226:229], v[18:21]
	s_setprio 0
	s_setprio 1
	v_mfma_f32_16x16x32_bf16 v[46:49], v[162:165], v[194:197], v[46:49]
	v_mfma_f32_16x16x32_bf16 v[42:45], v[186:189], v[194:197], v[42:45]
	v_mfma_f32_16x16x32_bf16 v[30:33], v[162:165], v[202:205], v[30:33]
	v_mfma_f32_16x16x32_bf16 v[26:29], v[186:189], v[202:205], v[26:29]
	v_mfma_f32_16x16x32_bf16 v[14:17], v[162:165], v[210:213], v[14:17]
	v_mfma_f32_16x16x32_bf16 v[10:13], v[186:189], v[210:213], v[10:13]
	v_mfma_f32_16x16x32_bf16 v[6:9], v[162:165], v[222:225], v[6:9]
	v_mfma_f32_16x16x32_bf16 v[2:5], v[186:189], v[222:225], v[2:5]
	v_mfma_f32_16x16x32_bf16 v[46:49], v[166:169], v[198:201], v[46:49]
	v_mfma_f32_16x16x32_bf16 v[42:45], v[190:193], v[198:201], v[42:45]
	v_mfma_f32_16x16x32_bf16 v[30:33], v[166:169], v[206:209], v[30:33]
	v_mfma_f32_16x16x32_bf16 v[26:29], v[190:193], v[206:209], v[26:29]
	v_mfma_f32_16x16x32_bf16 v[14:17], v[166:169], v[218:221], v[14:17]
	v_mfma_f32_16x16x32_bf16 v[10:13], v[190:193], v[218:221], v[10:13]
	v_mfma_f32_16x16x32_bf16 v[6:9], v[166:169], v[226:229], v[6:9]
	v_mfma_f32_16x16x32_bf16 v[2:5], v[190:193], v[226:229], v[2:5]
	s_setprio 0
	s_barrier
	s_add_i32 s29, s29, 2
	s_add_u32 s27, s27, 0x100
	s_addc_u32 s28, s28, 0
	s_cmp_gt_u32 s29, 29
	s_mov_b64 s[56:57], s[6:7]
	s_cbranch_scc0 .LBB0_917
	s_branch .Lk3_exit
.Lk3_Y:
	ds_read_b128 v[146:149], v175
	ds_read_b128 v[150:153], v175 offset:1024
	ds_read_b128 v[154:157], v175 offset:2048
	ds_read_b128 v[158:161], v175 offset:3072
	ds_read_b128 v[162:165], v176
	ds_read_b128 v[166:169], v176 offset:1024
	ds_read_b128 v[186:189], v176 offset:2048
	ds_read_b128 v[190:193], v176 offset:3072
	s_add_u32 s6, s56, 0x100
	s_addc_u32 s7, s57, 0
	s_cmp_eq_u32 s29, 28
	s_cselect_b32 s61, s53, s7
	s_cselect_b32 s60, s52, s6
	s_cselect_b32 s59, s15, s28
	s_cselect_b32 s58, s26, s27
	v_lshl_add_u64 v[170:171], s[56:57], 0, v[138:139]
	s_add_i32 m0, s65, 0xc000
	ds_read_b128 v[194:197], v177
	ds_read_b128 v[198:201], v177 offset:1024
	ds_read_b128 v[202:205], v177 offset:2048
	ds_read_b128 v[206:209], v177 offset:3072
	ds_read_b128 v[210:213], v177 offset:4096
	ds_read_b128 v[218:221], v177 offset:5120
	ds_read_b128 v[222:225], v177 offset:6144
	ds_read_b128 v[226:229], v177 offset:7168
	global_load_lds_dwordx4 v[170:171], off
	v_lshl_add_u64 v[170:171], s[56:57], 0, v[140:141]
	s_add_i32 m0, s65, 0xe000
	s_nop 0
	global_load_lds_dwordx4 v[170:171], off
	s_waitcnt vmcnt(8)
	s_waitcnt lgkmcnt(0)
	s_barrier
; #define PG8_STAGE(bufoff, gbase, voff) do { _Pragma("unroll") for (int _i = 0; _i < 2; ++_i) \
;         __builtin_amdgcn_global_load_lds((const unsigned*)((const char*)(gbase) + (voff)[_i]), (PG8_LAS unsigned*)(lds + (bufoff) + ldsw + _i * 8192), 16, 0, 0); } while (0)
; #define PG8_LDA(dst, b, h) do { _Pragma("unroll") for (int m = 0; m < 4; ++m) _Pragma("unroll") for (int k = 0; k < 2; ++k) dst[m][k] = *(const PG8_LAS bf16x8*)(lds + PG8_SA(b, h) + aoff + m * 2048 + k * 1024); } while (0)
; #define PG8_LDB(dst, b, h) do { _Pragma("unroll") for (int n = 0; n < 2; ++n) _Pragma("unroll") for (int k = 0; k < 2; ++k) dst[n][k] = *(const PG8_LAS bf16x8*)(lds + PG8_SB(b, h) + boff + n * 2048 + k * 1024); } while (0)
; #define PG8_WAIT_V(n) asm volatile("s_waitcnt vmcnt(" #n ")" ::: "memory")
; #define PG8_WAIT_L(n) asm volatile("s_waitcnt lgkmcnt(" #n ")" ::: "memory")
; #define PG8_BAR __builtin_amdgcn_s_barrier()
; #define PG8_SCHED __builtin_amdgcn_sched_barrier(0)
; template <class Epi, class Sched, bool ALIGN_EPI = false, bool SP2 = false, bool F8 = false>
; __device__ __forceinline__ void gemm_phase(PG8_LAS unsigned char* lds, const Gemm g, const Sched& S, const Epi& E) {
;     ...
;             PG8_WAIT_V(8); PG8_WAIT_L(0); PG8_BAR; PG8_MMA(0, 0, At, B0); PG8_MMA(0, 1, At, B1); PG8_BAR; PG8_SCHED;
;             PG8_LDA(At, 0, 1); PG8_STAGE(PG8_SB(0, 0), b2, voffB); PG8_STAGE(PG8_SB(0, 1), b2 + hstep, voffB); PG8_STAGE(PG8_SA(0, 0), a2, voffA);
;             PG8_WAIT_V(8); PG8_WAIT_L(0); PG8_BAR; PG8_MMA(1, 0, At, B0); PG8_MMA(1, 1, At, B1); PG8_BAR; PG8_SCHED;
;             PG8_LDB(B0, 1, 0); PG8_LDB(B1, 1, 1); PG8_SCHED; PG8_LDA(At, 1, 0); PG8_STAGE(PG8_SA(0, 1), a2 + hstepA, voffA);
;             PG8_WAIT_V(8); PG8_WAIT_L(0); PG8_BAR; PG8_MMA(0, 0, At, B0); PG8_MMA(0, 1, At, B1); PG8_BAR; PG8_SCHED;
	s_setprio 3
	s_waitcnt lgkmcnt(0)
	v_mfma_f32_16x16x32_bf16 v[126:129], v[146:149], v[194:197], v[126:129]
	v_mfma_f32_16x16x32_bf16 v[122:125], v[154:157], v[194:197], v[122:125]
	v_mfma_f32_16x16x32_bf16 v[118:121], v[146:149], v[202:205], v[118:121]
	v_mfma_f32_16x16x32_bf16 v[114:117], v[154:157], v[202:205], v[114:117]
	v_mfma_f32_16x16x32_bf16 v[110:113], v[146:149], v[210:213], v[110:113]
	v_mfma_f32_16x16x32_bf16 v[102:105], v[154:157], v[210:213], v[102:105]
	v_mfma_f32_16x16x32_bf16 v[94:97], v[146:149], v[222:225], v[94:97]
	v_mfma_f32_16x16x32_bf16 v[86:89], v[154:157], v[222:225], v[86:89]
	v_mfma_f32_16x16x32_bf16 v[126:129], v[150:153], v[198:201], v[126:129]
	v_mfma_f32_16x16x32_bf16 v[122:125], v[158:161], v[198:201], v[122:125]
	v_mfma_f32_16x16x32_bf16 v[118:121], v[150:153], v[206:209], v[118:121]
	v_mfma_f32_16x16x32_bf16 v[114:117], v[158:161], v[206:209], v[114:117]
	v_mfma_f32_16x16x32_bf16 v[110:113], v[150:153], v[218:221], v[110:113]
	v_mfma_f32_16x16x32_bf16 v[102:105], v[158:161], v[218:221], v[102:105]
	v_mfma_f32_16x16x32_bf16 v[94:97], v[150:153], v[226:229], v[94:97]
	v_mfma_f32_16x16x32_bf16 v[86:89], v[158:161], v[226:229], v[86:89]
	s_setprio 0
	s_setprio 3
	v_mfma_f32_16x16x32_bf16 v[106:109], v[162:165], v[194:197], v[106:109]
	v_mfma_f32_16x16x32_bf16 v[98:101], v[186:189], v[194:197], v[98:101]
	v_mfma_f32_16x16x32_bf16 v[90:93], v[162:165], v[202:205], v[90:93]
	v_mfma_f32_16x16x32_bf16 v[82:85], v[186:189], v[202:205], v[82:85]
	v_mfma_f32_16x16x32_bf16 v[78:81], v[162:165], v[210:213], v[78:81]
	v_mfma_f32_16x16x32_bf16 v[74:77], v[186:189], v[210:213], v[74:77]
	v_mfma_f32_16x16x32_bf16 v[70:73], v[162:165], v[222:225], v[70:73]
	v_mfma_f32_16x16x32_bf16 v[66:69], v[186:189], v[222:225], v[66:69]
	v_mfma_f32_16x16x32_bf16 v[106:109], v[166:169], v[198:201], v[106:109]
	v_mfma_f32_16x16x32_bf16 v[98:101], v[190:193], v[198:201], v[98:101]
	v_mfma_f32_16x16x32_bf16 v[90:93], v[166:169], v[206:209], v[90:93]
	v_mfma_f32_16x16x32_bf16 v[82:85], v[190:193], v[206:209], v[82:85]
	v_mfma_f32_16x16x32_bf16 v[78:81], v[166:169], v[218:221], v[78:81]
	v_mfma_f32_16x16x32_bf16 v[74:77], v[190:193], v[218:221], v[74:77]
	v_mfma_f32_16x16x32_bf16 v[70:73], v[166:169], v[226:229], v[70:73]
	v_mfma_f32_16x16x32_bf16 v[66:69], v[190:193], v[226:229], v[66:69]
	s_setprio 0
	s_add_i32 s24, s75, s62
	v_lshl_add_u64 v[170:171], s[58:59], 0, v[134:135]
	s_mov_b32 m0, s24
	ds_read_b128 v[194:197], v177 offset:16384
	ds_read_b128 v[198:201], v177 offset:17408
	ds_read_b128 v[202:205], v177 offset:18432
	ds_read_b128 v[206:209], v177 offset:19456
	ds_read_b128 v[210:213], v177 offset:20480
	ds_read_b128 v[218:221], v177 offset:21504
	ds_read_b128 v[222:225], v177 offset:22528
	ds_read_b128 v[226:229], v177 offset:23552
	global_load_lds_dwordx4 v[170:171], off
	s_add_i32 m0, s24, 0x2000
	s_add_u32 s24, s58, 0x80000
	v_lshl_add_u64 v[214:215], s[58:59], 0, v[130:131]
	s_addc_u32 s25, s59, 0
	s_add_i32 s33, s76, s62
	global_load_lds_dwordx4 v[214:215], off
	v_lshl_add_u64 v[230:231], s[24:25], 0, v[134:135]
	s_mov_b32 m0, s33
	v_lshl_add_u64 v[232:233], s[60:61], 0, v[132:133]
	global_load_lds_dwordx4 v[230:231], off
	v_lshl_add_u64 v[230:231], s[24:25], 0, v[130:131]
	s_add_i32 m0, s33, 0x2000
	s_nop 0
	global_load_lds_dwordx4 v[230:231], off
	v_lshl_add_u64 v[230:231], s[60:61], 0, v[136:137]
	s_mov_b32 m0, s65
	s_nop 0
	global_load_lds_dwordx4 v[230:231], off
	s_mov_b32 m0, s66
	s_nop 0
	global_load_lds_dwordx4 v[232:233], off
	s_waitcnt vmcnt(8)
	s_waitcnt lgkmcnt(0)
	s_barrier
	s_setprio 3
	s_waitcnt lgkmcnt(0)
	v_mfma_f32_16x16x32_bf16 v[62:65], v[146:149], v[194:197], v[62:65]
	v_mfma_f32_16x16x32_bf16 v[58:61], v[154:157], v[194:197], v[58:61]
	v_mfma_f32_16x16x32_bf16 v[54:57], v[146:149], v[202:205], v[54:57]
	v_mfma_f32_16x16x32_bf16 v[50:53], v[154:157], v[202:205], v[50:53]
	v_mfma_f32_16x16x32_bf16 v[38:41], v[146:149], v[210:213], v[38:41]
	v_mfma_f32_16x16x32_bf16 v[34:37], v[154:157], v[210:213], v[34:37]
	v_mfma_f32_16x16x32_bf16 v[22:25], v[146:149], v[222:225], v[22:25]
	v_mfma_f32_16x16x32_bf16 v[18:21], v[154:157], v[222:225], v[18:21]
	v_mfma_f32_16x16x32_bf16 v[62:65], v[150:153], v[198:201], v[62:65]
	v_mfma_f32_16x16x32_bf16 v[58:61], v[158:161], v[198:201], v[58:61]
	v_mfma_f32_16x16x32_bf16 v[54:57], v[150:153], v[206:209], v[54:57]
	v_mfma_f32_16x16x32_bf16 v[50:53], v[158:161], v[206:209], v[50:53]
	v_mfma_f32_16x16x32_bf16 v[38:41], v[150:153], v[218:221], v[38:41]
	v_mfma_f32_16x16x32_bf16 v[34:37], v[158:161], v[218:221], v[34:37]
	v_mfma_f32_16x16x32_bf16 v[22:25], v[150:153], v[226:229], v[22:25]
	v_mfma_f32_16x16x32_bf16 v[18:21], v[158:161], v[226:229], v[18:21]
	s_setprio 0
	s_setprio 3
	v_mfma_f32_16x16x32_bf16 v[46:49], v[162:165], v[194:197], v[46:49]
	v_mfma_f32_16x16x32_bf16 v[42:45], v[186:189], v[194:197], v[42:45]
	v_mfma_f32_16x16x32_bf16 v[30:33], v[162:165], v[202:205], v[30:33]
	v_mfma_f32_16x16x32_bf16 v[26:29], v[186:189], v[202:205], v[26:29]
	v_mfma_f32_16x16x32_bf16 v[14:17], v[162:165], v[210:213], v[14:17]
	v_mfma_f32_16x16x32_bf16 v[10:13], v[186:189], v[210:213], v[10:13]
	v_mfma_f32_16x16x32_bf16 v[6:9], v[162:165], v[222:225], v[6:9]
	v_mfma_f32_16x16x32_bf16 v[2:5], v[186:189], v[222:225], v[2:5]
	v_mfma_f32_16x16x32_bf16 v[46:49], v[166:169], v[198:201], v[46:49]
	v_mfma_f32_16x16x32_bf16 v[42:45], v[190:193], v[198:201], v[42:45]
	v_mfma_f32_16x16x32_bf16 v[30:33], v[166:169], v[206:209], v[30:33]
	v_mfma_f32_16x16x32_bf16 v[26:29], v[190:193], v[206:209], v[26:29]
	v_mfma_f32_16x16x32_bf16 v[14:17], v[166:169], v[218:221], v[14:17]
	v_mfma_f32_16x16x32_bf16 v[10:13], v[190:193], v[218:221], v[10:13]
	v_mfma_f32_16x16x32_bf16 v[6:9], v[166:169], v[226:229], v[6:9]
	v_mfma_f32_16x16x32_bf16 v[2:5], v[190:193], v[226:229], v[2:5]
	s_setprio 0
	s_add_i32 s33, 0, 0x18000
	s_add_i32 s36, 0, 0x1c000
	v_add_u32_e32 v158, s33, v174
	v_add_u32_e32 v185, s36, v174
	ds_read_b128 v[146:149], v158
	ds_read_b128 v[150:153], v158 offset:1024
	ds_read_b128 v[154:157], v158 offset:2048
	ds_read_b128 v[158:161], v158 offset:3072
	ds_read_b128 v[162:165], v185
	ds_read_b128 v[166:169], v185 offset:1024
	ds_read_b128 v[186:189], v185 offset:2048
	ds_read_b128 v[190:193], v185 offset:3072
	s_add_u32 s24, s60, 0x100000
	s_addc_u32 s25, s61, 0
	s_mov_b32 m0, s67
	v_lshl_add_u64 v[234:235], s[24:25], 0, v[136:137]
	ds_read_b128 v[194:197], v177 offset:32768
	ds_read_b128 v[198:201], v177 offset:33792
	ds_read_b128 v[202:205], v177 offset:34816
	ds_read_b128 v[206:209], v177 offset:35840
	ds_read_b128 v[210:213], v177 offset:36864
	ds_read_b128 v[218:221], v177 offset:37888
	ds_read_b128 v[222:225], v177 offset:38912
	ds_read_b128 v[226:229], v177 offset:39936
	global_load_lds_dwordx4 v[234:235], off
	v_lshl_add_u64 v[234:235], s[24:25], 0, v[132:133]
	s_mov_b32 m0, s68
	s_nop 0
	global_load_lds_dwordx4 v[234:235], off
	s_waitcnt vmcnt(8)
	s_waitcnt lgkmcnt(0)
	s_barrier
; #define PG8_STAGE(bufoff, gbase, voff) do { _Pragma("unroll") for (int _i = 0; _i < 2; ++_i) \
;         __builtin_amdgcn_global_load_lds((const unsigned*)((const char*)(gbase) + (voff)[_i]), (PG8_LAS unsigned*)(lds + (bufoff) + ldsw + _i * 8192), 16, 0, 0); } while (0)
; #define PG8_LDA(dst, b, h) do { _Pragma("unroll") for (int m = 0; m < 4; ++m) _Pragma("unroll") for (int k = 0; k < 2; ++k) dst[m][k] = *(const PG8_LAS bf16x8*)(lds + PG8_SA(b, h) + aoff + m * 2048 + k * 1024); } while (0)
; #define PG8_WAIT_V(n) asm volatile("s_waitcnt vmcnt(" #n ")" ::: "memory")
; #define PG8_WAIT_L(n) asm volatile("s_waitcnt lgkmcnt(" #n ")" ::: "memory")
; #define PG8_BAR __builtin_amdgcn_s_barrier()
; #define PG8_SCHED __builtin_amdgcn_sched_barrier(0)
; template <class Epi, class Sched, bool ALIGN_EPI = false, bool SP2 = false, bool F8 = false>
; __device__ __forceinline__ void gemm_phase(PG8_LAS unsigned char* lds, const Gemm g, const Sched& S, const Epi& E) {
;     ...
;             PG8_WAIT_V(8); PG8_WAIT_L(0); PG8_BAR; PG8_MMA(0, 0, At, B0); PG8_MMA(0, 1, At, B1); PG8_BAR; PG8_SCHED;
;             PG8_LDA(At, 1, 1); PG8_STAGE(PG8_SB(1, 0), b3, voffB); PG8_STAGE(PG8_SB(1, 1), b3 + hstep, voffB); PG8_STAGE(PG8_SA(1, 0), a3, voffA);
;             PG8_WAIT_V(8); PG8_WAIT_L(0); PG8_BAR; PG8_MMA(1, 0, At, B0); PG8_MMA(1, 1, At, B1); PG8_BAR; PG8_SCHED;
	s_setprio 3
	s_waitcnt lgkmcnt(0)
	v_mfma_f32_16x16x32_bf16 v[126:129], v[146:149], v[194:197], v[126:129]
	v_mfma_f32_16x16x32_bf16 v[122:125], v[154:157], v[194:197], v[122:125]
	v_mfma_f32_16x16x32_bf16 v[118:121], v[146:149], v[202:205], v[118:121]
	v_mfma_f32_16x16x32_bf16 v[114:117], v[154:157], v[202:205], v[114:117]
	v_mfma_f32_16x16x32_bf16 v[110:113], v[146:149], v[210:213], v[110:113]
	v_mfma_f32_16x16x32_bf16 v[102:105], v[154:157], v[210:213], v[102:105]
	v_mfma_f32_16x16x32_bf16 v[94:97], v[146:149], v[222:225], v[94:97]
	v_mfma_f32_16x16x32_bf16 v[86:89], v[154:157], v[222:225], v[86:89]
	v_mfma_f32_16x16x32_bf16 v[126:129], v[150:153], v[198:201], v[126:129]
	v_mfma_f32_16x16x32_bf16 v[122:125], v[158:161], v[198:201], v[122:125]
	v_mfma_f32_16x16x32_bf16 v[118:121], v[150:153], v[206:209], v[118:121]
	v_mfma_f32_16x16x32_bf16 v[114:117], v[158:161], v[206:209], v[114:117]
	v_mfma_f32_16x16x32_bf16 v[110:113], v[150:153], v[218:221], v[110:113]
	v_mfma_f32_16x16x32_bf16 v[102:105], v[158:161], v[218:221], v[102:105]
	v_mfma_f32_16x16x32_bf16 v[94:97], v[150:153], v[226:229], v[94:97]
	v_mfma_f32_16x16x32_bf16 v[86:89], v[158:161], v[226:229], v[86:89]
	s_setprio 0
	s_setprio 3
	v_mfma_f32_16x16x32_bf16 v[106:109], v[162:165], v[194:197], v[106:109]
	v_mfma_f32_16x16x32_bf16 v[98:101], v[186:189], v[194:197], v[98:101]
	v_mfma_f32_16x16x32_bf16 v[90:93], v[162:165], v[202:205], v[90:93]
	v_mfma_f32_16x16x32_bf16 v[82:85], v[186:189], v[202:205], v[82:85]
	v_mfma_f32_16x16x32_bf16 v[78:81], v[162:165], v[210:213], v[78:81]
	v_mfma_f32_16x16x32_bf16 v[74:77], v[186:189], v[210:213], v[74:77]
	v_mfma_f32_16x16x32_bf16 v[70:73], v[162:165], v[222:225], v[70:73]
	v_mfma_f32_16x16x32_bf16 v[66:69], v[186:189], v[222:225], v[66:69]
	v_mfma_f32_16x16x32_bf16 v[106:109], v[166:169], v[198:201], v[106:109]
	v_mfma_f32_16x16x32_bf16 v[98:101], v[190:193], v[198:201], v[98:101]
	v_mfma_f32_16x16x32_bf16 v[90:93], v[166:169], v[206:209], v[90:93]
	v_mfma_f32_16x16x32_bf16 v[82:85], v[190:193], v[206:209], v[82:85]
	v_mfma_f32_16x16x32_bf16 v[78:81], v[166:169], v[218:221], v[78:81]
	v_mfma_f32_16x16x32_bf16 v[74:77], v[190:193], v[218:221], v[74:77]
	v_mfma_f32_16x16x32_bf16 v[70:73], v[166:169], v[226:229], v[70:73]
	v_mfma_f32_16x16x32_bf16 v[66:69], v[190:193], v[226:229], v[66:69]
	s_setprio 0
	s_add_i32 s24, s33, s62
	v_lshl_add_u64 v[170:171], v[170:171], 0, s[40:41]
	s_mov_b32 m0, s24
	ds_read_b128 v[194:197], v177 offset:49152
	ds_read_b128 v[198:201], v177 offset:50176
	ds_read_b128 v[202:205], v177 offset:51200
	ds_read_b128 v[206:209], v177 offset:52224
	ds_read_b128 v[210:213], v177 offset:53248
	ds_read_b128 v[218:221], v177 offset:54272
	ds_read_b128 v[222:225], v177 offset:55296
	ds_read_b128 v[226:229], v177 offset:56320
	global_load_lds_dwordx4 v[170:171], off
	s_add_i32 m0, s24, 0x2000
	s_add_u32 s24, s58, 0x80080
	v_lshl_add_u64 v[170:171], v[214:215], 0, s[40:41]
	s_addc_u32 s25, s59, 0
	s_add_i32 s33, s36, s62
	global_load_lds_dwordx4 v[170:171], off
	v_lshl_add_u64 v[170:171], s[24:25], 0, v[134:135]
	s_mov_b32 m0, s33
	s_nop 0
	global_load_lds_dwordx4 v[170:171], off
	v_lshl_add_u64 v[170:171], s[24:25], 0, v[130:131]
	s_add_i32 m0, s33, 0x2000
	s_nop 0
	global_load_lds_dwordx4 v[170:171], off
	v_lshl_add_u64 v[170:171], v[230:231], 0, s[40:41]
	s_mov_b32 m0, s71
	s_nop 0
	global_load_lds_dwordx4 v[170:171], off
	v_lshl_add_u64 v[170:171], v[232:233], 0, s[40:41]
	s_mov_b32 m0, s72
	s_nop 0
	global_load_lds_dwordx4 v[170:171], off
	s_waitcnt vmcnt(8)
	s_waitcnt lgkmcnt(0)
	s_barrier
	s_setprio 3
	s_waitcnt lgkmcnt(0)
	v_mfma_f32_16x16x32_bf16 v[62:65], v[146:149], v[194:197], v[62:65]
	v_mfma_f32_16x16x32_bf16 v[58:61], v[154:157], v[194:197], v[58:61]
	v_mfma_f32_16x16x32_bf16 v[54:57], v[146:149], v[202:205], v[54:57]
	v_mfma_f32_16x16x32_bf16 v[50:53], v[154:157], v[202:205], v[50:53]
	v_mfma_f32_16x16x32_bf16 v[38:41], v[146:149], v[210:213], v[38:41]
	v_mfma_f32_16x16x32_bf16 v[34:37], v[154:157], v[210:213], v[34:37]
	v_mfma_f32_16x16x32_bf16 v[22:25], v[146:149], v[222:225], v[22:25]
	v_mfma_f32_16x16x32_bf16 v[18:21], v[154:157], v[222:225], v[18:21]
	v_mfma_f32_16x16x32_bf16 v[62:65], v[150:153], v[198:201], v[62:65]
	v_mfma_f32_16x16x32_bf16 v[58:61], v[158:161], v[198:201], v[58:61]
	v_mfma_f32_16x16x32_bf16 v[54:57], v[150:153], v[206:209], v[54:57]
	v_mfma_f32_16x16x32_bf16 v[50:53], v[158:161], v[206:209], v[50:53]
	v_mfma_f32_16x16x32_bf16 v[38:41], v[150:153], v[218:221], v[38:41]
	v_mfma_f32_16x16x32_bf16 v[34:37], v[158:161], v[218:221], v[34:37]
	v_mfma_f32_16x16x32_bf16 v[22:25], v[150:153], v[226:229], v[22:25]
	v_mfma_f32_16x16x32_bf16 v[18:21], v[158:161], v[226:229], v[18:21]
	s_setprio 0
	s_setprio 3
	v_mfma_f32_16x16x32_bf16 v[46:49], v[162:165], v[194:197], v[46:49]
	v_mfma_f32_16x16x32_bf16 v[42:45], v[186:189], v[194:197], v[42:45]
	v_mfma_f32_16x16x32_bf16 v[30:33], v[162:165], v[202:205], v[30:33]
	v_mfma_f32_16x16x32_bf16 v[26:29], v[186:189], v[202:205], v[26:29]
	v_mfma_f32_16x16x32_bf16 v[14:17], v[162:165], v[210:213], v[14:17]
	v_mfma_f32_16x16x32_bf16 v[10:13], v[186:189], v[210:213], v[10:13]
	v_mfma_f32_16x16x32_bf16 v[6:9], v[162:165], v[222:225], v[6:9]
	v_mfma_f32_16x16x32_bf16 v[2:5], v[186:189], v[222:225], v[2:5]
	v_mfma_f32_16x16x32_bf16 v[46:49], v[166:169], v[198:201], v[46:49]
	v_mfma_f32_16x16x32_bf16 v[42:45], v[190:193], v[198:201], v[42:45]
	v_mfma_f32_16x16x32_bf16 v[30:33], v[166:169], v[206:209], v[30:33]
	v_mfma_f32_16x16x32_bf16 v[26:29], v[190:193], v[206:209], v[26:29]
	v_mfma_f32_16x16x32_bf16 v[14:17], v[166:169], v[218:221], v[14:17]
	v_mfma_f32_16x16x32_bf16 v[10:13], v[190:193], v[218:221], v[10:13]
	v_mfma_f32_16x16x32_bf16 v[6:9], v[166:169], v[226:229], v[6:9]
	v_mfma_f32_16x16x32_bf16 v[2:5], v[190:193], v[226:229], v[2:5]
	s_setprio 0
	s_add_i32 s29, s29, 2
	s_add_u32 s27, s27, 0x100
	s_addc_u32 s28, s28, 0
	s_cmp_gt_u32 s29, 29
	s_mov_b64 s[56:57], s[6:7]
	s_cbranch_scc0 .Lk3_Y
;     __device__ __forceinline__ void operator()(f32x4 (&acc)[2][2][4][2], const Unit& u, int wr, int wc, int fr, int fq) const {
;     ...
;         const int b = u.pm >> 5, cp = u.pm & 31;
;         const int chl = 32 * wc + 8 * fq, ch = 128 * u.pn + chl;
;         const size_t tok00 = (size_t)b * 8192 + 2 * cp + wr;
;         {
;             const float* bp = bias + (size_t)b * bias_bstride + 256 * u.pn + chl;
;             int slot = 0;
; #pragma unroll
;             for (int j = 1; j < 8; ++j) if (pml[j] == u.pm) slot = j;
;             const f32x4 ba0 = *(const f32x4*)(bp), ba1 = *(const f32x4*)(bp + 4), bb0 = *(const f32x4*)(bp + 128), bb1 = *(const f32x4*)(bp + 132);
; #pragma unroll
;             for (int ai = 0; ai < 2; ++ai)
; #pragma unroll
;                 for (int m = 0; m < 4; ++m) { const int rl = ai * HALF + wr * 64 + m * 16 + fr; const float rsv = rs[slot * 256 + rl];
;                     acc[ai][0][m][0] = acc[ai][0][m][0] * rsv + ba0; acc[ai][0][m][1] = acc[ai][0][m][1] * rsv + ba1; acc[ai][1][m][0] = acc[ai][1][m][0] * rsv + bb0; acc[ai][1][m][1] = acc[ai][1][m][1] * rsv + bb1; }
;         }
;         __builtin_amdgcn_sched_barrier(0);
; #pragma unroll
;         for (int n = 0; n < 2; ++n) {
;             constexpr float NL2E = -1.4426950408889634f;
;             const f32x4 w0 = *(const f32x4*)(fcw + ch + 4 * n) * NL2E, w1 = *(const f32x4*)(fcw + nch + ch + 4 * n) * NL2E, w2 = *(const f32x4*)(fcw + 2 * nch + ch + 4 * n) * NL2E, cb = *(const f32x4*)(fcb + ch + 4 * n) * NL2E;
.Lk3_exit:
	s_and_b64 vcc, exec, s[44:45]
	s_cbranch_vccz .LBB0_920
.LBB0_920:
	s_ashr_i32 s56, s84, 5
	s_lshl_b32 s6, s14, 10
	s_mul_i32 s24, s56, 0xb000
	s_add_i32 s24, s24, s6
	s_add_u32 s6, s3, s24
	s_addc_u32 s7, s21, 0
	s_lshl_b32 s15, s14, 9
	s_lshl_b32 s25, s70, 2
	v_lshlrev_b32_e32 v146, 5, v173
	v_add_u32_e32 v146, s25, v146
	v_add_u32_e32 v147, s15, v146
	global_load_dwordx4 v[156:159], v146, s[6:7]
	global_load_dwordx4 v[160:163], v146, s[6:7] offset:16
	global_load_dwordx4 v[164:167], v146, s[6:7] offset:512
	global_load_dwordx4 v[168:171], v146, s[6:7] offset:528
	global_load_dwordx4 v[188:191], v147, s[8:9]
	global_load_dwordx4 v[192:195], v147, s[8:9] offset:16
	global_load_dwordx4 v[196:199], v147, s[46:47]
	global_load_dwordx4 v[200:203], v147, s[46:47] offset:16
	global_load_dwordx4 v[204:207], v147, s[48:49]
	global_load_dwordx4 v[208:211], v147, s[48:49] offset:16
	global_load_dwordx4 v[212:215], v147, s[10:11]
	global_load_dwordx4 v[218:221], v147, s[10:11] offset:16
	v_mov_b32_e32 v222, s77
	ds_read2_b32 v[222:223], v222 offset1:1
	v_mov_b32_e32 v224, s78
	v_mov_b32_e32 v226, s79
	v_mov_b32_e32 v228, s80
	ds_read2_b32 v[224:225], v224 offset1:1
	ds_read2_b32 v[226:227], v226 offset1:1
	ds_read_b32 v228, v228
	s_lshl_b32 s24, s84, 1
	s_and_b32 s24, s24, 62
	s_lshl_b32 s25, s56, 13
	s_add_i32 s24, s24, s25
	s_mul_i32 s24, s24, 0x1600
	s_lshl_b32 s25, s14, 7
	s_add_i32 s24, s24, s25
	s_add_u32 s28, s38, s24
	s_addc_u32 s29, s39, 0
	v_and_b32_e32 v186, 1, v173
	v_mul_u32_u24_e32 v185, 0x2c0000, v172
	v_mul_u32_u24_e32 v186, 0x57ff8, v186
	v_lshl_add_u32 v187, v173, 3, s70
	v_add3_u32 v185, v185, v186, v187
	s_mul_i32 s25, s23, 0x1600
	v_add_u32_e32 v185, s25, v185
	v_lshrrev_b32_e32 v230, 3, v172
	v_and_b32_e32 v232, 7, v172
	v_lshlrev_b32_e32 v232, 5, v232
	v_lshl_or_b32 v230, v230, 9, v232
	s_mov_b32 s26, 1.0
	s_mov_b32 s27, 1.0
	s_waitcnt lgkmcnt(0)
	v_cmp_eq_u32_e32 vcc, s84, v222
	s_nop 1
	v_cndmask_b32_e32 v231, 0, v178, vcc
	v_cmp_ne_u32_e32 vcc, s84, v223
	s_nop 1
	v_cndmask_b32_e32 v231, v179, v231, vcc
	v_cmp_ne_u32_e32 vcc, s84, v224
	s_nop 1
	v_cndmask_b32_e32 v231, v180, v231, vcc
	v_cmp_ne_u32_e32 vcc, s84, v225
	s_nop 1
	v_cndmask_b32_e32 v231, v1, v231, vcc
	v_cmp_ne_u32_e32 vcc, s84, v226
	s_nop 1
	v_cndmask_b32_e32 v231, v181, v231, vcc
	v_cmp_ne_u32_e32 vcc, s84, v227
	s_nop 1
	v_cndmask_b32_e32 v231, v182, v231, vcc
	v_cmp_ne_u32_e32 vcc, s84, v228
	s_nop 1
	v_cndmask_b32_e32 v231, v183, v231, vcc
	v_add3_u32 v230, v230, v231, s74
	ds_read_b128 v[148:151], v230
	ds_read_b128 v[152:155], v230 offset:16
	s_waitcnt lgkmcnt(0)
	s_waitcnt vmcnt(8)
	v_pk_fma_f32 v[126:127], v[126:127], v[148:149], v[156:157] op_sel_hi:[1,0,1]
	v_pk_fma_f32 v[128:129], v[128:129], v[148:149], v[158:159] op_sel_hi:[1,0,1]
	v_pk_fma_f32 v[122:123], v[122:123], v[148:149], v[160:161] op_sel_hi:[1,0,1]
	v_pk_fma_f32 v[124:125], v[124:125], v[148:149], v[162:163] op_sel_hi:[1,0,1]
	v_pk_fma_f32 v[118:119], v[118:119], v[148:149], v[156:157] op_sel:[0,1,0] op_sel_hi:[1,1,1]
	v_pk_fma_f32 v[120:121], v[120:121], v[148:149], v[158:159] op_sel:[0,1,0] op_sel_hi:[1,1,1]
	v_pk_fma_f32 v[114:115], v[114:115], v[148:149], v[160:161] op_sel:[0,1,0] op_sel_hi:[1,1,1]
	v_pk_fma_f32 v[116:117], v[116:117], v[148:149], v[162:163] op_sel:[0,1,0] op_sel_hi:[1,1,1]
	v_pk_fma_f32 v[110:111], v[110:111], v[150:151], v[156:157] op_sel_hi:[1,0,1]
	v_pk_fma_f32 v[112:113], v[112:113], v[150:151], v[158:159] op_sel_hi:[1,0,1]
	v_pk_fma_f32 v[102:103], v[102:103], v[150:151], v[160:161] op_sel_hi:[1,0,1]
	v_pk_fma_f32 v[104:105], v[104:105], v[150:151], v[162:163] op_sel_hi:[1,0,1]
	v_pk_fma_f32 v[94:95], v[94:95], v[150:151], v[156:157] op_sel:[0,1,0] op_sel_hi:[1,1,1]
	v_pk_fma_f32 v[96:97], v[96:97], v[150:151], v[158:159] op_sel:[0,1,0] op_sel_hi:[1,1,1]
	v_pk_fma_f32 v[86:87], v[86:87], v[150:151], v[160:161] op_sel:[0,1,0] op_sel_hi:[1,1,1]
	v_pk_fma_f32 v[88:89], v[88:89], v[150:151], v[162:163] op_sel:[0,1,0] op_sel_hi:[1,1,1]
	v_pk_fma_f32 v[62:63], v[62:63], v[152:153], v[156:157] op_sel_hi:[1,0,1]
	v_pk_fma_f32 v[64:65], v[64:65], v[152:153], v[158:159] op_sel_hi:[1,0,1]
	v_pk_fma_f32 v[58:59], v[58:59], v[152:153], v[160:161] op_sel_hi:[1,0,1]
	v_pk_fma_f32 v[60:61], v[60:61], v[152:153], v[162:163] op_sel_hi:[1,0,1]
	v_pk_fma_f32 v[54:55], v[54:55], v[152:153], v[156:157] op_sel:[0,1,0] op_sel_hi:[1,1,1]
	v_pk_fma_f32 v[56:57], v[56:57], v[152:153], v[158:159] op_sel:[0,1,0] op_sel_hi:[1,1,1]
	v_pk_fma_f32 v[50:51], v[50:51], v[152:153], v[160:161] op_sel:[0,1,0] op_sel_hi:[1,1,1]
	v_pk_fma_f32 v[52:53], v[52:53], v[152:153], v[162:163] op_sel:[0,1,0] op_sel_hi:[1,1,1]
	v_pk_fma_f32 v[38:39], v[38:39], v[154:155], v[156:157] op_sel_hi:[1,0,1]
	v_pk_fma_f32 v[40:41], v[40:41], v[154:155], v[158:159] op_sel_hi:[1,0,1]
	v_pk_fma_f32 v[34:35], v[34:35], v[154:155], v[160:161] op_sel_hi:[1,0,1]
	v_pk_fma_f32 v[36:37], v[36:37], v[154:155], v[162:163] op_sel_hi:[1,0,1]
	v_pk_fma_f32 v[22:23], v[22:23], v[154:155], v[156:157] op_sel:[0,1,0] op_sel_hi:[1,1,1]
	v_pk_fma_f32 v[24:25], v[24:25], v[154:155], v[158:159] op_sel:[0,1,0] op_sel_hi:[1,1,1]
	v_pk_fma_f32 v[18:19], v[18:19], v[154:155], v[160:161] op_sel:[0,1,0] op_sel_hi:[1,1,1]
	v_pk_fma_f32 v[20:21], v[20:21], v[154:155], v[162:163] op_sel:[0,1,0] op_sel_hi:[1,1,1]
	v_mul_f32_e32 v148, 0xbf317218, v148
	v_mul_f32_e32 v149, 0xbf317218, v149
	v_mul_f32_e32 v150, 0xbf317218, v150
	v_mul_f32_e32 v151, 0xbf317218, v151
	v_mul_f32_e32 v152, 0xbf317218, v152
	v_mul_f32_e32 v153, 0xbf317218, v153
	v_mul_f32_e32 v154, 0xbf317218, v154
	v_mul_f32_e32 v155, 0xbf317218, v155
	v_mul_f32_e32 v164, 0xbf317218, v164
;     __device__ __forceinline__ void operator()(f32x4 (&acc)[2][2][4][2], const Unit& u, int wr, int wc, int fr, int fq) const {
;     ...
;             const f32x4 w0 = *(const f32x4*)(fcw + ch + 4 * n) * NL2E, w1 = *(const f32x4*)(fcw + nch + ch + 4 * n) * NL2E, w2 = *(const f32x4*)(fcw + 2 * nch + ch + 4 * n) * NL2E, cb = *(const f32x4*)(fcb + ch + 4 * n) * NL2E;
; #pragma unroll
;             for (int e = 0; e < 4; ++e) {
;                 const float w0e = fr == 0 ? w0[e] : 0.f, w2e = fr == 15 ? w2[e] : 0.f;
;                 float tt[2][4];
; #pragma unroll
;                 for (int ai = 0; ai < 2; ++ai)
; #pragma unroll
;                     for (int m = 0; m < 4; ++m) { const float x = acc[ai][0][m][n][e];
;                         float t = __builtin_fmaf(w1[e], x, cb[e]); const float w0s = w0[e], w2s = w2[e];
;                         asm volatile("v_fmac_f32_dpp %0, %1, %2 row_shr:1 row_mask:0xf bank_mask:0xf bound_ctrl:1" : "+v"(t) : "v"(x), "v"(w0s));
;                         asm volatile("v_fmac_f32_dpp %0, %1, %2 row_shl:1 row_mask:0xf bank_mask:0xf bound_ctrl:1" : "+v"(t) : "v"(x), "v"(w2s));
;                         if (ai > 0 || m > 0) { const float xp = m > 0 ? acc[ai][0][m > 0 ? m - 1 : 0][n][e] : acc[0][0][3][n][e]; asm volatile("v_fmac_f32_dpp %0, %1, %2 row_ror:1 row_mask:0xf bank_mask:0xf" : "+v"(t) : "v"(xp), "v"(w0e)); }
;                         if (ai < 1 || m < 3) { const float xn = m < 3 ? acc[ai][0][m < 3 ? m + 1 : 3][n][e] : acc[1][0][0][n][e]; asm volatile("v_fmac_f32_dpp %0, %1, %2 row_ror:15 row_mask:0xf bank_mask:0xf" : "+v"(t) : "v"(xn), "v"(w2e)); }
;                         tt[ai][m] = t; }
	v_mul_f32_e32 v165, 0xbf317218, v165
	v_mul_f32_e32 v166, 0xbf317218, v166
	v_mul_f32_e32 v167, 0xbf317218, v167
	v_mul_f32_e32 v168, 0xbf317218, v168
	v_mul_f32_e32 v169, 0xbf317218, v169
	v_mul_f32_e32 v170, 0xbf317218, v170
	v_mul_f32_e32 v171, 0xbf317218, v171
	v_pk_fma_f32 v[106:107], v[106:107], v[148:149], v[164:165] op_sel_hi:[1,0,1]
	v_pk_fma_f32 v[108:109], v[108:109], v[148:149], v[166:167] op_sel_hi:[1,0,1]
	v_pk_fma_f32 v[98:99], v[98:99], v[148:149], v[168:169] op_sel_hi:[1,0,1]
	v_pk_fma_f32 v[100:101], v[100:101], v[148:149], v[170:171] op_sel_hi:[1,0,1]
	v_pk_fma_f32 v[90:91], v[90:91], v[148:149], v[164:165] op_sel:[0,1,0] op_sel_hi:[1,1,1]
	v_pk_fma_f32 v[92:93], v[92:93], v[148:149], v[166:167] op_sel:[0,1,0] op_sel_hi:[1,1,1]
	v_pk_fma_f32 v[82:83], v[82:83], v[148:149], v[168:169] op_sel:[0,1,0] op_sel_hi:[1,1,1]
	v_pk_fma_f32 v[84:85], v[84:85], v[148:149], v[170:171] op_sel:[0,1,0] op_sel_hi:[1,1,1]
	v_pk_fma_f32 v[78:79], v[78:79], v[150:151], v[164:165] op_sel_hi:[1,0,1]
	v_pk_fma_f32 v[80:81], v[80:81], v[150:151], v[166:167] op_sel_hi:[1,0,1]
	v_pk_fma_f32 v[74:75], v[74:75], v[150:151], v[168:169] op_sel_hi:[1,0,1]
	v_pk_fma_f32 v[76:77], v[76:77], v[150:151], v[170:171] op_sel_hi:[1,0,1]
	v_pk_fma_f32 v[70:71], v[70:71], v[150:151], v[164:165] op_sel:[0,1,0] op_sel_hi:[1,1,1]
	v_pk_fma_f32 v[72:73], v[72:73], v[150:151], v[166:167] op_sel:[0,1,0] op_sel_hi:[1,1,1]
	v_pk_fma_f32 v[66:67], v[66:67], v[150:151], v[168:169] op_sel:[0,1,0] op_sel_hi:[1,1,1]
	v_pk_fma_f32 v[68:69], v[68:69], v[150:151], v[170:171] op_sel:[0,1,0] op_sel_hi:[1,1,1]
	v_pk_fma_f32 v[46:47], v[46:47], v[152:153], v[164:165] op_sel_hi:[1,0,1]
	v_pk_fma_f32 v[48:49], v[48:49], v[152:153], v[166:167] op_sel_hi:[1,0,1]
	v_pk_fma_f32 v[42:43], v[42:43], v[152:153], v[168:169] op_sel_hi:[1,0,1]
	v_pk_fma_f32 v[44:45], v[44:45], v[152:153], v[170:171] op_sel_hi:[1,0,1]
	v_pk_fma_f32 v[30:31], v[30:31], v[152:153], v[164:165] op_sel:[0,1,0] op_sel_hi:[1,1,1]
	v_pk_fma_f32 v[32:33], v[32:33], v[152:153], v[166:167] op_sel:[0,1,0] op_sel_hi:[1,1,1]
	v_pk_fma_f32 v[26:27], v[26:27], v[152:153], v[168:169] op_sel:[0,1,0] op_sel_hi:[1,1,1]
	v_pk_fma_f32 v[28:29], v[28:29], v[152:153], v[170:171] op_sel:[0,1,0] op_sel_hi:[1,1,1]
	v_pk_fma_f32 v[14:15], v[14:15], v[154:155], v[164:165] op_sel_hi:[1,0,1]
	v_pk_fma_f32 v[16:17], v[16:17], v[154:155], v[166:167] op_sel_hi:[1,0,1]
	v_pk_fma_f32 v[10:11], v[10:11], v[154:155], v[168:169] op_sel_hi:[1,0,1]
	v_pk_fma_f32 v[12:13], v[12:13], v[154:155], v[170:171] op_sel_hi:[1,0,1]
	v_pk_fma_f32 v[6:7], v[6:7], v[154:155], v[164:165] op_sel:[0,1,0] op_sel_hi:[1,1,1]
	v_pk_fma_f32 v[8:9], v[8:9], v[154:155], v[166:167] op_sel:[0,1,0] op_sel_hi:[1,1,1]
	v_pk_fma_f32 v[2:3], v[2:3], v[154:155], v[168:169] op_sel:[0,1,0] op_sel_hi:[1,1,1]
	v_pk_fma_f32 v[4:5], v[4:5], v[154:155], v[170:171] op_sel:[0,1,0] op_sel_hi:[1,1,1]
	s_mov_b32 s14, 0xbfb8aa3b
	s_mov_b32 s15, 0xbfb8aa3b
	s_waitcnt vmcnt(0)
	v_pk_mul_f32 v[188:189], v[188:189], s[14:15]
	v_pk_mul_f32 v[190:191], v[190:191], s[14:15]
	v_pk_mul_f32 v[192:193], v[192:193], s[14:15]
	v_pk_mul_f32 v[194:195], v[194:195], s[14:15]
	v_pk_mul_f32 v[196:197], v[196:197], s[14:15]
	v_pk_mul_f32 v[198:199], v[198:199], s[14:15]
	v_pk_mul_f32 v[200:201], v[200:201], s[14:15]
	v_pk_mul_f32 v[202:203], v[202:203], s[14:15]
	v_pk_mul_f32 v[204:205], v[204:205], s[14:15]
	v_pk_mul_f32 v[206:207], v[206:207], s[14:15]
	v_pk_mul_f32 v[208:209], v[208:209], s[14:15]
	v_pk_mul_f32 v[210:211], v[210:211], s[14:15]
	v_pk_mul_f32 v[212:213], v[212:213], s[14:15]
	v_pk_mul_f32 v[214:215], v[214:215], s[14:15]
	v_pk_mul_f32 v[218:219], v[218:219], s[14:15]
	v_pk_mul_f32 v[220:221], v[220:221], s[14:15]
	v_pk_fma_f32 v[156:157], v[126:127], v[196:197], v[212:213]
	v_pk_fma_f32 v[158:159], v[118:119], v[196:197], v[212:213]
	v_pk_fma_f32 v[160:161], v[110:111], v[196:197], v[212:213]
	v_pk_fma_f32 v[162:163], v[94:95], v[196:197], v[212:213]
	v_pk_fma_f32 v[164:165], v[62:63], v[196:197], v[212:213]
	v_pk_fma_f32 v[166:167], v[54:55], v[196:197], v[212:213]
	v_pk_fma_f32 v[168:169], v[38:39], v[196:197], v[212:213]
	v_pk_fma_f32 v[170:171], v[22:23], v[196:197], v[212:213]
	v_pk_fma_f32 v[158:159], v[126:127], v[188:189], v[158:159]
	v_pk_fma_f32 v[160:161], v[118:119], v[188:189], v[160:161]
	v_pk_fma_f32 v[162:163], v[110:111], v[188:189], v[162:163]
	v_pk_fma_f32 v[164:165], v[94:95], v[188:189], v[164:165]
	v_pk_fma_f32 v[166:167], v[62:63], v[188:189], v[166:167]
	v_pk_fma_f32 v[168:169], v[54:55], v[188:189], v[168:169]
	v_pk_fma_f32 v[170:171], v[38:39], v[188:189], v[170:171]
	v_pk_fma_f32 v[156:157], v[118:119], v[204:205], v[156:157]
	v_pk_fma_f32 v[158:159], v[110:111], v[204:205], v[158:159]
	v_pk_fma_f32 v[160:161], v[94:95], v[204:205], v[160:161]
	v_pk_fma_f32 v[162:163], v[62:63], v[204:205], v[162:163]
	v_pk_fma_f32 v[164:165], v[54:55], v[204:205], v[164:165]
	v_pk_fma_f32 v[166:167], v[38:39], v[204:205], v[166:167]
	v_pk_fma_f32 v[168:169], v[22:23], v[204:205], v[168:169]
	v_fmac_f32_dpp v156, v22, v188 row_shr:1 row_mask:0xf bank_mask:0xf bound_ctrl:1
	v_fmac_f32_dpp v157, v23, v189 row_shr:1 row_mask:0xf bank_mask:0xf bound_ctrl:1
	v_fmac_f32_dpp v170, v126, v204 row_shl:1 row_mask:0xf bank_mask:0xf bound_ctrl:1
	v_fmac_f32_dpp v171, v127, v205 row_shl:1 row_mask:0xf bank_mask:0xf bound_ctrl:1
	v_exp_f32_e32 v222, v156
	v_exp_f32_e32 v223, v157
	v_exp_f32_e32 v224, v158
	v_exp_f32_e32 v225, v159
	v_exp_f32_e32 v226, v160
	v_exp_f32_e32 v227, v161
	v_exp_f32_e32 v228, v162
	v_exp_f32_e32 v229, v163
	v_exp_f32_e32 v230, v164
	v_exp_f32_e32 v231, v165
;     __device__ __forceinline__ void operator()(f32x4 (&acc)[2][2][4][2], const Unit& u, int wr, int wc, int fr, int fq) const {
;     ...
;             for (int e = 0; e < 4; ++e) {
;                 const float w0e = fr == 0 ? w0[e] : 0.f, w2e = fr == 15 ? w2[e] : 0.f;
;                 float tt[2][4];
; #pragma unroll
;                 for (int ai = 0; ai < 2; ++ai)
; #pragma unroll
;                     for (int m = 0; m < 4; ++m) { const float x = acc[ai][0][m][n][e];
;                         float t = __builtin_fmaf(w1[e], x, cb[e]); const float w0s = w0[e], w2s = w2[e];
;                         asm volatile("v_fmac_f32_dpp %0, %1, %2 row_shr:1 row_mask:0xf bank_mask:0xf bound_ctrl:1" : "+v"(t) : "v"(x), "v"(w0s));
;                         asm volatile("v_fmac_f32_dpp %0, %1, %2 row_shl:1 row_mask:0xf bank_mask:0xf bound_ctrl:1" : "+v"(t) : "v"(x), "v"(w2s));
;                         if (ai > 0 || m > 0) { const float xp = m > 0 ? acc[ai][0][m > 0 ? m - 1 : 0][n][e] : acc[0][0][3][n][e]; asm volatile("v_fmac_f32_dpp %0, %1, %2 row_ror:1 row_mask:0xf bank_mask:0xf" : "+v"(t) : "v"(xp), "v"(w0e)); }
;                         if (ai < 1 || m < 3) { const float xn = m < 3 ? acc[ai][0][m < 3 ? m + 1 : 3][n][e] : acc[1][0][0][n][e]; asm volatile("v_fmac_f32_dpp %0, %1, %2 row_ror:15 row_mask:0xf bank_mask:0xf" : "+v"(t) : "v"(xn), "v"(w2e)); }
;                         tt[ai][m] = t; }
; #pragma unroll
;                 for (int ai = 0; ai < 2; ++ai)
; #pragma unroll
;                     for (int m = 0; m < 4; ++m) { const float t = tt[ai][m];
;                         float res = (t * -0.6931471805599453f) * __builtin_amdgcn_rcpf(1.f + __builtin_amdgcn_exp2f(t)) * acc[ai][1][m][n][e];
;                         asm volatile("" : "+v"(res));
;                         acc[ai][0][m][n][e] = res;
	v_exp_f32_e32 v232, v166
	v_exp_f32_e32 v233, v167
	v_exp_f32_e32 v234, v168
	v_exp_f32_e32 v235, v169
	v_exp_f32_e32 v186, v170
	v_exp_f32_e32 v187, v171
	v_pk_add_f32 v[222:223], v[222:223], s[26:27]
	v_pk_add_f32 v[224:225], v[224:225], s[26:27]
	v_pk_add_f32 v[226:227], v[226:227], s[26:27]
	v_pk_add_f32 v[228:229], v[228:229], s[26:27]
	v_pk_add_f32 v[230:231], v[230:231], s[26:27]
	v_pk_add_f32 v[232:233], v[232:233], s[26:27]
	v_pk_add_f32 v[234:235], v[234:235], s[26:27]
	v_pk_add_f32 v[186:187], v[186:187], s[26:27]
	v_rcp_f32_e32 v222, v222
	v_rcp_f32_e32 v223, v223
	v_rcp_f32_e32 v224, v224
	v_rcp_f32_e32 v225, v225
	v_rcp_f32_e32 v226, v226
	v_rcp_f32_e32 v227, v227
	v_rcp_f32_e32 v228, v228
	v_rcp_f32_e32 v229, v229
	v_rcp_f32_e32 v230, v230
	v_rcp_f32_e32 v231, v231
	v_rcp_f32_e32 v232, v232
	v_rcp_f32_e32 v233, v233
	v_rcp_f32_e32 v234, v234
	v_rcp_f32_e32 v235, v235
	v_rcp_f32_e32 v186, v186
	v_rcp_f32_e32 v187, v187
	v_pk_mul_f32 v[156:157], v[156:157], v[222:223]
	v_pk_mul_f32 v[158:159], v[158:159], v[224:225]
	v_pk_mul_f32 v[160:161], v[160:161], v[226:227]
	v_pk_mul_f32 v[162:163], v[162:163], v[228:229]
	v_pk_mul_f32 v[164:165], v[164:165], v[230:231]
	v_pk_mul_f32 v[166:167], v[166:167], v[232:233]
	v_pk_mul_f32 v[168:169], v[168:169], v[234:235]
	v_pk_mul_f32 v[170:171], v[170:171], v[186:187]
	v_pk_mul_f32 v[126:127], v[156:157], v[106:107]
	v_pk_mul_f32 v[118:119], v[158:159], v[90:91]
	v_pk_mul_f32 v[110:111], v[160:161], v[78:79]
	v_pk_mul_f32 v[94:95], v[162:163], v[70:71]
	v_pk_mul_f32 v[62:63], v[164:165], v[46:47]
	v_pk_mul_f32 v[54:55], v[166:167], v[30:31]
	v_pk_mul_f32 v[38:39], v[168:169], v[14:15]
	v_pk_mul_f32 v[22:23], v[170:171], v[6:7]
	v_pk_fma_f32 v[156:157], v[128:129], v[198:199], v[214:215]
	v_pk_fma_f32 v[158:159], v[120:121], v[198:199], v[214:215]
	v_pk_fma_f32 v[160:161], v[112:113], v[198:199], v[214:215]
	v_pk_fma_f32 v[162:163], v[96:97], v[198:199], v[214:215]
	v_pk_fma_f32 v[164:165], v[64:65], v[198:199], v[214:215]
	v_pk_fma_f32 v[166:167], v[56:57], v[198:199], v[214:215]
	v_pk_fma_f32 v[168:169], v[40:41], v[198:199], v[214:215]
	v_pk_fma_f32 v[170:171], v[24:25], v[198:199], v[214:215]
	v_pk_fma_f32 v[158:159], v[128:129], v[190:191], v[158:159]
	v_pk_fma_f32 v[160:161], v[120:121], v[190:191], v[160:161]
	v_pk_fma_f32 v[162:163], v[112:113], v[190:191], v[162:163]
	v_pk_fma_f32 v[164:165], v[96:97], v[190:191], v[164:165]
	v_pk_fma_f32 v[166:167], v[64:65], v[190:191], v[166:167]
	v_pk_fma_f32 v[168:169], v[56:57], v[190:191], v[168:169]
	v_pk_fma_f32 v[170:171], v[40:41], v[190:191], v[170:171]
	v_pk_fma_f32 v[156:157], v[120:121], v[206:207], v[156:157]
	v_pk_fma_f32 v[158:159], v[112:113], v[206:207], v[158:159]
	v_pk_fma_f32 v[160:161], v[96:97], v[206:207], v[160:161]
	v_pk_fma_f32 v[162:163], v[64:65], v[206:207], v[162:163]
	v_pk_fma_f32 v[164:165], v[56:57], v[206:207], v[164:165]
	v_pk_fma_f32 v[166:167], v[40:41], v[206:207], v[166:167]
	v_pk_fma_f32 v[168:169], v[24:25], v[206:207], v[168:169]
	v_fmac_f32_dpp v156, v24, v190 row_shr:1 row_mask:0xf bank_mask:0xf bound_ctrl:1
	v_fmac_f32_dpp v157, v25, v191 row_shr:1 row_mask:0xf bank_mask:0xf bound_ctrl:1
	v_fmac_f32_dpp v170, v128, v206 row_shl:1 row_mask:0xf bank_mask:0xf bound_ctrl:1
	v_fmac_f32_dpp v171, v129, v207 row_shl:1 row_mask:0xf bank_mask:0xf bound_ctrl:1
	v_exp_f32_e32 v222, v156
	v_exp_f32_e32 v223, v157
	v_exp_f32_e32 v224, v158
	v_exp_f32_e32 v225, v159
	v_exp_f32_e32 v226, v160
	v_exp_f32_e32 v227, v161
	v_exp_f32_e32 v228, v162
	v_exp_f32_e32 v229, v163
	v_exp_f32_e32 v230, v164
	v_exp_f32_e32 v231, v165
	v_exp_f32_e32 v232, v166
	v_exp_f32_e32 v233, v167
	v_exp_f32_e32 v234, v168
	v_exp_f32_e32 v235, v169
	v_exp_f32_e32 v186, v170
	v_exp_f32_e32 v187, v171
	v_pk_add_f32 v[222:223], v[222:223], s[26:27]
	v_pk_add_f32 v[224:225], v[224:225], s[26:27]
	v_pk_add_f32 v[226:227], v[226:227], s[26:27]
	v_pk_add_f32 v[228:229], v[228:229], s[26:27]
	v_pk_add_f32 v[230:231], v[230:231], s[26:27]
	v_pk_add_f32 v[232:233], v[232:233], s[26:27]
	v_pk_add_f32 v[234:235], v[234:235], s[26:27]
	v_pk_add_f32 v[186:187], v[186:187], s[26:27]
	v_rcp_f32_e32 v222, v222
	v_rcp_f32_e32 v223, v223
	v_rcp_f32_e32 v224, v224
	v_rcp_f32_e32 v225, v225
	v_rcp_f32_e32 v226, v226
	v_rcp_f32_e32 v227, v227
	v_rcp_f32_e32 v228, v228
	v_rcp_f32_e32 v229, v229
	v_rcp_f32_e32 v230, v230
	v_rcp_f32_e32 v231, v231
	v_rcp_f32_e32 v232, v232
	v_rcp_f32_e32 v233, v233
	v_rcp_f32_e32 v234, v234
	v_rcp_f32_e32 v235, v235
	v_rcp_f32_e32 v186, v186
	v_rcp_f32_e32 v187, v187
	v_pk_mul_f32 v[156:157], v[156:157], v[222:223]
	v_pk_mul_f32 v[158:159], v[158:159], v[224:225]
	v_pk_mul_f32 v[160:161], v[160:161], v[226:227]
	v_pk_mul_f32 v[162:163], v[162:163], v[228:229]
	v_pk_mul_f32 v[164:165], v[164:165], v[230:231]
	v_pk_mul_f32 v[166:167], v[166:167], v[232:233]
	v_pk_mul_f32 v[168:169], v[168:169], v[234:235]
	v_pk_mul_f32 v[170:171], v[170:171], v[186:187]
	v_pk_mul_f32 v[128:129], v[156:157], v[108:109]
	v_pk_mul_f32 v[120:121], v[158:159], v[92:93]
	v_pk_mul_f32 v[112:113], v[160:161], v[80:81]
	v_pk_mul_f32 v[96:97], v[162:163], v[72:73]
	v_pk_mul_f32 v[64:65], v[164:165], v[48:49]
	v_pk_mul_f32 v[56:57], v[166:167], v[32:33]
	v_pk_mul_f32 v[40:41], v[168:169], v[16:17]
	v_pk_mul_f32 v[24:25], v[170:171], v[8:9]
	v_pk_fma_f32 v[156:157], v[122:123], v[200:201], v[218:219]
	v_pk_fma_f32 v[158:159], v[114:115], v[200:201], v[218:219]
	v_pk_fma_f32 v[160:161], v[102:103], v[200:201], v[218:219]
	v_pk_fma_f32 v[162:163], v[86:87], v[200:201], v[218:219]
	v_pk_fma_f32 v[164:165], v[58:59], v[200:201], v[218:219]
;     __device__ __forceinline__ void operator()(f32x4 (&acc)[2][2][4][2], const Unit& u, int wr, int wc, int fr, int fq) const {
;     ...
;             for (int e = 0; e < 4; ++e) {
;                 const float w0e = fr == 0 ? w0[e] : 0.f, w2e = fr == 15 ? w2[e] : 0.f;
;                 float tt[2][4];
; #pragma unroll
;                 for (int ai = 0; ai < 2; ++ai)
; #pragma unroll
;                     for (int m = 0; m < 4; ++m) { const float x = acc[ai][0][m][n][e];
;                         float t = __builtin_fmaf(w1[e], x, cb[e]); const float w0s = w0[e], w2s = w2[e];
;                         asm volatile("v_fmac_f32_dpp %0, %1, %2 row_shr:1 row_mask:0xf bank_mask:0xf bound_ctrl:1" : "+v"(t) : "v"(x), "v"(w0s));
;                         asm volatile("v_fmac_f32_dpp %0, %1, %2 row_shl:1 row_mask:0xf bank_mask:0xf bound_ctrl:1" : "+v"(t) : "v"(x), "v"(w2s));
;                         if (ai > 0 || m > 0) { const float xp = m > 0 ? acc[ai][0][m > 0 ? m - 1 : 0][n][e] : acc[0][0][3][n][e]; asm volatile("v_fmac_f32_dpp %0, %1, %2 row_ror:1 row_mask:0xf bank_mask:0xf" : "+v"(t) : "v"(xp), "v"(w0e)); }
;                         if (ai < 1 || m < 3) { const float xn = m < 3 ? acc[ai][0][m < 3 ? m + 1 : 3][n][e] : acc[1][0][0][n][e]; asm volatile("v_fmac_f32_dpp %0, %1, %2 row_ror:15 row_mask:0xf bank_mask:0xf" : "+v"(t) : "v"(xn), "v"(w2e)); }
;                         tt[ai][m] = t; }
; #pragma unroll
;                 for (int ai = 0; ai < 2; ++ai)
; #pragma unroll
;                     for (int m = 0; m < 4; ++m) { const float t = tt[ai][m];
;                         float res = (t * -0.6931471805599453f) * __builtin_amdgcn_rcpf(1.f + __builtin_amdgcn_exp2f(t)) * acc[ai][1][m][n][e];
;                         asm volatile("" : "+v"(res));
;                         acc[ai][0][m][n][e] = res;
	v_pk_fma_f32 v[166:167], v[50:51], v[200:201], v[218:219]
	v_pk_fma_f32 v[168:169], v[34:35], v[200:201], v[218:219]
	v_pk_fma_f32 v[170:171], v[18:19], v[200:201], v[218:219]
	v_pk_fma_f32 v[158:159], v[122:123], v[192:193], v[158:159]
	v_pk_fma_f32 v[160:161], v[114:115], v[192:193], v[160:161]
	v_pk_fma_f32 v[162:163], v[102:103], v[192:193], v[162:163]
	v_pk_fma_f32 v[164:165], v[86:87], v[192:193], v[164:165]
	v_pk_fma_f32 v[166:167], v[58:59], v[192:193], v[166:167]
	v_pk_fma_f32 v[168:169], v[50:51], v[192:193], v[168:169]
	v_pk_fma_f32 v[170:171], v[34:35], v[192:193], v[170:171]
	v_pk_fma_f32 v[156:157], v[114:115], v[208:209], v[156:157]
	v_pk_fma_f32 v[158:159], v[102:103], v[208:209], v[158:159]
	v_pk_fma_f32 v[160:161], v[86:87], v[208:209], v[160:161]
	v_pk_fma_f32 v[162:163], v[58:59], v[208:209], v[162:163]
	v_pk_fma_f32 v[164:165], v[50:51], v[208:209], v[164:165]
	v_pk_fma_f32 v[166:167], v[34:35], v[208:209], v[166:167]
	v_pk_fma_f32 v[168:169], v[18:19], v[208:209], v[168:169]
	v_fmac_f32_dpp v156, v18, v192 row_shr:1 row_mask:0xf bank_mask:0xf bound_ctrl:1
	v_fmac_f32_dpp v157, v19, v193 row_shr:1 row_mask:0xf bank_mask:0xf bound_ctrl:1
	v_fmac_f32_dpp v170, v122, v208 row_shl:1 row_mask:0xf bank_mask:0xf bound_ctrl:1
	v_fmac_f32_dpp v171, v123, v209 row_shl:1 row_mask:0xf bank_mask:0xf bound_ctrl:1
	v_exp_f32_e32 v222, v156
	v_exp_f32_e32 v223, v157
	v_exp_f32_e32 v224, v158
	v_exp_f32_e32 v225, v159
	v_exp_f32_e32 v226, v160
	v_exp_f32_e32 v227, v161
	v_exp_f32_e32 v228, v162
	v_exp_f32_e32 v229, v163
	v_exp_f32_e32 v230, v164
	v_exp_f32_e32 v231, v165
	v_exp_f32_e32 v232, v166
	v_exp_f32_e32 v233, v167
	v_exp_f32_e32 v234, v168
	v_exp_f32_e32 v235, v169
	v_exp_f32_e32 v186, v170
	v_exp_f32_e32 v187, v171
	v_pk_add_f32 v[222:223], v[222:223], s[26:27]
	v_pk_add_f32 v[224:225], v[224:225], s[26:27]
	v_pk_add_f32 v[226:227], v[226:227], s[26:27]
	v_pk_add_f32 v[228:229], v[228:229], s[26:27]
	v_pk_add_f32 v[230:231], v[230:231], s[26:27]
	v_pk_add_f32 v[232:233], v[232:233], s[26:27]
	v_pk_add_f32 v[234:235], v[234:235], s[26:27]
	v_pk_add_f32 v[186:187], v[186:187], s[26:27]
	v_rcp_f32_e32 v222, v222
	v_rcp_f32_e32 v223, v223
	v_rcp_f32_e32 v224, v224
	v_rcp_f32_e32 v225, v225
	v_rcp_f32_e32 v226, v226
	v_rcp_f32_e32 v227, v227
	v_rcp_f32_e32 v228, v228
	v_rcp_f32_e32 v229, v229
	v_rcp_f32_e32 v230, v230
	v_rcp_f32_e32 v231, v231
	v_rcp_f32_e32 v232, v232
	v_rcp_f32_e32 v233, v233
	v_rcp_f32_e32 v234, v234
	v_rcp_f32_e32 v235, v235
	v_rcp_f32_e32 v186, v186
	v_rcp_f32_e32 v187, v187
	v_pk_mul_f32 v[156:157], v[156:157], v[222:223]
	v_pk_mul_f32 v[158:159], v[158:159], v[224:225]
	v_pk_mul_f32 v[160:161], v[160:161], v[226:227]
	v_pk_mul_f32 v[162:163], v[162:163], v[228:229]
	v_pk_mul_f32 v[164:165], v[164:165], v[230:231]
	v_pk_mul_f32 v[166:167], v[166:167], v[232:233]
	v_pk_mul_f32 v[168:169], v[168:169], v[234:235]
	v_pk_mul_f32 v[170:171], v[170:171], v[186:187]
	v_pk_mul_f32 v[122:123], v[156:157], v[98:99]
	v_pk_mul_f32 v[114:115], v[158:159], v[82:83]
	v_pk_mul_f32 v[102:103], v[160:161], v[74:75]
	v_pk_mul_f32 v[86:87], v[162:163], v[66:67]
	v_pk_mul_f32 v[58:59], v[164:165], v[42:43]
	v_pk_mul_f32 v[50:51], v[166:167], v[26:27]
	v_pk_mul_f32 v[34:35], v[168:169], v[10:11]
	v_pk_mul_f32 v[18:19], v[170:171], v[2:3]
	v_pk_fma_f32 v[156:157], v[124:125], v[202:203], v[220:221]
	v_pk_fma_f32 v[158:159], v[116:117], v[202:203], v[220:221]
	v_pk_fma_f32 v[160:161], v[104:105], v[202:203], v[220:221]
	v_pk_fma_f32 v[162:163], v[88:89], v[202:203], v[220:221]
	v_pk_fma_f32 v[164:165], v[60:61], v[202:203], v[220:221]
	v_pk_fma_f32 v[166:167], v[52:53], v[202:203], v[220:221]
	v_pk_fma_f32 v[168:169], v[36:37], v[202:203], v[220:221]
	v_pk_fma_f32 v[170:171], v[20:21], v[202:203], v[220:221]
	v_pk_fma_f32 v[158:159], v[124:125], v[194:195], v[158:159]
	v_pk_fma_f32 v[160:161], v[116:117], v[194:195], v[160:161]
	v_pk_fma_f32 v[162:163], v[104:105], v[194:195], v[162:163]
	v_pk_fma_f32 v[164:165], v[88:89], v[194:195], v[164:165]
	v_pk_fma_f32 v[166:167], v[60:61], v[194:195], v[166:167]
	v_pk_fma_f32 v[168:169], v[52:53], v[194:195], v[168:169]
	v_pk_fma_f32 v[170:171], v[36:37], v[194:195], v[170:171]
	v_pk_fma_f32 v[156:157], v[116:117], v[210:211], v[156:157]
	v_pk_fma_f32 v[158:159], v[104:105], v[210:211], v[158:159]
	v_pk_fma_f32 v[160:161], v[88:89], v[210:211], v[160:161]
	v_pk_fma_f32 v[162:163], v[60:61], v[210:211], v[162:163]
	v_pk_fma_f32 v[164:165], v[52:53], v[210:211], v[164:165]
	v_pk_fma_f32 v[166:167], v[36:37], v[210:211], v[166:167]
	v_pk_fma_f32 v[168:169], v[20:21], v[210:211], v[168:169]
	v_fmac_f32_dpp v156, v20, v194 row_shr:1 row_mask:0xf bank_mask:0xf bound_ctrl:1
	v_fmac_f32_dpp v157, v21, v195 row_shr:1 row_mask:0xf bank_mask:0xf bound_ctrl:1
	v_fmac_f32_dpp v170, v124, v210 row_shl:1 row_mask:0xf bank_mask:0xf bound_ctrl:1
	v_fmac_f32_dpp v171, v125, v211 row_shl:1 row_mask:0xf bank_mask:0xf bound_ctrl:1
	v_exp_f32_e32 v222, v156
	v_exp_f32_e32 v223, v157
	v_exp_f32_e32 v224, v158
	v_exp_f32_e32 v225, v159
	v_exp_f32_e32 v226, v160
	v_exp_f32_e32 v227, v161
	v_exp_f32_e32 v228, v162
	v_exp_f32_e32 v229, v163
	v_exp_f32_e32 v230, v164
	v_exp_f32_e32 v231, v165
	v_exp_f32_e32 v232, v166
	v_exp_f32_e32 v233, v167
	v_exp_f32_e32 v234, v168
	v_exp_f32_e32 v235, v169
	v_exp_f32_e32 v186, v170
	v_exp_f32_e32 v187, v171
	v_pk_add_f32 v[222:223], v[222:223], s[26:27]
	v_pk_add_f32 v[224:225], v[224:225], s[26:27]
	v_pk_add_f32 v[226:227], v[226:227], s[26:27]
	v_pk_add_f32 v[228:229], v[228:229], s[26:27]
; __device__ __forceinline__ unsigned cvt_pk4_fp8(float a, float b, float c, float d) {
;     a = __builtin_amdgcn_fmed3f(a, -448.f, 448.f); b = __builtin_amdgcn_fmed3f(b, -448.f, 448.f); c = __builtin_amdgcn_fmed3f(c, -448.f, 448.f); d = __builtin_amdgcn_fmed3f(d, -448.f, 448.f);
;     int w = __builtin_amdgcn_cvt_pk_fp8_f32(a, b, 0, false); w = __builtin_amdgcn_cvt_pk_fp8_f32(c, d, w, true); return (unsigned)w; }
;     __device__ __forceinline__ void operator()(f32x4 (&acc)[2][2][4][2], const Unit& u, int wr, int wc, int fr, int fq) const {
;     ...
; #pragma unroll
;         for (int ai = 0; ai < 2; ++ai)
; #pragma unroll
;             for (int mp = 0; mp < 2; ++mp) {
;                 const f32x4 a0 = acc[ai][0][2 * mp][0], a1 = acc[ai][0][2 * mp][1], c0 = acc[ai][0][2 * mp + 1][0], c1 = acc[ai][0][2 * mp + 1][1];
;                 unsigned ax = cvt_pk4_fp8(a0[0], a0[1], a0[2], a0[3]), ay = cvt_pk4_fp8(a1[0], a1[1], a1[2], a1[3]), cx = cvt_pk4_fp8(c0[0], c0[1], c0[2], c0[3]), cy = cvt_pk4_fp8(c1[0], c1[1], c1[2], c1[3]);
;                 asm volatile("s_nop 1\n\tv_permlane16_swap_b32 %0, %1" : "+v"(ax), "+v"(cx)); asm volatile("s_nop 1\n\tv_permlane16_swap_b32 %0, %1" : "+v"(ay), "+v"(cy));
;                 const int od = fq & 1, lr = 64 * ai + 16 * (2 * mp + od) + fr;
;                 u32x4 w; w.x = ax; w.y = ay; w.z = cx; w.w = cy;
;                 *(u32x4*)((unsigned char*)ACT + (tok00 + (size_t)lr * 64) * lda + ch - 8 * od) = w; }
	v_pk_add_f32 v[230:231], v[230:231], s[26:27]
	v_pk_add_f32 v[232:233], v[232:233], s[26:27]
	v_pk_add_f32 v[234:235], v[234:235], s[26:27]
	v_pk_add_f32 v[186:187], v[186:187], s[26:27]
	v_rcp_f32_e32 v222, v222
	v_rcp_f32_e32 v223, v223
	v_rcp_f32_e32 v224, v224
	v_rcp_f32_e32 v225, v225
	v_rcp_f32_e32 v226, v226
	v_rcp_f32_e32 v227, v227
	v_rcp_f32_e32 v228, v228
	v_rcp_f32_e32 v229, v229
	v_rcp_f32_e32 v230, v230
	v_rcp_f32_e32 v231, v231
	v_rcp_f32_e32 v232, v232
	v_rcp_f32_e32 v233, v233
	v_rcp_f32_e32 v234, v234
	v_rcp_f32_e32 v235, v235
	v_rcp_f32_e32 v186, v186
	v_rcp_f32_e32 v187, v187
	v_pk_mul_f32 v[156:157], v[156:157], v[222:223]
	v_pk_mul_f32 v[158:159], v[158:159], v[224:225]
	v_pk_mul_f32 v[160:161], v[160:161], v[226:227]
	v_pk_mul_f32 v[162:163], v[162:163], v[228:229]
	v_pk_mul_f32 v[164:165], v[164:165], v[230:231]
	v_pk_mul_f32 v[166:167], v[166:167], v[232:233]
	v_pk_mul_f32 v[168:169], v[168:169], v[234:235]
	v_pk_mul_f32 v[170:171], v[170:171], v[186:187]
	v_pk_mul_f32 v[124:125], v[156:157], v[100:101]
	v_pk_mul_f32 v[116:117], v[158:159], v[84:85]
	v_pk_mul_f32 v[104:105], v[160:161], v[76:77]
	v_pk_mul_f32 v[88:89], v[162:163], v[68:69]
	v_pk_mul_f32 v[60:61], v[164:165], v[44:45]
	v_pk_mul_f32 v[52:53], v[166:167], v[28:29]
	v_pk_mul_f32 v[36:37], v[168:169], v[12:13]
	v_pk_mul_f32 v[20:21], v[170:171], v[4:5]
	v_med3_f32 v126, v126, s81, v184
	v_med3_f32 v127, v127, s81, v184
	v_med3_f32 v128, v128, s81, v184
	v_med3_f32 v129, v129, s81, v184
	v_med3_f32 v122, v122, s81, v184
	v_med3_f32 v123, v123, s81, v184
	v_med3_f32 v124, v124, s81, v184
	v_med3_f32 v125, v125, s81, v184
	v_med3_f32 v118, v118, s81, v184
	v_med3_f32 v119, v119, s81, v184
	v_med3_f32 v120, v120, s81, v184
	v_med3_f32 v121, v121, s81, v184
	v_med3_f32 v114, v114, s81, v184
	v_med3_f32 v115, v115, s81, v184
	v_med3_f32 v116, v116, s81, v184
	v_med3_f32 v117, v117, s81, v184
	v_cvt_pk_fp8_f32 v148, v126, v127
	v_cvt_pk_fp8_f32 v148, v128, v129 op_sel:[0,0,1]
	v_cvt_pk_fp8_f32 v149, v122, v123
	v_cvt_pk_fp8_f32 v149, v124, v125 op_sel:[0,0,1]
	v_cvt_pk_fp8_f32 v150, v118, v119
	v_cvt_pk_fp8_f32 v150, v120, v121 op_sel:[0,0,1]
	v_cvt_pk_fp8_f32 v151, v114, v115
	v_cvt_pk_fp8_f32 v151, v116, v117 op_sel:[0,0,1]
	s_nop 1
	v_permlane16_swap_b32 v148, v150
	v_permlane16_swap_b32 v149, v151
	global_store_dwordx4 v185, v[148:151], s[28:29]
	v_med3_f32 v110, v110, s81, v184
	v_med3_f32 v111, v111, s81, v184
	v_med3_f32 v112, v112, s81, v184
	v_med3_f32 v113, v113, s81, v184
	v_med3_f32 v102, v102, s81, v184
	v_med3_f32 v103, v103, s81, v184
	v_med3_f32 v104, v104, s81, v184
	v_med3_f32 v105, v105, s81, v184
	v_med3_f32 v94, v94, s81, v184
	v_med3_f32 v95, v95, s81, v184
	v_med3_f32 v96, v96, s81, v184
	v_med3_f32 v97, v97, s81, v184
	v_med3_f32 v86, v86, s81, v184
	v_med3_f32 v87, v87, s81, v184
	v_med3_f32 v88, v88, s81, v184
	v_med3_f32 v89, v89, s81, v184
	v_cvt_pk_fp8_f32 v152, v110, v111
	v_cvt_pk_fp8_f32 v152, v112, v113 op_sel:[0,0,1]
	v_cvt_pk_fp8_f32 v153, v102, v103
	v_cvt_pk_fp8_f32 v153, v104, v105 op_sel:[0,0,1]
	v_cvt_pk_fp8_f32 v154, v94, v95
	v_cvt_pk_fp8_f32 v154, v96, v97 op_sel:[0,0,1]
	v_cvt_pk_fp8_f32 v155, v86, v87
	v_cvt_pk_fp8_f32 v155, v88, v89 op_sel:[0,0,1]
	v_add_u32_e32 v185, 0xb0000, v185
	s_nop 1
	v_permlane16_swap_b32 v152, v154
	v_permlane16_swap_b32 v153, v155
	global_store_dwordx4 v185, v[152:155], s[28:29]
	v_med3_f32 v62, v62, s81, v184
	v_med3_f32 v63, v63, s81, v184
	v_med3_f32 v64, v64, s81, v184
	v_med3_f32 v65, v65, s81, v184
	v_med3_f32 v58, v58, s81, v184
	v_med3_f32 v59, v59, s81, v184
	v_med3_f32 v60, v60, s81, v184
	v_med3_f32 v61, v61, s81, v184
	v_med3_f32 v54, v54, s81, v184
	v_med3_f32 v55, v55, s81, v184
	v_med3_f32 v56, v56, s81, v184
	v_med3_f32 v57, v57, s81, v184
	v_med3_f32 v50, v50, s81, v184
	v_med3_f32 v51, v51, s81, v184
	v_med3_f32 v52, v52, s81, v184
	v_med3_f32 v53, v53, s81, v184
	v_cvt_pk_fp8_f32 v148, v62, v63
	v_cvt_pk_fp8_f32 v148, v64, v65 op_sel:[0,0,1]
	v_cvt_pk_fp8_f32 v149, v58, v59
	v_cvt_pk_fp8_f32 v149, v60, v61 op_sel:[0,0,1]
	v_cvt_pk_fp8_f32 v150, v54, v55
	v_cvt_pk_fp8_f32 v150, v56, v57 op_sel:[0,0,1]
	v_cvt_pk_fp8_f32 v151, v50, v51
	v_cvt_pk_fp8_f32 v151, v52, v53 op_sel:[0,0,1]
	v_add_u32_e32 v185, 0xb0000, v185
	s_nop 1
	v_permlane16_swap_b32 v148, v150
	v_permlane16_swap_b32 v149, v151
	global_store_dwordx4 v185, v[148:151], s[28:29]
	v_med3_f32 v38, v38, s81, v184
	v_med3_f32 v39, v39, s81, v184
	v_med3_f32 v40, v40, s81, v184
	v_med3_f32 v41, v41, s81, v184
	v_med3_f32 v34, v34, s81, v184
	v_med3_f32 v35, v35, s81, v184
	v_med3_f32 v36, v36, s81, v184
	v_med3_f32 v37, v37, s81, v184
	v_med3_f32 v22, v22, s81, v184
	v_med3_f32 v23, v23, s81, v184
	v_med3_f32 v24, v24, s81, v184
	v_med3_f32 v25, v25, s81, v184
	v_med3_f32 v18, v18, s81, v184
	v_med3_f32 v19, v19, s81, v184
	v_med3_f32 v20, v20, s81, v184
	v_med3_f32 v21, v21, s81, v184
	v_cvt_pk_fp8_f32 v152, v38, v39
	v_cvt_pk_fp8_f32 v152, v40, v41 op_sel:[0,0,1]
	v_cvt_pk_fp8_f32 v153, v34, v35
	v_cvt_pk_fp8_f32 v153, v36, v37 op_sel:[0,0,1]
	v_cvt_pk_fp8_f32 v154, v22, v23
	v_cvt_pk_fp8_f32 v154, v24, v25 op_sel:[0,0,1]
	v_cvt_pk_fp8_f32 v155, v18, v19
	v_cvt_pk_fp8_f32 v155, v20, v21 op_sel:[0,0,1]
	v_add_u32_e32 v185, 0xb0000, v185
	s_nop 1
	v_permlane16_swap_b32 v152, v154
	v_permlane16_swap_b32 v153, v155
	global_store_dwordx4 v185, v[152:155], s[28:29]
	s_and_b64 vcc, exec, s[4:5]
	s_mov_b64 s[4:5], -1
	s_cbranch_vccnz .LBB0_911
	s_andn2_b64 vcc, exec, s[12:13]
	s_cbranch_vccnz .LBB0_910
	s_branch .LBB0_910

;     __host__ __device__ bool next(int i, Unit& u) const { const long L = (long)i * G + c; if (L >= nwg) return false; u.pm = 0; u.pn = c % nN; return true; }
; #define PG8_STAGE(bufoff, gbase, voff) do { _Pragma("unroll") for (int _i = 0; _i < 2; ++_i) \
;         __builtin_amdgcn_global_load_lds((const unsigned*)((const char*)(gbase) + (voff)[_i]), (PG8_LAS unsigned*)(lds + (bufoff) + ldsw + _i * 8192), 16, 0, 0); } while (0)
; #define PG8_WAIT_V(n) asm volatile("s_waitcnt vmcnt(" #n ")" ::: "memory")
; template <class Epi, class Sched, bool ALIGN_EPI = false, bool SP2 = false, bool F8 = false>
; __device__ __forceinline__ void gemm_phase(PG8_LAS unsigned char* lds, const Gemm g, const Sched& S, const Epi& E) {
;     ...
; #pragma unroll
;     for (int i = 0; i < 2; ++i) { int R, C; stage_rc(tid * 16 + i * 8192, R, C); const int Rb = Epi::PERM ? ((R & ~31) + perm32(R & 31)) : R;
;         const int Ra = Epi::GRIDMAP ? ((R & 63) * 64 + (R >> 6)) : R;
;         voffA[i] = (unsigned)(Ra * K + C) * 2u; voffB[i] = (unsigned)(Rb * K + C) * 2u; }
;     const size_t kstep = (size_t)(BK * 2);
;     const size_t hstep = (size_t)HALF * K * 2;
;     const size_t tstep = 2 * hstep;
;     const size_t hstepA = Epi::GRIDMAP ? (size_t)4096 * K * 2 : hstep;
;     ...
;     const unsigned ldsw = (unsigned)wid * 1024u;
;     const int aoff = lds_byte(wr * 64 + fr, fq * 8), boff = lds_byte(wc * 32 + fr, fq * 8);
;     ...
;     Unit cur, nxt; int ui = 0;
;     if (!S.next(0, cur)) return;
;     f32x4 acc[2][2][4][2];
; #pragma unroll
;     for (int a = 0; a < 2; ++a)
; #pragma unroll
;         for (int b = 0; b < 2; ++b)
; #pragma unroll
;             for (int m = 0; m < 4; ++m)
; #pragma unroll
;                 for (int n = 0; n < 2; ++n) acc[a][b][m][n] = (f32x4){0.f, 0.f, 0.f, 0.f};
;     bf16x8 At[4][2], B0[2][2], B1[2][2];
;     const char* cA = PG8_ABASE(cur.pm); const char* cB = (const char*)g.Bt + (size_t)cur.pn * tstep;
;     S.a_ready(cur);
;     if constexpr (SP2) {
;         PG8_STAGE(PG8_SB(0, 0), cB, voffB); PG8_STAGE(PG8_SB(0, 1), cB + hstep, voffB); PG8_STAGE(PG8_SA(0, 0), cA, voffA); PG8_STAGE(PG8_SA(0, 1), cA + hstepA, voffA);
;         if (wr == 1) PG8_BAR;
;         PG8_WAIT_V(2); PG8_BAR;
;         PG8_STAGE(PG8_SB(1, 0), cB + kstep, voffB); PG8_STAGE(PG8_SA(1, 0), cA + kstep, voffA); PG8_STAGE(PG8_SB(1, 1), cB + hstep + kstep, voffB);
;         PG8_WAIT_V(6); PG8_BAR;
.LBB0_984:
	s_add_i32 s5, s8, s5
	s_ashr_i32 s8, s5, 31
	s_waitcnt vmcnt(6)
	v_lshrrev_b32_e32 v4, 1, v0
	s_lshr_b32 s8, s8, 26
	s_waitcnt vmcnt(4)
	v_and_b32_e32 v11, 24, v4
	v_lshrrev_b32_e32 v4, 5, v0
	s_add_i32 s8, s5, s8
	v_lshlrev_b32_e32 v1, 4, v0
	v_and_b32_e32 v2, 32, v0
	v_and_b32_e32 v4, 4, v4
	v_bfe_u32 v5, v0, 2, 2
	s_ashr_i32 s9, s8, 6
	s_and_b32 s8, s8, 0xffc0
	v_bfe_u32 v3, v0, 2, 4
	v_bitop3_b32 v1, v1, v2, 48 bitop3:0x6c
	v_and_b32_e32 v10, 64, v0
	v_or3_b32 v4, v4, v5, v11
	v_lshrrev_b32_e32 v5, 3, v0
	s_sub_i32 s8, s5, s8
	v_or_b32_e32 v2, v1, v10
	v_and_or_b32 v6, v5, 48, v3
	v_and_or_b32 v5, v5, 32, v4
	s_bfe_i32 s5, s8, 0x80000
	v_lshrrev_b32_e32 v2, 1, v2
	v_mul_u32_u24_e32 v5, 0xb00, v5
	s_bfe_u32 s5, s5, 0x3000c
	v_or_b32_e32 v5, v5, v2
	s_add_i32 s10, s8, s5
	v_lshlrev_b32_e32 v162, 1, v5
	v_bfe_u32 v5, v0, 3, 25
	s_bfe_i32 s5, s10, 0x80000
	s_and_b32 s10, s10, 0xf8
	v_or_b32_e32 v5, 64, v5
	s_movk_i32 s7, 0x70
	s_sub_i32 s8, s8, s10
	v_and_or_b32 v3, v5, s7, v3
	s_movk_i32 s7, 0x60
	s_lshl_b32 s9, s9, 3
	s_sext_i32_i16 s11, s5
	s_sext_i32_i8 s8, s8
	v_and_or_b32 v4, v5, s7, v4
	s_lshr_b32 s7, s6, 6
	s_add_i32 s63, s9, s8
	s_ashr_i32 s8, s11, 3
	s_lshr_b32 s4, s6, 8
	s_lshl_b32 s14, s7, 10
	s_lshr_b32 s5, s11, 3
	s_mul_hi_i32 s9, s8, 0x160000
	s_mul_i32 s8, s8, 0x160000
	v_mul_u32_u24_e32 v13, 0xb00, v3
	s_add_u32 s54, s80, s8
	v_or_b32_e32 v3, v13, v2
	s_addc_u32 s55, s81, s9
	s_add_i32 s15, s14, 0
	v_mul_u32_u24_e32 v12, 0xb00, v6
	v_lshlrev_b32_e32 v164, 1, v3
	v_mul_u32_u24_e32 v3, 0xb00, v4
	s_add_i32 m0, s15, 0x10000
	v_or_b32_e32 v6, v2, v12
	v_or_b32_e32 v2, v3, v2
	global_load_lds_dwordx4 v162, s[54:55]
	s_add_i32 m0, s15, 0x12000
	v_lshlrev_b32_e32 v166, 1, v2
	s_add_u32 s8, s54, 0xb0000
	global_load_lds_dwordx4 v166, s[54:55]
	s_addc_u32 s9, s55, 0
	s_add_i32 m0, s15, 0x14000
	s_mul_i32 s12, s63, 0x160000
	global_load_lds_dwordx4 v162, s[8:9]
	s_add_i32 m0, s15, 0x16000
	s_mul_hi_i32 s10, s63, 0x160000
	s_add_u32 s52, s38, s12
	s_addc_u32 s53, s39, s10
	s_add_i32 s21, s15, 0x2000
	v_lshlrev_b32_e32 v160, 1, v6
	global_load_lds_dwordx4 v166, s[8:9]
	s_mov_b32 m0, s15
	s_add_u32 s8, s52, 0xb0000
	global_load_lds_dwordx4 v160, s[52:53]
	s_mov_b32 m0, s21
	s_addc_u32 s9, s53, 0
	s_add_i32 s23, s15, 0x4000
	global_load_lds_dwordx4 v164, s[52:53]
	s_mov_b32 m0, s23
	s_add_i32 s26, s15, 0x6000
	global_load_lds_dwordx4 v160, s[8:9]
	s_mov_b32 m0, s26
	v_mov_b32_e32 v163, 0
	global_load_lds_dwordx4 v164, s[8:9]
	v_mov_b32_e32 v167, v163
	v_mov_b32_e32 v161, v163
	v_mov_b32_e32 v165, v163
	s_cmp_eq_u32 s4, 1
	s_mov_b32 s27, 0
	v_lshl_add_u64 v[8:9], s[54:55], 0, v[162:163]
	v_lshl_add_u64 v[4:5], s[54:55], 0, v[166:167]
	s_mov_b64 s[8:9], 0xb0000
	v_lshl_add_u64 v[2:3], s[52:53], 0, v[160:161]
	s_cselect_b64 s[10:11], -1, 0
	s_cmp_lg_u32 s4, 1
	v_lshl_add_u64 v[6:7], s[52:53], 0, v[164:165]
	s_cbranch_scc1 .LBB0_986
.LBB0_986:
	s_add_u32 s28, s18, 0x11a000
	s_addc_u32 s29, s19, 0
	s_lshl_b32 s7, s7, 5
	s_mov_b64 s[12:13], 0x80
	s_and_b32 s7, s7, 0x60
	s_add_i32 m0, s15, 0x18000
	v_lshl_add_u64 v[8:9], v[8:9], 0, s[12:13]
	s_lshl_b32 s36, s4, 13
	s_lshl_b32 s37, s7, 7
	s_waitcnt vmcnt(2)
	s_barrier
	global_load_lds_dwordx4 v[8:9], off
	v_lshl_add_u64 v[4:5], v[4:5], 0, s[12:13]
	s_add_i32 m0, s15, 0x1a000
	s_add_i32 s33, s15, 0x8000
	s_add_i32 s43, s15, 0xa000
	global_load_lds_dwordx4 v[4:5], off
	v_lshl_add_u64 v[2:3], v[2:3], 0, s[12:13]
	s_mov_b32 m0, s33
	s_add_u32 s24, s54, 0xb0080
	global_load_lds_dwordx4 v[2:3], off
	v_lshl_add_u64 v[2:3], v[6:7], 0, s[12:13]
	s_mov_b32 m0, s43
	s_addc_u32 s25, s55, 0
	global_load_lds_dwordx4 v[2:3], off
	s_add_i32 m0, s15, 0x1c000
	v_lshl_add_u64 v[2:3], s[24:25], 0, v[162:163]
	global_load_lds_dwordx4 v[2:3], off
	v_lshl_add_u64 v[2:3], s[24:25], 0, v[166:167]
	s_add_i32 m0, s15, 0x1e000
	v_lshlrev_b32_e32 v4, 2, v0
	global_load_lds_dwordx4 v[2:3], off
	v_and_b32_e32 v2, 15, v0
	v_lshl_or_b32 v194, s4, 6, v2
	v_lshlrev_b32_e32 v3, 1, v11
	v_lshlrev_b32_e32 v0, 6, v0
	s_movk_i32 s4, 0x3c0
	v_and_b32_e32 v4, 32, v4
	v_and_or_b32 v0, v0, s4, v3
	v_lshl_or_b32 v2, v2, 6, v3
	v_bitop3_b32 v195, s37, v0, v4 bitop3:0xf6
	s_waitcnt vmcnt(6)
	s_cmpk_lt_u32 s6, 0x100
	v_add_u16_e32 v0, v1, v10
	v_bitop3_b32 v2, v2, s36, v4 bitop3:0xde
	s_cselect_b64 s[40:41], -1, 0
	v_lshrrev_b16_e32 v0, 1, v0
	s_add_i32 s59, 0, 0x10000
	s_add_i32 s60, 0, 0x14000
	s_sext_i32_i8 s64, s5
	s_ashr_i32 s58, s90, 31
	v_or_b32_e32 v196, s7, v11
	v_add_lshl_u32 v168, v12, v0, 1
	v_mov_b32_e32 v169, v163
	v_add_lshl_u32 v170, v13, v0, 1
	v_mov_b32_e32 v171, v163
	v_mov_b64_e32 v[172:173], 0x200
	v_mov_b64_e32 v[174:175], 0x1ff
	v_add_u32_e32 v197, s59, v195
	v_add_u32_e32 v198, s60, v195
	v_add_u32_e32 v199, 0, v2
	s_mov_b32 s42, 0x3c800000
	s_mov_b64 s[44:45], 0x80000
	s_mov_b64 s[46:47], 0x90000
	s_mov_b64 s[48:49], 0xa0000
	s_barrier
	s_branch .LBB0_989

;     __host__ __device__ bool next(int i, Unit& u) const { const long L = (long)i * G + c; if (L >= nwg) return false; u.pm = 0; u.pn = c % nN; return true; }
; #define PG8_STAGE(bufoff, gbase, voff) do { _Pragma("unroll") for (int _i = 0; _i < 2; ++_i) \
;         __builtin_amdgcn_global_load_lds((const unsigned*)((const char*)(gbase) + (voff)[_i]), (PG8_LAS unsigned*)(lds + (bufoff) + ldsw + _i * 8192), 16, 0, 0); } while (0)
; #define PG8_LDA(dst, b, h) do { _Pragma("unroll") for (int m = 0; m < 4; ++m) _Pragma("unroll") for (int k = 0; k < 2; ++k) dst[m][k] = *(const PG8_LAS bf16x8*)(lds + PG8_SA(b, h) + aoff + m * 2048 + k * 1024); } while (0)
; #define PG8_LDB(dst, b, h) do { _Pragma("unroll") for (int n = 0; n < 2; ++n) _Pragma("unroll") for (int k = 0; k < 2; ++k) dst[n][k] = *(const PG8_LAS bf16x8*)(lds + PG8_SB(b, h) + boff + n * 2048 + k * 1024); } while (0)
; #define PG8_WAIT_V(n) asm volatile("s_waitcnt vmcnt(" #n ")" ::: "memory")
; #define PG8_WAIT_L(n) asm volatile("s_waitcnt lgkmcnt(" #n ")" ::: "memory")
; #define PG8_BAR __builtin_amdgcn_s_barrier()
; #define PG8_SCHED __builtin_amdgcn_sched_barrier(0)
; template <class Epi, class Sched, bool ALIGN_EPI = false, bool SP2 = false, bool F8 = false>
; __device__ __forceinline__ void gemm_phase(PG8_LAS unsigned char* lds, const Gemm g, const Sched& S, const Epi& E) {
;     ...
;         const bool has_next = S.next(ui + 1, nxt);
;         const char* nA = has_next ? PG8_ABASE(nxt.pm) : cA; const char* nB = has_next ? (const char*)g.Bt + (size_t)nxt.pn * tstep : cB;
;         for (int t = 0; t < nt; t += 2) {
;             const bool last = (t == nt - 2);
;             const char* a1 = cA + (size_t)(t + 1) * kstep;
;             const char* a2 = last ? nA : cA + (size_t)(t + 2) * kstep; const char* b2 = last ? nB : cB + (size_t)(t + 2) * kstep;
;             const char* a3 = a2 + kstep; const char* b3 = b2 + kstep;
;             if (last && has_next) S.a_ready(nxt);
;             if constexpr (SP2) {
;             PG8_LDB(B0, 0, 0); PG8_LDB(B1, 0, 1); PG8_SCHED; PG8_LDA(At, 0, 0); PG8_STAGE(PG8_SA(1, 1), a1 + hstepA, voffA);
;             PG8_WAIT_V(8); PG8_WAIT_L(0); PG8_BAR; PG8_MMA(0, 0, At, B0); PG8_MMA(0, 1, At, B1); PG8_BAR; PG8_SCHED;
.LBB0_999:
	s_add_u32 s52, s52, 0xb0080
	s_addc_u32 s53, s53, 0
	s_add_u32 s65, s54, 0x100
	s_waitcnt vmcnt(0)
	v_mov_b32_e32 v32, 0
	s_addc_u32 s66, s55, 0
	s_mov_b32 s67, -2
	v_mov_b32_e32 v33, 0
	v_pk_mul_f32 v[34:35], v[32:33], v[32:33]
	v_pk_mul_f32 v[36:37], v[32:33], v[32:33]
	v_pk_mul_f32 v[38:39], v[32:33], v[32:33]
	v_pk_mul_f32 v[40:41], v[32:33], v[32:33]
	v_pk_mul_f32 v[42:43], v[32:33], v[32:33]
	v_pk_mul_f32 v[44:45], v[32:33], v[32:33]
	v_pk_mul_f32 v[46:47], v[32:33], v[32:33]
	v_pk_mul_f32 v[48:49], v[32:33], v[32:33]
	v_pk_mul_f32 v[50:51], v[32:33], v[32:33]
	v_pk_mul_f32 v[52:53], v[32:33], v[32:33]
	v_pk_mul_f32 v[54:55], v[32:33], v[32:33]
	v_pk_mul_f32 v[56:57], v[32:33], v[32:33]
	v_pk_mul_f32 v[58:59], v[32:33], v[32:33]
	v_pk_mul_f32 v[60:61], v[32:33], v[32:33]
	v_pk_mul_f32 v[62:63], v[32:33], v[32:33]
	v_pk_mul_f32 v[64:65], v[32:33], v[32:33]
	v_pk_mul_f32 v[66:67], v[32:33], v[32:33]
	v_pk_mul_f32 v[68:69], v[32:33], v[32:33]
	v_pk_mul_f32 v[70:71], v[32:33], v[32:33]
	v_pk_mul_f32 v[72:73], v[32:33], v[32:33]
	v_pk_mul_f32 v[74:75], v[32:33], v[32:33]
	v_pk_mul_f32 v[76:77], v[32:33], v[32:33]
	v_pk_mul_f32 v[78:79], v[32:33], v[32:33]
	v_pk_mul_f32 v[80:81], v[32:33], v[32:33]
	v_pk_mul_f32 v[82:83], v[32:33], v[32:33]
	v_pk_mul_f32 v[84:85], v[32:33], v[32:33]
	v_pk_mul_f32 v[86:87], v[32:33], v[32:33]
	v_pk_mul_f32 v[88:89], v[32:33], v[32:33]
	v_pk_mul_f32 v[90:91], v[32:33], v[32:33]
	v_pk_mul_f32 v[92:93], v[32:33], v[32:33]
	v_pk_mul_f32 v[94:95], v[32:33], v[32:33]
	v_pk_mul_f32 v[96:97], v[32:33], v[32:33]
	v_pk_mul_f32 v[98:99], v[32:33], v[32:33]
	v_pk_mul_f32 v[100:101], v[32:33], v[32:33]
	v_pk_mul_f32 v[102:103], v[32:33], v[32:33]
	v_pk_mul_f32 v[104:105], v[32:33], v[32:33]
	v_pk_mul_f32 v[106:107], v[32:33], v[32:33]
	v_pk_mul_f32 v[108:109], v[32:33], v[32:33]
	v_pk_mul_f32 v[110:111], v[32:33], v[32:33]
	v_pk_mul_f32 v[112:113], v[32:33], v[32:33]
	v_pk_mul_f32 v[114:115], v[32:33], v[32:33]
	v_pk_mul_f32 v[116:117], v[32:33], v[32:33]
	v_pk_mul_f32 v[118:119], v[32:33], v[32:33]
	v_pk_mul_f32 v[120:121], v[32:33], v[32:33]
	v_pk_mul_f32 v[122:123], v[32:33], v[32:33]
	v_pk_mul_f32 v[124:125], v[32:33], v[32:33]
	v_pk_mul_f32 v[126:127], v[32:33], v[32:33]
	v_pk_mul_f32 v[128:129], v[32:33], v[32:33]
	v_pk_mul_f32 v[130:131], v[32:33], v[32:33]
	v_pk_mul_f32 v[132:133], v[32:33], v[32:33]
	v_pk_mul_f32 v[134:135], v[32:33], v[32:33]
	v_pk_mul_f32 v[136:137], v[32:33], v[32:33]
	v_pk_mul_f32 v[138:139], v[32:33], v[32:33]
	v_pk_mul_f32 v[140:141], v[32:33], v[32:33]
	v_pk_mul_f32 v[142:143], v[32:33], v[32:33]
	v_pk_mul_f32 v[144:145], v[32:33], v[32:33]
	v_pk_mul_f32 v[146:147], v[32:33], v[32:33]
	v_pk_mul_f32 v[148:149], v[32:33], v[32:33]
	v_pk_mul_f32 v[150:151], v[32:33], v[32:33]
	v_pk_mul_f32 v[152:153], v[32:33], v[32:33]
	v_pk_mul_f32 v[154:155], v[32:33], v[32:33]
	v_pk_mul_f32 v[156:157], v[32:33], v[32:33]
	v_pk_mul_f32 v[158:159], v[32:33], v[32:33]
	s_cmp_lg_u64 s[10:11], 0
	s_cbranch_scc1 .Lk4_Y
.LBB0_1000:
	ds_read_b128 v[24:27], v197
	ds_read_b128 v[28:31], v197 offset:1024
	ds_read_b128 v[16:19], v197 offset:2048
	ds_read_b128 v[20:23], v197 offset:3072
	ds_read_b128 v[8:11], v198
	ds_read_b128 v[12:15], v198 offset:1024
	ds_read_b128 v[0:3], v198 offset:2048
	ds_read_b128 v[4:7], v198 offset:3072
	s_add_u32 s24, s52, 0xfff50080
	s_addc_u32 s25, s53, -1
	s_cmp_eq_u32 s67, 40
	s_cselect_b32 s57, s7, s25
	s_cselect_b32 s56, s6, s24
	s_cselect_b32 s55, s51, s66
	s_cselect_b32 s54, s50, s65
	v_lshl_add_u64 v[192:193], s[52:53], 0, v[168:169]
	s_add_i32 m0, s15, 0xc000
	ds_read_b128 v[176:179], v199
	ds_read_b128 v[180:183], v199 offset:1024
	ds_read_b128 v[184:187], v199 offset:2048
	ds_read_b128 v[188:191], v199 offset:3072
	ds_read_b128 v[200:203], v199 offset:4096
	ds_read_b128 v[204:207], v199 offset:5120
	ds_read_b128 v[208:211], v199 offset:6144
	ds_read_b128 v[212:215], v199 offset:7168
	global_load_lds_dwordx4 v[192:193], off
	v_lshl_add_u64 v[192:193], s[52:53], 0, v[170:171]
	s_add_i32 m0, s15, 0xe000
	s_nop 0
	global_load_lds_dwordx4 v[192:193], off
	s_waitcnt vmcnt(8)
	s_waitcnt lgkmcnt(0)
	s_setprio 1
	s_waitcnt lgkmcnt(0)
	v_mfma_f32_16x16x128_f8f6f4 v[156:159], v[24:31], v[176:183], v[156:159]
	v_mfma_f32_16x16x128_f8f6f4 v[152:155], v[16:23], v[176:183], v[152:155]
	v_mfma_f32_16x16x128_f8f6f4 v[140:143], v[24:31], v[184:191], v[140:143]
	v_mfma_f32_16x16x128_f8f6f4 v[136:139], v[16:23], v[184:191], v[136:139]
	v_mfma_f32_16x16x128_f8f6f4 v[124:127], v[24:31], v[200:207], v[124:127]
	v_mfma_f32_16x16x128_f8f6f4 v[120:123], v[16:23], v[200:207], v[120:123]
	v_mfma_f32_16x16x128_f8f6f4 v[108:111], v[24:31], v[208:215], v[108:111]
	v_mfma_f32_16x16x128_f8f6f4 v[104:107], v[16:23], v[208:215], v[104:107]
	s_setprio 0
	s_setprio 1
	v_mfma_f32_16x16x128_f8f6f4 v[148:151], v[8:15], v[176:183], v[148:151]
	v_mfma_f32_16x16x128_f8f6f4 v[144:147], v[0:7], v[176:183], v[144:147]
	v_mfma_f32_16x16x128_f8f6f4 v[132:135], v[8:15], v[184:191], v[132:135]
	v_mfma_f32_16x16x128_f8f6f4 v[128:131], v[0:7], v[184:191], v[128:131]
	v_mfma_f32_16x16x128_f8f6f4 v[116:119], v[8:15], v[200:207], v[116:119]
	v_mfma_f32_16x16x128_f8f6f4 v[112:115], v[0:7], v[200:207], v[112:115]
	v_mfma_f32_16x16x128_f8f6f4 v[100:103], v[8:15], v[208:215], v[100:103]
	v_mfma_f32_16x16x128_f8f6f4 v[96:99], v[0:7], v[208:215], v[96:99]
	s_setprio 0
	s_barrier
; #define PG8_STAGE(bufoff, gbase, voff) do { _Pragma("unroll") for (int _i = 0; _i < 2; ++_i) \
;         __builtin_amdgcn_global_load_lds((const unsigned*)((const char*)(gbase) + (voff)[_i]), (PG8_LAS unsigned*)(lds + (bufoff) + ldsw + _i * 8192), 16, 0, 0); } while (0)
; #define PG8_LDA(dst, b, h) do { _Pragma("unroll") for (int m = 0; m < 4; ++m) _Pragma("unroll") for (int k = 0; k < 2; ++k) dst[m][k] = *(const PG8_LAS bf16x8*)(lds + PG8_SA(b, h) + aoff + m * 2048 + k * 1024); } while (0)
; #define PG8_LDB(dst, b, h) do { _Pragma("unroll") for (int n = 0; n < 2; ++n) _Pragma("unroll") for (int k = 0; k < 2; ++k) dst[n][k] = *(const PG8_LAS bf16x8*)(lds + PG8_SB(b, h) + boff + n * 2048 + k * 1024); } while (0)
; #define PG8_WAIT_V(n) asm volatile("s_waitcnt vmcnt(" #n ")" ::: "memory")
; #define PG8_WAIT_L(n) asm volatile("s_waitcnt lgkmcnt(" #n ")" ::: "memory")
; #define PG8_BAR __builtin_amdgcn_s_barrier()
; #define PG8_SCHED __builtin_amdgcn_sched_barrier(0)
; template <class Epi, class Sched, bool ALIGN_EPI = false, bool SP2 = false, bool F8 = false>
; __device__ __forceinline__ void gemm_phase(PG8_LAS unsigned char* lds, const Gemm g, const Sched& S, const Epi& E) {
;     ...
;             PG8_LDB(B0, 0, 0); PG8_LDB(B1, 0, 1); PG8_SCHED; PG8_LDA(At, 0, 0); PG8_STAGE(PG8_SA(1, 1), a1 + hstepA, voffA);
;             PG8_WAIT_V(8); PG8_WAIT_L(0); PG8_BAR; PG8_MMA(0, 0, At, B0); PG8_MMA(0, 1, At, B1); PG8_BAR; PG8_SCHED;
;             PG8_LDA(At, 0, 1); PG8_STAGE(PG8_SB(0, 0), b2, voffB); PG8_STAGE(PG8_SB(0, 1), b2 + hstep, voffB); PG8_STAGE(PG8_SA(0, 0), a2, voffA);
;             PG8_WAIT_V(8); PG8_WAIT_L(0); PG8_BAR; PG8_MMA(1, 0, At, B0); PG8_MMA(1, 1, At, B1); PG8_BAR; PG8_SCHED;
;             PG8_LDB(B0, 1, 0); PG8_LDB(B1, 1, 1); PG8_SCHED; PG8_LDA(At, 1, 0); PG8_STAGE(PG8_SA(0, 1), a2 + hstepA, voffA);
;             PG8_WAIT_V(8); PG8_WAIT_L(0); PG8_BAR; PG8_MMA(0, 0, At, B0); PG8_MMA(0, 1, At, B1); PG8_BAR; PG8_SCHED;
;             PG8_LDA(At, 1, 1); PG8_STAGE(PG8_SB(1, 0), b3, voffB); PG8_STAGE(PG8_SB(1, 1), b3 + hstep, voffB); PG8_STAGE(PG8_SA(1, 0), a3, voffA);
;             PG8_WAIT_V(8); PG8_WAIT_L(0); PG8_BAR; PG8_MMA(1, 0, At, B0); PG8_MMA(1, 1, At, B1); PG8_BAR; PG8_SCHED;
	s_add_i32 s24, s59, s14
	v_lshl_add_u64 v[176:177], s[54:55], 0, v[162:163]
	s_mov_b32 m0, s24
	ds_read_b128 v[184:187], v199 offset:16384
	ds_read_b128 v[188:191], v199 offset:17408
	ds_read_b128 v[200:203], v199 offset:18432
	ds_read_b128 v[204:207], v199 offset:19456
	ds_read_b128 v[208:211], v199 offset:20480
	ds_read_b128 v[212:215], v199 offset:21504
	ds_read_b128 v[218:221], v199 offset:22528
	ds_read_b128 v[222:225], v199 offset:23552
	global_load_lds_dwordx4 v[176:177], off
	s_add_i32 m0, s24, 0x2000
	s_add_u32 s24, s54, 0xb0000
	v_lshl_add_u64 v[178:179], s[54:55], 0, v[166:167]
	s_addc_u32 s25, s55, 0
	s_add_i32 s36, s60, s14
	global_load_lds_dwordx4 v[178:179], off
	v_lshl_add_u64 v[180:181], s[24:25], 0, v[162:163]
	s_mov_b32 m0, s36
	v_lshl_add_u64 v[182:183], s[56:57], 0, v[164:165]
	global_load_lds_dwordx4 v[180:181], off
	v_lshl_add_u64 v[180:181], s[24:25], 0, v[166:167]
	s_add_i32 m0, s36, 0x2000
	s_nop 0
	global_load_lds_dwordx4 v[180:181], off
	v_lshl_add_u64 v[180:181], s[56:57], 0, v[160:161]
	s_mov_b32 m0, s15
	s_nop 0
	global_load_lds_dwordx4 v[180:181], off
	s_mov_b32 m0, s21
	s_nop 0
	global_load_lds_dwordx4 v[182:183], off
	s_waitcnt vmcnt(8)
	s_waitcnt lgkmcnt(0)
	s_setprio 1
	s_waitcnt lgkmcnt(0)
	v_mfma_f32_16x16x128_f8f6f4 v[92:95], v[24:31], v[184:191], v[92:95]
	v_mfma_f32_16x16x128_f8f6f4 v[88:91], v[16:23], v[184:191], v[88:91]
	v_mfma_f32_16x16x128_f8f6f4 v[76:79], v[24:31], v[200:207], v[76:79]
	v_mfma_f32_16x16x128_f8f6f4 v[72:75], v[16:23], v[200:207], v[72:75]
	v_mfma_f32_16x16x128_f8f6f4 v[60:63], v[24:31], v[208:215], v[60:63]
	v_mfma_f32_16x16x128_f8f6f4 v[56:59], v[16:23], v[208:215], v[56:59]
	v_mfma_f32_16x16x128_f8f6f4 v[44:47], v[24:31], v[218:225], v[44:47]
	v_mfma_f32_16x16x128_f8f6f4 v[40:43], v[16:23], v[218:225], v[40:43]
	s_setprio 0
	s_setprio 1
	v_mfma_f32_16x16x128_f8f6f4 v[84:87], v[8:15], v[184:191], v[84:87]
	v_mfma_f32_16x16x128_f8f6f4 v[80:83], v[0:7], v[184:191], v[80:83]
	v_mfma_f32_16x16x128_f8f6f4 v[68:71], v[8:15], v[200:207], v[68:71]
	v_mfma_f32_16x16x128_f8f6f4 v[64:67], v[0:7], v[200:207], v[64:67]
	v_mfma_f32_16x16x128_f8f6f4 v[52:55], v[8:15], v[208:215], v[52:55]
	v_mfma_f32_16x16x128_f8f6f4 v[48:51], v[0:7], v[208:215], v[48:51]
	v_mfma_f32_16x16x128_f8f6f4 v[36:39], v[8:15], v[218:225], v[36:39]
	v_mfma_f32_16x16x128_f8f6f4 v[32:35], v[0:7], v[218:225], v[32:35]
	s_setprio 0
	s_barrier
	s_add_i32 s36, 0, 0x18000
	s_add_i32 s37, 0, 0x1c000
	v_add_u32_e32 v12, s36, v195
	v_add_u32_e32 v28, s37, v195
	ds_read_b128 v[0:3], v12
	ds_read_b128 v[4:7], v12 offset:1024
	ds_read_b128 v[8:11], v12 offset:2048
	ds_read_b128 v[12:15], v12 offset:3072
	ds_read_b128 v[16:19], v28
	ds_read_b128 v[20:23], v28 offset:1024
	ds_read_b128 v[24:27], v28 offset:2048
	ds_read_b128 v[28:31], v28 offset:3072
	s_add_u32 s24, s56, 0xb0000
	s_addc_u32 s25, s57, 0
	s_mov_b32 m0, s23
	v_lshl_add_u64 v[192:193], s[24:25], 0, v[160:161]
	ds_read_b128 v[184:187], v199 offset:32768
	ds_read_b128 v[188:191], v199 offset:33792
	ds_read_b128 v[200:203], v199 offset:34816
	ds_read_b128 v[204:207], v199 offset:35840
	ds_read_b128 v[208:211], v199 offset:36864
	ds_read_b128 v[212:215], v199 offset:37888
	ds_read_b128 v[218:221], v199 offset:38912
	ds_read_b128 v[222:225], v199 offset:39936
	global_load_lds_dwordx4 v[192:193], off
	v_lshl_add_u64 v[192:193], s[24:25], 0, v[164:165]
	s_mov_b32 m0, s26
	s_nop 0
	global_load_lds_dwordx4 v[192:193], off
	s_waitcnt vmcnt(8)
	s_waitcnt lgkmcnt(0)
	s_setprio 1
	s_waitcnt lgkmcnt(0)
	v_mfma_f32_16x16x128_f8f6f4 v[156:159], v[0:7], v[184:191], v[156:159]
	v_mfma_f32_16x16x128_f8f6f4 v[152:155], v[8:15], v[184:191], v[152:155]
	v_mfma_f32_16x16x128_f8f6f4 v[140:143], v[0:7], v[200:207], v[140:143]
	v_mfma_f32_16x16x128_f8f6f4 v[136:139], v[8:15], v[200:207], v[136:139]
	v_mfma_f32_16x16x128_f8f6f4 v[124:127], v[0:7], v[208:215], v[124:127]
	v_mfma_f32_16x16x128_f8f6f4 v[120:123], v[8:15], v[208:215], v[120:123]
	v_mfma_f32_16x16x128_f8f6f4 v[108:111], v[0:7], v[218:225], v[108:111]
	v_mfma_f32_16x16x128_f8f6f4 v[104:107], v[8:15], v[218:225], v[104:107]
	s_setprio 0
	s_setprio 1
	v_mfma_f32_16x16x128_f8f6f4 v[148:151], v[16:23], v[184:191], v[148:151]
	v_mfma_f32_16x16x128_f8f6f4 v[144:147], v[24:31], v[184:191], v[144:147]
	v_mfma_f32_16x16x128_f8f6f4 v[132:135], v[16:23], v[200:207], v[132:135]
	v_mfma_f32_16x16x128_f8f6f4 v[128:131], v[24:31], v[200:207], v[128:131]
	v_mfma_f32_16x16x128_f8f6f4 v[116:119], v[16:23], v[208:215], v[116:119]
	v_mfma_f32_16x16x128_f8f6f4 v[112:115], v[24:31], v[208:215], v[112:115]
	v_mfma_f32_16x16x128_f8f6f4 v[100:103], v[16:23], v[218:225], v[100:103]
	v_mfma_f32_16x16x128_f8f6f4 v[96:99], v[24:31], v[218:225], v[96:99]
	s_setprio 0
	s_barrier
; #define PG8_STAGE(bufoff, gbase, voff) do { _Pragma("unroll") for (int _i = 0; _i < 2; ++_i) \
;         __builtin_amdgcn_global_load_lds((const unsigned*)((const char*)(gbase) + (voff)[_i]), (PG8_LAS unsigned*)(lds + (bufoff) + ldsw + _i * 8192), 16, 0, 0); } while (0)
; #define PG8_LDA(dst, b, h) do { _Pragma("unroll") for (int m = 0; m < 4; ++m) _Pragma("unroll") for (int k = 0; k < 2; ++k) dst[m][k] = *(const PG8_LAS bf16x8*)(lds + PG8_SA(b, h) + aoff + m * 2048 + k * 1024); } while (0)
; #define PG8_WAIT_V(n) asm volatile("s_waitcnt vmcnt(" #n ")" ::: "memory")
; #define PG8_WAIT_L(n) asm volatile("s_waitcnt lgkmcnt(" #n ")" ::: "memory")
; #define PG8_BAR __builtin_amdgcn_s_barrier()
; template <class Epi, class Sched, bool ALIGN_EPI = false, bool SP2 = false, bool F8 = false>
; __device__ __forceinline__ void gemm_phase(PG8_LAS unsigned char* lds, const Gemm g, const Sched& S, const Epi& E) {
;     ...
;         for (int t = 0; t < nt; t += 2) {
;             const bool last = (t == nt - 2);
;             const char* a1 = cA + (size_t)(t + 1) * kstep;
;             const char* a2 = last ? nA : cA + (size_t)(t + 2) * kstep; const char* b2 = last ? nB : cB + (size_t)(t + 2) * kstep;
;             const char* a3 = a2 + kstep; const char* b3 = b2 + kstep;
;             if (last && has_next) S.a_ready(nxt);
;             if constexpr (SP2) {
;             PG8_LDB(B0, 0, 0); PG8_LDB(B1, 0, 1); PG8_SCHED; PG8_LDA(At, 0, 0); PG8_STAGE(PG8_SA(1, 1), a1 + hstepA, voffA);
;             PG8_WAIT_V(8); PG8_WAIT_L(0); PG8_BAR; PG8_MMA(0, 0, At, B0); PG8_MMA(0, 1, At, B1); PG8_BAR; PG8_SCHED;
;             PG8_LDA(At, 0, 1); PG8_STAGE(PG8_SB(0, 0), b2, voffB); PG8_STAGE(PG8_SB(0, 1), b2 + hstep, voffB); PG8_STAGE(PG8_SA(0, 0), a2, voffA);
;             PG8_WAIT_V(8); PG8_WAIT_L(0); PG8_BAR; PG8_MMA(1, 0, At, B0); PG8_MMA(1, 1, At, B1); PG8_BAR; PG8_SCHED;
;             PG8_LDB(B0, 1, 0); PG8_LDB(B1, 1, 1); PG8_SCHED; PG8_LDA(At, 1, 0); PG8_STAGE(PG8_SA(0, 1), a2 + hstepA, voffA);
;             PG8_WAIT_V(8); PG8_WAIT_L(0); PG8_BAR; PG8_MMA(0, 0, At, B0); PG8_MMA(0, 1, At, B1); PG8_BAR; PG8_SCHED;
;             PG8_LDA(At, 1, 1); PG8_STAGE(PG8_SB(1, 0), b3, voffB); PG8_STAGE(PG8_SB(1, 1), b3 + hstep, voffB); PG8_STAGE(PG8_SA(1, 0), a3, voffA);
;             PG8_WAIT_V(8); PG8_WAIT_L(0); PG8_BAR; PG8_MMA(1, 0, At, B0); PG8_MMA(1, 1, At, B1); PG8_BAR; PG8_SCHED;
	s_add_i32 s24, s36, s14
	v_lshl_add_u64 v[176:177], v[176:177], 0, s[12:13]
	s_mov_b32 m0, s24
	ds_read_b128 v[184:187], v199 offset:49152
	ds_read_b128 v[188:191], v199 offset:50176
	ds_read_b128 v[200:203], v199 offset:51200
	ds_read_b128 v[204:207], v199 offset:52224
	ds_read_b128 v[208:211], v199 offset:53248
	ds_read_b128 v[212:215], v199 offset:54272
	ds_read_b128 v[218:221], v199 offset:55296
	ds_read_b128 v[222:225], v199 offset:56320
	global_load_lds_dwordx4 v[176:177], off
	s_add_i32 m0, s24, 0x2000
	s_add_u32 s24, s54, 0xb0080
	v_lshl_add_u64 v[176:177], v[178:179], 0, s[12:13]
	s_addc_u32 s25, s55, 0
	s_add_i32 s36, s37, s14
	global_load_lds_dwordx4 v[176:177], off
	v_lshl_add_u64 v[176:177], s[24:25], 0, v[162:163]
	s_mov_b32 m0, s36
	s_nop 0
	global_load_lds_dwordx4 v[176:177], off
	v_lshl_add_u64 v[176:177], s[24:25], 0, v[166:167]
	s_add_i32 m0, s36, 0x2000
	s_nop 0
	global_load_lds_dwordx4 v[176:177], off
	v_lshl_add_u64 v[176:177], v[180:181], 0, s[12:13]
	s_mov_b32 m0, s33
	s_nop 0
	global_load_lds_dwordx4 v[176:177], off
	v_lshl_add_u64 v[176:177], v[182:183], 0, s[12:13]
	s_mov_b32 m0, s43
	s_nop 0
	global_load_lds_dwordx4 v[176:177], off
	s_waitcnt vmcnt(8)
	s_waitcnt lgkmcnt(0)
	s_setprio 1
	s_waitcnt lgkmcnt(0)
	v_mfma_f32_16x16x128_f8f6f4 v[92:95], v[0:7], v[184:191], v[92:95]
	v_mfma_f32_16x16x128_f8f6f4 v[88:91], v[8:15], v[184:191], v[88:91]
	v_mfma_f32_16x16x128_f8f6f4 v[76:79], v[0:7], v[200:207], v[76:79]
	v_mfma_f32_16x16x128_f8f6f4 v[72:75], v[8:15], v[200:207], v[72:75]
	v_mfma_f32_16x16x128_f8f6f4 v[60:63], v[0:7], v[208:215], v[60:63]
	v_mfma_f32_16x16x128_f8f6f4 v[56:59], v[8:15], v[208:215], v[56:59]
	v_mfma_f32_16x16x128_f8f6f4 v[44:47], v[0:7], v[218:225], v[44:47]
	v_mfma_f32_16x16x128_f8f6f4 v[40:43], v[8:15], v[218:225], v[40:43]
	s_setprio 0
	s_setprio 1
	v_mfma_f32_16x16x128_f8f6f4 v[84:87], v[16:23], v[184:191], v[84:87]
	v_mfma_f32_16x16x128_f8f6f4 v[80:83], v[24:31], v[184:191], v[80:83]
	v_mfma_f32_16x16x128_f8f6f4 v[68:71], v[16:23], v[200:207], v[68:71]
	v_mfma_f32_16x16x128_f8f6f4 v[64:67], v[24:31], v[200:207], v[64:67]
	v_mfma_f32_16x16x128_f8f6f4 v[52:55], v[16:23], v[208:215], v[52:55]
	v_mfma_f32_16x16x128_f8f6f4 v[48:51], v[24:31], v[208:215], v[48:51]
	v_mfma_f32_16x16x128_f8f6f4 v[36:39], v[16:23], v[218:225], v[36:39]
	v_mfma_f32_16x16x128_f8f6f4 v[32:35], v[24:31], v[218:225], v[32:35]
	s_setprio 0
	s_barrier
	s_add_i32 s67, s67, 2
	s_add_u32 s52, s52, 0x100
	s_addc_u32 s53, s53, 0
	s_add_u32 s65, s65, 0x100
	s_addc_u32 s66, s66, 0
	s_cmp_gt_u32 s67, 41
	s_cbranch_scc0 .LBB0_1000
	s_branch .Lk4_exit
.Lk4_Y:
	ds_read_b128 v[24:27], v197
	ds_read_b128 v[28:31], v197 offset:1024
	ds_read_b128 v[16:19], v197 offset:2048
	ds_read_b128 v[20:23], v197 offset:3072
	ds_read_b128 v[8:11], v198
	ds_read_b128 v[12:15], v198 offset:1024
	ds_read_b128 v[0:3], v198 offset:2048
	ds_read_b128 v[4:7], v198 offset:3072
	s_add_u32 s24, s52, 0xfff50080
	s_addc_u32 s25, s53, -1
	s_cmp_eq_u32 s67, 40
	s_cselect_b32 s57, s7, s25
	s_cselect_b32 s56, s6, s24
	s_cselect_b32 s55, s51, s66
	s_cselect_b32 s54, s50, s65
	v_lshl_add_u64 v[192:193], s[52:53], 0, v[168:169]
	s_add_i32 m0, s15, 0xc000
	ds_read_b128 v[176:179], v199
	ds_read_b128 v[180:183], v199 offset:1024
	ds_read_b128 v[184:187], v199 offset:2048
	ds_read_b128 v[188:191], v199 offset:3072
	ds_read_b128 v[200:203], v199 offset:4096
	ds_read_b128 v[204:207], v199 offset:5120
	ds_read_b128 v[208:211], v199 offset:6144
	ds_read_b128 v[212:215], v199 offset:7168
	global_load_lds_dwordx4 v[192:193], off
	v_lshl_add_u64 v[192:193], s[52:53], 0, v[170:171]
	s_add_i32 m0, s15, 0xe000
	s_nop 0
	global_load_lds_dwordx4 v[192:193], off
	s_waitcnt vmcnt(8)
	s_waitcnt lgkmcnt(0)
	s_barrier
	s_setprio 3
	s_waitcnt lgkmcnt(0)
	v_mfma_f32_16x16x128_f8f6f4 v[156:159], v[24:31], v[176:183], v[156:159]
	v_mfma_f32_16x16x128_f8f6f4 v[152:155], v[16:23], v[176:183], v[152:155]
	v_mfma_f32_16x16x128_f8f6f4 v[140:143], v[24:31], v[184:191], v[140:143]
	v_mfma_f32_16x16x128_f8f6f4 v[136:139], v[16:23], v[184:191], v[136:139]
	v_mfma_f32_16x16x128_f8f6f4 v[124:127], v[24:31], v[200:207], v[124:127]
	v_mfma_f32_16x16x128_f8f6f4 v[120:123], v[16:23], v[200:207], v[120:123]
	v_mfma_f32_16x16x128_f8f6f4 v[108:111], v[24:31], v[208:215], v[108:111]
	v_mfma_f32_16x16x128_f8f6f4 v[104:107], v[16:23], v[208:215], v[104:107]
	s_setprio 0
	s_setprio 3
	v_mfma_f32_16x16x128_f8f6f4 v[148:151], v[8:15], v[176:183], v[148:151]
	v_mfma_f32_16x16x128_f8f6f4 v[144:147], v[0:7], v[176:183], v[144:147]
	v_mfma_f32_16x16x128_f8f6f4 v[132:135], v[8:15], v[184:191], v[132:135]
	v_mfma_f32_16x16x128_f8f6f4 v[128:131], v[0:7], v[184:191], v[128:131]
	v_mfma_f32_16x16x128_f8f6f4 v[116:119], v[8:15], v[200:207], v[116:119]
	v_mfma_f32_16x16x128_f8f6f4 v[112:115], v[0:7], v[200:207], v[112:115]
	v_mfma_f32_16x16x128_f8f6f4 v[100:103], v[8:15], v[208:215], v[100:103]
	v_mfma_f32_16x16x128_f8f6f4 v[96:99], v[0:7], v[208:215], v[96:99]
	s_setprio 0
	s_add_i32 s24, s59, s14
	v_lshl_add_u64 v[176:177], s[54:55], 0, v[162:163]
	s_mov_b32 m0, s24
	ds_read_b128 v[184:187], v199 offset:16384
	ds_read_b128 v[188:191], v199 offset:17408
	ds_read_b128 v[200:203], v199 offset:18432
	ds_read_b128 v[204:207], v199 offset:19456
	ds_read_b128 v[208:211], v199 offset:20480
	ds_read_b128 v[212:215], v199 offset:21504
	ds_read_b128 v[218:221], v199 offset:22528
	ds_read_b128 v[222:225], v199 offset:23552
	global_load_lds_dwordx4 v[176:177], off
	s_add_i32 m0, s24, 0x2000
	s_add_u32 s24, s54, 0xb0000
	v_lshl_add_u64 v[178:179], s[54:55], 0, v[166:167]
	s_addc_u32 s25, s55, 0
	s_add_i32 s36, s60, s14
	global_load_lds_dwordx4 v[178:179], off
	v_lshl_add_u64 v[180:181], s[24:25], 0, v[162:163]
	s_mov_b32 m0, s36
	v_lshl_add_u64 v[182:183], s[56:57], 0, v[164:165]
	global_load_lds_dwordx4 v[180:181], off
	v_lshl_add_u64 v[180:181], s[24:25], 0, v[166:167]
	s_add_i32 m0, s36, 0x2000
	s_nop 0
	global_load_lds_dwordx4 v[180:181], off
	v_lshl_add_u64 v[180:181], s[56:57], 0, v[160:161]
	s_mov_b32 m0, s15
	s_nop 0
	global_load_lds_dwordx4 v[180:181], off
	s_mov_b32 m0, s21
	s_nop 0
	global_load_lds_dwordx4 v[182:183], off
	s_waitcnt vmcnt(8)
	s_waitcnt lgkmcnt(0)
	s_barrier
; #define PG8_STAGE(bufoff, gbase, voff) do { _Pragma("unroll") for (int _i = 0; _i < 2; ++_i) \
;         __builtin_amdgcn_global_load_lds((const unsigned*)((const char*)(gbase) + (voff)[_i]), (PG8_LAS unsigned*)(lds + (bufoff) + ldsw + _i * 8192), 16, 0, 0); } while (0)
; #define PG8_LDA(dst, b, h) do { _Pragma("unroll") for (int m = 0; m < 4; ++m) _Pragma("unroll") for (int k = 0; k < 2; ++k) dst[m][k] = *(const PG8_LAS bf16x8*)(lds + PG8_SA(b, h) + aoff + m * 2048 + k * 1024); } while (0)
; #define PG8_LDB(dst, b, h) do { _Pragma("unroll") for (int n = 0; n < 2; ++n) _Pragma("unroll") for (int k = 0; k < 2; ++k) dst[n][k] = *(const PG8_LAS bf16x8*)(lds + PG8_SB(b, h) + boff + n * 2048 + k * 1024); } while (0)
; #define PG8_WAIT_V(n) asm volatile("s_waitcnt vmcnt(" #n ")" ::: "memory")
; #define PG8_WAIT_L(n) asm volatile("s_waitcnt lgkmcnt(" #n ")" ::: "memory")
; #define PG8_BAR __builtin_amdgcn_s_barrier()
; #define PG8_SCHED __builtin_amdgcn_sched_barrier(0)
; template <class Epi, class Sched, bool ALIGN_EPI = false, bool SP2 = false, bool F8 = false>
; __device__ __forceinline__ void gemm_phase(PG8_LAS unsigned char* lds, const Gemm g, const Sched& S, const Epi& E) {
;     ...
;             PG8_LDB(B0, 0, 0); PG8_LDB(B1, 0, 1); PG8_SCHED; PG8_LDA(At, 0, 0); PG8_STAGE(PG8_SA(1, 1), a1 + hstepA, voffA);
;             PG8_WAIT_V(8); PG8_WAIT_L(0); PG8_BAR; PG8_MMA(0, 0, At, B0); PG8_MMA(0, 1, At, B1); PG8_BAR; PG8_SCHED;
;             PG8_LDA(At, 0, 1); PG8_STAGE(PG8_SB(0, 0), b2, voffB); PG8_STAGE(PG8_SB(0, 1), b2 + hstep, voffB); PG8_STAGE(PG8_SA(0, 0), a2, voffA);
;             PG8_WAIT_V(8); PG8_WAIT_L(0); PG8_BAR; PG8_MMA(1, 0, At, B0); PG8_MMA(1, 1, At, B1); PG8_BAR; PG8_SCHED;
;             PG8_LDB(B0, 1, 0); PG8_LDB(B1, 1, 1); PG8_SCHED; PG8_LDA(At, 1, 0); PG8_STAGE(PG8_SA(0, 1), a2 + hstepA, voffA);
;             PG8_WAIT_V(8); PG8_WAIT_L(0); PG8_BAR; PG8_MMA(0, 0, At, B0); PG8_MMA(0, 1, At, B1); PG8_BAR; PG8_SCHED;
;             PG8_LDA(At, 1, 1); PG8_STAGE(PG8_SB(1, 0), b3, voffB); PG8_STAGE(PG8_SB(1, 1), b3 + hstep, voffB); PG8_STAGE(PG8_SA(1, 0), a3, voffA);
;             PG8_WAIT_V(8); PG8_WAIT_L(0); PG8_BAR; PG8_MMA(1, 0, At, B0); PG8_MMA(1, 1, At, B1); PG8_BAR; PG8_SCHED;
	s_setprio 3
	s_waitcnt lgkmcnt(0)
	v_mfma_f32_16x16x128_f8f6f4 v[92:95], v[24:31], v[184:191], v[92:95]
	v_mfma_f32_16x16x128_f8f6f4 v[88:91], v[16:23], v[184:191], v[88:91]
	v_mfma_f32_16x16x128_f8f6f4 v[76:79], v[24:31], v[200:207], v[76:79]
	v_mfma_f32_16x16x128_f8f6f4 v[72:75], v[16:23], v[200:207], v[72:75]
	v_mfma_f32_16x16x128_f8f6f4 v[60:63], v[24:31], v[208:215], v[60:63]
	v_mfma_f32_16x16x128_f8f6f4 v[56:59], v[16:23], v[208:215], v[56:59]
	v_mfma_f32_16x16x128_f8f6f4 v[44:47], v[24:31], v[218:225], v[44:47]
	v_mfma_f32_16x16x128_f8f6f4 v[40:43], v[16:23], v[218:225], v[40:43]
	s_setprio 0
	s_setprio 3
	v_mfma_f32_16x16x128_f8f6f4 v[84:87], v[8:15], v[184:191], v[84:87]
	v_mfma_f32_16x16x128_f8f6f4 v[80:83], v[0:7], v[184:191], v[80:83]
	v_mfma_f32_16x16x128_f8f6f4 v[68:71], v[8:15], v[200:207], v[68:71]
	v_mfma_f32_16x16x128_f8f6f4 v[64:67], v[0:7], v[200:207], v[64:67]
	v_mfma_f32_16x16x128_f8f6f4 v[52:55], v[8:15], v[208:215], v[52:55]
	v_mfma_f32_16x16x128_f8f6f4 v[48:51], v[0:7], v[208:215], v[48:51]
	v_mfma_f32_16x16x128_f8f6f4 v[36:39], v[8:15], v[218:225], v[36:39]
	v_mfma_f32_16x16x128_f8f6f4 v[32:35], v[0:7], v[218:225], v[32:35]
	s_setprio 0
	s_add_i32 s36, 0, 0x18000
	s_add_i32 s37, 0, 0x1c000
	v_add_u32_e32 v12, s36, v195
	v_add_u32_e32 v28, s37, v195
	ds_read_b128 v[0:3], v12
	ds_read_b128 v[4:7], v12 offset:1024
	ds_read_b128 v[8:11], v12 offset:2048
	ds_read_b128 v[12:15], v12 offset:3072
	ds_read_b128 v[16:19], v28
	ds_read_b128 v[20:23], v28 offset:1024
	ds_read_b128 v[24:27], v28 offset:2048
	ds_read_b128 v[28:31], v28 offset:3072
	s_add_u32 s24, s56, 0xb0000
	s_addc_u32 s25, s57, 0
	s_mov_b32 m0, s23
	v_lshl_add_u64 v[192:193], s[24:25], 0, v[160:161]
	ds_read_b128 v[184:187], v199 offset:32768
	ds_read_b128 v[188:191], v199 offset:33792
	ds_read_b128 v[200:203], v199 offset:34816
	ds_read_b128 v[204:207], v199 offset:35840
	ds_read_b128 v[208:211], v199 offset:36864
	ds_read_b128 v[212:215], v199 offset:37888
	ds_read_b128 v[218:221], v199 offset:38912
	ds_read_b128 v[222:225], v199 offset:39936
	global_load_lds_dwordx4 v[192:193], off
	v_lshl_add_u64 v[192:193], s[24:25], 0, v[164:165]
	s_mov_b32 m0, s26
	s_nop 0
	global_load_lds_dwordx4 v[192:193], off
	s_waitcnt vmcnt(8)
	s_waitcnt lgkmcnt(0)
	s_barrier
	s_setprio 3
	s_waitcnt lgkmcnt(0)
	v_mfma_f32_16x16x128_f8f6f4 v[156:159], v[0:7], v[184:191], v[156:159]
	v_mfma_f32_16x16x128_f8f6f4 v[152:155], v[8:15], v[184:191], v[152:155]
	v_mfma_f32_16x16x128_f8f6f4 v[140:143], v[0:7], v[200:207], v[140:143]
	v_mfma_f32_16x16x128_f8f6f4 v[136:139], v[8:15], v[200:207], v[136:139]
	v_mfma_f32_16x16x128_f8f6f4 v[124:127], v[0:7], v[208:215], v[124:127]
	v_mfma_f32_16x16x128_f8f6f4 v[120:123], v[8:15], v[208:215], v[120:123]
	v_mfma_f32_16x16x128_f8f6f4 v[108:111], v[0:7], v[218:225], v[108:111]
	v_mfma_f32_16x16x128_f8f6f4 v[104:107], v[8:15], v[218:225], v[104:107]
	s_setprio 0
	s_setprio 3
	v_mfma_f32_16x16x128_f8f6f4 v[148:151], v[16:23], v[184:191], v[148:151]
	v_mfma_f32_16x16x128_f8f6f4 v[144:147], v[24:31], v[184:191], v[144:147]
	v_mfma_f32_16x16x128_f8f6f4 v[132:135], v[16:23], v[200:207], v[132:135]
	v_mfma_f32_16x16x128_f8f6f4 v[128:131], v[24:31], v[200:207], v[128:131]
	v_mfma_f32_16x16x128_f8f6f4 v[116:119], v[16:23], v[208:215], v[116:119]
	v_mfma_f32_16x16x128_f8f6f4 v[112:115], v[24:31], v[208:215], v[112:115]
	v_mfma_f32_16x16x128_f8f6f4 v[100:103], v[16:23], v[218:225], v[100:103]
	v_mfma_f32_16x16x128_f8f6f4 v[96:99], v[24:31], v[218:225], v[96:99]
	s_setprio 0
	s_add_i32 s24, s36, s14
	v_lshl_add_u64 v[176:177], v[176:177], 0, s[12:13]
	s_mov_b32 m0, s24
	ds_read_b128 v[184:187], v199 offset:49152
	ds_read_b128 v[188:191], v199 offset:50176
	ds_read_b128 v[200:203], v199 offset:51200
	ds_read_b128 v[204:207], v199 offset:52224
	ds_read_b128 v[208:211], v199 offset:53248
	ds_read_b128 v[212:215], v199 offset:54272
	ds_read_b128 v[218:221], v199 offset:55296
	ds_read_b128 v[222:225], v199 offset:56320
	global_load_lds_dwordx4 v[176:177], off
	s_add_i32 m0, s24, 0x2000
	s_add_u32 s24, s54, 0xb0080
	v_lshl_add_u64 v[176:177], v[178:179], 0, s[12:13]
	s_addc_u32 s25, s55, 0
	s_add_i32 s36, s37, s14
	global_load_lds_dwordx4 v[176:177], off
	v_lshl_add_u64 v[176:177], s[24:25], 0, v[162:163]
	s_mov_b32 m0, s36
	s_nop 0
	global_load_lds_dwordx4 v[176:177], off
	v_lshl_add_u64 v[176:177], s[24:25], 0, v[166:167]
	s_add_i32 m0, s36, 0x2000
	s_nop 0
	global_load_lds_dwordx4 v[176:177], off
	v_lshl_add_u64 v[176:177], v[180:181], 0, s[12:13]
	s_mov_b32 m0, s33
	s_nop 0
	global_load_lds_dwordx4 v[176:177], off
	v_lshl_add_u64 v[176:177], v[182:183], 0, s[12:13]
	s_mov_b32 m0, s43
	s_nop 0
	global_load_lds_dwordx4 v[176:177], off
	s_waitcnt vmcnt(8)
	s_waitcnt lgkmcnt(0)
	s_barrier
	s_setprio 3
	s_waitcnt lgkmcnt(0)
	v_mfma_f32_16x16x128_f8f6f4 v[92:95], v[0:7], v[184:191], v[92:95]
	v_mfma_f32_16x16x128_f8f6f4 v[88:91], v[8:15], v[184:191], v[88:91]
	v_mfma_f32_16x16x128_f8f6f4 v[76:79], v[0:7], v[200:207], v[76:79]
	v_mfma_f32_16x16x128_f8f6f4 v[72:75], v[8:15], v[200:207], v[72:75]
	v_mfma_f32_16x16x128_f8f6f4 v[60:63], v[0:7], v[208:215], v[60:63]
	v_mfma_f32_16x16x128_f8f6f4 v[56:59], v[8:15], v[208:215], v[56:59]
	v_mfma_f32_16x16x128_f8f6f4 v[44:47], v[0:7], v[218:225], v[44:47]
	v_mfma_f32_16x16x128_f8f6f4 v[40:43], v[8:15], v[218:225], v[40:43]
	s_setprio 0
	s_setprio 3
	v_mfma_f32_16x16x128_f8f6f4 v[84:87], v[16:23], v[184:191], v[84:87]
	v_mfma_f32_16x16x128_f8f6f4 v[80:83], v[24:31], v[184:191], v[80:83]
	v_mfma_f32_16x16x128_f8f6f4 v[68:71], v[16:23], v[200:207], v[68:71]
	v_mfma_f32_16x16x128_f8f6f4 v[64:67], v[24:31], v[200:207], v[64:67]
	v_mfma_f32_16x16x128_f8f6f4 v[52:55], v[16:23], v[208:215], v[52:55]
	v_mfma_f32_16x16x128_f8f6f4 v[48:51], v[24:31], v[208:215], v[48:51]
	v_mfma_f32_16x16x128_f8f6f4 v[36:39], v[16:23], v[218:225], v[36:39]
	v_mfma_f32_16x16x128_f8f6f4 v[32:35], v[24:31], v[218:225], v[32:35]
	s_setprio 0
	s_add_i32 s67, s67, 2
	s_add_u32 s52, s52, 0x100
	s_addc_u32 s53, s53, 0
	s_add_u32 s65, s65, 0x100
	s_addc_u32 s66, s66, 0
	s_cmp_gt_u32 s67, 41
	s_cbranch_scc0 .Lk4_Y
; #define PG8_BAR __builtin_amdgcn_s_barrier()
;     __device__ __forceinline__ void operator()(const f32x4 (&acc)[2][2][4][2], const Unit& u, int wr, int wc, int fr, int fq) const {
;         const int row0 = u.pm * BM + wr * 64 + fr, col0 = u.pn * BM + wc * 32 + 8 * fq;
;         const float* gp = gate + (size_t)((u.pm * BM) >> 13) * gate_bstride + col0;
;         const float* mp = mul + (size_t)((u.pm * BM) >> 13) * ldc + col0;
;         f32x4 gv[2][2], iv[2][2];
; #pragma unroll
;         for (int bj = 0; bj < 2; ++bj)
; #pragma unroll
;             for (int n = 0; n < 2; ++n) { gv[bj][n] = *(const f32x4*)(gp + bj * HALF + 4 * n) * ascale; const f32x4 mq = *(const f32x4*)(mp + bj * HALF + 4 * n);
;                 iv[bj][n] = (f32x4){__builtin_amdgcn_rcpf(mq[0]), __builtin_amdgcn_rcpf(mq[1]), __builtin_amdgcn_rcpf(mq[2]), __builtin_amdgcn_rcpf(mq[3])}; }
; #pragma unroll
;         for (int ai = 0; ai < 2; ++ai) {
;             u32x4 bq[4][2];
; #pragma unroll
;             for (int m = 0; m < 4; ++m)
; #pragma unroll
; template <class Epi, class Sched, bool ALIGN_EPI = false, bool SP2 = false, bool F8 = false>
; __device__ __forceinline__ void gemm_phase(PG8_LAS unsigned char* lds, const Gemm g, const Sched& S, const Epi& E) {
;     ...
;         if constexpr (F8) {
;             asm volatile("s_nop 7\n\ts_nop 7\n\ts_nop 7" : "+v"(acc[0][0][0][0]), "+v"(acc[0][0][0][1]), "+v"(acc[0][0][1][0]), "+v"(acc[0][0][1][1]), "+v"(acc[0][0][2][0]), "+v"(acc[0][0][2][1]), "+v"(acc[0][0][3][0]), "+v"(acc[0][0][3][1]) :: "memory");
;             asm volatile("" : "+v"(acc[0][1][0][0]), "+v"(acc[0][1][0][1]), "+v"(acc[0][1][1][0]), "+v"(acc[0][1][1][1]), "+v"(acc[0][1][2][0]), "+v"(acc[0][1][2][1]), "+v"(acc[0][1][3][0]), "+v"(acc[0][1][3][1]));
;             asm volatile("" : "+v"(acc[1][0][0][0]), "+v"(acc[1][0][0][1]), "+v"(acc[1][0][1][0]), "+v"(acc[1][0][1][1]), "+v"(acc[1][0][2][0]), "+v"(acc[1][0][2][1]), "+v"(acc[1][0][3][0]), "+v"(acc[1][0][3][1]));
;             asm volatile("" : "+v"(acc[1][1][0][0]), "+v"(acc[1][1][0][1]), "+v"(acc[1][1][1][0]), "+v"(acc[1][1][1][1]), "+v"(acc[1][1][2][0]), "+v"(acc[1][1][2][1]), "+v"(acc[1][1][3][0]), "+v"(acc[1][1][3][1])); }
;         if constexpr (ALIGN_EPI) { if (wr == 0) PG8_BAR; }
;         if constexpr (!Epi::AFTER_DRAIN) { E(acc, cur, wr, wc, fr, fq); S.done(cur); }
.Lk4_exit:
	s_nop 7
	s_nop 7
	s_nop 7
	s_and_b64 vcc, exec, s[40:41]
	s_cbranch_vccz .LBB0_1003
.LBB0_1003:
	s_ashr_i32 s24, s63, 5
	v_lshl_or_b32 v0, s64, 8, v196
	s_ashr_i32 s25, s24, 31
	s_mul_i32 s37, s24, 0xc000
	s_mul_hi_i32 s36, s24, 0xc000
	s_add_u32 s52, s28, s37
	v_ashrrev_i32_e32 v1, 31, v0
	s_addc_u32 s53, s29, s36
	v_lshlrev_b64 v[2:3], 2, v[0:1]
	v_lshl_add_u64 v[4:5], s[52:53], 0, v[2:3]
	global_load_dwordx4 v[10:13], v[4:5], off offset:16
	global_load_dwordx4 v[14:17], v[4:5], off
	global_load_dwordx4 v[18:21], v[4:5], off offset:528
	global_load_dwordx4 v[22:25], v[4:5], off offset:512
	v_lshl_add_u32 v4, s63, 8, v194
	v_lshlrev_b64 v[8:9], 1, v[0:1]
	v_ashrrev_i32_e32 v5, 31, v4
	v_lshl_add_u64 v[186:187], s[30:31], 0, v[8:9]
	v_lshlrev_b64 v[188:189], 12, v[4:5]
	v_lshl_add_u64 v[0:1], v[186:187], 0, v[188:189]
	s_lshl_b64 s[24:25], s[24:25], 13
	global_load_dwordx4 v[178:181], v[0:1], off
	s_add_u32 s24, s34, s24
	s_addc_u32 s25, s35, s25
	v_lshl_add_u64 v[2:3], s[24:25], 0, v[2:3]
	global_load_dwordx4 v[200:203], v[2:3], off
	global_load_dwordx4 v[204:207], v[2:3], off offset:16
	global_load_dwordx4 v[208:211], v[2:3], off offset:512
	global_load_dwordx4 v[212:215], v[2:3], off offset:528
	global_load_dwordx4 v[218:221], v[0:1], off offset:256
	v_or_b32_e32 v0, 16, v4
	v_ashrrev_i32_e32 v1, 31, v0
	v_lshlrev_b64 v[238:239], 12, v[0:1]
	v_lshl_add_u64 v[0:1], v[186:187], 0, v[238:239]
	global_load_dwordx4 v[222:225], v[0:1], off
	v_or_b32_e32 v2, 32, v4
	v_or_b32_e32 v4, 48, v4
	v_ashrrev_i32_e32 v3, 31, v2
	v_ashrrev_i32_e32 v5, 31, v4
	v_lshlrev_b64 v[192:193], 12, v[2:3]
	v_lshlrev_b64 v[190:191], 12, v[4:5]
	v_lshl_add_u64 v[2:3], v[186:187], 0, v[192:193]
	v_lshl_add_u64 v[26:27], v[186:187], 0, v[190:191]
	global_load_dwordx4 v[226:229], v[0:1], off offset:256
	global_load_dwordx4 v[230:233], v[2:3], off
	global_load_dwordx4 v[234:237], v[2:3], off offset:256
	global_load_dwordx4 v[4:7], v[26:27], off
	s_nop 0
	global_load_dwordx4 v[0:3], v[26:27], off offset:256
	v_lshl_add_u64 v[240:241], s[30:31], 0, v[188:189]
	s_and_b64 vcc, exec, s[4:5]
	s_mov_b64 s[4:5], -1
	s_waitcnt vmcnt(0)
	v_pk_mul_f32 v[26:27], v[12:13], s[42:43] op_sel_hi:[1,0]
	v_pk_mul_f32 v[30:31], v[16:17], s[42:43] op_sel_hi:[1,0]
	v_pk_mul_f32 v[176:177], v[14:15], s[42:43] op_sel_hi:[1,0]
	v_pk_mul_f32 v[28:29], v[10:11], s[42:43] op_sel_hi:[1,0]
	v_pk_mul_f32 v[14:15], v[24:25], s[42:43] op_sel_hi:[1,0]
	v_pk_mul_f32 v[16:17], v[22:23], s[42:43] op_sel_hi:[1,0]
	v_pk_mul_f32 v[10:11], v[20:21], s[42:43] op_sel_hi:[1,0]
	v_pk_mul_f32 v[12:13], v[18:19], s[42:43] op_sel_hi:[1,0]
	v_lshlrev_b32_e32 v242, 16, v178
	v_and_b32_e32 v243, 0xffff0000, v178
	v_lshlrev_b32_e32 v244, 16, v179
	v_and_b32_e32 v245, 0xffff0000, v179
	v_lshlrev_b32_e32 v246, 16, v180
	v_and_b32_e32 v247, 0xffff0000, v180
	v_lshlrev_b32_e32 v248, 16, v181
	v_and_b32_e32 v249, 0xffff0000, v181
	v_rcp_f32_e32 v184, v200
	v_rcp_f32_e32 v185, v201
	v_rcp_f32_e32 v180, v204
	v_rcp_f32_e32 v181, v205
	v_rcp_f32_e32 v178, v206
	v_rcp_f32_e32 v179, v207
	v_rcp_f32_e32 v182, v202
	v_rcp_f32_e32 v183, v203
	v_rcp_f32_e32 v24, v208
	v_rcp_f32_e32 v25, v209
	v_rcp_f32_e32 v22, v210
	v_rcp_f32_e32 v23, v211
	v_pk_mul_f32 v[200:201], v[184:185], v[242:243]
	v_pk_mul_f32 v[204:205], v[180:181], v[246:247]
	v_pk_mul_f32 v[206:207], v[178:179], v[248:249]
	v_rcp_f32_e32 v20, v212
	v_rcp_f32_e32 v21, v213
	v_rcp_f32_e32 v18, v214
	v_rcp_f32_e32 v19, v215
	v_pk_mul_f32 v[202:203], v[182:183], v[244:245]
	v_pk_fma_f32 v[156:157], v[156:157], v[176:177], v[200:201]
	v_pk_fma_f32 v[200:201], v[154:155], v[26:27], v[206:207]
	v_pk_fma_f32 v[154:155], v[152:153], v[28:29], v[204:205]
	v_pk_fma_f32 v[158:159], v[158:159], v[30:31], v[202:203]
	v_cvt_pk_bf16_f32 v152, v156, v157
	v_lshl_add_u64 v[156:157], v[240:241], 0, v[8:9]
	v_cvt_pk_bf16_f32 v153, v158, v159
	v_cvt_pk_bf16_f32 v154, v154, v155
	v_cvt_pk_bf16_f32 v155, v200, v201
	global_store_dwordx4 v[156:157], v[152:155], off
	v_lshlrev_b32_e32 v158, 16, v220
	v_and_b32_e32 v159, 0xffff0000, v220
	v_lshlrev_b32_e32 v152, 16, v218
	v_and_b32_e32 v153, 0xffff0000, v218
	v_lshlrev_b32_e32 v154, 16, v219
	v_and_b32_e32 v155, 0xffff0000, v219
	v_lshlrev_b32_e32 v200, 16, v221
	v_and_b32_e32 v201, 0xffff0000, v221
	v_pk_mul_f32 v[152:153], v[24:25], v[152:153]
	v_pk_mul_f32 v[154:155], v[22:23], v[154:155]
	v_pk_fma_f32 v[148:149], v[148:149], v[16:17], v[152:153]
	v_pk_fma_f32 v[150:151], v[150:151], v[14:15], v[154:155]
	v_pk_mul_f32 v[152:153], v[20:21], v[158:159]
	v_pk_mul_f32 v[154:155], v[18:19], v[200:201]
	s_nop 0
	v_pk_fma_f32 v[154:155], v[146:147], v[10:11], v[154:155]
	v_pk_fma_f32 v[146:147], v[144:145], v[12:13], v[152:153]
	v_cvt_pk_bf16_f32 v144, v148, v149
	v_cvt_pk_bf16_f32 v145, v150, v151
	v_lshlrev_b32_e32 v148, 16, v224
	v_cvt_pk_bf16_f32 v146, v146, v147
	v_cvt_pk_bf16_f32 v147, v154, v155
	global_store_dwordx4 v[156:157], v[144:147], off offset:256
	v_and_b32_e32 v149, 0xffff0000, v224
	v_lshlrev_b32_e32 v150, 16, v225
	v_lshlrev_b32_e32 v144, 16, v222
	v_and_b32_e32 v145, 0xffff0000, v222
	v_lshlrev_b32_e32 v146, 16, v223
	v_and_b32_e32 v147, 0xffff0000, v223
	v_and_b32_e32 v151, 0xffff0000, v225
	v_pk_mul_f32 v[144:145], v[184:185], v[144:145]
	v_pk_mul_f32 v[146:147], v[182:183], v[146:147]
	v_pk_fma_f32 v[140:141], v[140:141], v[176:177], v[144:145]
	v_pk_fma_f32 v[142:143], v[142:143], v[30:31], v[146:147]
	v_pk_mul_f32 v[144:145], v[180:181], v[148:149]
	v_pk_mul_f32 v[146:147], v[178:179], v[150:151]
	s_nop 0
	v_pk_fma_f32 v[146:147], v[138:139], v[26:27], v[146:147]
	v_pk_fma_f32 v[138:139], v[136:137], v[28:29], v[144:145]
; __device__ __forceinline__ unsigned cvt_pk_bf16(float lo, float hi) { unsigned r; asm volatile("v_cvt_pk_bf16_f32 %0, %1, %2" : "=v"(r) : "v"(lo), "v"(hi)); return r; }
;     __device__ __forceinline__ void operator()(const f32x4 (&acc)[2][2][4][2], const Unit& u, int wr, int wc, int fr, int fq) const {
;     ...
;         for (int ai = 0; ai < 2; ++ai) {
;             u32x4 bq[4][2];
; #pragma unroll
;             for (int m = 0; m < 4; ++m)
; #pragma unroll
;                 for (int bj = 0; bj < 2; ++bj) bq[m][bj] = *(const u32x4*)(base + (size_t)(row0 + ai * HALF + m * 16) * ldc + col0 + bj * HALF);
;             asm volatile("" ::: "memory");
; #pragma unroll
;             for (int m = 0; m < 4; ++m) { const size_t off = (size_t)(row0 + ai * HALF + m * 16) * ldc + col0;
; #pragma unroll
;                 for (int bj = 0; bj < 2; ++bj) { const u32x4 q = bq[m][bj];
;                     const f32x4 b0 = (f32x4){__builtin_bit_cast(float, q.x << 16), __builtin_bit_cast(float, q.x & 0xffff0000u), __builtin_bit_cast(float, q.y << 16), __builtin_bit_cast(float, q.y & 0xffff0000u)};
;                     const f32x4 b1 = (f32x4){__builtin_bit_cast(float, q.z << 16), __builtin_bit_cast(float, q.z & 0xffff0000u), __builtin_bit_cast(float, q.w << 16), __builtin_bit_cast(float, q.w & 0xffff0000u)};
;                     const f32x4 o0 = b0 * iv[bj][0] + gv[bj][0] * acc[ai][bj][m][0], o1 = b1 * iv[bj][1] + gv[bj][1] * acc[ai][bj][m][1];
;                     u32x4 w; w.x = cvt_pk_bf16(o0[0], o0[1]); w.y = cvt_pk_bf16(o0[2], o0[3]); w.z = cvt_pk_bf16(o1[0], o1[1]); w.w = cvt_pk_bf16(o1[2], o1[3]);
;                     *(u32x4*)(out + off + bj * HALF) = w; } }
	v_cvt_pk_bf16_f32 v136, v140, v141
	v_lshl_add_u64 v[140:141], s[30:31], 0, v[238:239]
	v_cvt_pk_bf16_f32 v137, v142, v143
	v_cvt_pk_bf16_f32 v138, v138, v139
	v_cvt_pk_bf16_f32 v139, v146, v147
	v_lshl_add_u64 v[140:141], v[140:141], 0, v[8:9]
	global_store_dwordx4 v[140:141], v[136:139], off
	v_lshlrev_b32_e32 v142, 16, v228
	v_and_b32_e32 v143, 0xffff0000, v228
	v_lshlrev_b32_e32 v136, 16, v226
	v_and_b32_e32 v137, 0xffff0000, v226
	v_lshlrev_b32_e32 v138, 16, v227
	v_and_b32_e32 v139, 0xffff0000, v227
	v_lshlrev_b32_e32 v144, 16, v229
	v_and_b32_e32 v145, 0xffff0000, v229
	v_pk_mul_f32 v[136:137], v[24:25], v[136:137]
	v_pk_mul_f32 v[138:139], v[22:23], v[138:139]
	v_pk_fma_f32 v[132:133], v[132:133], v[16:17], v[136:137]
	v_pk_fma_f32 v[134:135], v[134:135], v[14:15], v[138:139]
	v_pk_mul_f32 v[136:137], v[20:21], v[142:143]
	v_pk_mul_f32 v[138:139], v[18:19], v[144:145]
	s_nop 0
	v_pk_fma_f32 v[138:139], v[130:131], v[10:11], v[138:139]
	v_pk_fma_f32 v[130:131], v[128:129], v[12:13], v[136:137]
	v_cvt_pk_bf16_f32 v128, v132, v133
	v_cvt_pk_bf16_f32 v129, v134, v135
	v_lshlrev_b32_e32 v132, 16, v232
	v_cvt_pk_bf16_f32 v130, v130, v131
	v_cvt_pk_bf16_f32 v131, v138, v139
	global_store_dwordx4 v[140:141], v[128:131], off offset:256
	v_and_b32_e32 v133, 0xffff0000, v232
	v_lshlrev_b32_e32 v134, 16, v233
	v_lshlrev_b32_e32 v128, 16, v230
	v_and_b32_e32 v129, 0xffff0000, v230
	v_lshlrev_b32_e32 v130, 16, v231
	v_and_b32_e32 v131, 0xffff0000, v231
	v_and_b32_e32 v135, 0xffff0000, v233
	v_pk_mul_f32 v[128:129], v[184:185], v[128:129]
	v_pk_mul_f32 v[130:131], v[182:183], v[130:131]
	v_pk_fma_f32 v[124:125], v[124:125], v[176:177], v[128:129]
	v_pk_fma_f32 v[126:127], v[126:127], v[30:31], v[130:131]
	v_pk_mul_f32 v[128:129], v[180:181], v[132:133]
	v_pk_mul_f32 v[130:131], v[178:179], v[134:135]
	s_nop 0
	v_pk_fma_f32 v[130:131], v[122:123], v[26:27], v[130:131]
	v_pk_fma_f32 v[122:123], v[120:121], v[28:29], v[128:129]
	v_cvt_pk_bf16_f32 v120, v124, v125
	v_lshl_add_u64 v[124:125], s[30:31], 0, v[192:193]
	v_cvt_pk_bf16_f32 v121, v126, v127
	v_cvt_pk_bf16_f32 v122, v122, v123
	v_cvt_pk_bf16_f32 v123, v130, v131
	v_lshl_add_u64 v[124:125], v[124:125], 0, v[8:9]
	global_store_dwordx4 v[124:125], v[120:123], off
	v_lshlrev_b32_e32 v126, 16, v236
	v_and_b32_e32 v127, 0xffff0000, v236
	v_lshlrev_b32_e32 v120, 16, v234
	v_and_b32_e32 v121, 0xffff0000, v234
	v_lshlrev_b32_e32 v122, 16, v235
	v_and_b32_e32 v123, 0xffff0000, v235
	v_lshlrev_b32_e32 v128, 16, v237
	v_and_b32_e32 v129, 0xffff0000, v237
	v_pk_mul_f32 v[120:121], v[24:25], v[120:121]
	v_pk_mul_f32 v[122:123], v[22:23], v[122:123]
	v_pk_fma_f32 v[116:117], v[116:117], v[16:17], v[120:121]
	v_pk_fma_f32 v[118:119], v[118:119], v[14:15], v[122:123]
	v_pk_mul_f32 v[120:121], v[20:21], v[126:127]
	v_pk_mul_f32 v[122:123], v[18:19], v[128:129]
	v_lshl_add_u64 v[126:127], v[188:189], 0, s[48:49]
	v_pk_fma_f32 v[122:123], v[114:115], v[10:11], v[122:123]
	v_pk_fma_f32 v[114:115], v[112:113], v[12:13], v[120:121]
	v_cvt_pk_bf16_f32 v112, v116, v117
	v_cvt_pk_bf16_f32 v113, v118, v119
	s_nop 0
	v_cvt_pk_bf16_f32 v114, v114, v115
	v_cvt_pk_bf16_f32 v115, v122, v123
	global_store_dwordx4 v[124:125], v[112:115], off offset:256
	v_lshl_add_u64 v[122:123], v[188:189], 0, s[44:45]
	v_lshl_add_u64 v[124:125], v[188:189], 0, s[46:47]
	v_lshlrev_b32_e32 v112, 16, v4
	v_and_b32_e32 v113, 0xffff0000, v4
	v_lshlrev_b32_e32 v4, 16, v5
	v_and_b32_e32 v5, 0xffff0000, v5
	v_lshlrev_b32_e32 v114, 16, v6
	v_and_b32_e32 v115, 0xffff0000, v6
	v_lshlrev_b32_e32 v6, 16, v7
	v_and_b32_e32 v7, 0xffff0000, v7
	v_pk_mul_f32 v[112:113], v[184:185], v[112:113]
	v_pk_mul_f32 v[4:5], v[182:183], v[4:5]
	v_pk_mul_f32 v[6:7], v[178:179], v[6:7]
	v_pk_fma_f32 v[110:111], v[110:111], v[30:31], v[4:5]
	v_pk_fma_f32 v[4:5], v[108:109], v[176:177], v[112:113]
	v_pk_mul_f32 v[108:109], v[180:181], v[114:115]
	v_pk_fma_f32 v[106:107], v[106:107], v[26:27], v[6:7]
	v_pk_fma_f32 v[6:7], v[104:105], v[28:29], v[108:109]
	v_lshl_add_u64 v[104:105], s[30:31], 0, v[190:191]
	v_cvt_pk_bf16_f32 v4, v4, v5
	v_cvt_pk_bf16_f32 v5, v110, v111
	v_lshl_add_u64 v[104:105], v[104:105], 0, v[8:9]
	v_cvt_pk_bf16_f32 v6, v6, v7
	v_cvt_pk_bf16_f32 v7, v106, v107
	global_store_dwordx4 v[104:105], v[4:7], off
	s_nop 1
	v_lshlrev_b32_e32 v4, 16, v0
	v_and_b32_e32 v5, 0xffff0000, v0
	v_lshlrev_b32_e32 v0, 16, v1
	v_and_b32_e32 v1, 0xffff0000, v1
	v_lshlrev_b32_e32 v6, 16, v2
	v_and_b32_e32 v7, 0xffff0000, v2
	v_lshlrev_b32_e32 v2, 16, v3
	v_and_b32_e32 v3, 0xffff0000, v3
	v_pk_mul_f32 v[4:5], v[24:25], v[4:5]
	v_pk_mul_f32 v[0:1], v[22:23], v[0:1]
	v_pk_mul_f32 v[2:3], v[18:19], v[2:3]
	v_pk_fma_f32 v[102:103], v[102:103], v[14:15], v[0:1]
	v_pk_fma_f32 v[0:1], v[100:101], v[16:17], v[4:5]
	v_pk_mul_f32 v[4:5], v[20:21], v[6:7]
	v_pk_fma_f32 v[6:7], v[98:99], v[10:11], v[2:3]
	v_pk_fma_f32 v[2:3], v[96:97], v[12:13], v[4:5]
	v_cvt_pk_bf16_f32 v0, v0, v1
	v_cvt_pk_bf16_f32 v1, v102, v103
	v_lshl_add_u64 v[96:97], v[188:189], 0, s[8:9]
	v_cvt_pk_bf16_f32 v2, v2, v3
	v_cvt_pk_bf16_f32 v3, v6, v7
	global_store_dwordx4 v[104:105], v[0:3], off offset:256
	s_nop 1
	v_lshl_add_u64 v[0:1], v[186:187], 0, v[122:123]
	global_load_dwordx4 v[98:101], v[0:1], off
	global_load_dwordx4 v[102:105], v[0:1], off offset:256
	v_lshl_add_u64 v[0:1], v[186:187], 0, v[124:125]
	global_load_dwordx4 v[106:109], v[0:1], off
	global_load_dwordx4 v[110:113], v[0:1], off offset:256
	v_lshl_add_u64 v[0:1], v[186:187], 0, v[126:127]
	global_load_dwordx4 v[114:117], v[0:1], off
	global_load_dwordx4 v[118:121], v[0:1], off offset:256
	v_lshl_add_u64 v[0:1], v[186:187], 0, v[96:97]
	global_load_dwordx4 v[4:7], v[0:1], off
	s_nop 0
	global_load_dwordx4 v[0:3], v[0:1], off offset:256
	s_waitcnt vmcnt(7)
; __device__ __forceinline__ unsigned cvt_pk_bf16(float lo, float hi) { unsigned r; asm volatile("v_cvt_pk_bf16_f32 %0, %1, %2" : "=v"(r) : "v"(lo), "v"(hi)); return r; }
;     __device__ __forceinline__ void operator()(const f32x4 (&acc)[2][2][4][2], const Unit& u, int wr, int wc, int fr, int fq) const {
;     ...
;         for (int ai = 0; ai < 2; ++ai) {
;             u32x4 bq[4][2];
; #pragma unroll
;             for (int m = 0; m < 4; ++m)
; #pragma unroll
;                 for (int bj = 0; bj < 2; ++bj) bq[m][bj] = *(const u32x4*)(base + (size_t)(row0 + ai * HALF + m * 16) * ldc + col0 + bj * HALF);
;             asm volatile("" ::: "memory");
; #pragma unroll
;             for (int m = 0; m < 4; ++m) { const size_t off = (size_t)(row0 + ai * HALF + m * 16) * ldc + col0;
; #pragma unroll
;                 for (int bj = 0; bj < 2; ++bj) { const u32x4 q = bq[m][bj];
;                     const f32x4 b0 = (f32x4){__builtin_bit_cast(float, q.x << 16), __builtin_bit_cast(float, q.x & 0xffff0000u), __builtin_bit_cast(float, q.y << 16), __builtin_bit_cast(float, q.y & 0xffff0000u)};
;                     const f32x4 b1 = (f32x4){__builtin_bit_cast(float, q.z << 16), __builtin_bit_cast(float, q.z & 0xffff0000u), __builtin_bit_cast(float, q.w << 16), __builtin_bit_cast(float, q.w & 0xffff0000u)};
;                     const f32x4 o0 = b0 * iv[bj][0] + gv[bj][0] * acc[ai][bj][m][0], o1 = b1 * iv[bj][1] + gv[bj][1] * acc[ai][bj][m][1];
;                     u32x4 w; w.x = cvt_pk_bf16(o0[0], o0[1]); w.y = cvt_pk_bf16(o0[2], o0[3]); w.z = cvt_pk_bf16(o1[0], o1[1]); w.w = cvt_pk_bf16(o1[2], o1[3]);
;                     *(u32x4*)(out + off + bj * HALF) = w; } }
	v_lshlrev_b32_e32 v128, 16, v98
	v_and_b32_e32 v129, 0xffff0000, v98
	v_lshlrev_b32_e32 v98, 16, v99
	v_and_b32_e32 v99, 0xffff0000, v99
	v_lshlrev_b32_e32 v130, 16, v100
	v_and_b32_e32 v131, 0xffff0000, v100
	v_lshlrev_b32_e32 v100, 16, v101
	v_and_b32_e32 v101, 0xffff0000, v101
	v_pk_mul_f32 v[128:129], v[184:185], v[128:129]
	v_pk_mul_f32 v[98:99], v[182:183], v[98:99]
	v_pk_fma_f32 v[92:93], v[92:93], v[176:177], v[128:129]
	v_pk_fma_f32 v[94:95], v[94:95], v[30:31], v[98:99]
	v_pk_mul_f32 v[98:99], v[180:181], v[130:131]
	v_pk_mul_f32 v[100:101], v[178:179], v[100:101]
	s_nop 0
	v_pk_fma_f32 v[100:101], v[90:91], v[26:27], v[100:101]
	v_pk_fma_f32 v[90:91], v[88:89], v[28:29], v[98:99]
	v_cvt_pk_bf16_f32 v88, v92, v93
	v_lshl_add_u64 v[92:93], s[30:31], 0, v[122:123]
	v_cvt_pk_bf16_f32 v89, v94, v95
	v_cvt_pk_bf16_f32 v90, v90, v91
	v_cvt_pk_bf16_f32 v91, v100, v101
	v_lshl_add_u64 v[92:93], v[92:93], 0, v[8:9]
	global_store_dwordx4 v[92:93], v[88:91], off
	s_waitcnt vmcnt(7)
	v_lshlrev_b32_e32 v94, 16, v104
	v_and_b32_e32 v95, 0xffff0000, v104
	v_lshlrev_b32_e32 v88, 16, v102
	v_and_b32_e32 v89, 0xffff0000, v102
	v_lshlrev_b32_e32 v90, 16, v103
	v_and_b32_e32 v91, 0xffff0000, v103
	v_lshlrev_b32_e32 v98, 16, v105
	v_and_b32_e32 v99, 0xffff0000, v105
	v_pk_mul_f32 v[88:89], v[24:25], v[88:89]
	v_pk_mul_f32 v[90:91], v[22:23], v[90:91]
	v_pk_fma_f32 v[84:85], v[84:85], v[16:17], v[88:89]
	v_pk_fma_f32 v[86:87], v[86:87], v[14:15], v[90:91]
	v_pk_mul_f32 v[88:89], v[20:21], v[94:95]
	v_pk_mul_f32 v[90:91], v[18:19], v[98:99]
	s_nop 0
	v_pk_fma_f32 v[90:91], v[82:83], v[10:11], v[90:91]
	v_pk_fma_f32 v[82:83], v[80:81], v[12:13], v[88:89]
	v_cvt_pk_bf16_f32 v80, v84, v85
	v_cvt_pk_bf16_f32 v81, v86, v87
	s_waitcnt vmcnt(6)
	v_lshlrev_b32_e32 v84, 16, v108
	v_cvt_pk_bf16_f32 v82, v82, v83
	v_cvt_pk_bf16_f32 v83, v90, v91
	global_store_dwordx4 v[92:93], v[80:83], off offset:256
	v_and_b32_e32 v85, 0xffff0000, v108
	v_lshlrev_b32_e32 v86, 16, v109
	v_lshlrev_b32_e32 v80, 16, v106
	v_and_b32_e32 v81, 0xffff0000, v106
	v_lshlrev_b32_e32 v82, 16, v107
	v_and_b32_e32 v83, 0xffff0000, v107
	v_and_b32_e32 v87, 0xffff0000, v109
	v_pk_mul_f32 v[80:81], v[184:185], v[80:81]
	v_pk_mul_f32 v[82:83], v[182:183], v[82:83]
	v_pk_fma_f32 v[76:77], v[76:77], v[176:177], v[80:81]
	v_pk_fma_f32 v[78:79], v[78:79], v[30:31], v[82:83]
	v_pk_mul_f32 v[80:81], v[180:181], v[84:85]
	v_pk_mul_f32 v[82:83], v[178:179], v[86:87]
	s_nop 0
	v_pk_fma_f32 v[82:83], v[74:75], v[26:27], v[82:83]
	v_pk_fma_f32 v[74:75], v[72:73], v[28:29], v[80:81]
	v_cvt_pk_bf16_f32 v72, v76, v77
	v_lshl_add_u64 v[76:77], s[30:31], 0, v[124:125]
	v_cvt_pk_bf16_f32 v73, v78, v79
	v_cvt_pk_bf16_f32 v74, v74, v75
	v_cvt_pk_bf16_f32 v75, v82, v83
	v_lshl_add_u64 v[76:77], v[76:77], 0, v[8:9]
	global_store_dwordx4 v[76:77], v[72:75], off
	s_waitcnt vmcnt(7)
	v_lshlrev_b32_e32 v78, 16, v112
	v_and_b32_e32 v79, 0xffff0000, v112
	v_lshlrev_b32_e32 v72, 16, v110
	v_and_b32_e32 v73, 0xffff0000, v110
	v_lshlrev_b32_e32 v74, 16, v111
	v_and_b32_e32 v75, 0xffff0000, v111
	v_lshlrev_b32_e32 v80, 16, v113
	v_and_b32_e32 v81, 0xffff0000, v113
	v_pk_mul_f32 v[72:73], v[24:25], v[72:73]
	v_pk_mul_f32 v[74:75], v[22:23], v[74:75]
	v_pk_fma_f32 v[68:69], v[68:69], v[16:17], v[72:73]
	v_pk_fma_f32 v[70:71], v[70:71], v[14:15], v[74:75]
	v_pk_mul_f32 v[72:73], v[20:21], v[78:79]
	v_pk_mul_f32 v[74:75], v[18:19], v[80:81]
	s_nop 0
	v_pk_fma_f32 v[74:75], v[66:67], v[10:11], v[74:75]
	v_pk_fma_f32 v[66:67], v[64:65], v[12:13], v[72:73]
	v_cvt_pk_bf16_f32 v64, v68, v69
	v_cvt_pk_bf16_f32 v65, v70, v71
	s_waitcnt vmcnt(6)
; __device__ __forceinline__ unsigned cvt_pk_bf16(float lo, float hi) { unsigned r; asm volatile("v_cvt_pk_bf16_f32 %0, %1, %2" : "=v"(r) : "v"(lo), "v"(hi)); return r; }
; #define PG8_BAR __builtin_amdgcn_s_barrier()
;     __device__ __forceinline__ void operator()(const f32x4 (&acc)[2][2][4][2], const Unit& u, int wr, int wc, int fr, int fq) const {
;     ...
;         for (int ai = 0; ai < 2; ++ai) {
;             u32x4 bq[4][2];
; #pragma unroll
;             for (int m = 0; m < 4; ++m)
; #pragma unroll
;                 for (int bj = 0; bj < 2; ++bj) bq[m][bj] = *(const u32x4*)(base + (size_t)(row0 + ai * HALF + m * 16) * ldc + col0 + bj * HALF);
;             asm volatile("" ::: "memory");
; #pragma unroll
;             for (int m = 0; m < 4; ++m) { const size_t off = (size_t)(row0 + ai * HALF + m * 16) * ldc + col0;
; #pragma unroll
;                 for (int bj = 0; bj < 2; ++bj) { const u32x4 q = bq[m][bj];
;                     const f32x4 b0 = (f32x4){__builtin_bit_cast(float, q.x << 16), __builtin_bit_cast(float, q.x & 0xffff0000u), __builtin_bit_cast(float, q.y << 16), __builtin_bit_cast(float, q.y & 0xffff0000u)};
;                     const f32x4 b1 = (f32x4){__builtin_bit_cast(float, q.z << 16), __builtin_bit_cast(float, q.z & 0xffff0000u), __builtin_bit_cast(float, q.w << 16), __builtin_bit_cast(float, q.w & 0xffff0000u)};
;                     const f32x4 o0 = b0 * iv[bj][0] + gv[bj][0] * acc[ai][bj][m][0], o1 = b1 * iv[bj][1] + gv[bj][1] * acc[ai][bj][m][1];
;                     u32x4 w; w.x = cvt_pk_bf16(o0[0], o0[1]); w.y = cvt_pk_bf16(o0[2], o0[3]); w.z = cvt_pk_bf16(o1[0], o1[1]); w.w = cvt_pk_bf16(o1[2], o1[3]);
;                     *(u32x4*)(out + off + bj * HALF) = w; } }
; template <class Epi, class Sched, bool ALIGN_EPI = false, bool SP2 = false, bool F8 = false>
; __device__ __forceinline__ void gemm_phase(PG8_LAS unsigned char* lds, const Gemm g, const Sched& S, const Epi& E) {
;     ...
;         if (!has_next) break;
; #pragma unroll
;         for (int a = 0; a < 2; ++a)
; #pragma unroll
;             for (int b = 0; b < 2; ++b)
; #pragma unroll
;                 for (int m = 0; m < 4; ++m)
; #pragma unroll
;                     for (int n = 0; n < 2; ++n) acc[a][b][m][n] = (f32x4){0.f, 0.f, 0.f, 0.f};
;         cur = nxt; cA = nA; cB = nB; ++ui;
;         if constexpr (ALIGN_EPI) { if (wr == 1) PG8_BAR; }
;     }
	v_lshlrev_b32_e32 v68, 16, v116
	v_cvt_pk_bf16_f32 v66, v66, v67
	v_cvt_pk_bf16_f32 v67, v74, v75
	global_store_dwordx4 v[76:77], v[64:67], off offset:256
	v_and_b32_e32 v69, 0xffff0000, v116
	v_lshlrev_b32_e32 v70, 16, v117
	v_lshlrev_b32_e32 v64, 16, v114
	v_and_b32_e32 v65, 0xffff0000, v114
	v_lshlrev_b32_e32 v66, 16, v115
	v_and_b32_e32 v67, 0xffff0000, v115
	v_and_b32_e32 v71, 0xffff0000, v117
	v_pk_mul_f32 v[64:65], v[184:185], v[64:65]
	v_pk_mul_f32 v[66:67], v[182:183], v[66:67]
	v_pk_fma_f32 v[60:61], v[60:61], v[176:177], v[64:65]
	v_pk_fma_f32 v[62:63], v[62:63], v[30:31], v[66:67]
	v_pk_mul_f32 v[64:65], v[180:181], v[68:69]
	v_pk_mul_f32 v[66:67], v[178:179], v[70:71]
	s_nop 0
	v_pk_fma_f32 v[66:67], v[58:59], v[26:27], v[66:67]
	v_pk_fma_f32 v[58:59], v[56:57], v[28:29], v[64:65]
	v_cvt_pk_bf16_f32 v56, v60, v61
	v_lshl_add_u64 v[60:61], s[30:31], 0, v[126:127]
	v_cvt_pk_bf16_f32 v57, v62, v63
	v_cvt_pk_bf16_f32 v58, v58, v59
	v_cvt_pk_bf16_f32 v59, v66, v67
	v_lshl_add_u64 v[60:61], v[60:61], 0, v[8:9]
	global_store_dwordx4 v[60:61], v[56:59], off
	s_waitcnt vmcnt(7)
	v_lshlrev_b32_e32 v62, 16, v120
	v_and_b32_e32 v63, 0xffff0000, v120
	v_lshlrev_b32_e32 v56, 16, v118
	v_and_b32_e32 v57, 0xffff0000, v118
	v_lshlrev_b32_e32 v58, 16, v119
	v_and_b32_e32 v59, 0xffff0000, v119
	v_lshlrev_b32_e32 v64, 16, v121
	v_and_b32_e32 v65, 0xffff0000, v121
	v_pk_mul_f32 v[56:57], v[24:25], v[56:57]
	v_pk_mul_f32 v[58:59], v[22:23], v[58:59]
	v_pk_fma_f32 v[52:53], v[52:53], v[16:17], v[56:57]
	v_pk_fma_f32 v[54:55], v[54:55], v[14:15], v[58:59]
	v_pk_mul_f32 v[56:57], v[20:21], v[62:63]
	v_pk_mul_f32 v[58:59], v[18:19], v[64:65]
	s_nop 0
	v_pk_fma_f32 v[58:59], v[50:51], v[10:11], v[58:59]
	v_pk_fma_f32 v[50:51], v[48:49], v[12:13], v[56:57]
	v_cvt_pk_bf16_f32 v48, v52, v53
	v_cvt_pk_bf16_f32 v49, v54, v55
	s_nop 0
	v_cvt_pk_bf16_f32 v50, v50, v51
	v_cvt_pk_bf16_f32 v51, v58, v59
	global_store_dwordx4 v[60:61], v[48:51], off offset:256
	s_waitcnt vmcnt(7)
	s_nop 0
	v_lshlrev_b32_e32 v48, 16, v4
	v_and_b32_e32 v49, 0xffff0000, v4
	v_lshlrev_b32_e32 v4, 16, v5
	v_and_b32_e32 v5, 0xffff0000, v5
	v_lshlrev_b32_e32 v50, 16, v6
	v_and_b32_e32 v51, 0xffff0000, v6
	v_lshlrev_b32_e32 v6, 16, v7
	v_and_b32_e32 v7, 0xffff0000, v7
	v_pk_mul_f32 v[48:49], v[184:185], v[48:49]
	v_pk_mul_f32 v[4:5], v[182:183], v[4:5]
	v_pk_mul_f32 v[6:7], v[178:179], v[6:7]
	v_pk_fma_f32 v[30:31], v[46:47], v[30:31], v[4:5]
	v_pk_fma_f32 v[4:5], v[44:45], v[176:177], v[48:49]
	v_pk_mul_f32 v[44:45], v[180:181], v[50:51]
	v_pk_fma_f32 v[26:27], v[42:43], v[26:27], v[6:7]
	v_pk_fma_f32 v[6:7], v[40:41], v[28:29], v[44:45]
	v_cvt_pk_bf16_f32 v4, v4, v5
	v_cvt_pk_bf16_f32 v5, v30, v31
	s_nop 0
	v_cvt_pk_bf16_f32 v6, v6, v7
	v_cvt_pk_bf16_f32 v7, v26, v27
	v_lshl_add_u64 v[26:27], s[30:31], 0, v[96:97]
	v_lshl_add_u64 v[8:9], v[26:27], 0, v[8:9]
	global_store_dwordx4 v[8:9], v[4:7], off
	s_waitcnt vmcnt(7)
	s_nop 0
	v_lshlrev_b32_e32 v4, 16, v0
	v_and_b32_e32 v5, 0xffff0000, v0
	v_lshlrev_b32_e32 v0, 16, v1
	v_and_b32_e32 v1, 0xffff0000, v1
	v_lshlrev_b32_e32 v6, 16, v2
	v_and_b32_e32 v7, 0xffff0000, v2
	v_lshlrev_b32_e32 v2, 16, v3
	v_and_b32_e32 v3, 0xffff0000, v3
	v_pk_mul_f32 v[4:5], v[24:25], v[4:5]
	v_pk_mul_f32 v[0:1], v[22:23], v[0:1]
	v_pk_mul_f32 v[2:3], v[18:19], v[2:3]
	v_pk_fma_f32 v[14:15], v[38:39], v[14:15], v[0:1]
	v_pk_fma_f32 v[0:1], v[36:37], v[16:17], v[4:5]
	v_pk_mul_f32 v[4:5], v[20:21], v[6:7]
	v_pk_fma_f32 v[6:7], v[34:35], v[10:11], v[2:3]
	v_pk_fma_f32 v[2:3], v[32:33], v[12:13], v[4:5]
	v_cvt_pk_bf16_f32 v0, v0, v1
	v_cvt_pk_bf16_f32 v1, v14, v15
	s_nop 0
	v_cvt_pk_bf16_f32 v2, v2, v3
	v_cvt_pk_bf16_f32 v3, v6, v7
	global_store_dwordx4 v[8:9], v[0:3], off offset:256
	s_cbranch_vccnz .LBB0_988
	s_andn2_b64 vcc, exec, s[10:11]
	s_cbranch_vccnz .LBB0_987
	s_branch .LBB0_987
